# speedup vs baseline: 1.0510x; 1.0052x over previous
.LBB0_609:
	s_setprio 1
	v_ashrrev_i32_e32 v109, 31, v108
	v_lshlrev_b64 v[144:145], 10, v[108:109]
	v_add_u32_e32 v12, v1, v110
	v_mov_b32_e32 v146, v252
	v_mov_b32_e32 v147, v253
	v_readlane_b32 s48, v254, 40
	v_readlane_b32 s56, v254, 48
	v_readlane_b32 s57, v254, 49
	v_readlane_b32 s49, v254, 41
	v_readlane_b32 s50, v254, 42
	v_readlane_b32 s51, v254, 43
	v_readlane_b32 s52, v254, 44
	v_readlane_b32 s53, v254, 45
	v_readlane_b32 s54, v254, 46
	v_readlane_b32 s55, v254, 47
	v_readlane_b32 s58, v254, 50
	v_readlane_b32 s59, v254, 51
	v_readlane_b32 s60, v254, 52
	v_readlane_b32 s61, v254, 53
	v_readlane_b32 s62, v254, 54
	v_readlane_b32 s63, v254, 55
	ds_write2st64_b32 v107, v246, v247 offset1:1
	ds_write_b128 v12, v[248:251] offset:1024
	ds_read2_b32 v[2:3], v148 offset1:8
	s_waitcnt lgkmcnt(0)
	v_ashrrev_i32_e32 v5, 31, v2
	v_mov_b32_e32 v4, v2
	v_lshlrev_b64 v[4:5], 9, v[4:5]
	v_lshl_add_u64 v[4:5], v[112:113], 0, v[4:5]
	global_load_dwordx4 v[86:89], v[4:5], off
	global_load_dwordx4 v[90:93], v[4:5], off offset:128
	global_load_dwordx4 v[94:97], v[4:5], off offset:256
	global_load_dwordx4 v[98:101], v[4:5], off offset:384
	v_ashrrev_i32_e32 v5, 31, v3
	v_mov_b32_e32 v4, v3
	v_lshlrev_b64 v[2:3], 9, v[4:5]
	v_lshl_add_u64 v[26:27], v[112:113], 0, v[2:3]
	global_load_dwordx4 v[78:81], v[26:27], off
	global_load_dwordx4 v[70:73], v[26:27], off offset:128
	ds_read2_b32 v[34:35], v148 offset0:16 offset1:24
	ds_read2_b32 v[82:83], v148 offset0:32 offset1:40
	ds_read_b128 v[6:9], v156 offset:1024
	ds_read_b128 v[2:5], v156 offset:1040
	global_load_dwordx4 v[102:105], v[26:27], off offset:256
	s_waitcnt lgkmcnt(3)
	v_ashrrev_i32_e32 v29, 31, v34
	v_mov_b32_e32 v28, v34
	v_lshlrev_b64 v[28:29], 9, v[28:29]
	ds_read_b128 v[14:17], v156 offset:1280
	ds_read_b128 v[10:13], v156 offset:1296
	ds_read_b128 v[22:25], v156 offset:1536
	ds_read_b128 v[18:21], v156 offset:1552
	v_lshl_add_u64 v[36:37], v[112:113], 0, v[28:29]
	global_load_dwordx4 v[162:165], v[26:27], off offset:384
	global_load_dwordx4 v[166:169], v[36:37], off
	v_ashrrev_i32_e32 v39, 31, v35
	v_mov_b32_e32 v38, v35
	s_waitcnt lgkmcnt(6)
	v_ashrrev_i32_e32 v35, 31, v82
	v_mov_b32_e32 v34, v82
	v_lshlrev_b64 v[38:39], 9, v[38:39]
	v_lshlrev_b64 v[34:35], 9, v[34:35]
	v_lshl_add_u64 v[38:39], v[112:113], 0, v[38:39]
	v_lshl_add_u64 v[34:35], v[112:113], 0, v[34:35]
	ds_read_b128 v[26:29], v156 offset:1792
	ds_read_b128 v[30:33], v156 offset:1808
	global_load_dwordx4 v[170:173], v[36:37], off offset:128
	global_load_dwordx4 v[74:77], v[36:37], off offset:256
	global_load_dwordx4 v[66:69], v[36:37], off offset:384
	global_load_dwordx4 v[62:65], v[38:39], off
	global_load_dwordx4 v[54:57], v[38:39], off offset:128
	global_load_dwordx4 v[58:61], v[38:39], off offset:256
	global_load_dwordx4 v[50:53], v[38:39], off offset:384
	global_load_dwordx4 v[46:49], v[34:35], off
	global_load_dwordx4 v[42:45], v[34:35], off offset:128
	s_nop 0
	global_load_dwordx4 v[38:41], v[34:35], off offset:256
	s_nop 0
	global_load_dwordx4 v[34:37], v[34:35], off offset:384
	v_ashrrev_i32_e32 v85, 31, v83
	s_waitcnt vmcnt(19)
	v_lshrrev_b32_e32 v82, 4, v86
	v_lshrrev_b32_e32 v84, 4, v87
	v_and_b32_e32 v174, 0xf0f0f0f, v86
	v_and_b32_e32 v176, 0xf0f0f0f, v87
	v_and_b32_e32 v175, 0xf0f0f0f, v82
	v_and_b32_e32 v177, 0xf0f0f0f, v84
	v_and_b32_e32 v86, 0xf0f0f0f, v88
	s_waitcnt vmcnt(15)
	v_lshrrev_b32_e32 v181, 4, v78
	v_and_b32_e32 v192, 0xf0f0f0f, v79
	v_lshrrev_b32_e32 v79, 4, v79
	v_and_b32_e32 v190, 0xf0f0f0f, v78
	v_and_b32_e32 v191, 0xf0f0f0f, v181
	v_and_b32_e32 v193, 0xf0f0f0f, v79
	v_and_b32_e32 v78, 0xf0f0f0f, v80
	v_lshrrev_b32_e32 v195, 4, v80
	v_and_b32_e32 v80, 0xf0f0f0f, v81
	v_lshrrev_b32_e32 v81, 4, v81
	v_and_b32_e32 v79, 0xf0f0f0f, v195
	v_and_b32_e32 v81, 0xf0f0f0f, v81
	v_lshrrev_b32_e32 v87, 4, v88
	v_and_b32_e32 v88, 0xf0f0f0f, v89
	v_lshrrev_b32_e32 v89, 4, v89
	s_waitcnt lgkmcnt(7)
	v_mfma_i32_16x16x64_i8 v[190:193], v[190:193], v[6:9], 0
	v_and_b32_e32 v87, 0xf0f0f0f, v87
	v_and_b32_e32 v89, 0xf0f0f0f, v89
	s_waitcnt vmcnt(14)
	v_lshrrev_b32_e32 v197, 4, v70
	v_and_b32_e32 v196, 0xf0f0f0f, v71
	v_lshrrev_b32_e32 v71, 4, v71
	v_mfma_i32_16x16x64_i8 v[174:177], v[174:177], v[6:9], 0
	v_and_b32_e32 v194, 0xf0f0f0f, v70
	v_and_b32_e32 v195, 0xf0f0f0f, v197
	v_and_b32_e32 v197, 0xf0f0f0f, v71
	v_lshrrev_b32_e32 v179, 4, v90
	v_and_b32_e32 v180, 0xf0f0f0f, v91
	v_lshrrev_b32_e32 v91, 4, v91
	s_waitcnt lgkmcnt(6)
	v_mfma_i32_16x16x64_i8 v[78:81], v[78:81], v[2:5], v[190:193]
	v_and_b32_e32 v178, 0xf0f0f0f, v90
	v_and_b32_e32 v179, 0xf0f0f0f, v179
	v_and_b32_e32 v181, 0xf0f0f0f, v91
	v_and_b32_e32 v70, 0xf0f0f0f, v72
	v_lshrrev_b32_e32 v199, 4, v72
	v_and_b32_e32 v72, 0xf0f0f0f, v73
	v_lshrrev_b32_e32 v73, 4, v73
	v_mfma_i32_16x16x64_i8 v[86:89], v[86:89], v[2:5], v[174:177]
	v_and_b32_e32 v71, 0xf0f0f0f, v199
	v_and_b32_e32 v73, 0xf0f0f0f, v73
	v_and_b32_e32 v90, 0xf0f0f0f, v92
	v_lshrrev_b32_e32 v183, 4, v92
	v_and_b32_e32 v92, 0xf0f0f0f, v93
	v_lshrrev_b32_e32 v93, 4, v93
	s_waitcnt lgkmcnt(5)
	v_mfma_i32_16x16x64_i8 v[78:81], v[194:197], v[14:17], v[78:81]
	v_and_b32_e32 v91, 0xf0f0f0f, v183
	v_and_b32_e32 v93, 0xf0f0f0f, v93
	s_waitcnt vmcnt(13)
	v_lshrrev_b32_e32 v201, 4, v102
	v_and_b32_e32 v200, 0xf0f0f0f, v103
	v_lshrrev_b32_e32 v103, 4, v103
	v_mfma_i32_16x16x64_i8 v[86:89], v[178:181], v[14:17], v[86:89]
	v_and_b32_e32 v198, 0xf0f0f0f, v102
	v_and_b32_e32 v199, 0xf0f0f0f, v201
	v_and_b32_e32 v201, 0xf0f0f0f, v103
	v_lshrrev_b32_e32 v185, 4, v94
	v_and_b32_e32 v184, 0xf0f0f0f, v95
	v_lshrrev_b32_e32 v95, 4, v95
	s_waitcnt lgkmcnt(4)
	v_mfma_i32_16x16x64_i8 v[70:73], v[70:73], v[10:13], v[78:81]
	v_and_b32_e32 v182, 0xf0f0f0f, v94
	s_waitcnt vmcnt(12)
	v_and_b32_e32 v202, 0xf0f0f0f, v162
	v_lshrrev_b32_e32 v211, 4, v162
	s_waitcnt vmcnt(11)
	v_lshrrev_b32_e32 v162, 4, v166
	v_lshrrev_b32_e32 v82, 4, v167
	v_and_b32_e32 v183, 0xf0f0f0f, v185
	v_and_b32_e32 v185, 0xf0f0f0f, v95
	v_and_b32_e32 v102, 0xf0f0f0f, v104
	v_lshrrev_b32_e32 v203, 4, v104
	v_and_b32_e32 v104, 0xf0f0f0f, v105
	v_lshrrev_b32_e32 v105, 4, v105
	v_and_b32_e32 v204, 0xf0f0f0f, v166
	v_and_b32_e32 v206, 0xf0f0f0f, v167
	v_and_b32_e32 v205, 0xf0f0f0f, v162
	v_and_b32_e32 v207, 0xf0f0f0f, v82
	v_mfma_i32_16x16x64_i8 v[86:89], v[90:93], v[10:13], v[86:89]
	v_and_b32_e32 v103, 0xf0f0f0f, v203
	v_and_b32_e32 v105, 0xf0f0f0f, v105
	v_and_b32_e32 v94, 0xf0f0f0f, v96
	v_lshrrev_b32_e32 v187, 4, v96
	v_and_b32_e32 v96, 0xf0f0f0f, v97
	v_lshrrev_b32_e32 v97, 4, v97
	s_waitcnt lgkmcnt(3)
	v_mfma_i32_16x16x64_i8 v[70:73], v[198:201], v[22:25], v[70:73]
	v_lshrrev_b32_e32 v82, 4, v168
	v_and_b32_e32 v95, 0xf0f0f0f, v187
	v_and_b32_e32 v97, 0xf0f0f0f, v97
	v_and_b32_e32 v167, 0xf0f0f0f, v82
	v_lshrrev_b32_e32 v82, 4, v163
	v_mfma_i32_16x16x64_i8 v[78:81], v[182:185], v[22:25], v[86:89]
	v_and_b32_e32 v203, 0xf0f0f0f, v211
	v_lshrrev_b32_e32 v189, 4, v98
	v_and_b32_e32 v188, 0xf0f0f0f, v99
	v_mfma_i32_16x16x64_i8 v[206:209], v[204:207], v[6:9], 0
	v_and_b32_e32 v204, 0xf0f0f0f, v163
	v_and_b32_e32 v205, 0xf0f0f0f, v82
	v_lshrrev_b32_e32 v99, 4, v99
	v_lshrrev_b32_e32 v84, 4, v169
	s_waitcnt lgkmcnt(2)
	v_mfma_i32_16x16x64_i8 v[70:73], v[102:105], v[18:21], v[70:73]
	v_and_b32_e32 v186, 0xf0f0f0f, v98
	v_and_b32_e32 v166, 0xf0f0f0f, v168
	v_and_b32_e32 v168, 0xf0f0f0f, v169
	v_and_b32_e32 v169, 0xf0f0f0f, v84
	v_and_b32_e32 v187, 0xf0f0f0f, v189
	v_and_b32_e32 v189, 0xf0f0f0f, v99
	v_lshrrev_b32_e32 v84, 4, v164
	v_lshrrev_b32_e32 v91, 4, v165
	v_mfma_i32_16x16x64_i8 v[78:81], v[94:97], v[18:21], v[78:81]
	v_and_b32_e32 v162, 0xf0f0f0f, v164
	v_and_b32_e32 v164, 0xf0f0f0f, v165
	v_and_b32_e32 v163, 0xf0f0f0f, v84
	v_and_b32_e32 v165, 0xf0f0f0f, v91
	v_and_b32_e32 v98, 0xf0f0f0f, v100
	v_lshrrev_b32_e32 v210, 4, v100
	v_and_b32_e32 v100, 0xf0f0f0f, v101
	v_lshrrev_b32_e32 v101, 4, v101
	s_waitcnt vmcnt(10)
	v_lshrrev_b32_e32 v87, 4, v170
	v_lshrrev_b32_e32 v89, 4, v171
	s_waitcnt lgkmcnt(1)
	v_mfma_i32_16x16x64_i8 v[70:73], v[202:205], v[26:29], v[70:73]
	v_and_b32_e32 v86, 0xf0f0f0f, v170
	v_and_b32_e32 v88, 0xf0f0f0f, v171
	v_and_b32_e32 v99, 0xf0f0f0f, v210
	v_and_b32_e32 v101, 0xf0f0f0f, v101
	v_and_b32_e32 v87, 0xf0f0f0f, v87
	v_and_b32_e32 v89, 0xf0f0f0f, v89
	v_mfma_i32_16x16x64_i8 v[166:169], v[166:169], v[2:5], v[206:209]
	v_lshrrev_b32_e32 v82, 4, v172
	v_and_b32_e32 v90, 0xf0f0f0f, v172
	v_and_b32_e32 v92, 0xf0f0f0f, v173
	v_mfma_i32_16x16x64_i8 v[78:81], v[186:189], v[26:29], v[78:81]
	v_and_b32_e32 v91, 0xf0f0f0f, v82
	v_mov_b32_e32 v84, v83
	s_waitcnt vmcnt(3)
	v_and_b32_e32 v170, 0xf0f0f0f, v49
	s_waitcnt lgkmcnt(0)
	v_mfma_i32_16x16x64_i8 v[94:97], v[162:165], v[30:33], v[70:73]
	v_and_b32_e32 v162, 0xf0f0f0f, v56
	v_and_b32_e32 v164, 0xf0f0f0f, v57
	s_nop 0
	v_lshrrev_b32_e32 v70, 4, v173
	v_and_b32_e32 v93, 0xf0f0f0f, v70
	v_mfma_i32_16x16x64_i8 v[102:105], v[98:101], v[30:33], v[78:81]
	s_nop 1
	v_cndmask_b32_e32 v94, v95, v94, vcc
	v_mfma_i32_16x16x64_i8 v[70:73], v[86:89], v[14:17], v[166:169]
	v_lshlrev_b64 v[78:79], 9, v[84:85]
	v_lshl_add_u64 v[82:83], v[112:113], 0, v[78:79]
	v_and_b32_e32 v78, 0xf0f0f0f, v74
	v_lshrrev_b32_e32 v74, 4, v74
	v_and_b32_e32 v79, 0xf0f0f0f, v74
	v_lshrrev_b32_e32 v74, 4, v75
	v_and_b32_e32 v80, 0xf0f0f0f, v75
	v_and_b32_e32 v81, 0xf0f0f0f, v74
	v_mfma_i32_16x16x64_i8 v[70:73], v[90:93], v[10:13], v[70:73]
	v_and_b32_e32 v74, 0xf0f0f0f, v76
	v_lshrrev_b32_e32 v75, 4, v76
	v_and_b32_e32 v76, 0xf0f0f0f, v77
	v_lshrrev_b32_e32 v77, 4, v77
	v_and_b32_e32 v75, 0xf0f0f0f, v75
	v_and_b32_e32 v77, 0xf0f0f0f, v77
	v_mfma_i32_16x16x64_i8 v[70:73], v[78:81], v[22:25], v[70:73]
	global_load_dwordx4 v[90:93], v[82:83], off
	global_load_dwordx4 v[86:89], v[82:83], off offset:128
	ds_read2_b32 v[166:167], v148 offset0:48 offset1:56
	v_mfma_i32_16x16x64_i8 v[70:73], v[74:77], v[18:21], v[70:73]
	v_and_b32_e32 v74, 0xf0f0f0f, v66
	v_lshrrev_b32_e32 v66, 4, v66
	v_and_b32_e32 v75, 0xf0f0f0f, v66
	v_lshrrev_b32_e32 v66, 4, v67
	v_and_b32_e32 v76, 0xf0f0f0f, v67
	v_and_b32_e32 v77, 0xf0f0f0f, v66
	v_and_b32_e32 v66, 0xf0f0f0f, v68
	v_lshrrev_b32_e32 v67, 4, v68
	v_and_b32_e32 v68, 0xf0f0f0f, v69
	v_lshrrev_b32_e32 v69, 4, v69
	v_and_b32_e32 v67, 0xf0f0f0f, v67
	v_and_b32_e32 v69, 0xf0f0f0f, v69
	v_mfma_i32_16x16x64_i8 v[74:77], v[74:77], v[26:29], v[70:73]
	global_load_dwordx4 v[78:81], v[82:83], off offset:256
	s_nop 1
	global_load_dwordx4 v[70:73], v[82:83], off offset:384
	s_waitcnt lgkmcnt(0)
	v_ashrrev_i32_e32 v83, 31, v166
	v_mov_b32_e32 v82, v166
	v_mfma_i32_16x16x64_i8 v[98:101], v[66:69], v[30:33], v[74:77]
	v_and_b32_e32 v66, 0xf0f0f0f, v62
	v_lshrrev_b32_e32 v62, 4, v62
	v_and_b32_e32 v67, 0xf0f0f0f, v62
	v_lshrrev_b32_e32 v62, 4, v63
	v_and_b32_e32 v68, 0xf0f0f0f, v63
	v_and_b32_e32 v69, 0xf0f0f0f, v62
	v_and_b32_e32 v62, 0xf0f0f0f, v64
	v_lshrrev_b32_e32 v63, 4, v64
	v_and_b32_e32 v64, 0xf0f0f0f, v65
	v_lshrrev_b32_e32 v65, 4, v65
	v_and_b32_e32 v63, 0xf0f0f0f, v63
	v_and_b32_e32 v65, 0xf0f0f0f, v65
	v_mfma_i32_16x16x64_i8 v[66:69], v[66:69], v[6:9], 0
	v_lshlrev_b64 v[74:75], 9, v[82:83]
	v_lshl_add_u64 v[168:169], v[112:113], 0, v[74:75]
	v_mfma_i32_16x16x64_i8 v[62:65], v[62:65], v[2:5], v[66:69]
	s_nop 4
	v_and_b32_e32 v66, 0xf0f0f0f, v54
	v_lshrrev_b32_e32 v54, 4, v54
	v_and_b32_e32 v67, 0xf0f0f0f, v54
	v_lshrrev_b32_e32 v54, 4, v55
	v_and_b32_e32 v68, 0xf0f0f0f, v55
	v_and_b32_e32 v69, 0xf0f0f0f, v54
	v_lshrrev_b32_e32 v54, 4, v56
	v_and_b32_e32 v163, 0xf0f0f0f, v54
	v_lshrrev_b32_e32 v54, 4, v57
	v_and_b32_e32 v165, 0xf0f0f0f, v54
	v_mfma_i32_16x16x64_i8 v[66:69], v[66:69], v[14:17], v[62:65]
	global_load_dwordx4 v[82:85], v[168:169], off
	global_load_dwordx4 v[74:77], v[168:169], off offset:128
	s_nop 0
	global_load_dwordx4 v[62:65], v[168:169], off offset:256
	global_load_dwordx4 v[54:57], v[168:169], off offset:384
	v_and_b32_e32 v168, 0xf0f0f0f, v48
	v_mfma_i32_16x16x64_i8 v[66:69], v[162:165], v[10:13], v[66:69]
	v_and_b32_e32 v162, 0xf0f0f0f, v58
	v_lshrrev_b32_e32 v58, 4, v58
	v_and_b32_e32 v163, 0xf0f0f0f, v58
	v_lshrrev_b32_e32 v58, 4, v59
	v_and_b32_e32 v164, 0xf0f0f0f, v59
	v_and_b32_e32 v165, 0xf0f0f0f, v58
	v_and_b32_e32 v58, 0xf0f0f0f, v60
	v_lshrrev_b32_e32 v59, 4, v60
	v_and_b32_e32 v60, 0xf0f0f0f, v61
	v_lshrrev_b32_e32 v61, 4, v61
	v_and_b32_e32 v59, 0xf0f0f0f, v59
	v_and_b32_e32 v61, 0xf0f0f0f, v61
	v_mfma_i32_16x16x64_i8 v[66:69], v[162:165], v[22:25], v[66:69]
	v_ashrrev_i32_e32 v163, 31, v167
	v_mov_b32_e32 v162, v167
	v_lshlrev_b64 v[166:167], 9, v[162:163]
	v_mfma_i32_16x16x64_i8 v[58:61], v[58:61], v[18:21], v[66:69]
	v_and_b32_e32 v162, 0xf0f0f0f, v52
	v_and_b32_e32 v164, 0xf0f0f0f, v53
	v_lshl_add_u64 v[176:177], v[112:113], 0, v[166:167]
	s_nop 0
	v_and_b32_e32 v66, 0xf0f0f0f, v50
	v_lshrrev_b32_e32 v50, 4, v50
	v_and_b32_e32 v67, 0xf0f0f0f, v50
	v_lshrrev_b32_e32 v50, 4, v51
	v_and_b32_e32 v68, 0xf0f0f0f, v51
	v_and_b32_e32 v69, 0xf0f0f0f, v50
	v_lshrrev_b32_e32 v50, 4, v52
	v_and_b32_e32 v163, 0xf0f0f0f, v50
	v_lshrrev_b32_e32 v50, 4, v53
	v_and_b32_e32 v165, 0xf0f0f0f, v50
	v_mfma_i32_16x16x64_i8 v[66:69], v[66:69], v[26:29], v[58:61]
	s_nop 2
	global_load_dwordx4 v[58:61], v[176:177], off
	global_load_dwordx4 v[50:53], v[176:177], off offset:128
	v_mfma_i32_16x16x64_i8 v[164:167], v[162:165], v[30:33], v[66:69]
	v_cndmask_b32_e32 v162, v103, v102, vcc
	v_cndmask_b32_e32 v102, v105, v104, vcc
	s_nop 0
	v_and_b32_e32 v66, 0xf0f0f0f, v46
	v_lshrrev_b32_e32 v46, 4, v46
	v_and_b32_e32 v67, 0xf0f0f0f, v46
	v_lshrrev_b32_e32 v46, 4, v47
	v_and_b32_e32 v68, 0xf0f0f0f, v47
	v_and_b32_e32 v69, 0xf0f0f0f, v46
	v_lshrrev_b32_e32 v46, 4, v48
	v_and_b32_e32 v169, 0xf0f0f0f, v46
	v_lshrrev_b32_e32 v46, 4, v49
	v_and_b32_e32 v171, 0xf0f0f0f, v46
	v_mfma_i32_16x16x64_i8 v[172:175], v[66:69], v[6:9], 0
	v_add_u32_dpp v104, v162, v162 quad_perm:[1,0,3,2] row_mask:0xf bank_mask:0xf bound_ctrl:1
	v_cndmask_b32_e64 v162, 0, v104, s[4:5]
	global_load_dwordx4 v[66:69], v[176:177], off offset:256
	global_load_dwordx4 v[46:49], v[176:177], off offset:384
	v_mfma_i32_16x16x64_i8 v[168:171], v[168:171], v[2:5], v[172:175]
	v_cndmask_b32_e32 v104, v97, v96, vcc
	v_mov_b32_dpp v103, v102 quad_perm:[1,0,3,2] row_mask:0xf bank_mask:0xf bound_ctrl:1
	s_waitcnt vmcnt(14)
	v_and_b32_e32 v172, 0xf0f0f0f, v42
	v_lshrrev_b32_e32 v42, 4, v42
	v_and_b32_e32 v173, 0xf0f0f0f, v42
	v_lshrrev_b32_e32 v42, 4, v43
	v_and_b32_e32 v174, 0xf0f0f0f, v43
	v_and_b32_e32 v175, 0xf0f0f0f, v42
	v_and_b32_e32 v42, 0xf0f0f0f, v44
	v_lshrrev_b32_e32 v43, 4, v44
	v_and_b32_e32 v44, 0xf0f0f0f, v45
	v_lshrrev_b32_e32 v45, 4, v45
	v_and_b32_e32 v43, 0xf0f0f0f, v43
	v_and_b32_e32 v45, 0xf0f0f0f, v45
	v_mfma_i32_16x16x64_i8 v[168:171], v[172:175], v[14:17], v[168:171]
	v_mov_b32_dpp v105, v104 quad_perm:[1,0,3,2] row_mask:0xf bank_mask:0xf bound_ctrl:1
	v_mfma_i32_16x16x64_i8 v[42:45], v[42:45], v[10:13], v[168:171]
	s_waitcnt vmcnt(13)
	s_nop 4
	v_and_b32_e32 v168, 0xf0f0f0f, v38
	v_lshrrev_b32_e32 v38, 4, v38
	v_and_b32_e32 v169, 0xf0f0f0f, v38
	v_lshrrev_b32_e32 v38, 4, v39
	v_and_b32_e32 v170, 0xf0f0f0f, v39
	v_and_b32_e32 v171, 0xf0f0f0f, v38
	v_and_b32_e32 v38, 0xf0f0f0f, v40
	v_lshrrev_b32_e32 v39, 4, v40
	v_and_b32_e32 v40, 0xf0f0f0f, v41
	v_lshrrev_b32_e32 v41, 4, v41
	v_and_b32_e32 v39, 0xf0f0f0f, v39
	v_and_b32_e32 v41, 0xf0f0f0f, v41
	v_mfma_i32_16x16x64_i8 v[42:45], v[168:171], v[22:25], v[42:45]
	s_nop 0
	v_mfma_i32_16x16x64_i8 v[38:41], v[38:41], v[18:21], v[42:45]
	s_waitcnt vmcnt(12)
	s_nop 4
	v_and_b32_e32 v42, 0xf0f0f0f, v34
	v_lshrrev_b32_e32 v34, 4, v34
	v_and_b32_e32 v43, 0xf0f0f0f, v34
	v_lshrrev_b32_e32 v34, 4, v35
	v_and_b32_e32 v44, 0xf0f0f0f, v35
	v_and_b32_e32 v45, 0xf0f0f0f, v34
	v_and_b32_e32 v34, 0xf0f0f0f, v36
	v_lshrrev_b32_e32 v35, 4, v36
	v_and_b32_e32 v36, 0xf0f0f0f, v37
	v_lshrrev_b32_e32 v37, 4, v37
	v_and_b32_e32 v35, 0xf0f0f0f, v35
	v_and_b32_e32 v37, 0xf0f0f0f, v37
	v_mfma_i32_16x16x64_i8 v[38:41], v[42:45], v[26:29], v[38:41]
	v_add_u32_dpp v42, v94, v94 quad_perm:[1,0,3,2] row_mask:0xf bank_mask:0xf bound_ctrl:1
	s_waitcnt vmcnt(11)
	v_lshrrev_b32_e32 v43, 4, v92
	v_lshrrev_b32_e32 v45, 4, v93
	v_mfma_i32_16x16x64_i8 v[34:37], v[34:37], v[30:33], v[38:41]
	v_cndmask_b32_e64 v94, v162, v42, s[6:7]
	v_and_b32_e32 v42, 0xf0f0f0f, v92
	v_and_b32_e32 v43, 0xf0f0f0f, v43
	v_lshrrev_b32_e32 v39, 4, v90
	v_lshrrev_b32_e32 v41, 4, v91
	v_and_b32_e32 v38, 0xf0f0f0f, v90
	v_and_b32_e32 v39, 0xf0f0f0f, v39
	v_and_b32_e32 v40, 0xf0f0f0f, v91
	v_and_b32_e32 v41, 0xf0f0f0f, v41
	v_and_b32_e32 v44, 0xf0f0f0f, v93
	v_and_b32_e32 v45, 0xf0f0f0f, v45
	v_mfma_i32_16x16x64_i8 v[38:41], v[38:41], v[6:9], 0
	v_cndmask_b32_e32 v90, v99, v98, vcc
	v_cndmask_b32_e32 v91, v165, v164, vcc
	v_cndmask_b32_e32 v162, v101, v100, vcc
	v_mfma_i32_16x16x64_i8 v[38:41], v[42:45], v[2:5], v[38:41]
	s_waitcnt vmcnt(10)
	v_lshrrev_b32_e32 v43, 4, v86
	v_lshrrev_b32_e32 v45, 4, v87
	v_and_b32_e32 v42, 0xf0f0f0f, v86
	v_and_b32_e32 v43, 0xf0f0f0f, v43
	v_and_b32_e32 v44, 0xf0f0f0f, v87
	v_and_b32_e32 v45, 0xf0f0f0f, v45
	v_and_b32_e32 v86, 0xf0f0f0f, v88
	v_lshrrev_b32_e32 v87, 4, v88
	v_and_b32_e32 v88, 0xf0f0f0f, v89
	v_lshrrev_b32_e32 v89, 4, v89
	v_and_b32_e32 v87, 0xf0f0f0f, v87
	v_and_b32_e32 v89, 0xf0f0f0f, v89
	v_mfma_i32_16x16x64_i8 v[38:41], v[42:45], v[14:17], v[38:41]
	v_add_u32_dpp v42, v90, v90 quad_perm:[1,0,3,2] row_mask:0xf bank_mask:0xf bound_ctrl:1
	s_waitcnt vmcnt(9)
	v_lshrrev_b32_e32 v43, 4, v78
	v_lshrrev_b32_e32 v45, 4, v79
	v_cndmask_b32_e64 v90, v94, v42, s[8:9]
	v_and_b32_e32 v42, 0xf0f0f0f, v78
	v_and_b32_e32 v43, 0xf0f0f0f, v43
	v_and_b32_e32 v44, 0xf0f0f0f, v79
	v_and_b32_e32 v45, 0xf0f0f0f, v45
	v_mfma_i32_16x16x64_i8 v[38:41], v[86:89], v[10:13], v[38:41]
	v_and_b32_e32 v78, 0xf0f0f0f, v80
	v_lshrrev_b32_e32 v79, 4, v80
	v_and_b32_e32 v80, 0xf0f0f0f, v81
	v_lshrrev_b32_e32 v81, 4, v81
	v_and_b32_e32 v79, 0xf0f0f0f, v79
	v_and_b32_e32 v81, 0xf0f0f0f, v81
	v_mfma_i32_16x16x64_i8 v[38:41], v[42:45], v[22:25], v[38:41]
	ds_read2_b32 v[94:95], v148 offset0:64 offset1:72
	s_waitcnt vmcnt(8)
	v_lshrrev_b32_e32 v43, 4, v70
	v_lshrrev_b32_e32 v45, 4, v71
	v_and_b32_e32 v42, 0xf0f0f0f, v70
	v_and_b32_e32 v43, 0xf0f0f0f, v43
	v_and_b32_e32 v44, 0xf0f0f0f, v71
	v_and_b32_e32 v45, 0xf0f0f0f, v45
	v_mfma_i32_16x16x64_i8 v[38:41], v[78:81], v[18:21], v[38:41]
	v_and_b32_e32 v70, 0xf0f0f0f, v72
	v_lshrrev_b32_e32 v71, 4, v72
	v_and_b32_e32 v72, 0xf0f0f0f, v73
	v_lshrrev_b32_e32 v73, 4, v73
	s_waitcnt lgkmcnt(0)
	v_ashrrev_i32_e32 v79, 31, v94
	v_mov_b32_e32 v78, v94
	v_and_b32_e32 v71, 0xf0f0f0f, v71
	v_and_b32_e32 v73, 0xf0f0f0f, v73
	v_lshlrev_b64 v[78:79], 9, v[78:79]
	v_mfma_i32_16x16x64_i8 v[38:41], v[42:45], v[26:29], v[38:41]
	v_add_u32_dpp v42, v91, v91 quad_perm:[1,0,3,2] row_mask:0xf bank_mask:0xf bound_ctrl:1
	s_waitcnt vmcnt(7)
	v_lshrrev_b32_e32 v43, 4, v82
	v_lshrrev_b32_e32 v45, 4, v83
	v_lshl_add_u64 v[78:79], v[112:113], 0, v[78:79]
	v_cndmask_b32_e32 v164, v167, v166, vcc
	v_cndmask_b32_e64 v182, v90, v42, s[10:11]
	v_and_b32_e32 v42, 0xf0f0f0f, v82
	v_and_b32_e32 v43, 0xf0f0f0f, v43
	v_and_b32_e32 v44, 0xf0f0f0f, v83
	v_and_b32_e32 v45, 0xf0f0f0f, v45
	global_load_dwordx4 v[90:93], v[78:79], off
	global_load_dwordx4 v[166:169], v[78:79], off offset:128
	global_load_dwordx4 v[98:101], v[78:79], off offset:256
	global_load_dwordx4 v[86:89], v[78:79], off offset:384
	v_mfma_i32_16x16x64_i8 v[38:41], v[70:73], v[30:33], v[38:41]
	v_lshrrev_b32_e32 v71, 4, v84
	v_lshrrev_b32_e32 v73, 4, v85
	v_and_b32_e32 v70, 0xf0f0f0f, v84
	v_and_b32_e32 v71, 0xf0f0f0f, v71
	v_and_b32_e32 v72, 0xf0f0f0f, v85
	v_and_b32_e32 v73, 0xf0f0f0f, v73
	v_mfma_i32_16x16x64_i8 v[42:45], v[42:45], v[6:9], 0
	s_nop 0
	v_cndmask_b32_e32 v38, v39, v38, vcc
	v_mov_b32_dpp v163, v162 quad_perm:[1,0,3,2] row_mask:0xf bank_mask:0xf bound_ctrl:1
	v_mov_b32_dpp v165, v164 quad_perm:[1,0,3,2] row_mask:0xf bank_mask:0xf bound_ctrl:1
	v_mfma_i32_16x16x64_i8 v[42:45], v[70:73], v[2:5], v[42:45]
	s_waitcnt vmcnt(10)
	v_lshrrev_b32_e32 v71, 4, v74
	v_lshrrev_b32_e32 v73, 4, v75
	v_and_b32_e32 v70, 0xf0f0f0f, v74
	v_and_b32_e32 v71, 0xf0f0f0f, v71
	v_and_b32_e32 v72, 0xf0f0f0f, v75
	v_and_b32_e32 v73, 0xf0f0f0f, v73
	v_and_b32_e32 v74, 0xf0f0f0f, v76
	v_lshrrev_b32_e32 v75, 4, v76
	v_and_b32_e32 v76, 0xf0f0f0f, v77
	v_lshrrev_b32_e32 v77, 4, v77
	v_and_b32_e32 v75, 0xf0f0f0f, v75
	v_and_b32_e32 v77, 0xf0f0f0f, v77
	v_mfma_i32_16x16x64_i8 v[42:45], v[70:73], v[14:17], v[42:45]
	s_waitcnt vmcnt(9)
	v_and_b32_e32 v70, 0xf0f0f0f, v62
	v_lshrrev_b32_e32 v62, 4, v62
	v_and_b32_e32 v71, 0xf0f0f0f, v62
	v_lshrrev_b32_e32 v62, 4, v63
	v_and_b32_e32 v72, 0xf0f0f0f, v63
	v_and_b32_e32 v73, 0xf0f0f0f, v62
	v_mfma_i32_16x16x64_i8 v[42:45], v[74:77], v[10:13], v[42:45]
	v_and_b32_e32 v62, 0xf0f0f0f, v64
	v_lshrrev_b32_e32 v63, 4, v64
	v_and_b32_e32 v64, 0xf0f0f0f, v65
	v_lshrrev_b32_e32 v65, 4, v65
	v_and_b32_e32 v63, 0xf0f0f0f, v63
	v_and_b32_e32 v65, 0xf0f0f0f, v65
	v_mfma_i32_16x16x64_i8 v[42:45], v[70:73], v[22:25], v[42:45]
	v_ashrrev_i32_e32 v71, 31, v95
	v_mov_b32_e32 v70, v95
	v_lshlrev_b64 v[70:71], 9, v[70:71]
	v_mfma_i32_16x16x64_i8 v[42:45], v[62:65], v[18:21], v[42:45]
	s_waitcnt vmcnt(8)
	v_and_b32_e32 v62, 0xf0f0f0f, v54
	v_lshrrev_b32_e32 v54, 4, v54
	v_and_b32_e32 v63, 0xf0f0f0f, v54
	v_lshrrev_b32_e32 v54, 4, v55
	v_and_b32_e32 v64, 0xf0f0f0f, v55
	v_and_b32_e32 v65, 0xf0f0f0f, v54
	v_and_b32_e32 v54, 0xf0f0f0f, v56
	v_lshrrev_b32_e32 v55, 4, v56
	v_and_b32_e32 v56, 0xf0f0f0f, v57
	v_lshrrev_b32_e32 v57, 4, v57
	v_and_b32_e32 v55, 0xf0f0f0f, v55
	v_and_b32_e32 v57, 0xf0f0f0f, v57
	v_mfma_i32_16x16x64_i8 v[42:45], v[62:65], v[26:29], v[42:45]
	v_lshl_add_u64 v[62:63], v[112:113], 0, v[70:71]
	global_load_dwordx4 v[94:97], v[62:63], off
	global_load_dwordx4 v[74:77], v[62:63], off offset:128
	s_waitcnt vmcnt(3)
	v_and_b32_e32 v180, 0xf0f0f0f, v101
	v_mfma_i32_16x16x64_i8 v[70:73], v[54:57], v[30:33], v[42:45]
	v_lshrrev_b32_e32 v54, 4, v60
	s_waitcnt vmcnt(1)
	v_lshrrev_b32_e32 v39, 4, v94
	v_lshrrev_b32_e32 v43, 4, v58
	v_lshrrev_b32_e32 v45, 4, v59
	v_and_b32_e32 v42, 0xf0f0f0f, v58
	v_and_b32_e32 v43, 0xf0f0f0f, v43
	v_and_b32_e32 v44, 0xf0f0f0f, v59
	v_and_b32_e32 v45, 0xf0f0f0f, v45
	v_and_b32_e32 v59, 0xf0f0f0f, v54
	v_lshrrev_b32_e32 v54, 4, v61
	v_and_b32_e32 v58, 0xf0f0f0f, v60
	v_and_b32_e32 v60, 0xf0f0f0f, v61
	v_and_b32_e32 v61, 0xf0f0f0f, v54
	v_mfma_i32_16x16x64_i8 v[42:45], v[42:45], v[6:9], 0
	global_load_dwordx4 v[82:85], v[62:63], off offset:256
	global_load_dwordx4 v[54:57], v[62:63], off offset:384
	ds_read2_b32 v[174:175], v148 offset0:80 offset1:88
	s_waitcnt lgkmcnt(0)
	v_ashrrev_i32_e32 v177, 31, v175
	v_mfma_i32_16x16x64_i8 v[42:45], v[58:61], v[2:5], v[42:45]
	v_and_b32_e32 v58, 0xf0f0f0f, v50
	v_lshrrev_b32_e32 v50, 4, v50
	v_and_b32_e32 v59, 0xf0f0f0f, v50
	v_lshrrev_b32_e32 v50, 4, v51
	v_and_b32_e32 v60, 0xf0f0f0f, v51
	v_and_b32_e32 v61, 0xf0f0f0f, v50
	v_and_b32_e32 v50, 0xf0f0f0f, v52
	v_lshrrev_b32_e32 v51, 4, v52
	v_and_b32_e32 v52, 0xf0f0f0f, v53
	v_lshrrev_b32_e32 v53, 4, v53
	v_and_b32_e32 v51, 0xf0f0f0f, v51
	v_and_b32_e32 v53, 0xf0f0f0f, v53
	v_mfma_i32_16x16x64_i8 v[42:45], v[58:61], v[14:17], v[42:45]
	v_ashrrev_i32_e32 v59, 31, v174
	v_mov_b32_e32 v58, v174
	v_lshlrev_b64 v[62:63], 9, v[58:59]
	v_mfma_i32_16x16x64_i8 v[42:45], v[50:53], v[10:13], v[42:45]
	v_lshrrev_b32_e32 v51, 4, v66
	v_lshrrev_b32_e32 v53, 4, v67
	v_and_b32_e32 v50, 0xf0f0f0f, v66
	v_and_b32_e32 v51, 0xf0f0f0f, v51
	v_and_b32_e32 v52, 0xf0f0f0f, v67
	v_and_b32_e32 v53, 0xf0f0f0f, v53
	v_lshrrev_b32_e32 v59, 4, v68
	v_lshrrev_b32_e32 v61, 4, v69
	v_and_b32_e32 v58, 0xf0f0f0f, v68
	v_and_b32_e32 v59, 0xf0f0f0f, v59
	v_and_b32_e32 v60, 0xf0f0f0f, v69
	v_and_b32_e32 v61, 0xf0f0f0f, v61
	v_mfma_i32_16x16x64_i8 v[42:45], v[50:53], v[22:25], v[42:45]
	v_and_b32_e32 v50, 0xf0f0f0f, v46
	v_lshrrev_b32_e32 v46, 4, v46
	v_and_b32_e32 v51, 0xf0f0f0f, v46
	v_lshrrev_b32_e32 v46, 4, v47
	v_and_b32_e32 v52, 0xf0f0f0f, v47
	v_and_b32_e32 v53, 0xf0f0f0f, v46
	v_mfma_i32_16x16x64_i8 v[42:45], v[58:61], v[18:21], v[42:45]
	v_lshrrev_b32_e32 v46, 4, v48
	v_and_b32_e32 v67, 0xf0f0f0f, v46
	v_lshrrev_b32_e32 v46, 4, v49
	v_and_b32_e32 v66, 0xf0f0f0f, v48
	v_and_b32_e32 v68, 0xf0f0f0f, v49
	v_and_b32_e32 v69, 0xf0f0f0f, v46
	v_mfma_i32_16x16x64_i8 v[42:45], v[50:53], v[26:29], v[42:45]
	v_lshl_add_u64 v[170:171], v[112:113], 0, v[62:63]
	global_load_dwordx4 v[78:81], v[170:171], off
	global_load_dwordx4 v[62:65], v[170:171], off offset:128
	global_load_dwordx4 v[58:61], v[170:171], off offset:256
	global_load_dwordx4 v[46:49], v[170:171], off offset:384
	v_mfma_i32_16x16x64_i8 v[170:173], v[66:69], v[30:33], v[42:45]
	v_lshrrev_b32_e32 v51, 4, v92
	v_lshrrev_b32_e32 v53, 4, v93
	v_and_b32_e32 v50, 0xf0f0f0f, v92
	v_lshrrev_b32_e32 v43, 4, v90
	v_lshrrev_b32_e32 v45, 4, v91
	v_and_b32_e32 v42, 0xf0f0f0f, v90
	v_and_b32_e32 v43, 0xf0f0f0f, v43
	v_and_b32_e32 v44, 0xf0f0f0f, v91
	v_and_b32_e32 v45, 0xf0f0f0f, v45
	v_and_b32_e32 v51, 0xf0f0f0f, v51
	v_and_b32_e32 v52, 0xf0f0f0f, v93
	v_and_b32_e32 v53, 0xf0f0f0f, v53
	v_mfma_i32_16x16x64_i8 v[42:45], v[42:45], v[6:9], 0
	v_mov_b32_e32 v176, v175
	v_lshlrev_b64 v[66:67], 9, v[176:177]
	v_lshl_add_u64 v[178:179], v[112:113], 0, v[66:67]
	v_mfma_i32_16x16x64_i8 v[42:45], v[50:53], v[2:5], v[42:45]
	v_lshrrev_b32_e32 v51, 4, v166
	v_lshrrev_b32_e32 v53, 4, v167
	v_and_b32_e32 v50, 0xf0f0f0f, v166
	v_and_b32_e32 v51, 0xf0f0f0f, v51
	v_and_b32_e32 v52, 0xf0f0f0f, v167
	v_and_b32_e32 v53, 0xf0f0f0f, v53
	v_lshrrev_b32_e32 v66, 4, v168
	v_and_b32_e32 v167, 0xf0f0f0f, v66
	v_lshrrev_b32_e32 v66, 4, v169
	v_and_b32_e32 v166, 0xf0f0f0f, v168
	v_and_b32_e32 v168, 0xf0f0f0f, v169
	v_and_b32_e32 v169, 0xf0f0f0f, v66
	v_mfma_i32_16x16x64_i8 v[174:177], v[50:53], v[14:17], v[42:45]
	global_load_dwordx4 v[90:93], v[178:179], off
	global_load_dwordx4 v[66:69], v[178:179], off offset:128
	global_load_dwordx4 v[50:53], v[178:179], off offset:256
	global_load_dwordx4 v[42:45], v[178:179], off offset:384
	v_and_b32_e32 v178, 0xf0f0f0f, v100
	v_mfma_i32_16x16x64_i8 v[166:169], v[166:169], v[10:13], v[174:177]
	s_nop 2
	v_and_b32_e32 v174, 0xf0f0f0f, v98
	v_lshrrev_b32_e32 v98, 4, v98
	v_and_b32_e32 v175, 0xf0f0f0f, v98
	v_lshrrev_b32_e32 v98, 4, v99
	v_and_b32_e32 v176, 0xf0f0f0f, v99
	v_and_b32_e32 v177, 0xf0f0f0f, v98
	v_lshrrev_b32_e32 v98, 4, v100
	v_and_b32_e32 v179, 0xf0f0f0f, v98
	v_lshrrev_b32_e32 v98, 4, v101
	v_and_b32_e32 v181, 0xf0f0f0f, v98
	v_mfma_i32_16x16x64_i8 v[166:169], v[174:177], v[22:25], v[166:169]
	v_cndmask_b32_e32 v100, v35, v34, vcc
	v_cndmask_b32_e32 v98, v37, v36, vcc
	v_mfma_i32_16x16x64_i8 v[34:37], v[178:181], v[18:21], v[166:169]
	v_add_u32_dpp v100, v100, v100 quad_perm:[1,0,3,2] row_mask:0xf bank_mask:0xf bound_ctrl:1
	v_cndmask_b32_e64 v100, v182, v100, s[12:13]
	v_mov_b32_dpp v99, v98 quad_perm:[1,0,3,2] row_mask:0xf bank_mask:0xf bound_ctrl:1
	s_nop 1
	v_and_b32_e32 v166, 0xf0f0f0f, v86
	v_lshrrev_b32_e32 v86, 4, v86
	v_and_b32_e32 v167, 0xf0f0f0f, v86
	v_lshrrev_b32_e32 v86, 4, v87
	v_and_b32_e32 v168, 0xf0f0f0f, v87
	v_and_b32_e32 v169, 0xf0f0f0f, v86
	v_and_b32_e32 v86, 0xf0f0f0f, v88
	v_lshrrev_b32_e32 v87, 4, v88
	v_and_b32_e32 v88, 0xf0f0f0f, v89
	v_lshrrev_b32_e32 v89, 4, v89
	v_and_b32_e32 v87, 0xf0f0f0f, v87
	v_and_b32_e32 v89, 0xf0f0f0f, v89
	v_mfma_i32_16x16x64_i8 v[34:37], v[166:169], v[26:29], v[34:37]
	s_nop 0
	v_mfma_i32_16x16x64_i8 v[34:37], v[86:89], v[30:33], v[34:37]
	v_and_b32_e32 v87, 0xf0f0f0f, v39
	v_lshrrev_b32_e32 v39, 4, v95
	v_and_b32_e32 v86, 0xf0f0f0f, v94
	v_and_b32_e32 v88, 0xf0f0f0f, v95
	v_and_b32_e32 v89, 0xf0f0f0f, v39
	v_lshrrev_b32_e32 v39, 4, v96
	v_and_b32_e32 v95, 0xf0f0f0f, v39
	v_lshrrev_b32_e32 v39, 4, v97
	v_and_b32_e32 v94, 0xf0f0f0f, v96
	v_and_b32_e32 v96, 0xf0f0f0f, v97
	v_and_b32_e32 v97, 0xf0f0f0f, v39
	v_mfma_i32_16x16x64_i8 v[166:169], v[86:89], v[6:9], 0
	v_cndmask_b32_e32 v86, v41, v40, vcc
	v_add_u32_dpp v88, v38, v38 quad_perm:[1,0,3,2] row_mask:0xf bank_mask:0xf bound_ctrl:1
	v_cndmask_b32_e32 v89, v71, v70, vcc
	v_mfma_i32_16x16x64_i8 v[38:41], v[94:97], v[2:5], v[166:169]
	s_waitcnt vmcnt(10)
	v_and_b32_e32 v94, 0xf0f0f0f, v74
	v_lshrrev_b32_e32 v74, 4, v74
	v_and_b32_e32 v95, 0xf0f0f0f, v74
	v_lshrrev_b32_e32 v74, 4, v75
	v_and_b32_e32 v96, 0xf0f0f0f, v75
	v_and_b32_e32 v97, 0xf0f0f0f, v74
	v_and_b32_e32 v74, 0xf0f0f0f, v76
	v_lshrrev_b32_e32 v75, 4, v76
	v_and_b32_e32 v76, 0xf0f0f0f, v77
	v_lshrrev_b32_e32 v77, 4, v77
	v_and_b32_e32 v75, 0xf0f0f0f, v75
	v_and_b32_e32 v77, 0xf0f0f0f, v77
	v_mfma_i32_16x16x64_i8 v[38:41], v[94:97], v[14:17], v[38:41]
	s_waitcnt vmcnt(9)
	v_lshrrev_b32_e32 v71, 4, v82
	v_cndmask_b32_e32 v70, v73, v72, vcc
	v_and_b32_e32 v73, 0xf0f0f0f, v71
	v_lshrrev_b32_e32 v71, 4, v83
	v_mfma_i32_16x16x64_i8 v[38:41], v[74:77], v[10:13], v[38:41]
	v_and_b32_e32 v72, 0xf0f0f0f, v82
	v_and_b32_e32 v74, 0xf0f0f0f, v83
	v_and_b32_e32 v75, 0xf0f0f0f, v71
	v_lshrrev_b32_e32 v71, 4, v84
	v_and_b32_e32 v83, 0xf0f0f0f, v71
	v_lshrrev_b32_e32 v71, 4, v85
	v_and_b32_e32 v82, 0xf0f0f0f, v84
	v_and_b32_e32 v84, 0xf0f0f0f, v85
	v_and_b32_e32 v85, 0xf0f0f0f, v71
	v_cndmask_b32_e64 v88, v100, v88, s[14:15]
	v_mfma_i32_16x16x64_i8 v[38:41], v[72:75], v[22:25], v[38:41]
	v_add_u32_dpp v72, v89, v89 quad_perm:[1,0,3,2] row_mask:0xf bank_mask:0xf bound_ctrl:1
	v_cndmask_b32_e64 v88, v88, v72, s[16:17]
	s_waitcnt vmcnt(8)
	v_and_b32_e32 v72, 0xf0f0f0f, v54
	v_lshrrev_b32_e32 v54, 4, v54
	v_and_b32_e32 v73, 0xf0f0f0f, v54
	v_lshrrev_b32_e32 v54, 4, v55
	v_and_b32_e32 v74, 0xf0f0f0f, v55
	v_and_b32_e32 v75, 0xf0f0f0f, v54
	v_mfma_i32_16x16x64_i8 v[38:41], v[82:85], v[18:21], v[38:41]
	v_and_b32_e32 v54, 0xf0f0f0f, v56
	v_lshrrev_b32_e32 v55, 4, v56
	v_and_b32_e32 v56, 0xf0f0f0f, v57
	v_lshrrev_b32_e32 v57, 4, v57
	v_and_b32_e32 v55, 0xf0f0f0f, v55
	v_and_b32_e32 v57, 0xf0f0f0f, v57
	v_mfma_i32_16x16x64_i8 v[38:41], v[72:75], v[26:29], v[38:41]
	s_waitcnt vmcnt(7)
	v_lshrrev_b32_e32 v75, 4, v80
	v_lshrrev_b32_e32 v77, 4, v81
	v_and_b32_e32 v74, 0xf0f0f0f, v80
	v_mfma_i32_16x16x64_i8 v[54:57], v[54:57], v[30:33], v[38:41]
	v_and_b32_e32 v75, 0xf0f0f0f, v75
	v_and_b32_e32 v76, 0xf0f0f0f, v81
	v_and_b32_e32 v77, 0xf0f0f0f, v77
	v_lshrrev_b32_e32 v39, 4, v78
	v_lshrrev_b32_e32 v41, 4, v79
	v_and_b32_e32 v38, 0xf0f0f0f, v78
	v_and_b32_e32 v39, 0xf0f0f0f, v39
	v_and_b32_e32 v40, 0xf0f0f0f, v79
	v_and_b32_e32 v41, 0xf0f0f0f, v41
	v_cndmask_b32_e32 v82, v171, v170, vcc
	v_cndmask_b32_e32 v72, v173, v172, vcc
	v_mfma_i32_16x16x64_i8 v[38:41], v[38:41], v[6:9], 0
	v_add_u32_dpp v78, v82, v82 quad_perm:[1,0,3,2] row_mask:0xf bank_mask:0xf bound_ctrl:1
	v_cndmask_b32_e64 v190, v88, v78, s[18:19]
	ds_read2_b32 v[88:89], v148 offset0:96 offset1:104
	v_mfma_i32_16x16x64_i8 v[38:41], v[74:77], v[2:5], v[38:41]
	s_waitcnt vmcnt(6)
	v_and_b32_e32 v74, 0xf0f0f0f, v62
	v_lshrrev_b32_e32 v62, 4, v62
	v_and_b32_e32 v75, 0xf0f0f0f, v62
	v_lshrrev_b32_e32 v62, 4, v63
	v_and_b32_e32 v76, 0xf0f0f0f, v63
	v_and_b32_e32 v77, 0xf0f0f0f, v62
	v_and_b32_e32 v62, 0xf0f0f0f, v64
	v_lshrrev_b32_e32 v63, 4, v64
	v_and_b32_e32 v64, 0xf0f0f0f, v65
	v_lshrrev_b32_e32 v65, 4, v65
	v_and_b32_e32 v63, 0xf0f0f0f, v63
	v_and_b32_e32 v65, 0xf0f0f0f, v65
	v_mfma_i32_16x16x64_i8 v[38:41], v[74:77], v[14:17], v[38:41]
	s_waitcnt lgkmcnt(0)
	v_ashrrev_i32_e32 v75, 31, v88
	v_mov_b32_e32 v74, v88
	v_lshlrev_b64 v[74:75], 9, v[74:75]
	v_mfma_i32_16x16x64_i8 v[38:41], v[62:65], v[10:13], v[38:41]
	s_waitcnt vmcnt(5)
	v_and_b32_e32 v62, 0xf0f0f0f, v58
	v_lshrrev_b32_e32 v58, 4, v58
	v_and_b32_e32 v63, 0xf0f0f0f, v58
	v_lshrrev_b32_e32 v58, 4, v59
	v_and_b32_e32 v64, 0xf0f0f0f, v59
	v_and_b32_e32 v65, 0xf0f0f0f, v58
	v_lshl_add_u64 v[82:83], v[112:113], 0, v[74:75]
	v_and_b32_e32 v58, 0xf0f0f0f, v60
	v_mfma_i32_16x16x64_i8 v[38:41], v[62:65], v[22:25], v[38:41]
	global_load_dwordx4 v[62:65], v[82:83], off
	global_load_dwordx4 v[74:77], v[82:83], off offset:128
	global_load_dwordx4 v[78:81], v[82:83], off offset:256
	s_nop 0
	global_load_dwordx4 v[82:85], v[82:83], off offset:384
	v_lshrrev_b32_e32 v59, 4, v60
	v_and_b32_e32 v60, 0xf0f0f0f, v61
	v_lshrrev_b32_e32 v61, 4, v61
	v_and_b32_e32 v59, 0xf0f0f0f, v59
	v_and_b32_e32 v61, 0xf0f0f0f, v61
	v_ashrrev_i32_e32 v95, 31, v89
	v_mov_b32_e32 v94, v89
	v_mfma_i32_16x16x64_i8 v[38:41], v[58:61], v[18:21], v[38:41]
	s_waitcnt vmcnt(8)
	v_and_b32_e32 v58, 0xf0f0f0f, v46
	v_lshrrev_b32_e32 v46, 4, v46
	v_and_b32_e32 v59, 0xf0f0f0f, v46
	v_lshrrev_b32_e32 v46, 4, v47
	v_and_b32_e32 v60, 0xf0f0f0f, v47
	v_and_b32_e32 v61, 0xf0f0f0f, v46
	v_and_b32_e32 v46, 0xf0f0f0f, v48
	v_lshrrev_b32_e32 v47, 4, v48
	v_and_b32_e32 v48, 0xf0f0f0f, v49
	v_lshrrev_b32_e32 v49, 4, v49
	v_and_b32_e32 v47, 0xf0f0f0f, v47
	v_and_b32_e32 v49, 0xf0f0f0f, v49
	v_mfma_i32_16x16x64_i8 v[38:41], v[58:61], v[26:29], v[38:41]
	v_lshlrev_b64 v[88:89], 9, v[94:95]
	v_lshl_add_u64 v[96:97], v[112:113], 0, v[88:89]
	v_mov_b32_dpp v87, v86 quad_perm:[1,0,3,2] row_mask:0xf bank_mask:0xf bound_ctrl:1
	v_mfma_i32_16x16x64_i8 v[58:61], v[46:49], v[30:33], v[38:41]
	s_waitcnt vmcnt(7)
	v_and_b32_e32 v46, 0xf0f0f0f, v92
	v_lshrrev_b32_e32 v47, 4, v92
	v_and_b32_e32 v48, 0xf0f0f0f, v93
	v_lshrrev_b32_e32 v39, 4, v90
	v_lshrrev_b32_e32 v41, 4, v91
	v_and_b32_e32 v38, 0xf0f0f0f, v90
	v_and_b32_e32 v39, 0xf0f0f0f, v39
	v_and_b32_e32 v40, 0xf0f0f0f, v91
	v_and_b32_e32 v41, 0xf0f0f0f, v41
	v_lshrrev_b32_e32 v49, 4, v93
	global_load_dwordx4 v[88:91], v[96:97], off
	global_load_dwordx4 v[92:95], v[96:97], off offset:128
	v_and_b32_e32 v47, 0xf0f0f0f, v47
	v_and_b32_e32 v49, 0xf0f0f0f, v49
	v_mfma_i32_16x16x64_i8 v[38:41], v[38:41], v[6:9], 0
	ds_read2_b32 v[100:101], v148 offset0:112 offset1:120
	global_load_dwordx4 v[166:169], v[96:97], off offset:256
	global_load_dwordx4 v[170:173], v[96:97], off offset:384
	v_cndmask_b32_e32 v96, v35, v34, vcc
	v_mfma_i32_16x16x64_i8 v[38:41], v[46:49], v[2:5], v[38:41]
	s_waitcnt vmcnt(10)
	v_lshrrev_b32_e32 v47, 4, v66
	v_lshrrev_b32_e32 v49, 4, v67
	v_and_b32_e32 v46, 0xf0f0f0f, v66
	v_and_b32_e32 v47, 0xf0f0f0f, v47
	v_and_b32_e32 v48, 0xf0f0f0f, v67
	v_and_b32_e32 v49, 0xf0f0f0f, v49
	v_and_b32_e32 v66, 0xf0f0f0f, v68
	v_lshrrev_b32_e32 v67, 4, v68
	v_and_b32_e32 v68, 0xf0f0f0f, v69
	v_lshrrev_b32_e32 v69, 4, v69
	v_and_b32_e32 v67, 0xf0f0f0f, v67
	v_and_b32_e32 v69, 0xf0f0f0f, v69
	v_mfma_i32_16x16x64_i8 v[38:41], v[46:49], v[14:17], v[38:41]
	s_waitcnt vmcnt(9)
	v_lshrrev_b32_e32 v47, 4, v50
	v_lshrrev_b32_e32 v49, 4, v51
	v_and_b32_e32 v46, 0xf0f0f0f, v50
	v_and_b32_e32 v47, 0xf0f0f0f, v47
	v_and_b32_e32 v48, 0xf0f0f0f, v51
	v_and_b32_e32 v49, 0xf0f0f0f, v49
	v_mfma_i32_16x16x64_i8 v[38:41], v[66:69], v[10:13], v[38:41]
	v_and_b32_e32 v50, 0xf0f0f0f, v52
	v_lshrrev_b32_e32 v51, 4, v52
	v_and_b32_e32 v52, 0xf0f0f0f, v53
	v_lshrrev_b32_e32 v53, 4, v53
	v_and_b32_e32 v51, 0xf0f0f0f, v51
	v_and_b32_e32 v53, 0xf0f0f0f, v53
	v_mfma_i32_16x16x64_i8 v[38:41], v[46:49], v[22:25], v[38:41]
	s_waitcnt vmcnt(8)
	v_and_b32_e32 v46, 0xf0f0f0f, v42
	v_lshrrev_b32_e32 v42, 4, v42
	v_and_b32_e32 v47, 0xf0f0f0f, v42
	v_lshrrev_b32_e32 v42, 4, v43
	v_and_b32_e32 v48, 0xf0f0f0f, v43
	v_and_b32_e32 v49, 0xf0f0f0f, v42
	v_mfma_i32_16x16x64_i8 v[38:41], v[50:53], v[18:21], v[38:41]
	v_and_b32_e32 v42, 0xf0f0f0f, v44
	v_lshrrev_b32_e32 v43, 4, v44
	v_and_b32_e32 v44, 0xf0f0f0f, v45
	v_lshrrev_b32_e32 v45, 4, v45
	v_and_b32_e32 v43, 0xf0f0f0f, v43
	v_and_b32_e32 v45, 0xf0f0f0f, v45
	v_mfma_i32_16x16x64_i8 v[38:41], v[46:49], v[26:29], v[38:41]
	s_waitcnt lgkmcnt(0)
	v_ashrrev_i32_e32 v67, 31, v100
	v_mov_b32_e32 v66, v100
	v_lshlrev_b64 v[46:47], 9, v[66:67]
	v_lshl_add_u64 v[46:47], v[112:113], 0, v[46:47]
	v_mfma_i32_16x16x64_i8 v[174:177], v[42:45], v[30:33], v[38:41]
	s_waitcnt vmcnt(7)
	v_and_b32_e32 v42, 0xf0f0f0f, v64
	v_lshrrev_b32_e32 v43, 4, v64
	v_and_b32_e32 v44, 0xf0f0f0f, v65
	v_and_b32_e32 v38, 0xf0f0f0f, v62
	v_lshrrev_b32_e32 v39, 4, v62
	v_and_b32_e32 v40, 0xf0f0f0f, v63
	v_lshrrev_b32_e32 v41, 4, v63
	v_lshrrev_b32_e32 v45, 4, v65
	global_load_dwordx4 v[178:181], v[46:47], off
	global_load_dwordx4 v[182:185], v[46:47], off offset:128
	global_load_dwordx4 v[186:189], v[46:47], off offset:256
	global_load_dwordx4 v[62:65], v[46:47], off offset:384
	v_and_b32_e32 v39, 0xf0f0f0f, v39
	v_and_b32_e32 v41, 0xf0f0f0f, v41
	v_and_b32_e32 v43, 0xf0f0f0f, v43
	v_and_b32_e32 v45, 0xf0f0f0f, v45
	v_mfma_i32_16x16x64_i8 v[38:41], v[38:41], v[6:9], 0
	s_waitcnt vmcnt(10)
	v_lshrrev_b32_e32 v47, 4, v76
	v_lshrrev_b32_e32 v49, 4, v77
	v_and_b32_e32 v46, 0xf0f0f0f, v76
	v_mfma_i32_16x16x64_i8 v[38:41], v[42:45], v[2:5], v[38:41]
	v_lshrrev_b32_e32 v43, 4, v74
	v_lshrrev_b32_e32 v45, 4, v75
	v_and_b32_e32 v42, 0xf0f0f0f, v74
	v_and_b32_e32 v43, 0xf0f0f0f, v43
	v_and_b32_e32 v44, 0xf0f0f0f, v75
	v_and_b32_e32 v45, 0xf0f0f0f, v45
	v_and_b32_e32 v47, 0xf0f0f0f, v47
	v_and_b32_e32 v48, 0xf0f0f0f, v77
	v_and_b32_e32 v49, 0xf0f0f0f, v49
	v_mfma_i32_16x16x64_i8 v[38:41], v[42:45], v[14:17], v[38:41]
	v_ashrrev_i32_e32 v43, 31, v101
	v_mov_b32_e32 v42, v101
	v_lshlrev_b64 v[50:51], 9, v[42:43]
	s_waitcnt vmcnt(9)
	v_lshrrev_b32_e32 v43, 4, v78
	v_lshrrev_b32_e32 v45, 4, v79
	v_and_b32_e32 v42, 0xf0f0f0f, v78
	v_and_b32_e32 v43, 0xf0f0f0f, v43
	v_and_b32_e32 v44, 0xf0f0f0f, v79
	v_and_b32_e32 v45, 0xf0f0f0f, v45
	v_mfma_i32_16x16x64_i8 v[38:41], v[46:49], v[10:13], v[38:41]
	v_lshrrev_b32_e32 v47, 4, v80
	v_lshrrev_b32_e32 v49, 4, v81
	v_and_b32_e32 v46, 0xf0f0f0f, v80
	v_and_b32_e32 v47, 0xf0f0f0f, v47
	v_and_b32_e32 v48, 0xf0f0f0f, v81
	v_and_b32_e32 v49, 0xf0f0f0f, v49
	v_mfma_i32_16x16x64_i8 v[38:41], v[42:45], v[22:25], v[38:41]
	v_lshl_add_u64 v[78:79], v[112:113], 0, v[50:51]
	s_waitcnt vmcnt(8)
	v_lshrrev_b32_e32 v67, 4, v84
	v_lshrrev_b32_e32 v69, 4, v85
	v_mfma_i32_16x16x64_i8 v[38:41], v[46:49], v[18:21], v[38:41]
	v_lshrrev_b32_e32 v47, 4, v82
	v_lshrrev_b32_e32 v49, 4, v83
	v_and_b32_e32 v46, 0xf0f0f0f, v82
	v_and_b32_e32 v47, 0xf0f0f0f, v47
	v_and_b32_e32 v48, 0xf0f0f0f, v83
	v_and_b32_e32 v49, 0xf0f0f0f, v49
	global_load_dwordx4 v[50:53], v[78:79], off
	global_load_dwordx4 v[42:45], v[78:79], off offset:128
	v_and_b32_e32 v66, 0xf0f0f0f, v84
	v_and_b32_e32 v67, 0xf0f0f0f, v67
	v_and_b32_e32 v68, 0xf0f0f0f, v85
	v_and_b32_e32 v69, 0xf0f0f0f, v69
	v_mfma_i32_16x16x64_i8 v[74:77], v[46:49], v[26:29], v[38:41]
	s_waitcnt vmcnt(9)
	v_lshrrev_b32_e32 v34, 4, v88
	global_load_dwordx4 v[46:49], v[78:79], off offset:256
	global_load_dwordx4 v[38:41], v[78:79], off offset:384
	v_and_b32_e32 v78, 0xf0f0f0f, v90
	v_mfma_i32_16x16x64_i8 v[74:77], v[66:69], v[30:33], v[74:77]
	v_and_b32_e32 v67, 0xf0f0f0f, v34
	v_lshrrev_b32_e32 v34, 4, v89
	v_and_b32_e32 v66, 0xf0f0f0f, v88
	v_and_b32_e32 v68, 0xf0f0f0f, v89
	v_and_b32_e32 v69, 0xf0f0f0f, v34
	v_lshrrev_b32_e32 v34, 4, v90
	v_and_b32_e32 v79, 0xf0f0f0f, v34
	v_lshrrev_b32_e32 v34, 4, v91
	v_and_b32_e32 v80, 0xf0f0f0f, v91
	v_and_b32_e32 v81, 0xf0f0f0f, v34
	v_mfma_i32_16x16x64_i8 v[82:85], v[66:69], v[6:9], 0
	s_waitcnt vmcnt(10)
	v_lshrrev_b32_e32 v68, 4, v92
	v_cndmask_b32_e32 v66, v37, v36, vcc
	v_cndmask_b32_e32 v89, v55, v54, vcc
	v_mfma_i32_16x16x64_i8 v[34:37], v[78:81], v[2:5], v[82:85]
	v_and_b32_e32 v79, 0xf0f0f0f, v68
	v_lshrrev_b32_e32 v68, 4, v93
	v_and_b32_e32 v78, 0xf0f0f0f, v92
	v_and_b32_e32 v80, 0xf0f0f0f, v93
	v_and_b32_e32 v81, 0xf0f0f0f, v68
	v_lshrrev_b32_e32 v68, 4, v94
	v_and_b32_e32 v83, 0xf0f0f0f, v68
	v_lshrrev_b32_e32 v68, 4, v95
	v_and_b32_e32 v82, 0xf0f0f0f, v94
	v_and_b32_e32 v84, 0xf0f0f0f, v95
	v_and_b32_e32 v85, 0xf0f0f0f, v68
	v_mfma_i32_16x16x64_i8 v[34:37], v[78:81], v[14:17], v[34:37]
	v_cndmask_b32_e32 v68, v57, v56, vcc
	s_waitcnt vmcnt(9)
	v_lshrrev_b32_e32 v55, 4, v166
	v_lshrrev_b32_e32 v57, 4, v167
	v_and_b32_e32 v54, 0xf0f0f0f, v166
	v_and_b32_e32 v55, 0xf0f0f0f, v55
	v_and_b32_e32 v56, 0xf0f0f0f, v167
	v_and_b32_e32 v57, 0xf0f0f0f, v57
	v_mfma_i32_16x16x64_i8 v[34:37], v[82:85], v[10:13], v[34:37]
	v_lshrrev_b32_e32 v69, 4, v168
	v_and_b32_e32 v79, 0xf0f0f0f, v69
	v_lshrrev_b32_e32 v69, 4, v169
	v_and_b32_e32 v78, 0xf0f0f0f, v168
	v_and_b32_e32 v80, 0xf0f0f0f, v169
	v_and_b32_e32 v81, 0xf0f0f0f, v69
	v_mfma_i32_16x16x64_i8 v[34:37], v[54:57], v[22:25], v[34:37]
	s_waitcnt vmcnt(8)
	v_lshrrev_b32_e32 v55, 4, v170
	v_lshrrev_b32_e32 v57, 4, v171
	v_and_b32_e32 v54, 0xf0f0f0f, v170
	v_and_b32_e32 v55, 0xf0f0f0f, v55
	v_and_b32_e32 v56, 0xf0f0f0f, v171
	v_and_b32_e32 v57, 0xf0f0f0f, v57
	v_mfma_i32_16x16x64_i8 v[34:37], v[78:81], v[18:21], v[34:37]
	v_cndmask_b32_e32 v91, v59, v58, vcc
	v_lshrrev_b32_e32 v59, 4, v172
	v_and_b32_e32 v79, 0xf0f0f0f, v59
	v_lshrrev_b32_e32 v59, 4, v173
	v_and_b32_e32 v78, 0xf0f0f0f, v172
	v_and_b32_e32 v80, 0xf0f0f0f, v173
	v_and_b32_e32 v81, 0xf0f0f0f, v59
	v_mfma_i32_16x16x64_i8 v[34:37], v[54:57], v[26:29], v[34:37]
	s_waitcnt vmcnt(7)
	v_lshrrev_b32_e32 v55, 4, v178
	v_lshrrev_b32_e32 v57, 4, v179
	v_and_b32_e32 v54, 0xf0f0f0f, v178
	v_and_b32_e32 v55, 0xf0f0f0f, v55
	v_and_b32_e32 v56, 0xf0f0f0f, v179
	v_and_b32_e32 v57, 0xf0f0f0f, v57
	v_cndmask_b32_e32 v58, v61, v60, vcc
	v_lshrrev_b32_e32 v60, 4, v180
	v_mfma_i32_16x16x64_i8 v[34:37], v[78:81], v[30:33], v[34:37]
	v_and_b32_e32 v79, 0xf0f0f0f, v60
	v_lshrrev_b32_e32 v60, 4, v181
	v_and_b32_e32 v78, 0xf0f0f0f, v180
	v_and_b32_e32 v80, 0xf0f0f0f, v181
	v_and_b32_e32 v81, 0xf0f0f0f, v60
	v_mfma_i32_16x16x64_i8 v[54:57], v[54:57], v[6:9], 0
	v_cndmask_b32_e32 v82, v175, v174, vcc
	s_waitcnt vmcnt(6)
	v_lshrrev_b32_e32 v83, 4, v184
	v_lshrrev_b32_e32 v85, 4, v185
	v_mfma_i32_16x16x64_i8 v[54:57], v[78:81], v[2:5], v[54:57]
	v_lshrrev_b32_e32 v79, 4, v182
	v_lshrrev_b32_e32 v81, 4, v183
	v_and_b32_e32 v78, 0xf0f0f0f, v182
	v_and_b32_e32 v79, 0xf0f0f0f, v79
	v_and_b32_e32 v80, 0xf0f0f0f, v183
	v_and_b32_e32 v81, 0xf0f0f0f, v81
	v_add_u32_dpp v93, v82, v82 quad_perm:[1,0,3,2] row_mask:0xf bank_mask:0xf bound_ctrl:1
	v_and_b32_e32 v82, 0xf0f0f0f, v184
	v_and_b32_e32 v83, 0xf0f0f0f, v83
	v_and_b32_e32 v84, 0xf0f0f0f, v185
	v_and_b32_e32 v85, 0xf0f0f0f, v85
	v_mfma_i32_16x16x64_i8 v[54:57], v[78:81], v[14:17], v[54:57]
	s_waitcnt vmcnt(5)
	v_lshrrev_b32_e32 v79, 4, v186
	v_lshrrev_b32_e32 v81, 4, v187
	v_and_b32_e32 v78, 0xf0f0f0f, v186
	v_and_b32_e32 v79, 0xf0f0f0f, v79
	v_and_b32_e32 v80, 0xf0f0f0f, v187
	v_and_b32_e32 v81, 0xf0f0f0f, v81
	v_mfma_i32_16x16x64_i8 v[54:57], v[82:85], v[10:13], v[54:57]
	v_mov_b32_dpp v88, v96 quad_perm:[1,0,3,2] row_mask:0xf bank_mask:0xf bound_ctrl:1
	v_mov_b32_dpp v90, v89 quad_perm:[1,0,3,2] row_mask:0xf bank_mask:0xf bound_ctrl:1
	v_add_u32_e32 v88, v96, v88
	v_lshrrev_b32_e32 v83, 4, v188
	v_lshrrev_b32_e32 v85, 4, v189
	v_mov_b32_dpp v92, v91 quad_perm:[1,0,3,2] row_mask:0xf bank_mask:0xf bound_ctrl:1
	v_add_u32_e32 v89, v89, v90
	v_and_b32_e32 v82, 0xf0f0f0f, v188
	v_and_b32_e32 v83, 0xf0f0f0f, v83
	v_and_b32_e32 v84, 0xf0f0f0f, v189
	v_and_b32_e32 v85, 0xf0f0f0f, v85
	v_mfma_i32_16x16x64_i8 v[54:57], v[78:81], v[22:25], v[54:57]
	v_cndmask_b32_e64 v78, v190, v88, s[26:27]
	v_add_u32_e32 v91, v91, v92
	v_cndmask_b32_e64 v78, v78, v89, s[24:25]
	v_cndmask_b32_e64 v88, v78, v91, s[22:23]
	s_waitcnt vmcnt(4)
	v_and_b32_e32 v78, 0xf0f0f0f, v62
	v_lshrrev_b32_e32 v62, 4, v62
	v_and_b32_e32 v79, 0xf0f0f0f, v62
	v_lshrrev_b32_e32 v62, 4, v63
	v_and_b32_e32 v80, 0xf0f0f0f, v63
	v_and_b32_e32 v81, 0xf0f0f0f, v62
	v_mfma_i32_16x16x64_i8 v[54:57], v[82:85], v[18:21], v[54:57]
	v_lshrrev_b32_e32 v62, 4, v64
	v_and_b32_e32 v83, 0xf0f0f0f, v62
	v_lshrrev_b32_e32 v62, 4, v65
	v_and_b32_e32 v82, 0xf0f0f0f, v64
	v_and_b32_e32 v84, 0xf0f0f0f, v65
	v_and_b32_e32 v85, 0xf0f0f0f, v62
	ds_read_b64 v[64:65], v149
	v_mfma_i32_16x16x64_i8 v[54:57], v[78:81], v[26:29], v[54:57]
	v_cndmask_b32_e64 v63, v88, v93, s[20:21]
	v_cndmask_b32_e32 v88, v75, v74, vcc
	v_cndmask_b32_e32 v62, v77, v76, vcc
	v_mfma_i32_16x16x64_i8 v[74:77], v[82:85], v[30:33], v[54:57]
	s_waitcnt vmcnt(3)
	v_and_b32_e32 v78, 0xf0f0f0f, v50
	v_lshrrev_b32_e32 v50, 4, v50
	v_and_b32_e32 v79, 0xf0f0f0f, v50
	s_waitcnt lgkmcnt(0)
	v_ashrrev_i32_e32 v55, 31, v64
	v_mov_b32_e32 v54, v64
	v_lshl_add_u64 v[56:57], v[54:55], 2, s[56:57]
	global_load_dword v89, v[56:57], off
	v_ashrrev_i32_e32 v57, 31, v65
	v_mov_b32_e32 v56, v65
	v_lshl_add_u64 v[64:65], v[56:57], 2, s[56:57]
	global_load_dword v50, v[64:65], off
	v_and_b32_e32 v80, 0xf0f0f0f, v51
	v_lshrrev_b32_e32 v51, 4, v51
	v_and_b32_e32 v81, 0xf0f0f0f, v51
	v_lshrrev_b32_e32 v51, 4, v52
	v_and_b32_e32 v83, 0xf0f0f0f, v51
	v_lshrrev_b32_e32 v51, 4, v53
	v_and_b32_e32 v82, 0xf0f0f0f, v52
	v_and_b32_e32 v84, 0xf0f0f0f, v53
	v_and_b32_e32 v85, 0xf0f0f0f, v51
	v_mfma_i32_16x16x64_i8 v[78:81], v[78:81], v[6:9], 0
	v_add_u32_dpp v7, v88, v88 quad_perm:[1,0,3,2] row_mask:0xf bank_mask:0xf bound_ctrl:1
	v_cndmask_b32_e64 v51, v63, v7, s[28:29]
	s_waitcnt vmcnt(4)
	v_lshrrev_b32_e32 v7, 4, v42
	v_mfma_i32_16x16x64_i8 v[2:5], v[82:85], v[2:5], v[78:81]
	v_cndmask_b32_e32 v60, v177, v176, vcc
	v_mov_b32_dpp v71, v70 quad_perm:[1,0,3,2] row_mask:0xf bank_mask:0xf bound_ctrl:1
	v_mov_b32_dpp v73, v72 quad_perm:[1,0,3,2] row_mask:0xf bank_mask:0xf bound_ctrl:1
	v_and_b32_e32 v79, 0xf0f0f0f, v7
	v_lshrrev_b32_e32 v7, 4, v43
	v_and_b32_e32 v78, 0xf0f0f0f, v42
	v_and_b32_e32 v80, 0xf0f0f0f, v43
	v_and_b32_e32 v81, 0xf0f0f0f, v7
	v_lshrrev_b32_e32 v7, 4, v44
	v_and_b32_e32 v43, 0xf0f0f0f, v7
	v_lshrrev_b32_e32 v7, 4, v45
	v_and_b32_e32 v42, 0xf0f0f0f, v44
	v_and_b32_e32 v44, 0xf0f0f0f, v45
	v_and_b32_e32 v45, 0xf0f0f0f, v7
	v_mfma_i32_16x16x64_i8 v[14:17], v[78:81], v[14:17], v[2:5]
	v_mov_b32_dpp v67, v66 quad_perm:[1,0,3,2] row_mask:0xf bank_mask:0xf bound_ctrl:1
	v_mov_b32_dpp v69, v68 quad_perm:[1,0,3,2] row_mask:0xf bank_mask:0xf bound_ctrl:1
	v_mov_b32_dpp v59, v58 quad_perm:[1,0,3,2] row_mask:0xf bank_mask:0xf bound_ctrl:1
	s_waitcnt vmcnt(3)
	v_lshrrev_b32_e32 v3, 4, v46
	v_mfma_i32_16x16x64_i8 v[8:11], v[42:45], v[10:13], v[14:17]
	v_and_b32_e32 v13, 0xf0f0f0f, v3
	v_lshrrev_b32_e32 v3, 4, v47
	v_and_b32_e32 v12, 0xf0f0f0f, v46
	v_and_b32_e32 v14, 0xf0f0f0f, v47
	v_and_b32_e32 v15, 0xf0f0f0f, v3
	v_lshrrev_b32_e32 v3, 4, v48
	v_cndmask_b32_e32 v2, v35, v34, vcc
	v_and_b32_e32 v35, 0xf0f0f0f, v3
	v_lshrrev_b32_e32 v3, 4, v49
	v_cndmask_b32_e32 v5, v37, v36, vcc
	v_and_b32_e32 v34, 0xf0f0f0f, v48
	v_and_b32_e32 v36, 0xf0f0f0f, v49
	v_and_b32_e32 v37, 0xf0f0f0f, v3
	v_mfma_i32_16x16x64_i8 v[8:11], v[12:15], v[22:25], v[8:11]
	s_waitcnt vmcnt(2)
	v_lshrrev_b32_e32 v4, 4, v38
	v_and_b32_e32 v13, 0xf0f0f0f, v4
	v_lshrrev_b32_e32 v4, 4, v39
	v_and_b32_e32 v12, 0xf0f0f0f, v38
	v_and_b32_e32 v14, 0xf0f0f0f, v39
	v_and_b32_e32 v15, 0xf0f0f0f, v4
	v_mfma_i32_16x16x64_i8 v[8:11], v[34:37], v[18:21], v[8:11]
	v_lshrrev_b32_e32 v4, 4, v40
	v_and_b32_e32 v17, 0xf0f0f0f, v4
	v_lshrrev_b32_e32 v4, 4, v41
	v_and_b32_e32 v16, 0xf0f0f0f, v40
	v_and_b32_e32 v18, 0xf0f0f0f, v41
	v_and_b32_e32 v19, 0xf0f0f0f, v4
	v_mfma_i32_16x16x64_i8 v[10:13], v[12:15], v[26:29], v[8:11]
	v_add_u32_dpp v2, v2, v2 quad_perm:[1,0,3,2] row_mask:0xf bank_mask:0xf bound_ctrl:1
	v_cndmask_b32_e32 v3, v75, v74, vcc
	v_cndmask_b32_e64 v2, v51, v2, s[30:31]
	v_mfma_i32_16x16x64_i8 v[10:13], v[16:19], v[30:33], v[10:13]
	v_add_u32_dpp v3, v3, v3 quad_perm:[1,0,3,2] row_mask:0xf bank_mask:0xf bound_ctrl:1
	v_cndmask_b32_e64 v2, v2, v3, s[34:35]
	v_cndmask_b32_e32 v8, v77, v76, vcc
	v_mov_b32_dpp v61, v60 quad_perm:[1,0,3,2] row_mask:0xf bank_mask:0xf bound_ctrl:1
	v_mov_b32_dpp v6, v62 quad_perm:[1,0,3,2] row_mask:0xf bank_mask:0xf bound_ctrl:1
	s_nop 2
	v_cndmask_b32_e32 v3, v11, v10, vcc
	v_cndmask_b32_e32 v9, v13, v12, vcc
	v_mov_b32_dpp v7, v5 quad_perm:[1,0,3,2] row_mask:0xf bank_mask:0xf bound_ctrl:1
	v_add_u32_dpp v3, v3, v3 quad_perm:[1,0,3,2] row_mask:0xf bank_mask:0xf bound_ctrl:1
	v_cndmask_b32_e64 v2, v2, v3, s[36:37]
	v_cvt_f32_i32_e32 v2, v2
	v_mov_b32_dpp v10, v8 quad_perm:[1,0,3,2] row_mask:0xf bank_mask:0xf bound_ctrl:1
	v_mov_b32_dpp v11, v9 quad_perm:[1,0,3,2] row_mask:0xf bank_mask:0xf bound_ctrl:1
	v_fmac_f32_e32 v2, 0xc0f00000, v147
	s_waitcnt vmcnt(1)
	v_mul_f32_e32 v2, v89, v2
	v_mul_f32_e32 v2, v146, v2
	v_mul_f32_e32 v3, 0x3f3504f3, v2
	v_cmp_nlt_f32_e64 s[0:1], |v3|, 1.0
	s_and_saveexec_b64 s[38:39], s[0:1]
	s_xor_b64 s[0:1], exec, s[38:39]
	s_cbranch_execz .LBB0_611
	v_fma_f32 v4, |v3|, s3, v159
	v_fma_f32 v4, |v3|, v4, s33
	v_fma_f32 v4, |v3|, v4, s47
	v_fma_f32 v4, |v3|, v4, s64
	v_fma_f32 v4, |v3|, v4, s65
	v_fma_f32 v4, |v3|, v4, s66
	v_fma_f32 v4, |v3|, v4, |v3|
	v_mul_f32_e32 v12, 0xbfb8aa3b, v4
	v_fma_f32 v13, v4, s67, -v12
	v_rndne_f32_e32 v14, v12
	v_fmac_f32_e32 v13, 0xb2a5705f, v4
	v_sub_f32_e32 v12, v12, v14
	v_add_f32_e32 v12, v12, v13
	v_cvt_i32_f32_e32 v13, v14
	v_exp_f32_e32 v12, v12
	v_cmp_nlt_f32_e64 s[38:39], s76, v4
	v_ldexp_f32 v12, v12, v13
	s_nop 0
	v_cndmask_b32_e64 v12, 0, v12, s[38:39]
	v_cmp_ngt_f32_e64 s[38:39], s77, v4
	s_nop 1
	v_cndmask_b32_e64 v4, v160, v12, s[38:39]
	v_sub_f32_e32 v4, 1.0, v4

.LBB0_615:
	s_andn2_saveexec_b64 s[0:1], s[0:1]
	v_mul_f32_e32 v7, v6, v6
	v_fmamk_f32 v8, v7, 0xba1345e1, v157
	v_fmaak_f32 v8, v7, v8, 0xbcdac9b8
	v_fmaak_f32 v8, v7, v8, 0x3de703be
	v_fmaak_f32 v8, v7, v8, 0xbec09330
	v_fmaak_f32 v7, v7, v8, 0x3e0375d0
	v_fma_f32 v7, |v6|, v7, |v6|
	s_or_b64 exec, exec, s[0:1]
	v_readlane_b32 s48, v254, 40
	v_lshlrev_b64 v[8:9], 7, v[108:109]
	v_readlane_b32 s58, v254, 50
	v_readlane_b32 s59, v254, 51
	v_lshl_add_u64 v[8:9], v[8:9], 2, v[138:139]
	v_bfi_b32 v3, s78, v4, v3
	v_lshl_add_u64 v[10:11], v[54:55], 2, s[58:59]
	v_lshl_add_u64 v[12:13], v[56:57], 2, s[58:59]
	global_load_dwordx2 v[8:9], v[8:9], off
	s_nop 0
	global_load_dword v10, v[10:11], off
	s_nop 0
	global_load_dword v11, v[12:13], off
	v_mul_f32_e32 v4, 0.5, v5
	v_bfi_b32 v5, s78, v7, v6
	v_mul_f32_e32 v2, 0.5, v2
	v_add_f32_e32 v3, 1.0, v3
	v_add_f32_e32 v5, 1.0, v5
	v_mul_f32_e32 v2, v2, v3
	v_mul_f32_e32 v3, v4, v5
	v_mov_b32_e32 v92, 0
	s_mov_b32 s0, 0
	v_mov_b32_e32 v93, v92
	v_mov_b32_e32 v90, v92
	v_mov_b32_e32 v91, v92
	v_mov_b32_e32 v86, v92
	v_mov_b32_e32 v87, v92
	v_mov_b32_e32 v84, v92
	v_mov_b32_e32 v85, v92
	v_mov_b32_e32 v80, v92
	v_mov_b32_e32 v81, v92
	v_mov_b32_e32 v78, v92
	v_mov_b32_e32 v79, v92
	v_mov_b32_e32 v70, v92
	v_mov_b32_e32 v71, v92
	v_mov_b32_e32 v62, v92
	v_mov_b32_e32 v63, v92
	v_readlane_b32 s49, v254, 41
	v_readlane_b32 s50, v254, 42
	v_readlane_b32 s51, v254, 43
	v_readlane_b32 s52, v254, 44
	v_readlane_b32 s53, v254, 45
	v_readlane_b32 s54, v254, 46
	v_readlane_b32 s55, v254, 47
	v_readlane_b32 s56, v254, 48
	v_readlane_b32 s57, v254, 49
	v_readlane_b32 s60, v254, 52
	v_readlane_b32 s61, v254, 53
	v_readlane_b32 s62, v254, 54
	v_readlane_b32 s63, v254, 55
	s_waitcnt vmcnt(2)
	v_pk_mul_f32 v[2:3], v[2:3], v[8:9]
	s_waitcnt vmcnt(0)
	v_pk_mul_f32 v[24:25], v[2:3], v[10:11]
	ds_write_b64 v149, v[24:25] offset:512
	s_setprio 0
	v_lshl_add_u64 v[244:245], v[144:145], 2, v[136:137]
	global_load_dwordx4 v[228:231], v[244:245], off
	global_load_dwordx4 v[232:235], v[244:245], off offset:16
	global_load_dwordx4 v[236:239], v[244:245], off offset:32
	global_load_dwordx4 v[240:243], v[244:245], off offset:48
	v_add_u32_e32 v34, s2, v108
	v_min_u32_e32 v34, 0x7fff, v34
	v_mov_b32_e32 v35, 0
	v_lshlrev_b64 v[36:37], 9, v[34:35]
	v_lshlrev_b64 v[38:39], 10, v[34:35]
	v_lshlrev_b64 v[40:41], 2, v[34:35]
	v_lshl_add_u64 v[36:37], v[132:133], 0, v[36:37]
	v_lshl_add_u64 v[38:39], v[134:135], 0, v[38:39]
	v_lshl_add_u64 v[42:43], s[68:69], 0, v[40:41]
	v_lshl_add_u64 v[40:41], s[70:71], 0, v[40:41]
	global_load_dword v246, v[36:37], off
	global_load_dword v247, v[36:37], off offset:256
	global_load_dwordx4 v[248:251], v[38:39], off
	global_load_dword v252, v[42:43], off
	global_load_dword v253, v[40:41], off
	s_mov_b32 s0, 0x0f0f0f0f
	s_mov_b32 s1, 0xf0f0f0f0
	v_readfirstlane_b32 s38, v114
	v_readfirstlane_b32 s39, v115
	v_mul_f32_e32 v146, 0x3d800000, v24
	v_mul_f32_e32 v147, 0x3d800000, v25
	v_subrev_u32_e32 v100, s38, v114
	ds_write_b64 v149, v[146:147] offset:1536
	ds_read_b128 v[72:75], v1 offset:0
	ds_read_b128 v[94:97], v1 offset:16
	ds_read_b128 v[50:53], v1 offset:32
	ds_read_b128 v[54:57], v1 offset:48
	s_waitcnt lgkmcnt(2)
	v_lshl_add_u32 v72, v72, 9, v100
	v_lshl_add_u32 v73, v73, 9, v100
	v_lshl_add_u32 v74, v74, 9, v100
	v_lshl_add_u32 v75, v75, 9, v100
	v_lshl_add_u32 v94, v94, 9, v100
	v_lshl_add_u32 v95, v95, 9, v100
	v_lshl_add_u32 v96, v96, 9, v100
	v_lshl_add_u32 v97, v97, 9, v100
	global_load_dwordx2 v[164:165], v72, s[38:39]
	global_load_dwordx2 v[166:167], v73, s[38:39]
	global_load_dwordx2 v[168:169], v74, s[38:39]
	global_load_dwordx2 v[170:171], v75, s[38:39]
	global_load_dwordx2 v[172:173], v94, s[38:39]
	global_load_dwordx2 v[174:175], v95, s[38:39]
	global_load_dwordx2 v[176:177], v96, s[38:39]
	global_load_dwordx2 v[178:179], v97, s[38:39]
	ds_read_b128 v[72:75], v1 offset:64
	ds_read_b128 v[94:97], v1 offset:80
	s_waitcnt lgkmcnt(2)
	v_lshl_add_u32 v50, v50, 9, v100
	v_lshl_add_u32 v51, v51, 9, v100
	v_lshl_add_u32 v52, v52, 9, v100
	v_lshl_add_u32 v53, v53, 9, v100
	v_lshl_add_u32 v54, v54, 9, v100
	v_lshl_add_u32 v55, v55, 9, v100
	v_lshl_add_u32 v56, v56, 9, v100
	v_lshl_add_u32 v57, v57, 9, v100
	global_load_dwordx2 v[180:181], v50, s[38:39]
	global_load_dwordx2 v[182:183], v51, s[38:39]
	global_load_dwordx2 v[184:185], v52, s[38:39]
	global_load_dwordx2 v[186:187], v53, s[38:39]
	global_load_dwordx2 v[188:189], v54, s[38:39]
	global_load_dwordx2 v[190:191], v55, s[38:39]
	global_load_dwordx2 v[192:193], v56, s[38:39]
	global_load_dwordx2 v[194:195], v57, s[38:39]
	ds_read_b128 v[50:53], v1 offset:96
	ds_read_b128 v[54:57], v1 offset:112
	s_waitcnt lgkmcnt(2)
	v_lshl_add_u32 v72, v72, 9, v100
	v_lshl_add_u32 v73, v73, 9, v100
	v_lshl_add_u32 v74, v74, 9, v100
	v_lshl_add_u32 v75, v75, 9, v100
	v_lshl_add_u32 v94, v94, 9, v100
	v_lshl_add_u32 v95, v95, 9, v100
	v_lshl_add_u32 v96, v96, 9, v100
	v_lshl_add_u32 v97, v97, 9, v100
	global_load_dwordx2 v[196:197], v72, s[38:39]
	global_load_dwordx2 v[198:199], v73, s[38:39]
	global_load_dwordx2 v[200:201], v74, s[38:39]
	global_load_dwordx2 v[202:203], v75, s[38:39]
	global_load_dwordx2 v[204:205], v94, s[38:39]
	global_load_dwordx2 v[206:207], v95, s[38:39]
	global_load_dwordx2 v[208:209], v96, s[38:39]
	global_load_dwordx2 v[210:211], v97, s[38:39]
	ds_read_b128 v[72:75], v1 offset:128
	ds_read_b128 v[94:97], v1 offset:144
	s_waitcnt lgkmcnt(2)
	v_lshl_add_u32 v50, v50, 9, v100
	v_lshl_add_u32 v51, v51, 9, v100
	v_lshl_add_u32 v52, v52, 9, v100
	v_lshl_add_u32 v53, v53, 9, v100
	v_lshl_add_u32 v54, v54, 9, v100
	v_lshl_add_u32 v55, v55, 9, v100
	v_lshl_add_u32 v56, v56, 9, v100
	v_lshl_add_u32 v57, v57, 9, v100
	global_load_dwordx2 v[212:213], v50, s[38:39]
	global_load_dwordx2 v[214:215], v51, s[38:39]
	global_load_dwordx2 v[216:217], v52, s[38:39]
	global_load_dwordx2 v[218:219], v53, s[38:39]
	global_load_dwordx2 v[220:221], v54, s[38:39]
	global_load_dwordx2 v[222:223], v55, s[38:39]
	global_load_dwordx2 v[224:225], v56, s[38:39]
	global_load_dwordx2 v[226:227], v57, s[38:39]
	s_waitcnt lgkmcnt(0)
	v_lshl_add_u32 v72, v72, 9, v100
	v_lshl_add_u32 v73, v73, 9, v100
	v_lshl_add_u32 v74, v74, 9, v100
	v_lshl_add_u32 v75, v75, 9, v100
	v_lshl_add_u32 v94, v94, 9, v100
	v_lshl_add_u32 v95, v95, 9, v100
	v_lshl_add_u32 v96, v96, 9, v100
	v_lshl_add_u32 v97, v97, 9, v100
	global_load_dwordx2 v[2:3], v72, s[38:39]
	global_load_dwordx2 v[4:5], v73, s[38:39]
	global_load_dwordx2 v[6:7], v74, s[38:39]
	global_load_dwordx2 v[8:9], v75, s[38:39]
	global_load_dwordx2 v[10:11], v94, s[38:39]
	global_load_dwordx2 v[12:13], v95, s[38:39]
	global_load_dwordx2 v[14:15], v96, s[38:39]
	global_load_dwordx2 v[16:17], v97, s[38:39]
	v_add_f32_e32 v146, v24, v25
	ds_bpermute_b32 v147, v150, v146
	s_waitcnt lgkmcnt(0)
	v_add_f32_e32 v146, v146, v147
	ds_bpermute_b32 v147, v151, v146
	s_waitcnt lgkmcnt(0)
	v_add_f32_e32 v146, v146, v147
	ds_bpermute_b32 v147, v152, v146
	s_waitcnt lgkmcnt(0)
	v_add_f32_e32 v146, v146, v147
	ds_bpermute_b32 v147, v153, v146
	s_waitcnt lgkmcnt(0)
	v_add_f32_e32 v146, v146, v147
	ds_bpermute_b32 v147, v154, v146
	s_waitcnt lgkmcnt(0)
	v_add_f32_e32 v101, v146, v147
	ds_bpermute_b32 v162, v155, v101
	ds_read_b128 v[72:75], v1 offset:160
	ds_read_b128 v[94:97], v1 offset:176
	ds_read_b128 v[34:37], v1 offset:512
	ds_read_b128 v[38:41], v1 offset:528
	ds_read_b128 v[42:45], v1 offset:1536
	ds_read_b128 v[46:49], v1 offset:1552
	s_waitcnt lgkmcnt(0)
	v_lshl_add_u32 v72, v72, 9, v100
	v_lshl_add_u32 v73, v73, 9, v100
	v_lshl_add_u32 v74, v74, 9, v100
	v_lshl_add_u32 v75, v75, 9, v100
	v_lshl_add_u32 v94, v94, 9, v100
	v_lshl_add_u32 v95, v95, 9, v100
	v_lshl_add_u32 v96, v96, 9, v100
	v_lshl_add_u32 v97, v97, 9, v100
	global_load_dwordx2 v[18:19], v72, s[38:39]
	global_load_dwordx2 v[20:21], v73, s[38:39]
	global_load_dwordx2 v[22:23], v74, s[38:39]
	global_load_dwordx2 v[24:25], v75, s[38:39]
	global_load_dwordx2 v[26:27], v94, s[38:39]
	global_load_dwordx2 v[28:29], v95, s[38:39]
	global_load_dwordx2 v[30:31], v96, s[38:39]
	global_load_dwordx2 v[32:33], v97, s[38:39]
	ds_read_b128 v[72:75], v1 offset:192
	ds_read_b128 v[94:97], v1 offset:208
	ds_read_b128 v[50:53], v1 offset:544
	ds_read_b128 v[54:57], v1 offset:560
	ds_read_b128 v[58:61], v1 offset:1568
	ds_read_b128 v[64:67], v1 offset:1584
	s_waitcnt vmcnt(40)
	v_and_b32_e32 v68, s0, v164
	v_and_b32_e32 v69, s1, v164
	v_and_b32_e32 v76, s0, v165
	v_and_b32_e32 v77, s1, v165
	v_cvt_f32_ubyte0_e32 v98, v68
	v_cvt_f32_ubyte1_e32 v99, v68
	v_cvt_f32_ubyte2_e32 v102, v68
	v_cvt_f32_ubyte3_e32 v103, v68
	v_pk_fma_f32 v[92:93], v[34:35], v[98:99], v[92:93] op_sel_hi:[0,1,1]
	v_cvt_f32_ubyte0_e32 v104, v69
	v_cvt_f32_ubyte1_e32 v105, v69
	v_pk_fma_f32 v[90:91], v[34:35], v[102:103], v[90:91] op_sel_hi:[0,1,1]
	v_cvt_f32_ubyte2_e32 v146, v69
	v_cvt_f32_ubyte3_e32 v147, v69
	v_pk_fma_f32 v[86:87], v[42:43], v[104:105], v[86:87] op_sel_hi:[0,1,1]
	v_cvt_f32_ubyte0_e32 v98, v76
	v_cvt_f32_ubyte1_e32 v99, v76
	v_pk_fma_f32 v[84:85], v[42:43], v[146:147], v[84:85] op_sel_hi:[0,1,1]
	v_and_b32_e32 v82, s0, v166
	v_and_b32_e32 v83, s1, v166
	v_and_b32_e32 v88, s0, v167
	v_and_b32_e32 v89, s1, v167
	v_cvt_f32_ubyte2_e32 v102, v76
	v_cvt_f32_ubyte3_e32 v103, v76
	v_pk_fma_f32 v[80:81], v[34:35], v[98:99], v[80:81] op_sel_hi:[0,1,1]
	v_cvt_f32_ubyte0_e32 v104, v77
	v_cvt_f32_ubyte1_e32 v105, v77
	v_pk_fma_f32 v[78:79], v[34:35], v[102:103], v[78:79] op_sel_hi:[0,1,1]
	v_cvt_f32_ubyte2_e32 v146, v77
	v_cvt_f32_ubyte3_e32 v147, v77
	v_pk_fma_f32 v[70:71], v[42:43], v[104:105], v[70:71] op_sel_hi:[0,1,1]
	v_cvt_f32_ubyte0_e32 v98, v82
	v_cvt_f32_ubyte1_e32 v99, v82
	v_pk_fma_f32 v[62:63], v[42:43], v[146:147], v[62:63] op_sel_hi:[0,1,1]
	v_cvt_f32_ubyte2_e32 v102, v82
	v_cvt_f32_ubyte3_e32 v103, v82
	v_pk_fma_f32 v[92:93], v[34:35], v[98:99], v[92:93] op_sel:[1,0,0]
	v_cvt_f32_ubyte0_e32 v104, v83
	v_cvt_f32_ubyte1_e32 v105, v83
	v_pk_fma_f32 v[90:91], v[34:35], v[102:103], v[90:91] op_sel:[1,0,0]
	v_cvt_f32_ubyte2_e32 v146, v83
	v_cvt_f32_ubyte3_e32 v147, v83
	v_pk_fma_f32 v[86:87], v[42:43], v[104:105], v[86:87] op_sel:[1,0,0]
	v_cvt_f32_ubyte0_e32 v98, v88
	v_cvt_f32_ubyte1_e32 v99, v88
	v_pk_fma_f32 v[84:85], v[42:43], v[146:147], v[84:85] op_sel:[1,0,0]
	v_and_b32_e32 v68, s0, v168
	v_and_b32_e32 v69, s1, v168
	v_and_b32_e32 v76, s0, v169
	v_and_b32_e32 v77, s1, v169
	v_cvt_f32_ubyte2_e32 v102, v88
	v_cvt_f32_ubyte3_e32 v103, v88
	v_pk_fma_f32 v[80:81], v[34:35], v[98:99], v[80:81] op_sel:[1,0,0]
	v_cvt_f32_ubyte0_e32 v104, v89
	v_cvt_f32_ubyte1_e32 v105, v89
	v_pk_fma_f32 v[78:79], v[34:35], v[102:103], v[78:79] op_sel:[1,0,0]
	v_cvt_f32_ubyte2_e32 v146, v89
	v_cvt_f32_ubyte3_e32 v147, v89
	v_pk_fma_f32 v[70:71], v[42:43], v[104:105], v[70:71] op_sel:[1,0,0]
	v_cvt_f32_ubyte0_e32 v98, v68
	v_cvt_f32_ubyte1_e32 v99, v68
	v_pk_fma_f32 v[62:63], v[42:43], v[146:147], v[62:63] op_sel:[1,0,0]
	v_cvt_f32_ubyte2_e32 v102, v68
	v_cvt_f32_ubyte3_e32 v103, v68
	v_pk_fma_f32 v[92:93], v[36:37], v[98:99], v[92:93] op_sel_hi:[0,1,1]
	v_cvt_f32_ubyte0_e32 v104, v69
	v_cvt_f32_ubyte1_e32 v105, v69
	v_pk_fma_f32 v[90:91], v[36:37], v[102:103], v[90:91] op_sel_hi:[0,1,1]
	v_cvt_f32_ubyte2_e32 v146, v69
	v_cvt_f32_ubyte3_e32 v147, v69
	v_pk_fma_f32 v[86:87], v[44:45], v[104:105], v[86:87] op_sel_hi:[0,1,1]
	v_cvt_f32_ubyte0_e32 v98, v76
	v_cvt_f32_ubyte1_e32 v99, v76
	v_pk_fma_f32 v[84:85], v[44:45], v[146:147], v[84:85] op_sel_hi:[0,1,1]
	v_and_b32_e32 v82, s0, v170
	v_and_b32_e32 v83, s1, v170
	v_and_b32_e32 v88, s0, v171
	v_and_b32_e32 v89, s1, v171
	v_cvt_f32_ubyte2_e32 v102, v76
	v_cvt_f32_ubyte3_e32 v103, v76
	v_pk_fma_f32 v[80:81], v[36:37], v[98:99], v[80:81] op_sel_hi:[0,1,1]
	v_cvt_f32_ubyte0_e32 v104, v77
	v_cvt_f32_ubyte1_e32 v105, v77
	v_pk_fma_f32 v[78:79], v[36:37], v[102:103], v[78:79] op_sel_hi:[0,1,1]
	v_cvt_f32_ubyte2_e32 v146, v77
	v_cvt_f32_ubyte3_e32 v147, v77
	v_pk_fma_f32 v[70:71], v[44:45], v[104:105], v[70:71] op_sel_hi:[0,1,1]
	v_cvt_f32_ubyte0_e32 v98, v82
	v_cvt_f32_ubyte1_e32 v99, v82
	v_pk_fma_f32 v[62:63], v[44:45], v[146:147], v[62:63] op_sel_hi:[0,1,1]
	v_cvt_f32_ubyte2_e32 v102, v82
	v_cvt_f32_ubyte3_e32 v103, v82
	v_pk_fma_f32 v[92:93], v[36:37], v[98:99], v[92:93] op_sel:[1,0,0]
	v_cvt_f32_ubyte0_e32 v104, v83
	v_cvt_f32_ubyte1_e32 v105, v83
	v_pk_fma_f32 v[90:91], v[36:37], v[102:103], v[90:91] op_sel:[1,0,0]
	v_cvt_f32_ubyte2_e32 v146, v83
	v_cvt_f32_ubyte3_e32 v147, v83
	v_pk_fma_f32 v[86:87], v[44:45], v[104:105], v[86:87] op_sel:[1,0,0]
	v_cvt_f32_ubyte0_e32 v98, v88
	v_cvt_f32_ubyte1_e32 v99, v88
	v_pk_fma_f32 v[84:85], v[44:45], v[146:147], v[84:85] op_sel:[1,0,0]
	v_and_b32_e32 v68, s0, v172
	v_and_b32_e32 v69, s1, v172
	v_and_b32_e32 v76, s0, v173
	v_and_b32_e32 v77, s1, v173
	v_cvt_f32_ubyte2_e32 v102, v88
	v_cvt_f32_ubyte3_e32 v103, v88
	v_pk_fma_f32 v[80:81], v[36:37], v[98:99], v[80:81] op_sel:[1,0,0]
	v_cvt_f32_ubyte0_e32 v104, v89
	v_cvt_f32_ubyte1_e32 v105, v89
	v_pk_fma_f32 v[78:79], v[36:37], v[102:103], v[78:79] op_sel:[1,0,0]
	v_cvt_f32_ubyte2_e32 v146, v89
	v_cvt_f32_ubyte3_e32 v147, v89
	v_pk_fma_f32 v[70:71], v[44:45], v[104:105], v[70:71] op_sel:[1,0,0]
	v_cvt_f32_ubyte0_e32 v98, v68
	v_cvt_f32_ubyte1_e32 v99, v68
	v_pk_fma_f32 v[62:63], v[44:45], v[146:147], v[62:63] op_sel:[1,0,0]
	v_cvt_f32_ubyte2_e32 v102, v68
	v_cvt_f32_ubyte3_e32 v103, v68
	v_pk_fma_f32 v[92:93], v[38:39], v[98:99], v[92:93] op_sel_hi:[0,1,1]
	v_cvt_f32_ubyte0_e32 v104, v69
	v_cvt_f32_ubyte1_e32 v105, v69
	v_pk_fma_f32 v[90:91], v[38:39], v[102:103], v[90:91] op_sel_hi:[0,1,1]
	v_cvt_f32_ubyte2_e32 v146, v69
	v_cvt_f32_ubyte3_e32 v147, v69
	v_pk_fma_f32 v[86:87], v[46:47], v[104:105], v[86:87] op_sel_hi:[0,1,1]
	v_cvt_f32_ubyte0_e32 v98, v76
	v_cvt_f32_ubyte1_e32 v99, v76
	v_pk_fma_f32 v[84:85], v[46:47], v[146:147], v[84:85] op_sel_hi:[0,1,1]
	v_and_b32_e32 v82, s0, v174
	v_and_b32_e32 v83, s1, v174
	v_and_b32_e32 v88, s0, v175
	v_and_b32_e32 v89, s1, v175
	v_cvt_f32_ubyte2_e32 v102, v76
	v_cvt_f32_ubyte3_e32 v103, v76
	v_pk_fma_f32 v[80:81], v[38:39], v[98:99], v[80:81] op_sel_hi:[0,1,1]
	v_cvt_f32_ubyte0_e32 v104, v77
	v_cvt_f32_ubyte1_e32 v105, v77
	v_pk_fma_f32 v[78:79], v[38:39], v[102:103], v[78:79] op_sel_hi:[0,1,1]
	v_cvt_f32_ubyte2_e32 v146, v77
	v_cvt_f32_ubyte3_e32 v147, v77
	v_pk_fma_f32 v[70:71], v[46:47], v[104:105], v[70:71] op_sel_hi:[0,1,1]
	v_cvt_f32_ubyte0_e32 v98, v82
	v_cvt_f32_ubyte1_e32 v99, v82
	v_pk_fma_f32 v[62:63], v[46:47], v[146:147], v[62:63] op_sel_hi:[0,1,1]
	v_cvt_f32_ubyte2_e32 v102, v82
	v_cvt_f32_ubyte3_e32 v103, v82
	v_pk_fma_f32 v[92:93], v[38:39], v[98:99], v[92:93] op_sel:[1,0,0]
	v_cvt_f32_ubyte0_e32 v104, v83
	v_cvt_f32_ubyte1_e32 v105, v83
	v_pk_fma_f32 v[90:91], v[38:39], v[102:103], v[90:91] op_sel:[1,0,0]
	v_cvt_f32_ubyte2_e32 v146, v83
	v_cvt_f32_ubyte3_e32 v147, v83
	v_pk_fma_f32 v[86:87], v[46:47], v[104:105], v[86:87] op_sel:[1,0,0]
	v_cvt_f32_ubyte0_e32 v98, v88
	v_cvt_f32_ubyte1_e32 v99, v88
	v_pk_fma_f32 v[84:85], v[46:47], v[146:147], v[84:85] op_sel:[1,0,0]
	v_and_b32_e32 v68, s0, v176
	v_and_b32_e32 v69, s1, v176
	v_and_b32_e32 v76, s0, v177
	v_and_b32_e32 v77, s1, v177
	v_cvt_f32_ubyte2_e32 v102, v88
	v_cvt_f32_ubyte3_e32 v103, v88
	v_pk_fma_f32 v[80:81], v[38:39], v[98:99], v[80:81] op_sel:[1,0,0]
	v_cvt_f32_ubyte0_e32 v104, v89
	v_cvt_f32_ubyte1_e32 v105, v89
	v_pk_fma_f32 v[78:79], v[38:39], v[102:103], v[78:79] op_sel:[1,0,0]
	v_cvt_f32_ubyte2_e32 v146, v89
	v_cvt_f32_ubyte3_e32 v147, v89
	v_pk_fma_f32 v[70:71], v[46:47], v[104:105], v[70:71] op_sel:[1,0,0]
	v_cvt_f32_ubyte0_e32 v98, v68
	v_cvt_f32_ubyte1_e32 v99, v68
	v_pk_fma_f32 v[62:63], v[46:47], v[146:147], v[62:63] op_sel:[1,0,0]
	v_cvt_f32_ubyte2_e32 v102, v68
	v_cvt_f32_ubyte3_e32 v103, v68
	v_pk_fma_f32 v[92:93], v[40:41], v[98:99], v[92:93] op_sel_hi:[0,1,1]
	v_cvt_f32_ubyte0_e32 v104, v69
	v_cvt_f32_ubyte1_e32 v105, v69
	v_pk_fma_f32 v[90:91], v[40:41], v[102:103], v[90:91] op_sel_hi:[0,1,1]
	v_cvt_f32_ubyte2_e32 v146, v69
	v_cvt_f32_ubyte3_e32 v147, v69
	v_pk_fma_f32 v[86:87], v[48:49], v[104:105], v[86:87] op_sel_hi:[0,1,1]
	v_cvt_f32_ubyte0_e32 v98, v76
	v_cvt_f32_ubyte1_e32 v99, v76
	v_pk_fma_f32 v[84:85], v[48:49], v[146:147], v[84:85] op_sel_hi:[0,1,1]
	v_and_b32_e32 v82, s0, v178
	v_and_b32_e32 v83, s1, v178
	v_and_b32_e32 v88, s0, v179
	v_and_b32_e32 v89, s1, v179
	v_cvt_f32_ubyte2_e32 v102, v76
	v_cvt_f32_ubyte3_e32 v103, v76
	v_pk_fma_f32 v[80:81], v[40:41], v[98:99], v[80:81] op_sel_hi:[0,1,1]
	v_cvt_f32_ubyte0_e32 v104, v77
	v_cvt_f32_ubyte1_e32 v105, v77
	v_pk_fma_f32 v[78:79], v[40:41], v[102:103], v[78:79] op_sel_hi:[0,1,1]
	v_cvt_f32_ubyte2_e32 v146, v77
	v_cvt_f32_ubyte3_e32 v147, v77
	v_pk_fma_f32 v[70:71], v[48:49], v[104:105], v[70:71] op_sel_hi:[0,1,1]
	v_cvt_f32_ubyte0_e32 v98, v82
	v_cvt_f32_ubyte1_e32 v99, v82
	v_pk_fma_f32 v[62:63], v[48:49], v[146:147], v[62:63] op_sel_hi:[0,1,1]
	v_cvt_f32_ubyte2_e32 v102, v82
	v_cvt_f32_ubyte3_e32 v103, v82
	v_pk_fma_f32 v[92:93], v[40:41], v[98:99], v[92:93] op_sel:[1,0,0]
	v_cvt_f32_ubyte0_e32 v104, v83
	v_cvt_f32_ubyte1_e32 v105, v83
	v_pk_fma_f32 v[90:91], v[40:41], v[102:103], v[90:91] op_sel:[1,0,0]
	v_cvt_f32_ubyte2_e32 v146, v83
	v_cvt_f32_ubyte3_e32 v147, v83
	v_pk_fma_f32 v[86:87], v[48:49], v[104:105], v[86:87] op_sel:[1,0,0]
	v_cvt_f32_ubyte0_e32 v98, v88
	v_cvt_f32_ubyte1_e32 v99, v88
	v_pk_fma_f32 v[84:85], v[48:49], v[146:147], v[84:85] op_sel:[1,0,0]
	v_cvt_f32_ubyte2_e32 v102, v88
	v_cvt_f32_ubyte3_e32 v103, v88
	v_pk_fma_f32 v[80:81], v[40:41], v[98:99], v[80:81] op_sel:[1,0,0]
	v_cvt_f32_ubyte0_e32 v104, v89
	v_cvt_f32_ubyte1_e32 v105, v89
	v_pk_fma_f32 v[78:79], v[40:41], v[102:103], v[78:79] op_sel:[1,0,0]
	v_cvt_f32_ubyte2_e32 v146, v89
	v_cvt_f32_ubyte3_e32 v147, v89
	v_pk_fma_f32 v[70:71], v[48:49], v[104:105], v[70:71] op_sel:[1,0,0]
	v_pk_fma_f32 v[62:63], v[48:49], v[146:147], v[62:63] op_sel:[1,0,0]
	s_waitcnt lgkmcnt(0)
	v_lshl_add_u32 v72, v72, 9, v100
	v_lshl_add_u32 v73, v73, 9, v100
	v_lshl_add_u32 v74, v74, 9, v100
	v_lshl_add_u32 v75, v75, 9, v100
	v_lshl_add_u32 v94, v94, 9, v100
	v_lshl_add_u32 v95, v95, 9, v100
	v_lshl_add_u32 v96, v96, 9, v100
	v_lshl_add_u32 v97, v97, 9, v100
	global_load_dwordx2 v[164:165], v72, s[38:39]
	global_load_dwordx2 v[166:167], v73, s[38:39]
	global_load_dwordx2 v[168:169], v74, s[38:39]
	global_load_dwordx2 v[170:171], v75, s[38:39]
	global_load_dwordx2 v[172:173], v94, s[38:39]
	global_load_dwordx2 v[174:175], v95, s[38:39]
	global_load_dwordx2 v[176:177], v96, s[38:39]
	global_load_dwordx2 v[178:179], v97, s[38:39]
	ds_read_b128 v[72:75], v1 offset:224
	ds_read_b128 v[94:97], v1 offset:240
	ds_read_b128 v[34:37], v1 offset:576
	ds_read_b128 v[38:41], v1 offset:592
	ds_read_b128 v[42:45], v1 offset:1600
	ds_read_b128 v[46:49], v1 offset:1616
	s_waitcnt vmcnt(40)
	v_and_b32_e32 v68, s0, v180
	v_and_b32_e32 v69, s1, v180
	v_and_b32_e32 v76, s0, v181
	v_and_b32_e32 v77, s1, v181
	v_cvt_f32_ubyte0_e32 v98, v68
	v_cvt_f32_ubyte1_e32 v99, v68
	v_cvt_f32_ubyte2_e32 v102, v68
	v_cvt_f32_ubyte3_e32 v103, v68
	v_pk_fma_f32 v[92:93], v[50:51], v[98:99], v[92:93] op_sel_hi:[0,1,1]
	v_cvt_f32_ubyte0_e32 v104, v69
	v_cvt_f32_ubyte1_e32 v105, v69
	v_pk_fma_f32 v[90:91], v[50:51], v[102:103], v[90:91] op_sel_hi:[0,1,1]
	v_cvt_f32_ubyte2_e32 v146, v69
	v_cvt_f32_ubyte3_e32 v147, v69
	v_pk_fma_f32 v[86:87], v[58:59], v[104:105], v[86:87] op_sel_hi:[0,1,1]
	v_cvt_f32_ubyte0_e32 v98, v76
	v_cvt_f32_ubyte1_e32 v99, v76
	v_pk_fma_f32 v[84:85], v[58:59], v[146:147], v[84:85] op_sel_hi:[0,1,1]
	v_and_b32_e32 v82, s0, v182
	v_and_b32_e32 v83, s1, v182
	v_and_b32_e32 v88, s0, v183
	v_and_b32_e32 v89, s1, v183
	v_cvt_f32_ubyte2_e32 v102, v76
	v_cvt_f32_ubyte3_e32 v103, v76
	v_pk_fma_f32 v[80:81], v[50:51], v[98:99], v[80:81] op_sel_hi:[0,1,1]
	v_cvt_f32_ubyte0_e32 v104, v77
	v_cvt_f32_ubyte1_e32 v105, v77
	v_pk_fma_f32 v[78:79], v[50:51], v[102:103], v[78:79] op_sel_hi:[0,1,1]
	v_cvt_f32_ubyte2_e32 v146, v77
	v_cvt_f32_ubyte3_e32 v147, v77
	v_pk_fma_f32 v[70:71], v[58:59], v[104:105], v[70:71] op_sel_hi:[0,1,1]
	v_cvt_f32_ubyte0_e32 v98, v82
	v_cvt_f32_ubyte1_e32 v99, v82
	v_pk_fma_f32 v[62:63], v[58:59], v[146:147], v[62:63] op_sel_hi:[0,1,1]
	v_cvt_f32_ubyte2_e32 v102, v82
	v_cvt_f32_ubyte3_e32 v103, v82
	v_pk_fma_f32 v[92:93], v[50:51], v[98:99], v[92:93] op_sel:[1,0,0]
	v_cvt_f32_ubyte0_e32 v104, v83
	v_cvt_f32_ubyte1_e32 v105, v83
	v_pk_fma_f32 v[90:91], v[50:51], v[102:103], v[90:91] op_sel:[1,0,0]
	v_cvt_f32_ubyte2_e32 v146, v83
	v_cvt_f32_ubyte3_e32 v147, v83
	v_pk_fma_f32 v[86:87], v[58:59], v[104:105], v[86:87] op_sel:[1,0,0]
	v_cvt_f32_ubyte0_e32 v98, v88
	v_cvt_f32_ubyte1_e32 v99, v88
	v_pk_fma_f32 v[84:85], v[58:59], v[146:147], v[84:85] op_sel:[1,0,0]
	v_and_b32_e32 v68, s0, v184
	v_and_b32_e32 v69, s1, v184
	v_and_b32_e32 v76, s0, v185
	v_and_b32_e32 v77, s1, v185
	v_cvt_f32_ubyte2_e32 v102, v88
	v_cvt_f32_ubyte3_e32 v103, v88
	v_pk_fma_f32 v[80:81], v[50:51], v[98:99], v[80:81] op_sel:[1,0,0]
	v_cvt_f32_ubyte0_e32 v104, v89
	v_cvt_f32_ubyte1_e32 v105, v89
	v_pk_fma_f32 v[78:79], v[50:51], v[102:103], v[78:79] op_sel:[1,0,0]
	v_cvt_f32_ubyte2_e32 v146, v89
	v_cvt_f32_ubyte3_e32 v147, v89
	v_pk_fma_f32 v[70:71], v[58:59], v[104:105], v[70:71] op_sel:[1,0,0]
	v_cvt_f32_ubyte0_e32 v98, v68
	v_cvt_f32_ubyte1_e32 v99, v68
	v_pk_fma_f32 v[62:63], v[58:59], v[146:147], v[62:63] op_sel:[1,0,0]
	v_cvt_f32_ubyte2_e32 v102, v68
	v_cvt_f32_ubyte3_e32 v103, v68
	v_pk_fma_f32 v[92:93], v[52:53], v[98:99], v[92:93] op_sel_hi:[0,1,1]
	v_cvt_f32_ubyte0_e32 v104, v69
	v_cvt_f32_ubyte1_e32 v105, v69
	v_pk_fma_f32 v[90:91], v[52:53], v[102:103], v[90:91] op_sel_hi:[0,1,1]
	v_cvt_f32_ubyte2_e32 v146, v69
	v_cvt_f32_ubyte3_e32 v147, v69
	v_pk_fma_f32 v[86:87], v[60:61], v[104:105], v[86:87] op_sel_hi:[0,1,1]
	v_cvt_f32_ubyte0_e32 v98, v76
	v_cvt_f32_ubyte1_e32 v99, v76
	v_pk_fma_f32 v[84:85], v[60:61], v[146:147], v[84:85] op_sel_hi:[0,1,1]
	v_and_b32_e32 v82, s0, v186
	v_and_b32_e32 v83, s1, v186
	v_and_b32_e32 v88, s0, v187
	v_and_b32_e32 v89, s1, v187
	v_cvt_f32_ubyte2_e32 v102, v76
	v_cvt_f32_ubyte3_e32 v103, v76
	v_pk_fma_f32 v[80:81], v[52:53], v[98:99], v[80:81] op_sel_hi:[0,1,1]
	v_cvt_f32_ubyte0_e32 v104, v77
	v_cvt_f32_ubyte1_e32 v105, v77
	v_pk_fma_f32 v[78:79], v[52:53], v[102:103], v[78:79] op_sel_hi:[0,1,1]
	v_cvt_f32_ubyte2_e32 v146, v77
	v_cvt_f32_ubyte3_e32 v147, v77
	v_pk_fma_f32 v[70:71], v[60:61], v[104:105], v[70:71] op_sel_hi:[0,1,1]
	v_cvt_f32_ubyte0_e32 v98, v82
	v_cvt_f32_ubyte1_e32 v99, v82
	v_pk_fma_f32 v[62:63], v[60:61], v[146:147], v[62:63] op_sel_hi:[0,1,1]
	v_cvt_f32_ubyte2_e32 v102, v82
	v_cvt_f32_ubyte3_e32 v103, v82
	v_pk_fma_f32 v[92:93], v[52:53], v[98:99], v[92:93] op_sel:[1,0,0]
	v_cvt_f32_ubyte0_e32 v104, v83
	v_cvt_f32_ubyte1_e32 v105, v83
	v_pk_fma_f32 v[90:91], v[52:53], v[102:103], v[90:91] op_sel:[1,0,0]
	v_cvt_f32_ubyte2_e32 v146, v83
	v_cvt_f32_ubyte3_e32 v147, v83
	v_pk_fma_f32 v[86:87], v[60:61], v[104:105], v[86:87] op_sel:[1,0,0]
	v_cvt_f32_ubyte0_e32 v98, v88
	v_cvt_f32_ubyte1_e32 v99, v88
	v_pk_fma_f32 v[84:85], v[60:61], v[146:147], v[84:85] op_sel:[1,0,0]
	v_and_b32_e32 v68, s0, v188
	v_and_b32_e32 v69, s1, v188
	v_and_b32_e32 v76, s0, v189
	v_and_b32_e32 v77, s1, v189
	v_cvt_f32_ubyte2_e32 v102, v88
	v_cvt_f32_ubyte3_e32 v103, v88
	v_pk_fma_f32 v[80:81], v[52:53], v[98:99], v[80:81] op_sel:[1,0,0]
	v_cvt_f32_ubyte0_e32 v104, v89
	v_cvt_f32_ubyte1_e32 v105, v89
	v_pk_fma_f32 v[78:79], v[52:53], v[102:103], v[78:79] op_sel:[1,0,0]
	v_cvt_f32_ubyte2_e32 v146, v89
	v_cvt_f32_ubyte3_e32 v147, v89
	v_pk_fma_f32 v[70:71], v[60:61], v[104:105], v[70:71] op_sel:[1,0,0]
	v_cvt_f32_ubyte0_e32 v98, v68
	v_cvt_f32_ubyte1_e32 v99, v68
	v_pk_fma_f32 v[62:63], v[60:61], v[146:147], v[62:63] op_sel:[1,0,0]
	v_cvt_f32_ubyte2_e32 v102, v68
	v_cvt_f32_ubyte3_e32 v103, v68
	v_pk_fma_f32 v[92:93], v[54:55], v[98:99], v[92:93] op_sel_hi:[0,1,1]
	v_cvt_f32_ubyte0_e32 v104, v69
	v_cvt_f32_ubyte1_e32 v105, v69
	v_pk_fma_f32 v[90:91], v[54:55], v[102:103], v[90:91] op_sel_hi:[0,1,1]
	v_cvt_f32_ubyte2_e32 v146, v69
	v_cvt_f32_ubyte3_e32 v147, v69
	v_pk_fma_f32 v[86:87], v[64:65], v[104:105], v[86:87] op_sel_hi:[0,1,1]
	v_cvt_f32_ubyte0_e32 v98, v76
	v_cvt_f32_ubyte1_e32 v99, v76
	v_pk_fma_f32 v[84:85], v[64:65], v[146:147], v[84:85] op_sel_hi:[0,1,1]
	v_and_b32_e32 v82, s0, v190
	v_and_b32_e32 v83, s1, v190
	v_and_b32_e32 v88, s0, v191
	v_and_b32_e32 v89, s1, v191
	v_cvt_f32_ubyte2_e32 v102, v76
	v_cvt_f32_ubyte3_e32 v103, v76
	v_pk_fma_f32 v[80:81], v[54:55], v[98:99], v[80:81] op_sel_hi:[0,1,1]
	v_cvt_f32_ubyte0_e32 v104, v77
	v_cvt_f32_ubyte1_e32 v105, v77
	v_pk_fma_f32 v[78:79], v[54:55], v[102:103], v[78:79] op_sel_hi:[0,1,1]
	v_cvt_f32_ubyte2_e32 v146, v77
	v_cvt_f32_ubyte3_e32 v147, v77
	v_pk_fma_f32 v[70:71], v[64:65], v[104:105], v[70:71] op_sel_hi:[0,1,1]
	v_cvt_f32_ubyte0_e32 v98, v82
	v_cvt_f32_ubyte1_e32 v99, v82
	v_pk_fma_f32 v[62:63], v[64:65], v[146:147], v[62:63] op_sel_hi:[0,1,1]
	v_cvt_f32_ubyte2_e32 v102, v82
	v_cvt_f32_ubyte3_e32 v103, v82
	v_pk_fma_f32 v[92:93], v[54:55], v[98:99], v[92:93] op_sel:[1,0,0]
	v_cvt_f32_ubyte0_e32 v104, v83
	v_cvt_f32_ubyte1_e32 v105, v83
	v_pk_fma_f32 v[90:91], v[54:55], v[102:103], v[90:91] op_sel:[1,0,0]
	v_cvt_f32_ubyte2_e32 v146, v83
	v_cvt_f32_ubyte3_e32 v147, v83
	v_pk_fma_f32 v[86:87], v[64:65], v[104:105], v[86:87] op_sel:[1,0,0]
	v_cvt_f32_ubyte0_e32 v98, v88
	v_cvt_f32_ubyte1_e32 v99, v88
	v_pk_fma_f32 v[84:85], v[64:65], v[146:147], v[84:85] op_sel:[1,0,0]
	v_and_b32_e32 v68, s0, v192
	v_and_b32_e32 v69, s1, v192
	v_and_b32_e32 v76, s0, v193
	v_and_b32_e32 v77, s1, v193
	v_cvt_f32_ubyte2_e32 v102, v88
	v_cvt_f32_ubyte3_e32 v103, v88
	v_pk_fma_f32 v[80:81], v[54:55], v[98:99], v[80:81] op_sel:[1,0,0]
	v_cvt_f32_ubyte0_e32 v104, v89
	v_cvt_f32_ubyte1_e32 v105, v89
	v_pk_fma_f32 v[78:79], v[54:55], v[102:103], v[78:79] op_sel:[1,0,0]
	v_cvt_f32_ubyte2_e32 v146, v89
	v_cvt_f32_ubyte3_e32 v147, v89
	v_pk_fma_f32 v[70:71], v[64:65], v[104:105], v[70:71] op_sel:[1,0,0]
	v_cvt_f32_ubyte0_e32 v98, v68
	v_cvt_f32_ubyte1_e32 v99, v68
	v_pk_fma_f32 v[62:63], v[64:65], v[146:147], v[62:63] op_sel:[1,0,0]
	v_cvt_f32_ubyte2_e32 v102, v68
	v_cvt_f32_ubyte3_e32 v103, v68
	v_pk_fma_f32 v[92:93], v[56:57], v[98:99], v[92:93] op_sel_hi:[0,1,1]
	v_cvt_f32_ubyte0_e32 v104, v69
	v_cvt_f32_ubyte1_e32 v105, v69
	v_pk_fma_f32 v[90:91], v[56:57], v[102:103], v[90:91] op_sel_hi:[0,1,1]
	v_cvt_f32_ubyte2_e32 v146, v69
	v_cvt_f32_ubyte3_e32 v147, v69
	v_pk_fma_f32 v[86:87], v[66:67], v[104:105], v[86:87] op_sel_hi:[0,1,1]
	v_cvt_f32_ubyte0_e32 v98, v76
	v_cvt_f32_ubyte1_e32 v99, v76
	v_pk_fma_f32 v[84:85], v[66:67], v[146:147], v[84:85] op_sel_hi:[0,1,1]
	v_and_b32_e32 v82, s0, v194
	v_and_b32_e32 v83, s1, v194
	v_and_b32_e32 v88, s0, v195
	v_and_b32_e32 v89, s1, v195
	v_cvt_f32_ubyte2_e32 v102, v76
	v_cvt_f32_ubyte3_e32 v103, v76
	v_pk_fma_f32 v[80:81], v[56:57], v[98:99], v[80:81] op_sel_hi:[0,1,1]
	v_cvt_f32_ubyte0_e32 v104, v77
	v_cvt_f32_ubyte1_e32 v105, v77
	v_pk_fma_f32 v[78:79], v[56:57], v[102:103], v[78:79] op_sel_hi:[0,1,1]
	v_cvt_f32_ubyte2_e32 v146, v77
	v_cvt_f32_ubyte3_e32 v147, v77
	v_pk_fma_f32 v[70:71], v[66:67], v[104:105], v[70:71] op_sel_hi:[0,1,1]
	v_cvt_f32_ubyte0_e32 v98, v82
	v_cvt_f32_ubyte1_e32 v99, v82
	v_pk_fma_f32 v[62:63], v[66:67], v[146:147], v[62:63] op_sel_hi:[0,1,1]
	v_cvt_f32_ubyte2_e32 v102, v82
	v_cvt_f32_ubyte3_e32 v103, v82
	v_pk_fma_f32 v[92:93], v[56:57], v[98:99], v[92:93] op_sel:[1,0,0]
	v_cvt_f32_ubyte0_e32 v104, v83
	v_cvt_f32_ubyte1_e32 v105, v83
	v_pk_fma_f32 v[90:91], v[56:57], v[102:103], v[90:91] op_sel:[1,0,0]
	v_cvt_f32_ubyte2_e32 v146, v83
	v_cvt_f32_ubyte3_e32 v147, v83
	v_pk_fma_f32 v[86:87], v[66:67], v[104:105], v[86:87] op_sel:[1,0,0]
	v_cvt_f32_ubyte0_e32 v98, v88
	v_cvt_f32_ubyte1_e32 v99, v88
	v_pk_fma_f32 v[84:85], v[66:67], v[146:147], v[84:85] op_sel:[1,0,0]
	v_cvt_f32_ubyte2_e32 v102, v88
	v_cvt_f32_ubyte3_e32 v103, v88
	v_pk_fma_f32 v[80:81], v[56:57], v[98:99], v[80:81] op_sel:[1,0,0]
	v_cvt_f32_ubyte0_e32 v104, v89
	v_cvt_f32_ubyte1_e32 v105, v89
	v_pk_fma_f32 v[78:79], v[56:57], v[102:103], v[78:79] op_sel:[1,0,0]
	v_cvt_f32_ubyte2_e32 v146, v89
	v_cvt_f32_ubyte3_e32 v147, v89
	v_pk_fma_f32 v[70:71], v[66:67], v[104:105], v[70:71] op_sel:[1,0,0]
	v_pk_fma_f32 v[62:63], v[66:67], v[146:147], v[62:63] op_sel:[1,0,0]
	s_waitcnt lgkmcnt(0)
	v_lshl_add_u32 v72, v72, 9, v100
	v_lshl_add_u32 v73, v73, 9, v100
	v_lshl_add_u32 v74, v74, 9, v100
	v_lshl_add_u32 v75, v75, 9, v100
	v_lshl_add_u32 v94, v94, 9, v100
	v_lshl_add_u32 v95, v95, 9, v100
	v_lshl_add_u32 v96, v96, 9, v100
	v_lshl_add_u32 v97, v97, 9, v100
	global_load_dwordx2 v[180:181], v72, s[38:39]
	global_load_dwordx2 v[182:183], v73, s[38:39]
	global_load_dwordx2 v[184:185], v74, s[38:39]
	global_load_dwordx2 v[186:187], v75, s[38:39]
	global_load_dwordx2 v[188:189], v94, s[38:39]
	global_load_dwordx2 v[190:191], v95, s[38:39]
	global_load_dwordx2 v[192:193], v96, s[38:39]
	global_load_dwordx2 v[194:195], v97, s[38:39]
	ds_read_b128 v[72:75], v1 offset:256
	ds_read_b128 v[94:97], v1 offset:272
	ds_read_b128 v[50:53], v1 offset:608
	ds_read_b128 v[54:57], v1 offset:624
	ds_read_b128 v[58:61], v1 offset:1632
	ds_read_b128 v[64:67], v1 offset:1648
	s_waitcnt vmcnt(40)
	v_and_b32_e32 v68, s0, v196
	v_and_b32_e32 v69, s1, v196
	v_and_b32_e32 v76, s0, v197
	v_and_b32_e32 v77, s1, v197
	v_cvt_f32_ubyte0_e32 v98, v68
	v_cvt_f32_ubyte1_e32 v99, v68
	v_cvt_f32_ubyte2_e32 v102, v68
	v_cvt_f32_ubyte3_e32 v103, v68
	v_pk_fma_f32 v[92:93], v[34:35], v[98:99], v[92:93] op_sel_hi:[0,1,1]
	v_cvt_f32_ubyte0_e32 v104, v69
	v_cvt_f32_ubyte1_e32 v105, v69
	v_pk_fma_f32 v[90:91], v[34:35], v[102:103], v[90:91] op_sel_hi:[0,1,1]
	v_cvt_f32_ubyte2_e32 v146, v69
	v_cvt_f32_ubyte3_e32 v147, v69
	v_pk_fma_f32 v[86:87], v[42:43], v[104:105], v[86:87] op_sel_hi:[0,1,1]
	v_cvt_f32_ubyte0_e32 v98, v76
	v_cvt_f32_ubyte1_e32 v99, v76
	v_pk_fma_f32 v[84:85], v[42:43], v[146:147], v[84:85] op_sel_hi:[0,1,1]
	v_and_b32_e32 v82, s0, v198
	v_and_b32_e32 v83, s1, v198
	v_and_b32_e32 v88, s0, v199
	v_and_b32_e32 v89, s1, v199
	v_cvt_f32_ubyte2_e32 v102, v76
	v_cvt_f32_ubyte3_e32 v103, v76
	v_pk_fma_f32 v[80:81], v[34:35], v[98:99], v[80:81] op_sel_hi:[0,1,1]
	v_cvt_f32_ubyte0_e32 v104, v77
	v_cvt_f32_ubyte1_e32 v105, v77
	v_pk_fma_f32 v[78:79], v[34:35], v[102:103], v[78:79] op_sel_hi:[0,1,1]
	v_cvt_f32_ubyte2_e32 v146, v77
	v_cvt_f32_ubyte3_e32 v147, v77
	v_pk_fma_f32 v[70:71], v[42:43], v[104:105], v[70:71] op_sel_hi:[0,1,1]
	v_cvt_f32_ubyte0_e32 v98, v82
	v_cvt_f32_ubyte1_e32 v99, v82
	v_pk_fma_f32 v[62:63], v[42:43], v[146:147], v[62:63] op_sel_hi:[0,1,1]
	v_cvt_f32_ubyte2_e32 v102, v82
	v_cvt_f32_ubyte3_e32 v103, v82
	v_pk_fma_f32 v[92:93], v[34:35], v[98:99], v[92:93] op_sel:[1,0,0]
	v_cvt_f32_ubyte0_e32 v104, v83
	v_cvt_f32_ubyte1_e32 v105, v83
	v_pk_fma_f32 v[90:91], v[34:35], v[102:103], v[90:91] op_sel:[1,0,0]
	v_cvt_f32_ubyte2_e32 v146, v83
	v_cvt_f32_ubyte3_e32 v147, v83
	v_pk_fma_f32 v[86:87], v[42:43], v[104:105], v[86:87] op_sel:[1,0,0]
	v_cvt_f32_ubyte0_e32 v98, v88
	v_cvt_f32_ubyte1_e32 v99, v88
	v_pk_fma_f32 v[84:85], v[42:43], v[146:147], v[84:85] op_sel:[1,0,0]
	v_and_b32_e32 v68, s0, v200
	v_and_b32_e32 v69, s1, v200
	v_and_b32_e32 v76, s0, v201
	v_and_b32_e32 v77, s1, v201
	v_cvt_f32_ubyte2_e32 v102, v88
	v_cvt_f32_ubyte3_e32 v103, v88
	v_pk_fma_f32 v[80:81], v[34:35], v[98:99], v[80:81] op_sel:[1,0,0]
	v_cvt_f32_ubyte0_e32 v104, v89
	v_cvt_f32_ubyte1_e32 v105, v89
	v_pk_fma_f32 v[78:79], v[34:35], v[102:103], v[78:79] op_sel:[1,0,0]
	v_cvt_f32_ubyte2_e32 v146, v89
	v_cvt_f32_ubyte3_e32 v147, v89
	v_pk_fma_f32 v[70:71], v[42:43], v[104:105], v[70:71] op_sel:[1,0,0]
	v_cvt_f32_ubyte0_e32 v98, v68
	v_cvt_f32_ubyte1_e32 v99, v68
	v_pk_fma_f32 v[62:63], v[42:43], v[146:147], v[62:63] op_sel:[1,0,0]
	v_cvt_f32_ubyte2_e32 v102, v68
	v_cvt_f32_ubyte3_e32 v103, v68
	v_pk_fma_f32 v[92:93], v[36:37], v[98:99], v[92:93] op_sel_hi:[0,1,1]
	v_cvt_f32_ubyte0_e32 v104, v69
	v_cvt_f32_ubyte1_e32 v105, v69
	v_pk_fma_f32 v[90:91], v[36:37], v[102:103], v[90:91] op_sel_hi:[0,1,1]
	v_cvt_f32_ubyte2_e32 v146, v69
	v_cvt_f32_ubyte3_e32 v147, v69
	v_pk_fma_f32 v[86:87], v[44:45], v[104:105], v[86:87] op_sel_hi:[0,1,1]
	v_cvt_f32_ubyte0_e32 v98, v76
	v_cvt_f32_ubyte1_e32 v99, v76
	v_pk_fma_f32 v[84:85], v[44:45], v[146:147], v[84:85] op_sel_hi:[0,1,1]
	v_and_b32_e32 v82, s0, v202
	v_and_b32_e32 v83, s1, v202
	v_and_b32_e32 v88, s0, v203
	v_and_b32_e32 v89, s1, v203
	v_cvt_f32_ubyte2_e32 v102, v76
	v_cvt_f32_ubyte3_e32 v103, v76
	v_pk_fma_f32 v[80:81], v[36:37], v[98:99], v[80:81] op_sel_hi:[0,1,1]
	v_cvt_f32_ubyte0_e32 v104, v77
	v_cvt_f32_ubyte1_e32 v105, v77
	v_pk_fma_f32 v[78:79], v[36:37], v[102:103], v[78:79] op_sel_hi:[0,1,1]
	v_cvt_f32_ubyte2_e32 v146, v77
	v_cvt_f32_ubyte3_e32 v147, v77
	v_pk_fma_f32 v[70:71], v[44:45], v[104:105], v[70:71] op_sel_hi:[0,1,1]
	v_cvt_f32_ubyte0_e32 v98, v82
	v_cvt_f32_ubyte1_e32 v99, v82
	v_pk_fma_f32 v[62:63], v[44:45], v[146:147], v[62:63] op_sel_hi:[0,1,1]
	v_cvt_f32_ubyte2_e32 v102, v82
	v_cvt_f32_ubyte3_e32 v103, v82
	v_pk_fma_f32 v[92:93], v[36:37], v[98:99], v[92:93] op_sel:[1,0,0]
	v_cvt_f32_ubyte0_e32 v104, v83
	v_cvt_f32_ubyte1_e32 v105, v83
	v_pk_fma_f32 v[90:91], v[36:37], v[102:103], v[90:91] op_sel:[1,0,0]
	v_cvt_f32_ubyte2_e32 v146, v83
	v_cvt_f32_ubyte3_e32 v147, v83
	v_pk_fma_f32 v[86:87], v[44:45], v[104:105], v[86:87] op_sel:[1,0,0]
	v_cvt_f32_ubyte0_e32 v98, v88
	v_cvt_f32_ubyte1_e32 v99, v88
	v_pk_fma_f32 v[84:85], v[44:45], v[146:147], v[84:85] op_sel:[1,0,0]
	v_and_b32_e32 v68, s0, v204
	v_and_b32_e32 v69, s1, v204
	v_and_b32_e32 v76, s0, v205
	v_and_b32_e32 v77, s1, v205
	v_cvt_f32_ubyte2_e32 v102, v88
	v_cvt_f32_ubyte3_e32 v103, v88
	v_pk_fma_f32 v[80:81], v[36:37], v[98:99], v[80:81] op_sel:[1,0,0]
	v_cvt_f32_ubyte0_e32 v104, v89
	v_cvt_f32_ubyte1_e32 v105, v89
	v_pk_fma_f32 v[78:79], v[36:37], v[102:103], v[78:79] op_sel:[1,0,0]
	v_cvt_f32_ubyte2_e32 v146, v89
	v_cvt_f32_ubyte3_e32 v147, v89
	v_pk_fma_f32 v[70:71], v[44:45], v[104:105], v[70:71] op_sel:[1,0,0]
	v_cvt_f32_ubyte0_e32 v98, v68
	v_cvt_f32_ubyte1_e32 v99, v68
	v_pk_fma_f32 v[62:63], v[44:45], v[146:147], v[62:63] op_sel:[1,0,0]
	v_cvt_f32_ubyte2_e32 v102, v68
	v_cvt_f32_ubyte3_e32 v103, v68
	v_pk_fma_f32 v[92:93], v[38:39], v[98:99], v[92:93] op_sel_hi:[0,1,1]
	v_cvt_f32_ubyte0_e32 v104, v69
	v_cvt_f32_ubyte1_e32 v105, v69
	v_pk_fma_f32 v[90:91], v[38:39], v[102:103], v[90:91] op_sel_hi:[0,1,1]
	v_cvt_f32_ubyte2_e32 v146, v69
	v_cvt_f32_ubyte3_e32 v147, v69
	v_pk_fma_f32 v[86:87], v[46:47], v[104:105], v[86:87] op_sel_hi:[0,1,1]
	v_cvt_f32_ubyte0_e32 v98, v76
	v_cvt_f32_ubyte1_e32 v99, v76
	v_pk_fma_f32 v[84:85], v[46:47], v[146:147], v[84:85] op_sel_hi:[0,1,1]
	v_and_b32_e32 v82, s0, v206
	v_and_b32_e32 v83, s1, v206
	v_and_b32_e32 v88, s0, v207
	v_and_b32_e32 v89, s1, v207
	v_cvt_f32_ubyte2_e32 v102, v76
	v_cvt_f32_ubyte3_e32 v103, v76
	v_pk_fma_f32 v[80:81], v[38:39], v[98:99], v[80:81] op_sel_hi:[0,1,1]
	v_cvt_f32_ubyte0_e32 v104, v77
	v_cvt_f32_ubyte1_e32 v105, v77
	v_pk_fma_f32 v[78:79], v[38:39], v[102:103], v[78:79] op_sel_hi:[0,1,1]
	v_cvt_f32_ubyte2_e32 v146, v77
	v_cvt_f32_ubyte3_e32 v147, v77
	v_pk_fma_f32 v[70:71], v[46:47], v[104:105], v[70:71] op_sel_hi:[0,1,1]
	v_cvt_f32_ubyte0_e32 v98, v82
	v_cvt_f32_ubyte1_e32 v99, v82
	v_pk_fma_f32 v[62:63], v[46:47], v[146:147], v[62:63] op_sel_hi:[0,1,1]
	v_cvt_f32_ubyte2_e32 v102, v82
	v_cvt_f32_ubyte3_e32 v103, v82
	v_pk_fma_f32 v[92:93], v[38:39], v[98:99], v[92:93] op_sel:[1,0,0]
	v_cvt_f32_ubyte0_e32 v104, v83
	v_cvt_f32_ubyte1_e32 v105, v83
	v_pk_fma_f32 v[90:91], v[38:39], v[102:103], v[90:91] op_sel:[1,0,0]
	v_cvt_f32_ubyte2_e32 v146, v83
	v_cvt_f32_ubyte3_e32 v147, v83
	v_pk_fma_f32 v[86:87], v[46:47], v[104:105], v[86:87] op_sel:[1,0,0]
	v_cvt_f32_ubyte0_e32 v98, v88
	v_cvt_f32_ubyte1_e32 v99, v88
	v_pk_fma_f32 v[84:85], v[46:47], v[146:147], v[84:85] op_sel:[1,0,0]
	v_and_b32_e32 v68, s0, v208
	v_and_b32_e32 v69, s1, v208
	v_and_b32_e32 v76, s0, v209
	v_and_b32_e32 v77, s1, v209
	v_cvt_f32_ubyte2_e32 v102, v88
	v_cvt_f32_ubyte3_e32 v103, v88
	v_pk_fma_f32 v[80:81], v[38:39], v[98:99], v[80:81] op_sel:[1,0,0]
	v_cvt_f32_ubyte0_e32 v104, v89
	v_cvt_f32_ubyte1_e32 v105, v89
	v_pk_fma_f32 v[78:79], v[38:39], v[102:103], v[78:79] op_sel:[1,0,0]
	v_cvt_f32_ubyte2_e32 v146, v89
	v_cvt_f32_ubyte3_e32 v147, v89
	v_pk_fma_f32 v[70:71], v[46:47], v[104:105], v[70:71] op_sel:[1,0,0]
	v_cvt_f32_ubyte0_e32 v98, v68
	v_cvt_f32_ubyte1_e32 v99, v68
	v_pk_fma_f32 v[62:63], v[46:47], v[146:147], v[62:63] op_sel:[1,0,0]
	v_cvt_f32_ubyte2_e32 v102, v68
	v_cvt_f32_ubyte3_e32 v103, v68
	v_pk_fma_f32 v[92:93], v[40:41], v[98:99], v[92:93] op_sel_hi:[0,1,1]
	v_cvt_f32_ubyte0_e32 v104, v69
	v_cvt_f32_ubyte1_e32 v105, v69
	v_pk_fma_f32 v[90:91], v[40:41], v[102:103], v[90:91] op_sel_hi:[0,1,1]
	v_cvt_f32_ubyte2_e32 v146, v69
	v_cvt_f32_ubyte3_e32 v147, v69
	v_pk_fma_f32 v[86:87], v[48:49], v[104:105], v[86:87] op_sel_hi:[0,1,1]
	v_cvt_f32_ubyte0_e32 v98, v76
	v_cvt_f32_ubyte1_e32 v99, v76
	v_pk_fma_f32 v[84:85], v[48:49], v[146:147], v[84:85] op_sel_hi:[0,1,1]
	v_and_b32_e32 v82, s0, v210
	v_and_b32_e32 v83, s1, v210
	v_and_b32_e32 v88, s0, v211
	v_and_b32_e32 v89, s1, v211
	v_cvt_f32_ubyte2_e32 v102, v76
	v_cvt_f32_ubyte3_e32 v103, v76
	v_pk_fma_f32 v[80:81], v[40:41], v[98:99], v[80:81] op_sel_hi:[0,1,1]
	v_cvt_f32_ubyte0_e32 v104, v77
	v_cvt_f32_ubyte1_e32 v105, v77
	v_pk_fma_f32 v[78:79], v[40:41], v[102:103], v[78:79] op_sel_hi:[0,1,1]
	v_cvt_f32_ubyte2_e32 v146, v77
	v_cvt_f32_ubyte3_e32 v147, v77
	v_pk_fma_f32 v[70:71], v[48:49], v[104:105], v[70:71] op_sel_hi:[0,1,1]
	v_cvt_f32_ubyte0_e32 v98, v82
	v_cvt_f32_ubyte1_e32 v99, v82
	v_pk_fma_f32 v[62:63], v[48:49], v[146:147], v[62:63] op_sel_hi:[0,1,1]
	v_cvt_f32_ubyte2_e32 v102, v82
	v_cvt_f32_ubyte3_e32 v103, v82
	v_pk_fma_f32 v[92:93], v[40:41], v[98:99], v[92:93] op_sel:[1,0,0]
	v_cvt_f32_ubyte0_e32 v104, v83
	v_cvt_f32_ubyte1_e32 v105, v83
	v_pk_fma_f32 v[90:91], v[40:41], v[102:103], v[90:91] op_sel:[1,0,0]
	v_cvt_f32_ubyte2_e32 v146, v83
	v_cvt_f32_ubyte3_e32 v147, v83
	v_pk_fma_f32 v[86:87], v[48:49], v[104:105], v[86:87] op_sel:[1,0,0]
	v_cvt_f32_ubyte0_e32 v98, v88
	v_cvt_f32_ubyte1_e32 v99, v88
	v_pk_fma_f32 v[84:85], v[48:49], v[146:147], v[84:85] op_sel:[1,0,0]
	v_cvt_f32_ubyte2_e32 v102, v88
	v_cvt_f32_ubyte3_e32 v103, v88
	v_pk_fma_f32 v[80:81], v[40:41], v[98:99], v[80:81] op_sel:[1,0,0]
	v_cvt_f32_ubyte0_e32 v104, v89
	v_cvt_f32_ubyte1_e32 v105, v89
	v_pk_fma_f32 v[78:79], v[40:41], v[102:103], v[78:79] op_sel:[1,0,0]
	v_cvt_f32_ubyte2_e32 v146, v89
	v_cvt_f32_ubyte3_e32 v147, v89
	v_pk_fma_f32 v[70:71], v[48:49], v[104:105], v[70:71] op_sel:[1,0,0]
	v_pk_fma_f32 v[62:63], v[48:49], v[146:147], v[62:63] op_sel:[1,0,0]
	s_waitcnt lgkmcnt(0)
	v_lshl_add_u32 v72, v72, 9, v100
	v_lshl_add_u32 v73, v73, 9, v100
	v_lshl_add_u32 v74, v74, 9, v100
	v_lshl_add_u32 v75, v75, 9, v100
	v_lshl_add_u32 v94, v94, 9, v100
	v_lshl_add_u32 v95, v95, 9, v100
	v_lshl_add_u32 v96, v96, 9, v100
	v_lshl_add_u32 v97, v97, 9, v100
	global_load_dwordx2 v[196:197], v72, s[38:39]
	global_load_dwordx2 v[198:199], v73, s[38:39]
	global_load_dwordx2 v[200:201], v74, s[38:39]
	global_load_dwordx2 v[202:203], v75, s[38:39]
	global_load_dwordx2 v[204:205], v94, s[38:39]
	global_load_dwordx2 v[206:207], v95, s[38:39]
	global_load_dwordx2 v[208:209], v96, s[38:39]
	global_load_dwordx2 v[210:211], v97, s[38:39]
	ds_read_b128 v[72:75], v1 offset:288
	ds_read_b128 v[94:97], v1 offset:304
	ds_read_b128 v[34:37], v1 offset:640
	ds_read_b128 v[38:41], v1 offset:656
	ds_read_b128 v[42:45], v1 offset:1664
	ds_read_b128 v[46:49], v1 offset:1680
	s_waitcnt vmcnt(40)
	v_and_b32_e32 v68, s0, v212
	v_and_b32_e32 v69, s1, v212
	v_and_b32_e32 v76, s0, v213
	v_and_b32_e32 v77, s1, v213
	v_cvt_f32_ubyte0_e32 v98, v68
	v_cvt_f32_ubyte1_e32 v99, v68
	v_cvt_f32_ubyte2_e32 v102, v68
	v_cvt_f32_ubyte3_e32 v103, v68
	v_pk_fma_f32 v[92:93], v[50:51], v[98:99], v[92:93] op_sel_hi:[0,1,1]
	v_cvt_f32_ubyte0_e32 v104, v69
	v_cvt_f32_ubyte1_e32 v105, v69
	v_pk_fma_f32 v[90:91], v[50:51], v[102:103], v[90:91] op_sel_hi:[0,1,1]
	v_cvt_f32_ubyte2_e32 v146, v69
	v_cvt_f32_ubyte3_e32 v147, v69
	v_pk_fma_f32 v[86:87], v[58:59], v[104:105], v[86:87] op_sel_hi:[0,1,1]
	v_cvt_f32_ubyte0_e32 v98, v76
	v_cvt_f32_ubyte1_e32 v99, v76
	v_pk_fma_f32 v[84:85], v[58:59], v[146:147], v[84:85] op_sel_hi:[0,1,1]
	v_and_b32_e32 v82, s0, v214
	v_and_b32_e32 v83, s1, v214
	v_and_b32_e32 v88, s0, v215
	v_and_b32_e32 v89, s1, v215
	v_cvt_f32_ubyte2_e32 v102, v76
	v_cvt_f32_ubyte3_e32 v103, v76
	v_pk_fma_f32 v[80:81], v[50:51], v[98:99], v[80:81] op_sel_hi:[0,1,1]
	v_cvt_f32_ubyte0_e32 v104, v77
	v_cvt_f32_ubyte1_e32 v105, v77
	v_pk_fma_f32 v[78:79], v[50:51], v[102:103], v[78:79] op_sel_hi:[0,1,1]
	v_cvt_f32_ubyte2_e32 v146, v77
	v_cvt_f32_ubyte3_e32 v147, v77
	v_pk_fma_f32 v[70:71], v[58:59], v[104:105], v[70:71] op_sel_hi:[0,1,1]
	v_cvt_f32_ubyte0_e32 v98, v82
	v_cvt_f32_ubyte1_e32 v99, v82
	v_pk_fma_f32 v[62:63], v[58:59], v[146:147], v[62:63] op_sel_hi:[0,1,1]
	v_cvt_f32_ubyte2_e32 v102, v82
	v_cvt_f32_ubyte3_e32 v103, v82
	v_pk_fma_f32 v[92:93], v[50:51], v[98:99], v[92:93] op_sel:[1,0,0]
	v_cvt_f32_ubyte0_e32 v104, v83
	v_cvt_f32_ubyte1_e32 v105, v83
	v_pk_fma_f32 v[90:91], v[50:51], v[102:103], v[90:91] op_sel:[1,0,0]
	v_cvt_f32_ubyte2_e32 v146, v83
	v_cvt_f32_ubyte3_e32 v147, v83
	v_pk_fma_f32 v[86:87], v[58:59], v[104:105], v[86:87] op_sel:[1,0,0]
	v_cvt_f32_ubyte0_e32 v98, v88
	v_cvt_f32_ubyte1_e32 v99, v88
	v_pk_fma_f32 v[84:85], v[58:59], v[146:147], v[84:85] op_sel:[1,0,0]
	v_and_b32_e32 v68, s0, v216
	v_and_b32_e32 v69, s1, v216
	v_and_b32_e32 v76, s0, v217
	v_and_b32_e32 v77, s1, v217
	v_cvt_f32_ubyte2_e32 v102, v88
	v_cvt_f32_ubyte3_e32 v103, v88
	v_pk_fma_f32 v[80:81], v[50:51], v[98:99], v[80:81] op_sel:[1,0,0]
	v_cvt_f32_ubyte0_e32 v104, v89
	v_cvt_f32_ubyte1_e32 v105, v89
	v_pk_fma_f32 v[78:79], v[50:51], v[102:103], v[78:79] op_sel:[1,0,0]
	v_cvt_f32_ubyte2_e32 v146, v89
	v_cvt_f32_ubyte3_e32 v147, v89
	v_pk_fma_f32 v[70:71], v[58:59], v[104:105], v[70:71] op_sel:[1,0,0]
	v_cvt_f32_ubyte0_e32 v98, v68
	v_cvt_f32_ubyte1_e32 v99, v68
	v_pk_fma_f32 v[62:63], v[58:59], v[146:147], v[62:63] op_sel:[1,0,0]
	v_cvt_f32_ubyte2_e32 v102, v68
	v_cvt_f32_ubyte3_e32 v103, v68
	v_pk_fma_f32 v[92:93], v[52:53], v[98:99], v[92:93] op_sel_hi:[0,1,1]
	v_cvt_f32_ubyte0_e32 v104, v69
	v_cvt_f32_ubyte1_e32 v105, v69
	v_pk_fma_f32 v[90:91], v[52:53], v[102:103], v[90:91] op_sel_hi:[0,1,1]
	v_cvt_f32_ubyte2_e32 v146, v69
	v_cvt_f32_ubyte3_e32 v147, v69
	v_pk_fma_f32 v[86:87], v[60:61], v[104:105], v[86:87] op_sel_hi:[0,1,1]
	v_cvt_f32_ubyte0_e32 v98, v76
	v_cvt_f32_ubyte1_e32 v99, v76
	v_pk_fma_f32 v[84:85], v[60:61], v[146:147], v[84:85] op_sel_hi:[0,1,1]
	v_and_b32_e32 v82, s0, v218
	v_and_b32_e32 v83, s1, v218
	v_and_b32_e32 v88, s0, v219
	v_and_b32_e32 v89, s1, v219
	v_cvt_f32_ubyte2_e32 v102, v76
	v_cvt_f32_ubyte3_e32 v103, v76
	v_pk_fma_f32 v[80:81], v[52:53], v[98:99], v[80:81] op_sel_hi:[0,1,1]
	v_cvt_f32_ubyte0_e32 v104, v77
	v_cvt_f32_ubyte1_e32 v105, v77
	v_pk_fma_f32 v[78:79], v[52:53], v[102:103], v[78:79] op_sel_hi:[0,1,1]
	v_cvt_f32_ubyte2_e32 v146, v77
	v_cvt_f32_ubyte3_e32 v147, v77
	v_pk_fma_f32 v[70:71], v[60:61], v[104:105], v[70:71] op_sel_hi:[0,1,1]
	v_cvt_f32_ubyte0_e32 v98, v82
	v_cvt_f32_ubyte1_e32 v99, v82
	v_pk_fma_f32 v[62:63], v[60:61], v[146:147], v[62:63] op_sel_hi:[0,1,1]
	v_cvt_f32_ubyte2_e32 v102, v82
	v_cvt_f32_ubyte3_e32 v103, v82
	v_pk_fma_f32 v[92:93], v[52:53], v[98:99], v[92:93] op_sel:[1,0,0]
	v_cvt_f32_ubyte0_e32 v104, v83
	v_cvt_f32_ubyte1_e32 v105, v83
	v_pk_fma_f32 v[90:91], v[52:53], v[102:103], v[90:91] op_sel:[1,0,0]
	v_cvt_f32_ubyte2_e32 v146, v83
	v_cvt_f32_ubyte3_e32 v147, v83
	v_pk_fma_f32 v[86:87], v[60:61], v[104:105], v[86:87] op_sel:[1,0,0]
	v_cvt_f32_ubyte0_e32 v98, v88
	v_cvt_f32_ubyte1_e32 v99, v88
	v_pk_fma_f32 v[84:85], v[60:61], v[146:147], v[84:85] op_sel:[1,0,0]
	v_and_b32_e32 v68, s0, v220
	v_and_b32_e32 v69, s1, v220
	v_and_b32_e32 v76, s0, v221
	v_and_b32_e32 v77, s1, v221
	v_cvt_f32_ubyte2_e32 v102, v88
	v_cvt_f32_ubyte3_e32 v103, v88
	v_pk_fma_f32 v[80:81], v[52:53], v[98:99], v[80:81] op_sel:[1,0,0]
	v_cvt_f32_ubyte0_e32 v104, v89
	v_cvt_f32_ubyte1_e32 v105, v89
	v_pk_fma_f32 v[78:79], v[52:53], v[102:103], v[78:79] op_sel:[1,0,0]
	v_cvt_f32_ubyte2_e32 v146, v89
	v_cvt_f32_ubyte3_e32 v147, v89
	v_pk_fma_f32 v[70:71], v[60:61], v[104:105], v[70:71] op_sel:[1,0,0]
	v_cvt_f32_ubyte0_e32 v98, v68
	v_cvt_f32_ubyte1_e32 v99, v68
	v_pk_fma_f32 v[62:63], v[60:61], v[146:147], v[62:63] op_sel:[1,0,0]
	v_cvt_f32_ubyte2_e32 v102, v68
	v_cvt_f32_ubyte3_e32 v103, v68
	v_pk_fma_f32 v[92:93], v[54:55], v[98:99], v[92:93] op_sel_hi:[0,1,1]
	v_cvt_f32_ubyte0_e32 v104, v69
	v_cvt_f32_ubyte1_e32 v105, v69
	v_pk_fma_f32 v[90:91], v[54:55], v[102:103], v[90:91] op_sel_hi:[0,1,1]
	v_cvt_f32_ubyte2_e32 v146, v69
	v_cvt_f32_ubyte3_e32 v147, v69
	v_pk_fma_f32 v[86:87], v[64:65], v[104:105], v[86:87] op_sel_hi:[0,1,1]
	v_cvt_f32_ubyte0_e32 v98, v76
	v_cvt_f32_ubyte1_e32 v99, v76
	v_pk_fma_f32 v[84:85], v[64:65], v[146:147], v[84:85] op_sel_hi:[0,1,1]
	v_and_b32_e32 v82, s0, v222
	v_and_b32_e32 v83, s1, v222
	v_and_b32_e32 v88, s0, v223
	v_and_b32_e32 v89, s1, v223
	v_cvt_f32_ubyte2_e32 v102, v76
	v_cvt_f32_ubyte3_e32 v103, v76
	v_pk_fma_f32 v[80:81], v[54:55], v[98:99], v[80:81] op_sel_hi:[0,1,1]
	v_cvt_f32_ubyte0_e32 v104, v77
	v_cvt_f32_ubyte1_e32 v105, v77
	v_pk_fma_f32 v[78:79], v[54:55], v[102:103], v[78:79] op_sel_hi:[0,1,1]
	v_cvt_f32_ubyte2_e32 v146, v77
	v_cvt_f32_ubyte3_e32 v147, v77
	v_pk_fma_f32 v[70:71], v[64:65], v[104:105], v[70:71] op_sel_hi:[0,1,1]
	v_cvt_f32_ubyte0_e32 v98, v82
	v_cvt_f32_ubyte1_e32 v99, v82
	v_pk_fma_f32 v[62:63], v[64:65], v[146:147], v[62:63] op_sel_hi:[0,1,1]
	v_cvt_f32_ubyte2_e32 v102, v82
	v_cvt_f32_ubyte3_e32 v103, v82
	v_pk_fma_f32 v[92:93], v[54:55], v[98:99], v[92:93] op_sel:[1,0,0]
	v_cvt_f32_ubyte0_e32 v104, v83
	v_cvt_f32_ubyte1_e32 v105, v83
	v_pk_fma_f32 v[90:91], v[54:55], v[102:103], v[90:91] op_sel:[1,0,0]
	v_cvt_f32_ubyte2_e32 v146, v83
	v_cvt_f32_ubyte3_e32 v147, v83
	v_pk_fma_f32 v[86:87], v[64:65], v[104:105], v[86:87] op_sel:[1,0,0]
	v_cvt_f32_ubyte0_e32 v98, v88
	v_cvt_f32_ubyte1_e32 v99, v88
	v_pk_fma_f32 v[84:85], v[64:65], v[146:147], v[84:85] op_sel:[1,0,0]
	v_and_b32_e32 v68, s0, v224
	v_and_b32_e32 v69, s1, v224
	v_and_b32_e32 v76, s0, v225
	v_and_b32_e32 v77, s1, v225
	v_cvt_f32_ubyte2_e32 v102, v88
	v_cvt_f32_ubyte3_e32 v103, v88
	v_pk_fma_f32 v[80:81], v[54:55], v[98:99], v[80:81] op_sel:[1,0,0]
	v_cvt_f32_ubyte0_e32 v104, v89
	v_cvt_f32_ubyte1_e32 v105, v89
	v_pk_fma_f32 v[78:79], v[54:55], v[102:103], v[78:79] op_sel:[1,0,0]
	v_cvt_f32_ubyte2_e32 v146, v89
	v_cvt_f32_ubyte3_e32 v147, v89
	v_pk_fma_f32 v[70:71], v[64:65], v[104:105], v[70:71] op_sel:[1,0,0]
	v_cvt_f32_ubyte0_e32 v98, v68
	v_cvt_f32_ubyte1_e32 v99, v68
	v_pk_fma_f32 v[62:63], v[64:65], v[146:147], v[62:63] op_sel:[1,0,0]
	v_cvt_f32_ubyte2_e32 v102, v68
	v_cvt_f32_ubyte3_e32 v103, v68
	v_pk_fma_f32 v[92:93], v[56:57], v[98:99], v[92:93] op_sel_hi:[0,1,1]
	v_cvt_f32_ubyte0_e32 v104, v69
	v_cvt_f32_ubyte1_e32 v105, v69
	v_pk_fma_f32 v[90:91], v[56:57], v[102:103], v[90:91] op_sel_hi:[0,1,1]
	v_cvt_f32_ubyte2_e32 v146, v69
	v_cvt_f32_ubyte3_e32 v147, v69
	v_pk_fma_f32 v[86:87], v[66:67], v[104:105], v[86:87] op_sel_hi:[0,1,1]
	v_cvt_f32_ubyte0_e32 v98, v76
	v_cvt_f32_ubyte1_e32 v99, v76
	v_pk_fma_f32 v[84:85], v[66:67], v[146:147], v[84:85] op_sel_hi:[0,1,1]
	v_and_b32_e32 v82, s0, v226
	v_and_b32_e32 v83, s1, v226
	v_and_b32_e32 v88, s0, v227
	v_and_b32_e32 v89, s1, v227
	v_cvt_f32_ubyte2_e32 v102, v76
	v_cvt_f32_ubyte3_e32 v103, v76
	v_pk_fma_f32 v[80:81], v[56:57], v[98:99], v[80:81] op_sel_hi:[0,1,1]
	v_cvt_f32_ubyte0_e32 v104, v77
	v_cvt_f32_ubyte1_e32 v105, v77
	v_pk_fma_f32 v[78:79], v[56:57], v[102:103], v[78:79] op_sel_hi:[0,1,1]
	v_cvt_f32_ubyte2_e32 v146, v77
	v_cvt_f32_ubyte3_e32 v147, v77
	v_pk_fma_f32 v[70:71], v[66:67], v[104:105], v[70:71] op_sel_hi:[0,1,1]
	v_cvt_f32_ubyte0_e32 v98, v82
	v_cvt_f32_ubyte1_e32 v99, v82
	v_pk_fma_f32 v[62:63], v[66:67], v[146:147], v[62:63] op_sel_hi:[0,1,1]
	v_cvt_f32_ubyte2_e32 v102, v82
	v_cvt_f32_ubyte3_e32 v103, v82
	v_pk_fma_f32 v[92:93], v[56:57], v[98:99], v[92:93] op_sel:[1,0,0]
	v_cvt_f32_ubyte0_e32 v104, v83
	v_cvt_f32_ubyte1_e32 v105, v83
	v_pk_fma_f32 v[90:91], v[56:57], v[102:103], v[90:91] op_sel:[1,0,0]
	v_cvt_f32_ubyte2_e32 v146, v83
	v_cvt_f32_ubyte3_e32 v147, v83
	v_pk_fma_f32 v[86:87], v[66:67], v[104:105], v[86:87] op_sel:[1,0,0]
	v_cvt_f32_ubyte0_e32 v98, v88
	v_cvt_f32_ubyte1_e32 v99, v88
	v_pk_fma_f32 v[84:85], v[66:67], v[146:147], v[84:85] op_sel:[1,0,0]
	v_cvt_f32_ubyte2_e32 v102, v88
	v_cvt_f32_ubyte3_e32 v103, v88
	v_pk_fma_f32 v[80:81], v[56:57], v[98:99], v[80:81] op_sel:[1,0,0]
	v_cvt_f32_ubyte0_e32 v104, v89
	v_cvt_f32_ubyte1_e32 v105, v89
	v_pk_fma_f32 v[78:79], v[56:57], v[102:103], v[78:79] op_sel:[1,0,0]
	v_cvt_f32_ubyte2_e32 v146, v89
	v_cvt_f32_ubyte3_e32 v147, v89
	v_pk_fma_f32 v[70:71], v[66:67], v[104:105], v[70:71] op_sel:[1,0,0]
	v_pk_fma_f32 v[62:63], v[66:67], v[146:147], v[62:63] op_sel:[1,0,0]
	s_waitcnt lgkmcnt(0)
	v_lshl_add_u32 v72, v72, 9, v100
	v_lshl_add_u32 v73, v73, 9, v100
	v_lshl_add_u32 v74, v74, 9, v100
	v_lshl_add_u32 v75, v75, 9, v100
	v_lshl_add_u32 v94, v94, 9, v100
	v_lshl_add_u32 v95, v95, 9, v100
	v_lshl_add_u32 v96, v96, 9, v100
	v_lshl_add_u32 v97, v97, 9, v100
	global_load_dwordx2 v[212:213], v72, s[38:39]
	global_load_dwordx2 v[214:215], v73, s[38:39]
	global_load_dwordx2 v[216:217], v74, s[38:39]
	global_load_dwordx2 v[218:219], v75, s[38:39]
	global_load_dwordx2 v[220:221], v94, s[38:39]
	global_load_dwordx2 v[222:223], v95, s[38:39]
	global_load_dwordx2 v[224:225], v96, s[38:39]
	global_load_dwordx2 v[226:227], v97, s[38:39]
	ds_read_b128 v[72:75], v1 offset:320
	ds_read_b128 v[94:97], v1 offset:336
	ds_read_b128 v[50:53], v1 offset:672
	ds_read_b128 v[54:57], v1 offset:688
	ds_read_b128 v[58:61], v1 offset:1696
	ds_read_b128 v[64:67], v1 offset:1712
	s_waitcnt vmcnt(40)
	v_and_b32_e32 v68, s0, v2
	v_and_b32_e32 v69, s1, v2
	v_and_b32_e32 v76, s0, v3
	v_and_b32_e32 v77, s1, v3
	v_cvt_f32_ubyte0_e32 v98, v68
	v_cvt_f32_ubyte1_e32 v99, v68
	v_cvt_f32_ubyte2_e32 v102, v68
	v_cvt_f32_ubyte3_e32 v103, v68
	v_pk_fma_f32 v[92:93], v[34:35], v[98:99], v[92:93] op_sel_hi:[0,1,1]
	v_cvt_f32_ubyte0_e32 v104, v69
	v_cvt_f32_ubyte1_e32 v105, v69
	v_pk_fma_f32 v[90:91], v[34:35], v[102:103], v[90:91] op_sel_hi:[0,1,1]
	v_cvt_f32_ubyte2_e32 v146, v69
	v_cvt_f32_ubyte3_e32 v147, v69
	v_pk_fma_f32 v[86:87], v[42:43], v[104:105], v[86:87] op_sel_hi:[0,1,1]
	v_cvt_f32_ubyte0_e32 v98, v76
	v_cvt_f32_ubyte1_e32 v99, v76
	v_pk_fma_f32 v[84:85], v[42:43], v[146:147], v[84:85] op_sel_hi:[0,1,1]
	v_and_b32_e32 v82, s0, v4
	v_and_b32_e32 v83, s1, v4
	v_and_b32_e32 v88, s0, v5
	v_and_b32_e32 v89, s1, v5
	v_cvt_f32_ubyte2_e32 v102, v76
	v_cvt_f32_ubyte3_e32 v103, v76
	v_pk_fma_f32 v[80:81], v[34:35], v[98:99], v[80:81] op_sel_hi:[0,1,1]
	v_cvt_f32_ubyte0_e32 v104, v77
	v_cvt_f32_ubyte1_e32 v105, v77
	v_pk_fma_f32 v[78:79], v[34:35], v[102:103], v[78:79] op_sel_hi:[0,1,1]
	v_cvt_f32_ubyte2_e32 v146, v77
	v_cvt_f32_ubyte3_e32 v147, v77
	v_pk_fma_f32 v[70:71], v[42:43], v[104:105], v[70:71] op_sel_hi:[0,1,1]
	v_cvt_f32_ubyte0_e32 v98, v82
	v_cvt_f32_ubyte1_e32 v99, v82
	v_pk_fma_f32 v[62:63], v[42:43], v[146:147], v[62:63] op_sel_hi:[0,1,1]
	v_cvt_f32_ubyte2_e32 v102, v82
	v_cvt_f32_ubyte3_e32 v103, v82
	v_pk_fma_f32 v[92:93], v[34:35], v[98:99], v[92:93] op_sel:[1,0,0]
	v_cvt_f32_ubyte0_e32 v104, v83
	v_cvt_f32_ubyte1_e32 v105, v83
	v_pk_fma_f32 v[90:91], v[34:35], v[102:103], v[90:91] op_sel:[1,0,0]
	v_cvt_f32_ubyte2_e32 v146, v83
	v_cvt_f32_ubyte3_e32 v147, v83
	v_pk_fma_f32 v[86:87], v[42:43], v[104:105], v[86:87] op_sel:[1,0,0]
	v_cvt_f32_ubyte0_e32 v98, v88
	v_cvt_f32_ubyte1_e32 v99, v88
	v_pk_fma_f32 v[84:85], v[42:43], v[146:147], v[84:85] op_sel:[1,0,0]
	v_and_b32_e32 v68, s0, v6
	v_and_b32_e32 v69, s1, v6
	v_and_b32_e32 v76, s0, v7
	v_and_b32_e32 v77, s1, v7
	v_cvt_f32_ubyte2_e32 v102, v88
	v_cvt_f32_ubyte3_e32 v103, v88
	v_pk_fma_f32 v[80:81], v[34:35], v[98:99], v[80:81] op_sel:[1,0,0]
	v_cvt_f32_ubyte0_e32 v104, v89
	v_cvt_f32_ubyte1_e32 v105, v89
	v_pk_fma_f32 v[78:79], v[34:35], v[102:103], v[78:79] op_sel:[1,0,0]
	v_cvt_f32_ubyte2_e32 v146, v89
	v_cvt_f32_ubyte3_e32 v147, v89
	v_pk_fma_f32 v[70:71], v[42:43], v[104:105], v[70:71] op_sel:[1,0,0]
	v_cvt_f32_ubyte0_e32 v98, v68
	v_cvt_f32_ubyte1_e32 v99, v68
	v_pk_fma_f32 v[62:63], v[42:43], v[146:147], v[62:63] op_sel:[1,0,0]
	v_cvt_f32_ubyte2_e32 v102, v68
	v_cvt_f32_ubyte3_e32 v103, v68
	v_pk_fma_f32 v[92:93], v[36:37], v[98:99], v[92:93] op_sel_hi:[0,1,1]
	v_cvt_f32_ubyte0_e32 v104, v69
	v_cvt_f32_ubyte1_e32 v105, v69
	v_pk_fma_f32 v[90:91], v[36:37], v[102:103], v[90:91] op_sel_hi:[0,1,1]
	v_cvt_f32_ubyte2_e32 v146, v69
	v_cvt_f32_ubyte3_e32 v147, v69
	v_pk_fma_f32 v[86:87], v[44:45], v[104:105], v[86:87] op_sel_hi:[0,1,1]
	v_cvt_f32_ubyte0_e32 v98, v76
	v_cvt_f32_ubyte1_e32 v99, v76
	v_pk_fma_f32 v[84:85], v[44:45], v[146:147], v[84:85] op_sel_hi:[0,1,1]
	v_and_b32_e32 v82, s0, v8
	v_and_b32_e32 v83, s1, v8
	v_and_b32_e32 v88, s0, v9
	v_and_b32_e32 v89, s1, v9
	v_cvt_f32_ubyte2_e32 v102, v76
	v_cvt_f32_ubyte3_e32 v103, v76
	v_pk_fma_f32 v[80:81], v[36:37], v[98:99], v[80:81] op_sel_hi:[0,1,1]
	v_cvt_f32_ubyte0_e32 v104, v77
	v_cvt_f32_ubyte1_e32 v105, v77
	v_pk_fma_f32 v[78:79], v[36:37], v[102:103], v[78:79] op_sel_hi:[0,1,1]
	v_cvt_f32_ubyte2_e32 v146, v77
	v_cvt_f32_ubyte3_e32 v147, v77
	v_pk_fma_f32 v[70:71], v[44:45], v[104:105], v[70:71] op_sel_hi:[0,1,1]
	v_cvt_f32_ubyte0_e32 v98, v82
	v_cvt_f32_ubyte1_e32 v99, v82
	v_pk_fma_f32 v[62:63], v[44:45], v[146:147], v[62:63] op_sel_hi:[0,1,1]
	v_cvt_f32_ubyte2_e32 v102, v82
	v_cvt_f32_ubyte3_e32 v103, v82
	v_pk_fma_f32 v[92:93], v[36:37], v[98:99], v[92:93] op_sel:[1,0,0]
	v_cvt_f32_ubyte0_e32 v104, v83
	v_cvt_f32_ubyte1_e32 v105, v83
	v_pk_fma_f32 v[90:91], v[36:37], v[102:103], v[90:91] op_sel:[1,0,0]
	v_cvt_f32_ubyte2_e32 v146, v83
	v_cvt_f32_ubyte3_e32 v147, v83
	v_pk_fma_f32 v[86:87], v[44:45], v[104:105], v[86:87] op_sel:[1,0,0]
	v_cvt_f32_ubyte0_e32 v98, v88
	v_cvt_f32_ubyte1_e32 v99, v88
	v_pk_fma_f32 v[84:85], v[44:45], v[146:147], v[84:85] op_sel:[1,0,0]
	v_and_b32_e32 v68, s0, v10
	v_and_b32_e32 v69, s1, v10
	v_and_b32_e32 v76, s0, v11
	v_and_b32_e32 v77, s1, v11
	v_cvt_f32_ubyte2_e32 v102, v88
	v_cvt_f32_ubyte3_e32 v103, v88
	v_pk_fma_f32 v[80:81], v[36:37], v[98:99], v[80:81] op_sel:[1,0,0]
	v_cvt_f32_ubyte0_e32 v104, v89
	v_cvt_f32_ubyte1_e32 v105, v89
	v_pk_fma_f32 v[78:79], v[36:37], v[102:103], v[78:79] op_sel:[1,0,0]
	v_cvt_f32_ubyte2_e32 v146, v89
	v_cvt_f32_ubyte3_e32 v147, v89
	v_pk_fma_f32 v[70:71], v[44:45], v[104:105], v[70:71] op_sel:[1,0,0]
	v_cvt_f32_ubyte0_e32 v98, v68
	v_cvt_f32_ubyte1_e32 v99, v68
	v_pk_fma_f32 v[62:63], v[44:45], v[146:147], v[62:63] op_sel:[1,0,0]
	v_cvt_f32_ubyte2_e32 v102, v68
	v_cvt_f32_ubyte3_e32 v103, v68
	v_pk_fma_f32 v[92:93], v[38:39], v[98:99], v[92:93] op_sel_hi:[0,1,1]
	v_cvt_f32_ubyte0_e32 v104, v69
	v_cvt_f32_ubyte1_e32 v105, v69
	v_pk_fma_f32 v[90:91], v[38:39], v[102:103], v[90:91] op_sel_hi:[0,1,1]
	v_cvt_f32_ubyte2_e32 v146, v69
	v_cvt_f32_ubyte3_e32 v147, v69
	v_pk_fma_f32 v[86:87], v[46:47], v[104:105], v[86:87] op_sel_hi:[0,1,1]
	v_cvt_f32_ubyte0_e32 v98, v76
	v_cvt_f32_ubyte1_e32 v99, v76
	v_pk_fma_f32 v[84:85], v[46:47], v[146:147], v[84:85] op_sel_hi:[0,1,1]
	v_and_b32_e32 v82, s0, v12
	v_and_b32_e32 v83, s1, v12
	v_and_b32_e32 v88, s0, v13
	v_and_b32_e32 v89, s1, v13
	v_cvt_f32_ubyte2_e32 v102, v76
	v_cvt_f32_ubyte3_e32 v103, v76
	v_pk_fma_f32 v[80:81], v[38:39], v[98:99], v[80:81] op_sel_hi:[0,1,1]
	v_cvt_f32_ubyte0_e32 v104, v77
	v_cvt_f32_ubyte1_e32 v105, v77
	v_pk_fma_f32 v[78:79], v[38:39], v[102:103], v[78:79] op_sel_hi:[0,1,1]
	v_cvt_f32_ubyte2_e32 v146, v77
	v_cvt_f32_ubyte3_e32 v147, v77
	v_pk_fma_f32 v[70:71], v[46:47], v[104:105], v[70:71] op_sel_hi:[0,1,1]
	v_cvt_f32_ubyte0_e32 v98, v82
	v_cvt_f32_ubyte1_e32 v99, v82
	v_pk_fma_f32 v[62:63], v[46:47], v[146:147], v[62:63] op_sel_hi:[0,1,1]
	v_cvt_f32_ubyte2_e32 v102, v82
	v_cvt_f32_ubyte3_e32 v103, v82
	v_pk_fma_f32 v[92:93], v[38:39], v[98:99], v[92:93] op_sel:[1,0,0]
	v_cvt_f32_ubyte0_e32 v104, v83
	v_cvt_f32_ubyte1_e32 v105, v83
	v_pk_fma_f32 v[90:91], v[38:39], v[102:103], v[90:91] op_sel:[1,0,0]
	v_cvt_f32_ubyte2_e32 v146, v83
	v_cvt_f32_ubyte3_e32 v147, v83
	v_pk_fma_f32 v[86:87], v[46:47], v[104:105], v[86:87] op_sel:[1,0,0]
	v_cvt_f32_ubyte0_e32 v98, v88
	v_cvt_f32_ubyte1_e32 v99, v88
	v_pk_fma_f32 v[84:85], v[46:47], v[146:147], v[84:85] op_sel:[1,0,0]
	v_and_b32_e32 v68, s0, v14
	v_and_b32_e32 v69, s1, v14
	v_and_b32_e32 v76, s0, v15
	v_and_b32_e32 v77, s1, v15
	v_cvt_f32_ubyte2_e32 v102, v88
	v_cvt_f32_ubyte3_e32 v103, v88
	v_pk_fma_f32 v[80:81], v[38:39], v[98:99], v[80:81] op_sel:[1,0,0]
	v_cvt_f32_ubyte0_e32 v104, v89
	v_cvt_f32_ubyte1_e32 v105, v89
	v_pk_fma_f32 v[78:79], v[38:39], v[102:103], v[78:79] op_sel:[1,0,0]
	v_cvt_f32_ubyte2_e32 v146, v89
	v_cvt_f32_ubyte3_e32 v147, v89
	v_pk_fma_f32 v[70:71], v[46:47], v[104:105], v[70:71] op_sel:[1,0,0]
	v_cvt_f32_ubyte0_e32 v98, v68
	v_cvt_f32_ubyte1_e32 v99, v68
	v_pk_fma_f32 v[62:63], v[46:47], v[146:147], v[62:63] op_sel:[1,0,0]
	v_cvt_f32_ubyte2_e32 v102, v68
	v_cvt_f32_ubyte3_e32 v103, v68
	v_pk_fma_f32 v[92:93], v[40:41], v[98:99], v[92:93] op_sel_hi:[0,1,1]
	v_cvt_f32_ubyte0_e32 v104, v69
	v_cvt_f32_ubyte1_e32 v105, v69
	v_pk_fma_f32 v[90:91], v[40:41], v[102:103], v[90:91] op_sel_hi:[0,1,1]
	v_cvt_f32_ubyte2_e32 v146, v69
	v_cvt_f32_ubyte3_e32 v147, v69
	v_pk_fma_f32 v[86:87], v[48:49], v[104:105], v[86:87] op_sel_hi:[0,1,1]
	v_cvt_f32_ubyte0_e32 v98, v76
	v_cvt_f32_ubyte1_e32 v99, v76
	v_pk_fma_f32 v[84:85], v[48:49], v[146:147], v[84:85] op_sel_hi:[0,1,1]
	v_and_b32_e32 v82, s0, v16
	v_and_b32_e32 v83, s1, v16
	v_and_b32_e32 v88, s0, v17
	v_and_b32_e32 v89, s1, v17
	v_cvt_f32_ubyte2_e32 v102, v76
	v_cvt_f32_ubyte3_e32 v103, v76
	v_pk_fma_f32 v[80:81], v[40:41], v[98:99], v[80:81] op_sel_hi:[0,1,1]
	v_cvt_f32_ubyte0_e32 v104, v77
	v_cvt_f32_ubyte1_e32 v105, v77
	v_pk_fma_f32 v[78:79], v[40:41], v[102:103], v[78:79] op_sel_hi:[0,1,1]
	v_cvt_f32_ubyte2_e32 v146, v77
	v_cvt_f32_ubyte3_e32 v147, v77
	v_pk_fma_f32 v[70:71], v[48:49], v[104:105], v[70:71] op_sel_hi:[0,1,1]
	v_cvt_f32_ubyte0_e32 v98, v82
	v_cvt_f32_ubyte1_e32 v99, v82
	v_pk_fma_f32 v[62:63], v[48:49], v[146:147], v[62:63] op_sel_hi:[0,1,1]
	v_cvt_f32_ubyte2_e32 v102, v82
	v_cvt_f32_ubyte3_e32 v103, v82
	v_pk_fma_f32 v[92:93], v[40:41], v[98:99], v[92:93] op_sel:[1,0,0]
	v_cvt_f32_ubyte0_e32 v104, v83
	v_cvt_f32_ubyte1_e32 v105, v83
	v_pk_fma_f32 v[90:91], v[40:41], v[102:103], v[90:91] op_sel:[1,0,0]
	v_cvt_f32_ubyte2_e32 v146, v83
	v_cvt_f32_ubyte3_e32 v147, v83
	v_pk_fma_f32 v[86:87], v[48:49], v[104:105], v[86:87] op_sel:[1,0,0]
	v_cvt_f32_ubyte0_e32 v98, v88
	v_cvt_f32_ubyte1_e32 v99, v88
	v_pk_fma_f32 v[84:85], v[48:49], v[146:147], v[84:85] op_sel:[1,0,0]
	v_cvt_f32_ubyte2_e32 v102, v88
	v_cvt_f32_ubyte3_e32 v103, v88
	v_pk_fma_f32 v[80:81], v[40:41], v[98:99], v[80:81] op_sel:[1,0,0]
	v_cvt_f32_ubyte0_e32 v104, v89
	v_cvt_f32_ubyte1_e32 v105, v89
	v_pk_fma_f32 v[78:79], v[40:41], v[102:103], v[78:79] op_sel:[1,0,0]
	v_cvt_f32_ubyte2_e32 v146, v89
	v_cvt_f32_ubyte3_e32 v147, v89
	v_pk_fma_f32 v[70:71], v[48:49], v[104:105], v[70:71] op_sel:[1,0,0]
	v_pk_fma_f32 v[62:63], v[48:49], v[146:147], v[62:63] op_sel:[1,0,0]
	s_waitcnt lgkmcnt(0)
	v_lshl_add_u32 v72, v72, 9, v100
	v_lshl_add_u32 v73, v73, 9, v100
	v_lshl_add_u32 v74, v74, 9, v100
	v_lshl_add_u32 v75, v75, 9, v100
	v_lshl_add_u32 v94, v94, 9, v100
	v_lshl_add_u32 v95, v95, 9, v100
	v_lshl_add_u32 v96, v96, 9, v100
	v_lshl_add_u32 v97, v97, 9, v100
	global_load_dwordx2 v[2:3], v72, s[38:39]
	global_load_dwordx2 v[4:5], v73, s[38:39]
	global_load_dwordx2 v[6:7], v74, s[38:39]
	global_load_dwordx2 v[8:9], v75, s[38:39]
	global_load_dwordx2 v[10:11], v94, s[38:39]
	global_load_dwordx2 v[12:13], v95, s[38:39]
	global_load_dwordx2 v[14:15], v96, s[38:39]
	global_load_dwordx2 v[16:17], v97, s[38:39]
	ds_read_b128 v[72:75], v1 offset:352
	ds_read_b128 v[94:97], v1 offset:368
	ds_read_b128 v[34:37], v1 offset:704
	ds_read_b128 v[38:41], v1 offset:720
	ds_read_b128 v[42:45], v1 offset:1728
	ds_read_b128 v[46:49], v1 offset:1744
	s_waitcnt vmcnt(40)
	v_and_b32_e32 v68, s0, v18
	v_and_b32_e32 v69, s1, v18
	v_and_b32_e32 v76, s0, v19
	v_and_b32_e32 v77, s1, v19
	v_cvt_f32_ubyte0_e32 v98, v68
	v_cvt_f32_ubyte1_e32 v99, v68
	v_cvt_f32_ubyte2_e32 v102, v68
	v_cvt_f32_ubyte3_e32 v103, v68
	v_pk_fma_f32 v[92:93], v[50:51], v[98:99], v[92:93] op_sel_hi:[0,1,1]
	v_cvt_f32_ubyte0_e32 v104, v69
	v_cvt_f32_ubyte1_e32 v105, v69
	v_pk_fma_f32 v[90:91], v[50:51], v[102:103], v[90:91] op_sel_hi:[0,1,1]
	v_cvt_f32_ubyte2_e32 v146, v69
	v_cvt_f32_ubyte3_e32 v147, v69
	v_pk_fma_f32 v[86:87], v[58:59], v[104:105], v[86:87] op_sel_hi:[0,1,1]
	v_cvt_f32_ubyte0_e32 v98, v76
	v_cvt_f32_ubyte1_e32 v99, v76
	v_pk_fma_f32 v[84:85], v[58:59], v[146:147], v[84:85] op_sel_hi:[0,1,1]
	v_and_b32_e32 v82, s0, v20
	v_and_b32_e32 v83, s1, v20
	v_and_b32_e32 v88, s0, v21
	v_and_b32_e32 v89, s1, v21
	v_cvt_f32_ubyte2_e32 v102, v76
	v_cvt_f32_ubyte3_e32 v103, v76
	v_pk_fma_f32 v[80:81], v[50:51], v[98:99], v[80:81] op_sel_hi:[0,1,1]
	v_cvt_f32_ubyte0_e32 v104, v77
	v_cvt_f32_ubyte1_e32 v105, v77
	v_pk_fma_f32 v[78:79], v[50:51], v[102:103], v[78:79] op_sel_hi:[0,1,1]
	v_cvt_f32_ubyte2_e32 v146, v77
	v_cvt_f32_ubyte3_e32 v147, v77
	v_pk_fma_f32 v[70:71], v[58:59], v[104:105], v[70:71] op_sel_hi:[0,1,1]
	v_cvt_f32_ubyte0_e32 v98, v82
	v_cvt_f32_ubyte1_e32 v99, v82
	v_pk_fma_f32 v[62:63], v[58:59], v[146:147], v[62:63] op_sel_hi:[0,1,1]
	v_cvt_f32_ubyte2_e32 v102, v82
	v_cvt_f32_ubyte3_e32 v103, v82
	v_pk_fma_f32 v[92:93], v[50:51], v[98:99], v[92:93] op_sel:[1,0,0]
	v_cvt_f32_ubyte0_e32 v104, v83
	v_cvt_f32_ubyte1_e32 v105, v83
	v_pk_fma_f32 v[90:91], v[50:51], v[102:103], v[90:91] op_sel:[1,0,0]
	v_cvt_f32_ubyte2_e32 v146, v83
	v_cvt_f32_ubyte3_e32 v147, v83
	v_pk_fma_f32 v[86:87], v[58:59], v[104:105], v[86:87] op_sel:[1,0,0]
	v_cvt_f32_ubyte0_e32 v98, v88
	v_cvt_f32_ubyte1_e32 v99, v88
	v_pk_fma_f32 v[84:85], v[58:59], v[146:147], v[84:85] op_sel:[1,0,0]
	v_and_b32_e32 v68, s0, v22
	v_and_b32_e32 v69, s1, v22
	v_and_b32_e32 v76, s0, v23
	v_and_b32_e32 v77, s1, v23
	v_cvt_f32_ubyte2_e32 v102, v88
	v_cvt_f32_ubyte3_e32 v103, v88
	v_pk_fma_f32 v[80:81], v[50:51], v[98:99], v[80:81] op_sel:[1,0,0]
	v_cvt_f32_ubyte0_e32 v104, v89
	v_cvt_f32_ubyte1_e32 v105, v89
	v_pk_fma_f32 v[78:79], v[50:51], v[102:103], v[78:79] op_sel:[1,0,0]
	v_cvt_f32_ubyte2_e32 v146, v89
	v_cvt_f32_ubyte3_e32 v147, v89
	v_pk_fma_f32 v[70:71], v[58:59], v[104:105], v[70:71] op_sel:[1,0,0]
	v_cvt_f32_ubyte0_e32 v98, v68
	v_cvt_f32_ubyte1_e32 v99, v68
	v_pk_fma_f32 v[62:63], v[58:59], v[146:147], v[62:63] op_sel:[1,0,0]
	v_cvt_f32_ubyte2_e32 v102, v68
	v_cvt_f32_ubyte3_e32 v103, v68
	v_pk_fma_f32 v[92:93], v[52:53], v[98:99], v[92:93] op_sel_hi:[0,1,1]
	v_cvt_f32_ubyte0_e32 v104, v69
	v_cvt_f32_ubyte1_e32 v105, v69
	v_pk_fma_f32 v[90:91], v[52:53], v[102:103], v[90:91] op_sel_hi:[0,1,1]
	v_cvt_f32_ubyte2_e32 v146, v69
	v_cvt_f32_ubyte3_e32 v147, v69
	v_pk_fma_f32 v[86:87], v[60:61], v[104:105], v[86:87] op_sel_hi:[0,1,1]
	v_cvt_f32_ubyte0_e32 v98, v76
	v_cvt_f32_ubyte1_e32 v99, v76
	v_pk_fma_f32 v[84:85], v[60:61], v[146:147], v[84:85] op_sel_hi:[0,1,1]
	v_and_b32_e32 v82, s0, v24
	v_and_b32_e32 v83, s1, v24
	v_and_b32_e32 v88, s0, v25
	v_and_b32_e32 v89, s1, v25
	v_cvt_f32_ubyte2_e32 v102, v76
	v_cvt_f32_ubyte3_e32 v103, v76
	v_pk_fma_f32 v[80:81], v[52:53], v[98:99], v[80:81] op_sel_hi:[0,1,1]
	v_cvt_f32_ubyte0_e32 v104, v77
	v_cvt_f32_ubyte1_e32 v105, v77
	v_pk_fma_f32 v[78:79], v[52:53], v[102:103], v[78:79] op_sel_hi:[0,1,1]
	v_cvt_f32_ubyte2_e32 v146, v77
	v_cvt_f32_ubyte3_e32 v147, v77
	v_pk_fma_f32 v[70:71], v[60:61], v[104:105], v[70:71] op_sel_hi:[0,1,1]
	v_cvt_f32_ubyte0_e32 v98, v82
	v_cvt_f32_ubyte1_e32 v99, v82
	v_pk_fma_f32 v[62:63], v[60:61], v[146:147], v[62:63] op_sel_hi:[0,1,1]
	v_cvt_f32_ubyte2_e32 v102, v82
	v_cvt_f32_ubyte3_e32 v103, v82
	v_pk_fma_f32 v[92:93], v[52:53], v[98:99], v[92:93] op_sel:[1,0,0]
	v_cvt_f32_ubyte0_e32 v104, v83
	v_cvt_f32_ubyte1_e32 v105, v83
	v_pk_fma_f32 v[90:91], v[52:53], v[102:103], v[90:91] op_sel:[1,0,0]
	v_cvt_f32_ubyte2_e32 v146, v83
	v_cvt_f32_ubyte3_e32 v147, v83
	v_pk_fma_f32 v[86:87], v[60:61], v[104:105], v[86:87] op_sel:[1,0,0]
	v_cvt_f32_ubyte0_e32 v98, v88
	v_cvt_f32_ubyte1_e32 v99, v88
	v_pk_fma_f32 v[84:85], v[60:61], v[146:147], v[84:85] op_sel:[1,0,0]
	v_and_b32_e32 v68, s0, v26
	v_and_b32_e32 v69, s1, v26
	v_and_b32_e32 v76, s0, v27
	v_and_b32_e32 v77, s1, v27
	v_cvt_f32_ubyte2_e32 v102, v88
	v_cvt_f32_ubyte3_e32 v103, v88
	v_pk_fma_f32 v[80:81], v[52:53], v[98:99], v[80:81] op_sel:[1,0,0]
	v_cvt_f32_ubyte0_e32 v104, v89
	v_cvt_f32_ubyte1_e32 v105, v89
	v_pk_fma_f32 v[78:79], v[52:53], v[102:103], v[78:79] op_sel:[1,0,0]
	v_cvt_f32_ubyte2_e32 v146, v89
	v_cvt_f32_ubyte3_e32 v147, v89
	v_pk_fma_f32 v[70:71], v[60:61], v[104:105], v[70:71] op_sel:[1,0,0]
	v_cvt_f32_ubyte0_e32 v98, v68
	v_cvt_f32_ubyte1_e32 v99, v68
	v_pk_fma_f32 v[62:63], v[60:61], v[146:147], v[62:63] op_sel:[1,0,0]
	v_cvt_f32_ubyte2_e32 v102, v68
	v_cvt_f32_ubyte3_e32 v103, v68
	v_pk_fma_f32 v[92:93], v[54:55], v[98:99], v[92:93] op_sel_hi:[0,1,1]
	v_cvt_f32_ubyte0_e32 v104, v69
	v_cvt_f32_ubyte1_e32 v105, v69
	v_pk_fma_f32 v[90:91], v[54:55], v[102:103], v[90:91] op_sel_hi:[0,1,1]
	v_cvt_f32_ubyte2_e32 v146, v69
	v_cvt_f32_ubyte3_e32 v147, v69
	v_pk_fma_f32 v[86:87], v[64:65], v[104:105], v[86:87] op_sel_hi:[0,1,1]
	v_cvt_f32_ubyte0_e32 v98, v76
	v_cvt_f32_ubyte1_e32 v99, v76
	v_pk_fma_f32 v[84:85], v[64:65], v[146:147], v[84:85] op_sel_hi:[0,1,1]
	v_and_b32_e32 v82, s0, v28
	v_and_b32_e32 v83, s1, v28
	v_and_b32_e32 v88, s0, v29
	v_and_b32_e32 v89, s1, v29
	v_cvt_f32_ubyte2_e32 v102, v76
	v_cvt_f32_ubyte3_e32 v103, v76
	v_pk_fma_f32 v[80:81], v[54:55], v[98:99], v[80:81] op_sel_hi:[0,1,1]
	v_cvt_f32_ubyte0_e32 v104, v77
	v_cvt_f32_ubyte1_e32 v105, v77
	v_pk_fma_f32 v[78:79], v[54:55], v[102:103], v[78:79] op_sel_hi:[0,1,1]
	v_cvt_f32_ubyte2_e32 v146, v77
	v_cvt_f32_ubyte3_e32 v147, v77
	v_pk_fma_f32 v[70:71], v[64:65], v[104:105], v[70:71] op_sel_hi:[0,1,1]
	v_cvt_f32_ubyte0_e32 v98, v82
	v_cvt_f32_ubyte1_e32 v99, v82
	v_pk_fma_f32 v[62:63], v[64:65], v[146:147], v[62:63] op_sel_hi:[0,1,1]
	v_cvt_f32_ubyte2_e32 v102, v82
	v_cvt_f32_ubyte3_e32 v103, v82
	v_pk_fma_f32 v[92:93], v[54:55], v[98:99], v[92:93] op_sel:[1,0,0]
	v_cvt_f32_ubyte0_e32 v104, v83
	v_cvt_f32_ubyte1_e32 v105, v83
	v_pk_fma_f32 v[90:91], v[54:55], v[102:103], v[90:91] op_sel:[1,0,0]
	v_cvt_f32_ubyte2_e32 v146, v83
	v_cvt_f32_ubyte3_e32 v147, v83
	v_pk_fma_f32 v[86:87], v[64:65], v[104:105], v[86:87] op_sel:[1,0,0]
	v_cvt_f32_ubyte0_e32 v98, v88
	v_cvt_f32_ubyte1_e32 v99, v88
	v_pk_fma_f32 v[84:85], v[64:65], v[146:147], v[84:85] op_sel:[1,0,0]
	v_and_b32_e32 v68, s0, v30
	v_and_b32_e32 v69, s1, v30
	v_and_b32_e32 v76, s0, v31
	v_and_b32_e32 v77, s1, v31
	v_cvt_f32_ubyte2_e32 v102, v88
	v_cvt_f32_ubyte3_e32 v103, v88
	v_pk_fma_f32 v[80:81], v[54:55], v[98:99], v[80:81] op_sel:[1,0,0]
	v_cvt_f32_ubyte0_e32 v104, v89
	v_cvt_f32_ubyte1_e32 v105, v89
	v_pk_fma_f32 v[78:79], v[54:55], v[102:103], v[78:79] op_sel:[1,0,0]
	v_cvt_f32_ubyte2_e32 v146, v89
	v_cvt_f32_ubyte3_e32 v147, v89
	v_pk_fma_f32 v[70:71], v[64:65], v[104:105], v[70:71] op_sel:[1,0,0]
	v_cvt_f32_ubyte0_e32 v98, v68
	v_cvt_f32_ubyte1_e32 v99, v68
	v_pk_fma_f32 v[62:63], v[64:65], v[146:147], v[62:63] op_sel:[1,0,0]
	v_cvt_f32_ubyte2_e32 v102, v68
	v_cvt_f32_ubyte3_e32 v103, v68
	v_pk_fma_f32 v[92:93], v[56:57], v[98:99], v[92:93] op_sel_hi:[0,1,1]
	v_cvt_f32_ubyte0_e32 v104, v69
	v_cvt_f32_ubyte1_e32 v105, v69
	v_pk_fma_f32 v[90:91], v[56:57], v[102:103], v[90:91] op_sel_hi:[0,1,1]
	v_cvt_f32_ubyte2_e32 v146, v69
	v_cvt_f32_ubyte3_e32 v147, v69
	v_pk_fma_f32 v[86:87], v[66:67], v[104:105], v[86:87] op_sel_hi:[0,1,1]
	v_cvt_f32_ubyte0_e32 v98, v76
	v_cvt_f32_ubyte1_e32 v99, v76
	v_pk_fma_f32 v[84:85], v[66:67], v[146:147], v[84:85] op_sel_hi:[0,1,1]
	v_and_b32_e32 v82, s0, v32
	v_and_b32_e32 v83, s1, v32
	v_and_b32_e32 v88, s0, v33
	v_and_b32_e32 v89, s1, v33
	v_cvt_f32_ubyte2_e32 v102, v76
	v_cvt_f32_ubyte3_e32 v103, v76
	v_pk_fma_f32 v[80:81], v[56:57], v[98:99], v[80:81] op_sel_hi:[0,1,1]
	v_cvt_f32_ubyte0_e32 v104, v77
	v_cvt_f32_ubyte1_e32 v105, v77
	v_pk_fma_f32 v[78:79], v[56:57], v[102:103], v[78:79] op_sel_hi:[0,1,1]
	v_cvt_f32_ubyte2_e32 v146, v77
	v_cvt_f32_ubyte3_e32 v147, v77
	v_pk_fma_f32 v[70:71], v[66:67], v[104:105], v[70:71] op_sel_hi:[0,1,1]
	v_cvt_f32_ubyte0_e32 v98, v82
	v_cvt_f32_ubyte1_e32 v99, v82
	v_pk_fma_f32 v[62:63], v[66:67], v[146:147], v[62:63] op_sel_hi:[0,1,1]
	v_cvt_f32_ubyte2_e32 v102, v82
	v_cvt_f32_ubyte3_e32 v103, v82
	v_pk_fma_f32 v[92:93], v[56:57], v[98:99], v[92:93] op_sel:[1,0,0]
	v_cvt_f32_ubyte0_e32 v104, v83
	v_cvt_f32_ubyte1_e32 v105, v83
	v_pk_fma_f32 v[90:91], v[56:57], v[102:103], v[90:91] op_sel:[1,0,0]
	v_cvt_f32_ubyte2_e32 v146, v83
	v_cvt_f32_ubyte3_e32 v147, v83
	v_pk_fma_f32 v[86:87], v[66:67], v[104:105], v[86:87] op_sel:[1,0,0]
	v_cvt_f32_ubyte0_e32 v98, v88
	v_cvt_f32_ubyte1_e32 v99, v88
	v_pk_fma_f32 v[84:85], v[66:67], v[146:147], v[84:85] op_sel:[1,0,0]
	v_cvt_f32_ubyte2_e32 v102, v88
	v_cvt_f32_ubyte3_e32 v103, v88
	v_pk_fma_f32 v[80:81], v[56:57], v[98:99], v[80:81] op_sel:[1,0,0]
	v_cvt_f32_ubyte0_e32 v104, v89
	v_cvt_f32_ubyte1_e32 v105, v89
	v_pk_fma_f32 v[78:79], v[56:57], v[102:103], v[78:79] op_sel:[1,0,0]
	v_cvt_f32_ubyte2_e32 v146, v89
	v_cvt_f32_ubyte3_e32 v147, v89
	v_pk_fma_f32 v[70:71], v[66:67], v[104:105], v[70:71] op_sel:[1,0,0]
	v_pk_fma_f32 v[62:63], v[66:67], v[146:147], v[62:63] op_sel:[1,0,0]
	s_waitcnt lgkmcnt(0)
	v_lshl_add_u32 v72, v72, 9, v100
	v_lshl_add_u32 v73, v73, 9, v100
	v_lshl_add_u32 v74, v74, 9, v100
	v_lshl_add_u32 v75, v75, 9, v100
	v_lshl_add_u32 v94, v94, 9, v100
	v_lshl_add_u32 v95, v95, 9, v100
	v_lshl_add_u32 v96, v96, 9, v100
	v_lshl_add_u32 v97, v97, 9, v100
	global_load_dwordx2 v[18:19], v72, s[38:39]
	global_load_dwordx2 v[20:21], v73, s[38:39]
	global_load_dwordx2 v[22:23], v74, s[38:39]
	global_load_dwordx2 v[24:25], v75, s[38:39]
	global_load_dwordx2 v[26:27], v94, s[38:39]
	global_load_dwordx2 v[28:29], v95, s[38:39]
	global_load_dwordx2 v[30:31], v96, s[38:39]
	global_load_dwordx2 v[32:33], v97, s[38:39]
	ds_read_b128 v[72:75], v1 offset:384
	ds_read_b128 v[94:97], v1 offset:400
	ds_read_b128 v[50:53], v1 offset:736
	ds_read_b128 v[54:57], v1 offset:752
	ds_read_b128 v[58:61], v1 offset:1760
	ds_read_b128 v[64:67], v1 offset:1776
	s_waitcnt vmcnt(40)
	v_and_b32_e32 v68, s0, v164
	v_and_b32_e32 v69, s1, v164
	v_and_b32_e32 v76, s0, v165
	v_and_b32_e32 v77, s1, v165
	v_cvt_f32_ubyte0_e32 v98, v68
	v_cvt_f32_ubyte1_e32 v99, v68
	v_cvt_f32_ubyte2_e32 v102, v68
	v_cvt_f32_ubyte3_e32 v103, v68
	v_pk_fma_f32 v[92:93], v[34:35], v[98:99], v[92:93] op_sel_hi:[0,1,1]
	v_cvt_f32_ubyte0_e32 v104, v69
	v_cvt_f32_ubyte1_e32 v105, v69
	v_pk_fma_f32 v[90:91], v[34:35], v[102:103], v[90:91] op_sel_hi:[0,1,1]
	v_cvt_f32_ubyte2_e32 v146, v69
	v_cvt_f32_ubyte3_e32 v147, v69
	v_pk_fma_f32 v[86:87], v[42:43], v[104:105], v[86:87] op_sel_hi:[0,1,1]
	v_cvt_f32_ubyte0_e32 v98, v76
	v_cvt_f32_ubyte1_e32 v99, v76
	v_pk_fma_f32 v[84:85], v[42:43], v[146:147], v[84:85] op_sel_hi:[0,1,1]
	v_and_b32_e32 v82, s0, v166
	v_and_b32_e32 v83, s1, v166
	v_and_b32_e32 v88, s0, v167
	v_and_b32_e32 v89, s1, v167
	v_cvt_f32_ubyte2_e32 v102, v76
	v_cvt_f32_ubyte3_e32 v103, v76
	v_pk_fma_f32 v[80:81], v[34:35], v[98:99], v[80:81] op_sel_hi:[0,1,1]
	v_cvt_f32_ubyte0_e32 v104, v77
	v_cvt_f32_ubyte1_e32 v105, v77
	v_pk_fma_f32 v[78:79], v[34:35], v[102:103], v[78:79] op_sel_hi:[0,1,1]
	v_cvt_f32_ubyte2_e32 v146, v77
	v_cvt_f32_ubyte3_e32 v147, v77
	v_pk_fma_f32 v[70:71], v[42:43], v[104:105], v[70:71] op_sel_hi:[0,1,1]
	v_cvt_f32_ubyte0_e32 v98, v82
	v_cvt_f32_ubyte1_e32 v99, v82
	v_pk_fma_f32 v[62:63], v[42:43], v[146:147], v[62:63] op_sel_hi:[0,1,1]
	v_cvt_f32_ubyte2_e32 v102, v82
	v_cvt_f32_ubyte3_e32 v103, v82
	v_pk_fma_f32 v[92:93], v[34:35], v[98:99], v[92:93] op_sel:[1,0,0]
	v_cvt_f32_ubyte0_e32 v104, v83
	v_cvt_f32_ubyte1_e32 v105, v83
	v_pk_fma_f32 v[90:91], v[34:35], v[102:103], v[90:91] op_sel:[1,0,0]
	v_cvt_f32_ubyte2_e32 v146, v83
	v_cvt_f32_ubyte3_e32 v147, v83
	v_pk_fma_f32 v[86:87], v[42:43], v[104:105], v[86:87] op_sel:[1,0,0]
	v_cvt_f32_ubyte0_e32 v98, v88
	v_cvt_f32_ubyte1_e32 v99, v88
	v_pk_fma_f32 v[84:85], v[42:43], v[146:147], v[84:85] op_sel:[1,0,0]
	v_and_b32_e32 v68, s0, v168
	v_and_b32_e32 v69, s1, v168
	v_and_b32_e32 v76, s0, v169
	v_and_b32_e32 v77, s1, v169
	v_cvt_f32_ubyte2_e32 v102, v88
	v_cvt_f32_ubyte3_e32 v103, v88
	v_pk_fma_f32 v[80:81], v[34:35], v[98:99], v[80:81] op_sel:[1,0,0]
	v_cvt_f32_ubyte0_e32 v104, v89
	v_cvt_f32_ubyte1_e32 v105, v89
	v_pk_fma_f32 v[78:79], v[34:35], v[102:103], v[78:79] op_sel:[1,0,0]
	v_cvt_f32_ubyte2_e32 v146, v89
	v_cvt_f32_ubyte3_e32 v147, v89
	v_pk_fma_f32 v[70:71], v[42:43], v[104:105], v[70:71] op_sel:[1,0,0]
	v_cvt_f32_ubyte0_e32 v98, v68
	v_cvt_f32_ubyte1_e32 v99, v68
	v_pk_fma_f32 v[62:63], v[42:43], v[146:147], v[62:63] op_sel:[1,0,0]
	v_cvt_f32_ubyte2_e32 v102, v68
	v_cvt_f32_ubyte3_e32 v103, v68
	v_pk_fma_f32 v[92:93], v[36:37], v[98:99], v[92:93] op_sel_hi:[0,1,1]
	v_cvt_f32_ubyte0_e32 v104, v69
	v_cvt_f32_ubyte1_e32 v105, v69
	v_pk_fma_f32 v[90:91], v[36:37], v[102:103], v[90:91] op_sel_hi:[0,1,1]
	v_cvt_f32_ubyte2_e32 v146, v69
	v_cvt_f32_ubyte3_e32 v147, v69
	v_pk_fma_f32 v[86:87], v[44:45], v[104:105], v[86:87] op_sel_hi:[0,1,1]
	v_cvt_f32_ubyte0_e32 v98, v76
	v_cvt_f32_ubyte1_e32 v99, v76
	v_pk_fma_f32 v[84:85], v[44:45], v[146:147], v[84:85] op_sel_hi:[0,1,1]
	v_and_b32_e32 v82, s0, v170
	v_and_b32_e32 v83, s1, v170
	v_and_b32_e32 v88, s0, v171
	v_and_b32_e32 v89, s1, v171
	v_cvt_f32_ubyte2_e32 v102, v76
	v_cvt_f32_ubyte3_e32 v103, v76
	v_pk_fma_f32 v[80:81], v[36:37], v[98:99], v[80:81] op_sel_hi:[0,1,1]
	v_cvt_f32_ubyte0_e32 v104, v77
	v_cvt_f32_ubyte1_e32 v105, v77
	v_pk_fma_f32 v[78:79], v[36:37], v[102:103], v[78:79] op_sel_hi:[0,1,1]
	v_cvt_f32_ubyte2_e32 v146, v77
	v_cvt_f32_ubyte3_e32 v147, v77
	v_pk_fma_f32 v[70:71], v[44:45], v[104:105], v[70:71] op_sel_hi:[0,1,1]
	v_cvt_f32_ubyte0_e32 v98, v82
	v_cvt_f32_ubyte1_e32 v99, v82
	v_pk_fma_f32 v[62:63], v[44:45], v[146:147], v[62:63] op_sel_hi:[0,1,1]
	v_cvt_f32_ubyte2_e32 v102, v82
	v_cvt_f32_ubyte3_e32 v103, v82
	v_pk_fma_f32 v[92:93], v[36:37], v[98:99], v[92:93] op_sel:[1,0,0]
	v_cvt_f32_ubyte0_e32 v104, v83
	v_cvt_f32_ubyte1_e32 v105, v83
	v_pk_fma_f32 v[90:91], v[36:37], v[102:103], v[90:91] op_sel:[1,0,0]
	v_cvt_f32_ubyte2_e32 v146, v83
	v_cvt_f32_ubyte3_e32 v147, v83
	v_pk_fma_f32 v[86:87], v[44:45], v[104:105], v[86:87] op_sel:[1,0,0]
	v_cvt_f32_ubyte0_e32 v98, v88
	v_cvt_f32_ubyte1_e32 v99, v88
	v_pk_fma_f32 v[84:85], v[44:45], v[146:147], v[84:85] op_sel:[1,0,0]
	v_and_b32_e32 v68, s0, v172
	v_and_b32_e32 v69, s1, v172
	v_and_b32_e32 v76, s0, v173
	v_and_b32_e32 v77, s1, v173
	v_cvt_f32_ubyte2_e32 v102, v88
	v_cvt_f32_ubyte3_e32 v103, v88
	v_pk_fma_f32 v[80:81], v[36:37], v[98:99], v[80:81] op_sel:[1,0,0]
	v_cvt_f32_ubyte0_e32 v104, v89
	v_cvt_f32_ubyte1_e32 v105, v89
	v_pk_fma_f32 v[78:79], v[36:37], v[102:103], v[78:79] op_sel:[1,0,0]
	v_cvt_f32_ubyte2_e32 v146, v89
	v_cvt_f32_ubyte3_e32 v147, v89
	v_pk_fma_f32 v[70:71], v[44:45], v[104:105], v[70:71] op_sel:[1,0,0]
	v_cvt_f32_ubyte0_e32 v98, v68
	v_cvt_f32_ubyte1_e32 v99, v68
	v_pk_fma_f32 v[62:63], v[44:45], v[146:147], v[62:63] op_sel:[1,0,0]
	v_cvt_f32_ubyte2_e32 v102, v68
	v_cvt_f32_ubyte3_e32 v103, v68
	v_pk_fma_f32 v[92:93], v[38:39], v[98:99], v[92:93] op_sel_hi:[0,1,1]
	v_cvt_f32_ubyte0_e32 v104, v69
	v_cvt_f32_ubyte1_e32 v105, v69
	v_pk_fma_f32 v[90:91], v[38:39], v[102:103], v[90:91] op_sel_hi:[0,1,1]
	v_cvt_f32_ubyte2_e32 v146, v69
	v_cvt_f32_ubyte3_e32 v147, v69
	v_pk_fma_f32 v[86:87], v[46:47], v[104:105], v[86:87] op_sel_hi:[0,1,1]
	v_cvt_f32_ubyte0_e32 v98, v76
	v_cvt_f32_ubyte1_e32 v99, v76
	v_pk_fma_f32 v[84:85], v[46:47], v[146:147], v[84:85] op_sel_hi:[0,1,1]
	v_and_b32_e32 v82, s0, v174
	v_and_b32_e32 v83, s1, v174
	v_and_b32_e32 v88, s0, v175
	v_and_b32_e32 v89, s1, v175
	v_cvt_f32_ubyte2_e32 v102, v76
	v_cvt_f32_ubyte3_e32 v103, v76
	v_pk_fma_f32 v[80:81], v[38:39], v[98:99], v[80:81] op_sel_hi:[0,1,1]
	v_cvt_f32_ubyte0_e32 v104, v77
	v_cvt_f32_ubyte1_e32 v105, v77
	v_pk_fma_f32 v[78:79], v[38:39], v[102:103], v[78:79] op_sel_hi:[0,1,1]
	v_cvt_f32_ubyte2_e32 v146, v77
	v_cvt_f32_ubyte3_e32 v147, v77
	v_pk_fma_f32 v[70:71], v[46:47], v[104:105], v[70:71] op_sel_hi:[0,1,1]
	v_cvt_f32_ubyte0_e32 v98, v82
	v_cvt_f32_ubyte1_e32 v99, v82
	v_pk_fma_f32 v[62:63], v[46:47], v[146:147], v[62:63] op_sel_hi:[0,1,1]
	v_cvt_f32_ubyte2_e32 v102, v82
	v_cvt_f32_ubyte3_e32 v103, v82
	v_pk_fma_f32 v[92:93], v[38:39], v[98:99], v[92:93] op_sel:[1,0,0]
	v_cvt_f32_ubyte0_e32 v104, v83
	v_cvt_f32_ubyte1_e32 v105, v83
	v_pk_fma_f32 v[90:91], v[38:39], v[102:103], v[90:91] op_sel:[1,0,0]
	v_cvt_f32_ubyte2_e32 v146, v83
	v_cvt_f32_ubyte3_e32 v147, v83
	v_pk_fma_f32 v[86:87], v[46:47], v[104:105], v[86:87] op_sel:[1,0,0]
	v_cvt_f32_ubyte0_e32 v98, v88
	v_cvt_f32_ubyte1_e32 v99, v88
	v_pk_fma_f32 v[84:85], v[46:47], v[146:147], v[84:85] op_sel:[1,0,0]
	v_and_b32_e32 v68, s0, v176
	v_and_b32_e32 v69, s1, v176
	v_and_b32_e32 v76, s0, v177
	v_and_b32_e32 v77, s1, v177
	v_cvt_f32_ubyte2_e32 v102, v88
	v_cvt_f32_ubyte3_e32 v103, v88
	v_pk_fma_f32 v[80:81], v[38:39], v[98:99], v[80:81] op_sel:[1,0,0]
	v_cvt_f32_ubyte0_e32 v104, v89
	v_cvt_f32_ubyte1_e32 v105, v89
	v_pk_fma_f32 v[78:79], v[38:39], v[102:103], v[78:79] op_sel:[1,0,0]
	v_cvt_f32_ubyte2_e32 v146, v89
	v_cvt_f32_ubyte3_e32 v147, v89
	v_pk_fma_f32 v[70:71], v[46:47], v[104:105], v[70:71] op_sel:[1,0,0]
	v_cvt_f32_ubyte0_e32 v98, v68
	v_cvt_f32_ubyte1_e32 v99, v68
	v_pk_fma_f32 v[62:63], v[46:47], v[146:147], v[62:63] op_sel:[1,0,0]
	v_cvt_f32_ubyte2_e32 v102, v68
	v_cvt_f32_ubyte3_e32 v103, v68
	v_pk_fma_f32 v[92:93], v[40:41], v[98:99], v[92:93] op_sel_hi:[0,1,1]
	v_cvt_f32_ubyte0_e32 v104, v69
	v_cvt_f32_ubyte1_e32 v105, v69
	v_pk_fma_f32 v[90:91], v[40:41], v[102:103], v[90:91] op_sel_hi:[0,1,1]
	v_cvt_f32_ubyte2_e32 v146, v69
	v_cvt_f32_ubyte3_e32 v147, v69
	v_pk_fma_f32 v[86:87], v[48:49], v[104:105], v[86:87] op_sel_hi:[0,1,1]
	v_cvt_f32_ubyte0_e32 v98, v76
	v_cvt_f32_ubyte1_e32 v99, v76
	v_pk_fma_f32 v[84:85], v[48:49], v[146:147], v[84:85] op_sel_hi:[0,1,1]
	v_and_b32_e32 v82, s0, v178
	v_and_b32_e32 v83, s1, v178
	v_and_b32_e32 v88, s0, v179
	v_and_b32_e32 v89, s1, v179
	v_cvt_f32_ubyte2_e32 v102, v76
	v_cvt_f32_ubyte3_e32 v103, v76
	v_pk_fma_f32 v[80:81], v[40:41], v[98:99], v[80:81] op_sel_hi:[0,1,1]
	v_cvt_f32_ubyte0_e32 v104, v77
	v_cvt_f32_ubyte1_e32 v105, v77
	v_pk_fma_f32 v[78:79], v[40:41], v[102:103], v[78:79] op_sel_hi:[0,1,1]
	v_cvt_f32_ubyte2_e32 v146, v77
	v_cvt_f32_ubyte3_e32 v147, v77
	v_pk_fma_f32 v[70:71], v[48:49], v[104:105], v[70:71] op_sel_hi:[0,1,1]
	v_cvt_f32_ubyte0_e32 v98, v82
	v_cvt_f32_ubyte1_e32 v99, v82
	v_pk_fma_f32 v[62:63], v[48:49], v[146:147], v[62:63] op_sel_hi:[0,1,1]
	v_cvt_f32_ubyte2_e32 v102, v82
	v_cvt_f32_ubyte3_e32 v103, v82
	v_pk_fma_f32 v[92:93], v[40:41], v[98:99], v[92:93] op_sel:[1,0,0]
	v_cvt_f32_ubyte0_e32 v104, v83
	v_cvt_f32_ubyte1_e32 v105, v83
	v_pk_fma_f32 v[90:91], v[40:41], v[102:103], v[90:91] op_sel:[1,0,0]
	v_cvt_f32_ubyte2_e32 v146, v83
	v_cvt_f32_ubyte3_e32 v147, v83
	v_pk_fma_f32 v[86:87], v[48:49], v[104:105], v[86:87] op_sel:[1,0,0]
	v_cvt_f32_ubyte0_e32 v98, v88
	v_cvt_f32_ubyte1_e32 v99, v88
	v_pk_fma_f32 v[84:85], v[48:49], v[146:147], v[84:85] op_sel:[1,0,0]
	v_cvt_f32_ubyte2_e32 v102, v88
	v_cvt_f32_ubyte3_e32 v103, v88
	v_pk_fma_f32 v[80:81], v[40:41], v[98:99], v[80:81] op_sel:[1,0,0]
	v_cvt_f32_ubyte0_e32 v104, v89
	v_cvt_f32_ubyte1_e32 v105, v89
	v_pk_fma_f32 v[78:79], v[40:41], v[102:103], v[78:79] op_sel:[1,0,0]
	v_cvt_f32_ubyte2_e32 v146, v89
	v_cvt_f32_ubyte3_e32 v147, v89
	v_pk_fma_f32 v[70:71], v[48:49], v[104:105], v[70:71] op_sel:[1,0,0]
	v_pk_fma_f32 v[62:63], v[48:49], v[146:147], v[62:63] op_sel:[1,0,0]
	s_waitcnt lgkmcnt(0)
	v_lshl_add_u32 v72, v72, 9, v100
	v_lshl_add_u32 v73, v73, 9, v100
	v_lshl_add_u32 v74, v74, 9, v100
	v_lshl_add_u32 v75, v75, 9, v100
	v_lshl_add_u32 v94, v94, 9, v100
	v_lshl_add_u32 v95, v95, 9, v100
	v_lshl_add_u32 v96, v96, 9, v100
	v_lshl_add_u32 v97, v97, 9, v100
	global_load_dwordx2 v[164:165], v72, s[38:39]
	global_load_dwordx2 v[166:167], v73, s[38:39]
	global_load_dwordx2 v[168:169], v74, s[38:39]
	global_load_dwordx2 v[170:171], v75, s[38:39]
	global_load_dwordx2 v[172:173], v94, s[38:39]
	global_load_dwordx2 v[174:175], v95, s[38:39]
	global_load_dwordx2 v[176:177], v96, s[38:39]
	global_load_dwordx2 v[178:179], v97, s[38:39]
	ds_read_b128 v[72:75], v1 offset:416
	ds_read_b128 v[94:97], v1 offset:432
	ds_read_b128 v[34:37], v1 offset:768
	ds_read_b128 v[38:41], v1 offset:784
	ds_read_b128 v[42:45], v1 offset:1792
	ds_read_b128 v[46:49], v1 offset:1808
	s_waitcnt vmcnt(40)
	v_and_b32_e32 v68, s0, v180
	v_and_b32_e32 v69, s1, v180
	v_and_b32_e32 v76, s0, v181
	v_and_b32_e32 v77, s1, v181
	v_cvt_f32_ubyte0_e32 v98, v68
	v_cvt_f32_ubyte1_e32 v99, v68
	v_cvt_f32_ubyte2_e32 v102, v68
	v_cvt_f32_ubyte3_e32 v103, v68
	v_pk_fma_f32 v[92:93], v[50:51], v[98:99], v[92:93] op_sel_hi:[0,1,1]
	v_cvt_f32_ubyte0_e32 v104, v69
	v_cvt_f32_ubyte1_e32 v105, v69
	v_pk_fma_f32 v[90:91], v[50:51], v[102:103], v[90:91] op_sel_hi:[0,1,1]
	v_cvt_f32_ubyte2_e32 v146, v69
	v_cvt_f32_ubyte3_e32 v147, v69
	v_pk_fma_f32 v[86:87], v[58:59], v[104:105], v[86:87] op_sel_hi:[0,1,1]
	v_cvt_f32_ubyte0_e32 v98, v76
	v_cvt_f32_ubyte1_e32 v99, v76
	v_pk_fma_f32 v[84:85], v[58:59], v[146:147], v[84:85] op_sel_hi:[0,1,1]
	v_and_b32_e32 v82, s0, v182
	v_and_b32_e32 v83, s1, v182
	v_and_b32_e32 v88, s0, v183
	v_and_b32_e32 v89, s1, v183
	v_cvt_f32_ubyte2_e32 v102, v76
	v_cvt_f32_ubyte3_e32 v103, v76
	v_pk_fma_f32 v[80:81], v[50:51], v[98:99], v[80:81] op_sel_hi:[0,1,1]
	v_cvt_f32_ubyte0_e32 v104, v77
	v_cvt_f32_ubyte1_e32 v105, v77
	v_pk_fma_f32 v[78:79], v[50:51], v[102:103], v[78:79] op_sel_hi:[0,1,1]
	v_cvt_f32_ubyte2_e32 v146, v77
	v_cvt_f32_ubyte3_e32 v147, v77
	v_pk_fma_f32 v[70:71], v[58:59], v[104:105], v[70:71] op_sel_hi:[0,1,1]
	v_cvt_f32_ubyte0_e32 v98, v82
	v_cvt_f32_ubyte1_e32 v99, v82
	v_pk_fma_f32 v[62:63], v[58:59], v[146:147], v[62:63] op_sel_hi:[0,1,1]
	v_cvt_f32_ubyte2_e32 v102, v82
	v_cvt_f32_ubyte3_e32 v103, v82
	v_pk_fma_f32 v[92:93], v[50:51], v[98:99], v[92:93] op_sel:[1,0,0]
	v_cvt_f32_ubyte0_e32 v104, v83
	v_cvt_f32_ubyte1_e32 v105, v83
	v_pk_fma_f32 v[90:91], v[50:51], v[102:103], v[90:91] op_sel:[1,0,0]
	v_cvt_f32_ubyte2_e32 v146, v83
	v_cvt_f32_ubyte3_e32 v147, v83
	v_pk_fma_f32 v[86:87], v[58:59], v[104:105], v[86:87] op_sel:[1,0,0]
	v_cvt_f32_ubyte0_e32 v98, v88
	v_cvt_f32_ubyte1_e32 v99, v88
	v_pk_fma_f32 v[84:85], v[58:59], v[146:147], v[84:85] op_sel:[1,0,0]
	v_and_b32_e32 v68, s0, v184
	v_and_b32_e32 v69, s1, v184
	v_and_b32_e32 v76, s0, v185
	v_and_b32_e32 v77, s1, v185
	v_cvt_f32_ubyte2_e32 v102, v88
	v_cvt_f32_ubyte3_e32 v103, v88
	v_pk_fma_f32 v[80:81], v[50:51], v[98:99], v[80:81] op_sel:[1,0,0]
	v_cvt_f32_ubyte0_e32 v104, v89
	v_cvt_f32_ubyte1_e32 v105, v89
	v_pk_fma_f32 v[78:79], v[50:51], v[102:103], v[78:79] op_sel:[1,0,0]
	v_cvt_f32_ubyte2_e32 v146, v89
	v_cvt_f32_ubyte3_e32 v147, v89
	v_pk_fma_f32 v[70:71], v[58:59], v[104:105], v[70:71] op_sel:[1,0,0]
	v_cvt_f32_ubyte0_e32 v98, v68
	v_cvt_f32_ubyte1_e32 v99, v68
	v_pk_fma_f32 v[62:63], v[58:59], v[146:147], v[62:63] op_sel:[1,0,0]
	v_cvt_f32_ubyte2_e32 v102, v68
	v_cvt_f32_ubyte3_e32 v103, v68
	v_pk_fma_f32 v[92:93], v[52:53], v[98:99], v[92:93] op_sel_hi:[0,1,1]
	v_cvt_f32_ubyte0_e32 v104, v69
	v_cvt_f32_ubyte1_e32 v105, v69
	v_pk_fma_f32 v[90:91], v[52:53], v[102:103], v[90:91] op_sel_hi:[0,1,1]
	v_cvt_f32_ubyte2_e32 v146, v69
	v_cvt_f32_ubyte3_e32 v147, v69
	v_pk_fma_f32 v[86:87], v[60:61], v[104:105], v[86:87] op_sel_hi:[0,1,1]
	v_cvt_f32_ubyte0_e32 v98, v76
	v_cvt_f32_ubyte1_e32 v99, v76
	v_pk_fma_f32 v[84:85], v[60:61], v[146:147], v[84:85] op_sel_hi:[0,1,1]
	v_and_b32_e32 v82, s0, v186
	v_and_b32_e32 v83, s1, v186
	v_and_b32_e32 v88, s0, v187
	v_and_b32_e32 v89, s1, v187
	v_cvt_f32_ubyte2_e32 v102, v76
	v_cvt_f32_ubyte3_e32 v103, v76
	v_pk_fma_f32 v[80:81], v[52:53], v[98:99], v[80:81] op_sel_hi:[0,1,1]
	v_cvt_f32_ubyte0_e32 v104, v77
	v_cvt_f32_ubyte1_e32 v105, v77
	v_pk_fma_f32 v[78:79], v[52:53], v[102:103], v[78:79] op_sel_hi:[0,1,1]
	v_cvt_f32_ubyte2_e32 v146, v77
	v_cvt_f32_ubyte3_e32 v147, v77
	v_pk_fma_f32 v[70:71], v[60:61], v[104:105], v[70:71] op_sel_hi:[0,1,1]
	v_cvt_f32_ubyte0_e32 v98, v82
	v_cvt_f32_ubyte1_e32 v99, v82
	v_pk_fma_f32 v[62:63], v[60:61], v[146:147], v[62:63] op_sel_hi:[0,1,1]
	v_cvt_f32_ubyte2_e32 v102, v82
	v_cvt_f32_ubyte3_e32 v103, v82
	v_pk_fma_f32 v[92:93], v[52:53], v[98:99], v[92:93] op_sel:[1,0,0]
	v_cvt_f32_ubyte0_e32 v104, v83
	v_cvt_f32_ubyte1_e32 v105, v83
	v_pk_fma_f32 v[90:91], v[52:53], v[102:103], v[90:91] op_sel:[1,0,0]
	v_cvt_f32_ubyte2_e32 v146, v83
	v_cvt_f32_ubyte3_e32 v147, v83
	v_pk_fma_f32 v[86:87], v[60:61], v[104:105], v[86:87] op_sel:[1,0,0]
	v_cvt_f32_ubyte0_e32 v98, v88
	v_cvt_f32_ubyte1_e32 v99, v88
	v_pk_fma_f32 v[84:85], v[60:61], v[146:147], v[84:85] op_sel:[1,0,0]
	v_and_b32_e32 v68, s0, v188
	v_and_b32_e32 v69, s1, v188
	v_and_b32_e32 v76, s0, v189
	v_and_b32_e32 v77, s1, v189
	v_cvt_f32_ubyte2_e32 v102, v88
	v_cvt_f32_ubyte3_e32 v103, v88
	v_pk_fma_f32 v[80:81], v[52:53], v[98:99], v[80:81] op_sel:[1,0,0]
	v_cvt_f32_ubyte0_e32 v104, v89
	v_cvt_f32_ubyte1_e32 v105, v89
	v_pk_fma_f32 v[78:79], v[52:53], v[102:103], v[78:79] op_sel:[1,0,0]
	v_cvt_f32_ubyte2_e32 v146, v89
	v_cvt_f32_ubyte3_e32 v147, v89
	v_pk_fma_f32 v[70:71], v[60:61], v[104:105], v[70:71] op_sel:[1,0,0]
	v_cvt_f32_ubyte0_e32 v98, v68
	v_cvt_f32_ubyte1_e32 v99, v68
	v_pk_fma_f32 v[62:63], v[60:61], v[146:147], v[62:63] op_sel:[1,0,0]
	v_cvt_f32_ubyte2_e32 v102, v68
	v_cvt_f32_ubyte3_e32 v103, v68
	v_pk_fma_f32 v[92:93], v[54:55], v[98:99], v[92:93] op_sel_hi:[0,1,1]
	v_cvt_f32_ubyte0_e32 v104, v69
	v_cvt_f32_ubyte1_e32 v105, v69
	v_pk_fma_f32 v[90:91], v[54:55], v[102:103], v[90:91] op_sel_hi:[0,1,1]
	v_cvt_f32_ubyte2_e32 v146, v69
	v_cvt_f32_ubyte3_e32 v147, v69
	v_pk_fma_f32 v[86:87], v[64:65], v[104:105], v[86:87] op_sel_hi:[0,1,1]
	v_cvt_f32_ubyte0_e32 v98, v76
	v_cvt_f32_ubyte1_e32 v99, v76
	v_pk_fma_f32 v[84:85], v[64:65], v[146:147], v[84:85] op_sel_hi:[0,1,1]
	v_and_b32_e32 v82, s0, v190
	v_and_b32_e32 v83, s1, v190
	v_and_b32_e32 v88, s0, v191
	v_and_b32_e32 v89, s1, v191
	v_cvt_f32_ubyte2_e32 v102, v76
	v_cvt_f32_ubyte3_e32 v103, v76
	v_pk_fma_f32 v[80:81], v[54:55], v[98:99], v[80:81] op_sel_hi:[0,1,1]
	v_cvt_f32_ubyte0_e32 v104, v77
	v_cvt_f32_ubyte1_e32 v105, v77
	v_pk_fma_f32 v[78:79], v[54:55], v[102:103], v[78:79] op_sel_hi:[0,1,1]
	v_cvt_f32_ubyte2_e32 v146, v77
	v_cvt_f32_ubyte3_e32 v147, v77
	v_pk_fma_f32 v[70:71], v[64:65], v[104:105], v[70:71] op_sel_hi:[0,1,1]
	v_cvt_f32_ubyte0_e32 v98, v82
	v_cvt_f32_ubyte1_e32 v99, v82
	v_pk_fma_f32 v[62:63], v[64:65], v[146:147], v[62:63] op_sel_hi:[0,1,1]
	v_cvt_f32_ubyte2_e32 v102, v82
	v_cvt_f32_ubyte3_e32 v103, v82
	v_pk_fma_f32 v[92:93], v[54:55], v[98:99], v[92:93] op_sel:[1,0,0]
	v_cvt_f32_ubyte0_e32 v104, v83
	v_cvt_f32_ubyte1_e32 v105, v83
	v_pk_fma_f32 v[90:91], v[54:55], v[102:103], v[90:91] op_sel:[1,0,0]
	v_cvt_f32_ubyte2_e32 v146, v83
	v_cvt_f32_ubyte3_e32 v147, v83
	v_pk_fma_f32 v[86:87], v[64:65], v[104:105], v[86:87] op_sel:[1,0,0]
	v_cvt_f32_ubyte0_e32 v98, v88
	v_cvt_f32_ubyte1_e32 v99, v88
	v_pk_fma_f32 v[84:85], v[64:65], v[146:147], v[84:85] op_sel:[1,0,0]
	v_and_b32_e32 v68, s0, v192
	v_and_b32_e32 v69, s1, v192
	v_and_b32_e32 v76, s0, v193
	v_and_b32_e32 v77, s1, v193
	v_cvt_f32_ubyte2_e32 v102, v88
	v_cvt_f32_ubyte3_e32 v103, v88
	v_pk_fma_f32 v[80:81], v[54:55], v[98:99], v[80:81] op_sel:[1,0,0]
	v_cvt_f32_ubyte0_e32 v104, v89
	v_cvt_f32_ubyte1_e32 v105, v89
	v_pk_fma_f32 v[78:79], v[54:55], v[102:103], v[78:79] op_sel:[1,0,0]
	v_cvt_f32_ubyte2_e32 v146, v89
	v_cvt_f32_ubyte3_e32 v147, v89
	v_pk_fma_f32 v[70:71], v[64:65], v[104:105], v[70:71] op_sel:[1,0,0]
	v_cvt_f32_ubyte0_e32 v98, v68
	v_cvt_f32_ubyte1_e32 v99, v68
	v_pk_fma_f32 v[62:63], v[64:65], v[146:147], v[62:63] op_sel:[1,0,0]
	v_cvt_f32_ubyte2_e32 v102, v68
	v_cvt_f32_ubyte3_e32 v103, v68
	v_pk_fma_f32 v[92:93], v[56:57], v[98:99], v[92:93] op_sel_hi:[0,1,1]
	v_cvt_f32_ubyte0_e32 v104, v69
	v_cvt_f32_ubyte1_e32 v105, v69
	v_pk_fma_f32 v[90:91], v[56:57], v[102:103], v[90:91] op_sel_hi:[0,1,1]
	v_cvt_f32_ubyte2_e32 v146, v69
	v_cvt_f32_ubyte3_e32 v147, v69
	v_pk_fma_f32 v[86:87], v[66:67], v[104:105], v[86:87] op_sel_hi:[0,1,1]
	v_cvt_f32_ubyte0_e32 v98, v76
	v_cvt_f32_ubyte1_e32 v99, v76
	v_pk_fma_f32 v[84:85], v[66:67], v[146:147], v[84:85] op_sel_hi:[0,1,1]
	v_and_b32_e32 v82, s0, v194
	v_and_b32_e32 v83, s1, v194
	v_and_b32_e32 v88, s0, v195
	v_and_b32_e32 v89, s1, v195
	v_cvt_f32_ubyte2_e32 v102, v76
	v_cvt_f32_ubyte3_e32 v103, v76
	v_pk_fma_f32 v[80:81], v[56:57], v[98:99], v[80:81] op_sel_hi:[0,1,1]
	v_cvt_f32_ubyte0_e32 v104, v77
	v_cvt_f32_ubyte1_e32 v105, v77
	v_pk_fma_f32 v[78:79], v[56:57], v[102:103], v[78:79] op_sel_hi:[0,1,1]
	v_cvt_f32_ubyte2_e32 v146, v77
	v_cvt_f32_ubyte3_e32 v147, v77
	v_pk_fma_f32 v[70:71], v[66:67], v[104:105], v[70:71] op_sel_hi:[0,1,1]
	v_cvt_f32_ubyte0_e32 v98, v82
	v_cvt_f32_ubyte1_e32 v99, v82
	v_pk_fma_f32 v[62:63], v[66:67], v[146:147], v[62:63] op_sel_hi:[0,1,1]
	v_cvt_f32_ubyte2_e32 v102, v82
	v_cvt_f32_ubyte3_e32 v103, v82
	v_pk_fma_f32 v[92:93], v[56:57], v[98:99], v[92:93] op_sel:[1,0,0]
	v_cvt_f32_ubyte0_e32 v104, v83
	v_cvt_f32_ubyte1_e32 v105, v83
	v_pk_fma_f32 v[90:91], v[56:57], v[102:103], v[90:91] op_sel:[1,0,0]
	v_cvt_f32_ubyte2_e32 v146, v83
	v_cvt_f32_ubyte3_e32 v147, v83
	v_pk_fma_f32 v[86:87], v[66:67], v[104:105], v[86:87] op_sel:[1,0,0]
	v_cvt_f32_ubyte0_e32 v98, v88
	v_cvt_f32_ubyte1_e32 v99, v88
	v_pk_fma_f32 v[84:85], v[66:67], v[146:147], v[84:85] op_sel:[1,0,0]
	v_cvt_f32_ubyte2_e32 v102, v88
	v_cvt_f32_ubyte3_e32 v103, v88
	v_pk_fma_f32 v[80:81], v[56:57], v[98:99], v[80:81] op_sel:[1,0,0]
	v_cvt_f32_ubyte0_e32 v104, v89
	v_cvt_f32_ubyte1_e32 v105, v89
	v_pk_fma_f32 v[78:79], v[56:57], v[102:103], v[78:79] op_sel:[1,0,0]
	v_cvt_f32_ubyte2_e32 v146, v89
	v_cvt_f32_ubyte3_e32 v147, v89
	v_pk_fma_f32 v[70:71], v[66:67], v[104:105], v[70:71] op_sel:[1,0,0]
	v_pk_fma_f32 v[62:63], v[66:67], v[146:147], v[62:63] op_sel:[1,0,0]
	s_waitcnt lgkmcnt(0)
	v_lshl_add_u32 v72, v72, 9, v100
	v_lshl_add_u32 v73, v73, 9, v100
	v_lshl_add_u32 v74, v74, 9, v100
	v_lshl_add_u32 v75, v75, 9, v100
	v_lshl_add_u32 v94, v94, 9, v100
	v_lshl_add_u32 v95, v95, 9, v100
	v_lshl_add_u32 v96, v96, 9, v100
	v_lshl_add_u32 v97, v97, 9, v100
	global_load_dwordx2 v[180:181], v72, s[38:39]
	global_load_dwordx2 v[182:183], v73, s[38:39]
	global_load_dwordx2 v[184:185], v74, s[38:39]
	global_load_dwordx2 v[186:187], v75, s[38:39]
	global_load_dwordx2 v[188:189], v94, s[38:39]
	global_load_dwordx2 v[190:191], v95, s[38:39]
	global_load_dwordx2 v[192:193], v96, s[38:39]
	global_load_dwordx2 v[194:195], v97, s[38:39]
	ds_read_b128 v[72:75], v1 offset:448
	ds_read_b128 v[94:97], v1 offset:464
	ds_read_b128 v[50:53], v1 offset:800
	ds_read_b128 v[54:57], v1 offset:816
	ds_read_b128 v[58:61], v1 offset:1824
	ds_read_b128 v[64:67], v1 offset:1840
	s_waitcnt vmcnt(40)
	v_and_b32_e32 v68, s0, v196
	v_and_b32_e32 v69, s1, v196
	v_and_b32_e32 v76, s0, v197
	v_and_b32_e32 v77, s1, v197
	v_cvt_f32_ubyte0_e32 v98, v68
	v_cvt_f32_ubyte1_e32 v99, v68
	v_cvt_f32_ubyte2_e32 v102, v68
	v_cvt_f32_ubyte3_e32 v103, v68
	v_pk_fma_f32 v[92:93], v[34:35], v[98:99], v[92:93] op_sel_hi:[0,1,1]
	v_cvt_f32_ubyte0_e32 v104, v69
	v_cvt_f32_ubyte1_e32 v105, v69
	v_pk_fma_f32 v[90:91], v[34:35], v[102:103], v[90:91] op_sel_hi:[0,1,1]
	v_cvt_f32_ubyte2_e32 v146, v69
	v_cvt_f32_ubyte3_e32 v147, v69
	v_pk_fma_f32 v[86:87], v[42:43], v[104:105], v[86:87] op_sel_hi:[0,1,1]
	v_cvt_f32_ubyte0_e32 v98, v76
	v_cvt_f32_ubyte1_e32 v99, v76
	v_pk_fma_f32 v[84:85], v[42:43], v[146:147], v[84:85] op_sel_hi:[0,1,1]
	v_and_b32_e32 v82, s0, v198
	v_and_b32_e32 v83, s1, v198
	v_and_b32_e32 v88, s0, v199
	v_and_b32_e32 v89, s1, v199
	v_cvt_f32_ubyte2_e32 v102, v76
	v_cvt_f32_ubyte3_e32 v103, v76
	v_pk_fma_f32 v[80:81], v[34:35], v[98:99], v[80:81] op_sel_hi:[0,1,1]
	v_cvt_f32_ubyte0_e32 v104, v77
	v_cvt_f32_ubyte1_e32 v105, v77
	v_pk_fma_f32 v[78:79], v[34:35], v[102:103], v[78:79] op_sel_hi:[0,1,1]
	v_cvt_f32_ubyte2_e32 v146, v77
	v_cvt_f32_ubyte3_e32 v147, v77
	v_pk_fma_f32 v[70:71], v[42:43], v[104:105], v[70:71] op_sel_hi:[0,1,1]
	v_cvt_f32_ubyte0_e32 v98, v82
	v_cvt_f32_ubyte1_e32 v99, v82
	v_pk_fma_f32 v[62:63], v[42:43], v[146:147], v[62:63] op_sel_hi:[0,1,1]
	v_cvt_f32_ubyte2_e32 v102, v82
	v_cvt_f32_ubyte3_e32 v103, v82
	v_pk_fma_f32 v[92:93], v[34:35], v[98:99], v[92:93] op_sel:[1,0,0]
	v_cvt_f32_ubyte0_e32 v104, v83
	v_cvt_f32_ubyte1_e32 v105, v83
	v_pk_fma_f32 v[90:91], v[34:35], v[102:103], v[90:91] op_sel:[1,0,0]
	v_cvt_f32_ubyte2_e32 v146, v83
	v_cvt_f32_ubyte3_e32 v147, v83
	v_pk_fma_f32 v[86:87], v[42:43], v[104:105], v[86:87] op_sel:[1,0,0]
	v_cvt_f32_ubyte0_e32 v98, v88
	v_cvt_f32_ubyte1_e32 v99, v88
	v_pk_fma_f32 v[84:85], v[42:43], v[146:147], v[84:85] op_sel:[1,0,0]
	v_and_b32_e32 v68, s0, v200
	v_and_b32_e32 v69, s1, v200
	v_and_b32_e32 v76, s0, v201
	v_and_b32_e32 v77, s1, v201
	v_cvt_f32_ubyte2_e32 v102, v88
	v_cvt_f32_ubyte3_e32 v103, v88
	v_pk_fma_f32 v[80:81], v[34:35], v[98:99], v[80:81] op_sel:[1,0,0]
	v_cvt_f32_ubyte0_e32 v104, v89
	v_cvt_f32_ubyte1_e32 v105, v89
	v_pk_fma_f32 v[78:79], v[34:35], v[102:103], v[78:79] op_sel:[1,0,0]
	v_cvt_f32_ubyte2_e32 v146, v89
	v_cvt_f32_ubyte3_e32 v147, v89
	v_pk_fma_f32 v[70:71], v[42:43], v[104:105], v[70:71] op_sel:[1,0,0]
	v_cvt_f32_ubyte0_e32 v98, v68
	v_cvt_f32_ubyte1_e32 v99, v68
	v_pk_fma_f32 v[62:63], v[42:43], v[146:147], v[62:63] op_sel:[1,0,0]
	v_cvt_f32_ubyte2_e32 v102, v68
	v_cvt_f32_ubyte3_e32 v103, v68
	v_pk_fma_f32 v[92:93], v[36:37], v[98:99], v[92:93] op_sel_hi:[0,1,1]
	v_cvt_f32_ubyte0_e32 v104, v69
	v_cvt_f32_ubyte1_e32 v105, v69
	v_pk_fma_f32 v[90:91], v[36:37], v[102:103], v[90:91] op_sel_hi:[0,1,1]
	v_cvt_f32_ubyte2_e32 v146, v69
	v_cvt_f32_ubyte3_e32 v147, v69
	v_pk_fma_f32 v[86:87], v[44:45], v[104:105], v[86:87] op_sel_hi:[0,1,1]
	v_cvt_f32_ubyte0_e32 v98, v76
	v_cvt_f32_ubyte1_e32 v99, v76
	v_pk_fma_f32 v[84:85], v[44:45], v[146:147], v[84:85] op_sel_hi:[0,1,1]
	v_and_b32_e32 v82, s0, v202
	v_and_b32_e32 v83, s1, v202
	v_and_b32_e32 v88, s0, v203
	v_and_b32_e32 v89, s1, v203
	v_cvt_f32_ubyte2_e32 v102, v76
	v_cvt_f32_ubyte3_e32 v103, v76
	v_pk_fma_f32 v[80:81], v[36:37], v[98:99], v[80:81] op_sel_hi:[0,1,1]
	v_cvt_f32_ubyte0_e32 v104, v77
	v_cvt_f32_ubyte1_e32 v105, v77
	v_pk_fma_f32 v[78:79], v[36:37], v[102:103], v[78:79] op_sel_hi:[0,1,1]
	v_cvt_f32_ubyte2_e32 v146, v77
	v_cvt_f32_ubyte3_e32 v147, v77
	v_pk_fma_f32 v[70:71], v[44:45], v[104:105], v[70:71] op_sel_hi:[0,1,1]
	v_cvt_f32_ubyte0_e32 v98, v82
	v_cvt_f32_ubyte1_e32 v99, v82
	v_pk_fma_f32 v[62:63], v[44:45], v[146:147], v[62:63] op_sel_hi:[0,1,1]
	v_cvt_f32_ubyte2_e32 v102, v82
	v_cvt_f32_ubyte3_e32 v103, v82
	v_pk_fma_f32 v[92:93], v[36:37], v[98:99], v[92:93] op_sel:[1,0,0]
	v_cvt_f32_ubyte0_e32 v104, v83
	v_cvt_f32_ubyte1_e32 v105, v83
	v_pk_fma_f32 v[90:91], v[36:37], v[102:103], v[90:91] op_sel:[1,0,0]
	v_cvt_f32_ubyte2_e32 v146, v83
	v_cvt_f32_ubyte3_e32 v147, v83
	v_pk_fma_f32 v[86:87], v[44:45], v[104:105], v[86:87] op_sel:[1,0,0]
	v_cvt_f32_ubyte0_e32 v98, v88
	v_cvt_f32_ubyte1_e32 v99, v88
	v_pk_fma_f32 v[84:85], v[44:45], v[146:147], v[84:85] op_sel:[1,0,0]
	v_and_b32_e32 v68, s0, v204
	v_and_b32_e32 v69, s1, v204
	v_and_b32_e32 v76, s0, v205
	v_and_b32_e32 v77, s1, v205
	v_cvt_f32_ubyte2_e32 v102, v88
	v_cvt_f32_ubyte3_e32 v103, v88
	v_pk_fma_f32 v[80:81], v[36:37], v[98:99], v[80:81] op_sel:[1,0,0]
	v_cvt_f32_ubyte0_e32 v104, v89
	v_cvt_f32_ubyte1_e32 v105, v89
	v_pk_fma_f32 v[78:79], v[36:37], v[102:103], v[78:79] op_sel:[1,0,0]
	v_cvt_f32_ubyte2_e32 v146, v89
	v_cvt_f32_ubyte3_e32 v147, v89
	v_pk_fma_f32 v[70:71], v[44:45], v[104:105], v[70:71] op_sel:[1,0,0]
	v_cvt_f32_ubyte0_e32 v98, v68
	v_cvt_f32_ubyte1_e32 v99, v68
	v_pk_fma_f32 v[62:63], v[44:45], v[146:147], v[62:63] op_sel:[1,0,0]
	v_cvt_f32_ubyte2_e32 v102, v68
	v_cvt_f32_ubyte3_e32 v103, v68
	v_pk_fma_f32 v[92:93], v[38:39], v[98:99], v[92:93] op_sel_hi:[0,1,1]
	v_cvt_f32_ubyte0_e32 v104, v69
	v_cvt_f32_ubyte1_e32 v105, v69
	v_pk_fma_f32 v[90:91], v[38:39], v[102:103], v[90:91] op_sel_hi:[0,1,1]
	v_cvt_f32_ubyte2_e32 v146, v69
	v_cvt_f32_ubyte3_e32 v147, v69
	v_pk_fma_f32 v[86:87], v[46:47], v[104:105], v[86:87] op_sel_hi:[0,1,1]
	v_cvt_f32_ubyte0_e32 v98, v76
	v_cvt_f32_ubyte1_e32 v99, v76
	v_pk_fma_f32 v[84:85], v[46:47], v[146:147], v[84:85] op_sel_hi:[0,1,1]
	v_and_b32_e32 v82, s0, v206
	v_and_b32_e32 v83, s1, v206
	v_and_b32_e32 v88, s0, v207
	v_and_b32_e32 v89, s1, v207
	v_cvt_f32_ubyte2_e32 v102, v76
	v_cvt_f32_ubyte3_e32 v103, v76
	v_pk_fma_f32 v[80:81], v[38:39], v[98:99], v[80:81] op_sel_hi:[0,1,1]
	v_cvt_f32_ubyte0_e32 v104, v77
	v_cvt_f32_ubyte1_e32 v105, v77
	v_pk_fma_f32 v[78:79], v[38:39], v[102:103], v[78:79] op_sel_hi:[0,1,1]
	v_cvt_f32_ubyte2_e32 v146, v77
	v_cvt_f32_ubyte3_e32 v147, v77
	v_pk_fma_f32 v[70:71], v[46:47], v[104:105], v[70:71] op_sel_hi:[0,1,1]
	v_cvt_f32_ubyte0_e32 v98, v82
	v_cvt_f32_ubyte1_e32 v99, v82
	v_pk_fma_f32 v[62:63], v[46:47], v[146:147], v[62:63] op_sel_hi:[0,1,1]
	v_cvt_f32_ubyte2_e32 v102, v82
	v_cvt_f32_ubyte3_e32 v103, v82
	v_pk_fma_f32 v[92:93], v[38:39], v[98:99], v[92:93] op_sel:[1,0,0]
	v_cvt_f32_ubyte0_e32 v104, v83
	v_cvt_f32_ubyte1_e32 v105, v83
	v_pk_fma_f32 v[90:91], v[38:39], v[102:103], v[90:91] op_sel:[1,0,0]
	v_cvt_f32_ubyte2_e32 v146, v83
	v_cvt_f32_ubyte3_e32 v147, v83
	v_pk_fma_f32 v[86:87], v[46:47], v[104:105], v[86:87] op_sel:[1,0,0]
	v_cvt_f32_ubyte0_e32 v98, v88
	v_cvt_f32_ubyte1_e32 v99, v88
	v_pk_fma_f32 v[84:85], v[46:47], v[146:147], v[84:85] op_sel:[1,0,0]
	v_and_b32_e32 v68, s0, v208
	v_and_b32_e32 v69, s1, v208
	v_and_b32_e32 v76, s0, v209
	v_and_b32_e32 v77, s1, v209
	v_cvt_f32_ubyte2_e32 v102, v88
	v_cvt_f32_ubyte3_e32 v103, v88
	v_pk_fma_f32 v[80:81], v[38:39], v[98:99], v[80:81] op_sel:[1,0,0]
	v_cvt_f32_ubyte0_e32 v104, v89
	v_cvt_f32_ubyte1_e32 v105, v89
	v_pk_fma_f32 v[78:79], v[38:39], v[102:103], v[78:79] op_sel:[1,0,0]
	v_cvt_f32_ubyte2_e32 v146, v89
	v_cvt_f32_ubyte3_e32 v147, v89
	v_pk_fma_f32 v[70:71], v[46:47], v[104:105], v[70:71] op_sel:[1,0,0]
	v_cvt_f32_ubyte0_e32 v98, v68
	v_cvt_f32_ubyte1_e32 v99, v68
	v_pk_fma_f32 v[62:63], v[46:47], v[146:147], v[62:63] op_sel:[1,0,0]
	v_cvt_f32_ubyte2_e32 v102, v68
	v_cvt_f32_ubyte3_e32 v103, v68
	v_pk_fma_f32 v[92:93], v[40:41], v[98:99], v[92:93] op_sel_hi:[0,1,1]
	v_cvt_f32_ubyte0_e32 v104, v69
	v_cvt_f32_ubyte1_e32 v105, v69
	v_pk_fma_f32 v[90:91], v[40:41], v[102:103], v[90:91] op_sel_hi:[0,1,1]
	v_cvt_f32_ubyte2_e32 v146, v69
	v_cvt_f32_ubyte3_e32 v147, v69
	v_pk_fma_f32 v[86:87], v[48:49], v[104:105], v[86:87] op_sel_hi:[0,1,1]
	v_cvt_f32_ubyte0_e32 v98, v76
	v_cvt_f32_ubyte1_e32 v99, v76
	v_pk_fma_f32 v[84:85], v[48:49], v[146:147], v[84:85] op_sel_hi:[0,1,1]
	v_and_b32_e32 v82, s0, v210
	v_and_b32_e32 v83, s1, v210
	v_and_b32_e32 v88, s0, v211
	v_and_b32_e32 v89, s1, v211
	v_cvt_f32_ubyte2_e32 v102, v76
	v_cvt_f32_ubyte3_e32 v103, v76
	v_pk_fma_f32 v[80:81], v[40:41], v[98:99], v[80:81] op_sel_hi:[0,1,1]
	v_cvt_f32_ubyte0_e32 v104, v77
	v_cvt_f32_ubyte1_e32 v105, v77
	v_pk_fma_f32 v[78:79], v[40:41], v[102:103], v[78:79] op_sel_hi:[0,1,1]
	v_cvt_f32_ubyte2_e32 v146, v77
	v_cvt_f32_ubyte3_e32 v147, v77
	v_pk_fma_f32 v[70:71], v[48:49], v[104:105], v[70:71] op_sel_hi:[0,1,1]
	v_cvt_f32_ubyte0_e32 v98, v82
	v_cvt_f32_ubyte1_e32 v99, v82
	v_pk_fma_f32 v[62:63], v[48:49], v[146:147], v[62:63] op_sel_hi:[0,1,1]
	v_cvt_f32_ubyte2_e32 v102, v82
	v_cvt_f32_ubyte3_e32 v103, v82
	v_pk_fma_f32 v[92:93], v[40:41], v[98:99], v[92:93] op_sel:[1,0,0]
	v_cvt_f32_ubyte0_e32 v104, v83
	v_cvt_f32_ubyte1_e32 v105, v83
	v_pk_fma_f32 v[90:91], v[40:41], v[102:103], v[90:91] op_sel:[1,0,0]
	v_cvt_f32_ubyte2_e32 v146, v83
	v_cvt_f32_ubyte3_e32 v147, v83
	v_pk_fma_f32 v[86:87], v[48:49], v[104:105], v[86:87] op_sel:[1,0,0]
	v_cvt_f32_ubyte0_e32 v98, v88
	v_cvt_f32_ubyte1_e32 v99, v88
	v_pk_fma_f32 v[84:85], v[48:49], v[146:147], v[84:85] op_sel:[1,0,0]
	v_cvt_f32_ubyte2_e32 v102, v88
	v_cvt_f32_ubyte3_e32 v103, v88
	v_pk_fma_f32 v[80:81], v[40:41], v[98:99], v[80:81] op_sel:[1,0,0]
	v_cvt_f32_ubyte0_e32 v104, v89
	v_cvt_f32_ubyte1_e32 v105, v89
	v_pk_fma_f32 v[78:79], v[40:41], v[102:103], v[78:79] op_sel:[1,0,0]
	v_cvt_f32_ubyte2_e32 v146, v89
	v_cvt_f32_ubyte3_e32 v147, v89
	v_pk_fma_f32 v[70:71], v[48:49], v[104:105], v[70:71] op_sel:[1,0,0]
	v_pk_fma_f32 v[62:63], v[48:49], v[146:147], v[62:63] op_sel:[1,0,0]
	s_waitcnt lgkmcnt(0)
	v_lshl_add_u32 v72, v72, 9, v100
	v_lshl_add_u32 v73, v73, 9, v100
	v_lshl_add_u32 v74, v74, 9, v100
	v_lshl_add_u32 v75, v75, 9, v100
	v_lshl_add_u32 v94, v94, 9, v100
	v_lshl_add_u32 v95, v95, 9, v100
	v_lshl_add_u32 v96, v96, 9, v100
	v_lshl_add_u32 v97, v97, 9, v100
	global_load_dwordx2 v[196:197], v72, s[38:39]
	global_load_dwordx2 v[198:199], v73, s[38:39]
	global_load_dwordx2 v[200:201], v74, s[38:39]
	global_load_dwordx2 v[202:203], v75, s[38:39]
	global_load_dwordx2 v[204:205], v94, s[38:39]
	global_load_dwordx2 v[206:207], v95, s[38:39]
	global_load_dwordx2 v[208:209], v96, s[38:39]
	global_load_dwordx2 v[210:211], v97, s[38:39]
	ds_read_b128 v[72:75], v1 offset:480
	ds_read_b128 v[94:97], v1 offset:496
	ds_read_b128 v[34:37], v1 offset:832
	ds_read_b128 v[38:41], v1 offset:848
	ds_read_b128 v[42:45], v1 offset:1856
	ds_read_b128 v[46:49], v1 offset:1872
	s_waitcnt vmcnt(40)
	v_and_b32_e32 v68, s0, v212
	v_and_b32_e32 v69, s1, v212
	v_and_b32_e32 v76, s0, v213
	v_and_b32_e32 v77, s1, v213
	v_cvt_f32_ubyte0_e32 v98, v68
	v_cvt_f32_ubyte1_e32 v99, v68
	v_cvt_f32_ubyte2_e32 v102, v68
	v_cvt_f32_ubyte3_e32 v103, v68
	v_pk_fma_f32 v[92:93], v[50:51], v[98:99], v[92:93] op_sel_hi:[0,1,1]
	v_cvt_f32_ubyte0_e32 v104, v69
	v_cvt_f32_ubyte1_e32 v105, v69
	v_pk_fma_f32 v[90:91], v[50:51], v[102:103], v[90:91] op_sel_hi:[0,1,1]
	v_cvt_f32_ubyte2_e32 v146, v69
	v_cvt_f32_ubyte3_e32 v147, v69
	v_pk_fma_f32 v[86:87], v[58:59], v[104:105], v[86:87] op_sel_hi:[0,1,1]
	v_cvt_f32_ubyte0_e32 v98, v76
	v_cvt_f32_ubyte1_e32 v99, v76
	v_pk_fma_f32 v[84:85], v[58:59], v[146:147], v[84:85] op_sel_hi:[0,1,1]
	v_and_b32_e32 v82, s0, v214
	v_and_b32_e32 v83, s1, v214
	v_and_b32_e32 v88, s0, v215
	v_and_b32_e32 v89, s1, v215
	v_cvt_f32_ubyte2_e32 v102, v76
	v_cvt_f32_ubyte3_e32 v103, v76
	v_pk_fma_f32 v[80:81], v[50:51], v[98:99], v[80:81] op_sel_hi:[0,1,1]
	v_cvt_f32_ubyte0_e32 v104, v77
	v_cvt_f32_ubyte1_e32 v105, v77
	v_pk_fma_f32 v[78:79], v[50:51], v[102:103], v[78:79] op_sel_hi:[0,1,1]
	v_cvt_f32_ubyte2_e32 v146, v77
	v_cvt_f32_ubyte3_e32 v147, v77
	v_pk_fma_f32 v[70:71], v[58:59], v[104:105], v[70:71] op_sel_hi:[0,1,1]
	v_cvt_f32_ubyte0_e32 v98, v82
	v_cvt_f32_ubyte1_e32 v99, v82
	v_pk_fma_f32 v[62:63], v[58:59], v[146:147], v[62:63] op_sel_hi:[0,1,1]
	v_cvt_f32_ubyte2_e32 v102, v82
	v_cvt_f32_ubyte3_e32 v103, v82
	v_pk_fma_f32 v[92:93], v[50:51], v[98:99], v[92:93] op_sel:[1,0,0]
	v_cvt_f32_ubyte0_e32 v104, v83
	v_cvt_f32_ubyte1_e32 v105, v83
	v_pk_fma_f32 v[90:91], v[50:51], v[102:103], v[90:91] op_sel:[1,0,0]
	v_cvt_f32_ubyte2_e32 v146, v83
	v_cvt_f32_ubyte3_e32 v147, v83
	v_pk_fma_f32 v[86:87], v[58:59], v[104:105], v[86:87] op_sel:[1,0,0]
	v_cvt_f32_ubyte0_e32 v98, v88
	v_cvt_f32_ubyte1_e32 v99, v88
	v_pk_fma_f32 v[84:85], v[58:59], v[146:147], v[84:85] op_sel:[1,0,0]
	v_and_b32_e32 v68, s0, v216
	v_and_b32_e32 v69, s1, v216
	v_and_b32_e32 v76, s0, v217
	v_and_b32_e32 v77, s1, v217
	v_cvt_f32_ubyte2_e32 v102, v88
	v_cvt_f32_ubyte3_e32 v103, v88
	v_pk_fma_f32 v[80:81], v[50:51], v[98:99], v[80:81] op_sel:[1,0,0]
	v_cvt_f32_ubyte0_e32 v104, v89
	v_cvt_f32_ubyte1_e32 v105, v89
	v_pk_fma_f32 v[78:79], v[50:51], v[102:103], v[78:79] op_sel:[1,0,0]
	v_cvt_f32_ubyte2_e32 v146, v89
	v_cvt_f32_ubyte3_e32 v147, v89
	v_pk_fma_f32 v[70:71], v[58:59], v[104:105], v[70:71] op_sel:[1,0,0]
	v_cvt_f32_ubyte0_e32 v98, v68
	v_cvt_f32_ubyte1_e32 v99, v68
	v_pk_fma_f32 v[62:63], v[58:59], v[146:147], v[62:63] op_sel:[1,0,0]
	v_cvt_f32_ubyte2_e32 v102, v68
	v_cvt_f32_ubyte3_e32 v103, v68
	v_pk_fma_f32 v[92:93], v[52:53], v[98:99], v[92:93] op_sel_hi:[0,1,1]
	v_cvt_f32_ubyte0_e32 v104, v69
	v_cvt_f32_ubyte1_e32 v105, v69
	v_pk_fma_f32 v[90:91], v[52:53], v[102:103], v[90:91] op_sel_hi:[0,1,1]
	v_cvt_f32_ubyte2_e32 v146, v69
	v_cvt_f32_ubyte3_e32 v147, v69
	v_pk_fma_f32 v[86:87], v[60:61], v[104:105], v[86:87] op_sel_hi:[0,1,1]
	v_cvt_f32_ubyte0_e32 v98, v76
	v_cvt_f32_ubyte1_e32 v99, v76
	v_pk_fma_f32 v[84:85], v[60:61], v[146:147], v[84:85] op_sel_hi:[0,1,1]
	v_and_b32_e32 v82, s0, v218
	v_and_b32_e32 v83, s1, v218
	v_and_b32_e32 v88, s0, v219
	v_and_b32_e32 v89, s1, v219
	v_cvt_f32_ubyte2_e32 v102, v76
	v_cvt_f32_ubyte3_e32 v103, v76
	v_pk_fma_f32 v[80:81], v[52:53], v[98:99], v[80:81] op_sel_hi:[0,1,1]
	v_cvt_f32_ubyte0_e32 v104, v77
	v_cvt_f32_ubyte1_e32 v105, v77
	v_pk_fma_f32 v[78:79], v[52:53], v[102:103], v[78:79] op_sel_hi:[0,1,1]
	v_cvt_f32_ubyte2_e32 v146, v77
	v_cvt_f32_ubyte3_e32 v147, v77
	v_pk_fma_f32 v[70:71], v[60:61], v[104:105], v[70:71] op_sel_hi:[0,1,1]
	v_cvt_f32_ubyte0_e32 v98, v82
	v_cvt_f32_ubyte1_e32 v99, v82
	v_pk_fma_f32 v[62:63], v[60:61], v[146:147], v[62:63] op_sel_hi:[0,1,1]
	v_cvt_f32_ubyte2_e32 v102, v82
	v_cvt_f32_ubyte3_e32 v103, v82
	v_pk_fma_f32 v[92:93], v[52:53], v[98:99], v[92:93] op_sel:[1,0,0]
	v_cvt_f32_ubyte0_e32 v104, v83
	v_cvt_f32_ubyte1_e32 v105, v83
	v_pk_fma_f32 v[90:91], v[52:53], v[102:103], v[90:91] op_sel:[1,0,0]
	v_cvt_f32_ubyte2_e32 v146, v83
	v_cvt_f32_ubyte3_e32 v147, v83
	v_pk_fma_f32 v[86:87], v[60:61], v[104:105], v[86:87] op_sel:[1,0,0]
	v_cvt_f32_ubyte0_e32 v98, v88
	v_cvt_f32_ubyte1_e32 v99, v88
	v_pk_fma_f32 v[84:85], v[60:61], v[146:147], v[84:85] op_sel:[1,0,0]
	v_and_b32_e32 v68, s0, v220
	v_and_b32_e32 v69, s1, v220
	v_and_b32_e32 v76, s0, v221
	v_and_b32_e32 v77, s1, v221
	v_cvt_f32_ubyte2_e32 v102, v88
	v_cvt_f32_ubyte3_e32 v103, v88
	v_pk_fma_f32 v[80:81], v[52:53], v[98:99], v[80:81] op_sel:[1,0,0]
	v_cvt_f32_ubyte0_e32 v104, v89
	v_cvt_f32_ubyte1_e32 v105, v89
	v_pk_fma_f32 v[78:79], v[52:53], v[102:103], v[78:79] op_sel:[1,0,0]
	v_cvt_f32_ubyte2_e32 v146, v89
	v_cvt_f32_ubyte3_e32 v147, v89
	v_pk_fma_f32 v[70:71], v[60:61], v[104:105], v[70:71] op_sel:[1,0,0]
	v_cvt_f32_ubyte0_e32 v98, v68
	v_cvt_f32_ubyte1_e32 v99, v68
	v_pk_fma_f32 v[62:63], v[60:61], v[146:147], v[62:63] op_sel:[1,0,0]
	v_cvt_f32_ubyte2_e32 v102, v68
	v_cvt_f32_ubyte3_e32 v103, v68
	v_pk_fma_f32 v[92:93], v[54:55], v[98:99], v[92:93] op_sel_hi:[0,1,1]
	v_cvt_f32_ubyte0_e32 v104, v69
	v_cvt_f32_ubyte1_e32 v105, v69
	v_pk_fma_f32 v[90:91], v[54:55], v[102:103], v[90:91] op_sel_hi:[0,1,1]
	v_cvt_f32_ubyte2_e32 v146, v69
	v_cvt_f32_ubyte3_e32 v147, v69
	v_pk_fma_f32 v[86:87], v[64:65], v[104:105], v[86:87] op_sel_hi:[0,1,1]
	v_cvt_f32_ubyte0_e32 v98, v76
	v_cvt_f32_ubyte1_e32 v99, v76
	v_pk_fma_f32 v[84:85], v[64:65], v[146:147], v[84:85] op_sel_hi:[0,1,1]
	v_and_b32_e32 v82, s0, v222
	v_and_b32_e32 v83, s1, v222
	v_and_b32_e32 v88, s0, v223
	v_and_b32_e32 v89, s1, v223
	v_cvt_f32_ubyte2_e32 v102, v76
	v_cvt_f32_ubyte3_e32 v103, v76
	v_pk_fma_f32 v[80:81], v[54:55], v[98:99], v[80:81] op_sel_hi:[0,1,1]
	v_cvt_f32_ubyte0_e32 v104, v77
	v_cvt_f32_ubyte1_e32 v105, v77
	v_pk_fma_f32 v[78:79], v[54:55], v[102:103], v[78:79] op_sel_hi:[0,1,1]
	v_cvt_f32_ubyte2_e32 v146, v77
	v_cvt_f32_ubyte3_e32 v147, v77
	v_pk_fma_f32 v[70:71], v[64:65], v[104:105], v[70:71] op_sel_hi:[0,1,1]
	v_cvt_f32_ubyte0_e32 v98, v82
	v_cvt_f32_ubyte1_e32 v99, v82
	v_pk_fma_f32 v[62:63], v[64:65], v[146:147], v[62:63] op_sel_hi:[0,1,1]
	v_cvt_f32_ubyte2_e32 v102, v82
	v_cvt_f32_ubyte3_e32 v103, v82
	v_pk_fma_f32 v[92:93], v[54:55], v[98:99], v[92:93] op_sel:[1,0,0]
	v_cvt_f32_ubyte0_e32 v104, v83
	v_cvt_f32_ubyte1_e32 v105, v83
	v_pk_fma_f32 v[90:91], v[54:55], v[102:103], v[90:91] op_sel:[1,0,0]
	v_cvt_f32_ubyte2_e32 v146, v83
	v_cvt_f32_ubyte3_e32 v147, v83
	v_pk_fma_f32 v[86:87], v[64:65], v[104:105], v[86:87] op_sel:[1,0,0]
	v_cvt_f32_ubyte0_e32 v98, v88
	v_cvt_f32_ubyte1_e32 v99, v88
	v_pk_fma_f32 v[84:85], v[64:65], v[146:147], v[84:85] op_sel:[1,0,0]
	v_and_b32_e32 v68, s0, v224
	v_and_b32_e32 v69, s1, v224
	v_and_b32_e32 v76, s0, v225
	v_and_b32_e32 v77, s1, v225
	v_cvt_f32_ubyte2_e32 v102, v88
	v_cvt_f32_ubyte3_e32 v103, v88
	v_pk_fma_f32 v[80:81], v[54:55], v[98:99], v[80:81] op_sel:[1,0,0]
	v_cvt_f32_ubyte0_e32 v104, v89
	v_cvt_f32_ubyte1_e32 v105, v89
	v_pk_fma_f32 v[78:79], v[54:55], v[102:103], v[78:79] op_sel:[1,0,0]
	v_cvt_f32_ubyte2_e32 v146, v89
	v_cvt_f32_ubyte3_e32 v147, v89
	v_pk_fma_f32 v[70:71], v[64:65], v[104:105], v[70:71] op_sel:[1,0,0]
	v_cvt_f32_ubyte0_e32 v98, v68
	v_cvt_f32_ubyte1_e32 v99, v68
	v_pk_fma_f32 v[62:63], v[64:65], v[146:147], v[62:63] op_sel:[1,0,0]
	v_cvt_f32_ubyte2_e32 v102, v68
	v_cvt_f32_ubyte3_e32 v103, v68
	v_pk_fma_f32 v[92:93], v[56:57], v[98:99], v[92:93] op_sel_hi:[0,1,1]
	v_cvt_f32_ubyte0_e32 v104, v69
	v_cvt_f32_ubyte1_e32 v105, v69
	v_pk_fma_f32 v[90:91], v[56:57], v[102:103], v[90:91] op_sel_hi:[0,1,1]
	v_cvt_f32_ubyte2_e32 v146, v69
	v_cvt_f32_ubyte3_e32 v147, v69
	v_pk_fma_f32 v[86:87], v[66:67], v[104:105], v[86:87] op_sel_hi:[0,1,1]
	v_cvt_f32_ubyte0_e32 v98, v76
	v_cvt_f32_ubyte1_e32 v99, v76
	v_pk_fma_f32 v[84:85], v[66:67], v[146:147], v[84:85] op_sel_hi:[0,1,1]
	v_and_b32_e32 v82, s0, v226
	v_and_b32_e32 v83, s1, v226
	v_and_b32_e32 v88, s0, v227
	v_and_b32_e32 v89, s1, v227
	v_cvt_f32_ubyte2_e32 v102, v76
	v_cvt_f32_ubyte3_e32 v103, v76
	v_pk_fma_f32 v[80:81], v[56:57], v[98:99], v[80:81] op_sel_hi:[0,1,1]
	v_cvt_f32_ubyte0_e32 v104, v77
	v_cvt_f32_ubyte1_e32 v105, v77
	v_pk_fma_f32 v[78:79], v[56:57], v[102:103], v[78:79] op_sel_hi:[0,1,1]
	v_cvt_f32_ubyte2_e32 v146, v77
	v_cvt_f32_ubyte3_e32 v147, v77
	v_pk_fma_f32 v[70:71], v[66:67], v[104:105], v[70:71] op_sel_hi:[0,1,1]
	v_cvt_f32_ubyte0_e32 v98, v82
	v_cvt_f32_ubyte1_e32 v99, v82
	v_pk_fma_f32 v[62:63], v[66:67], v[146:147], v[62:63] op_sel_hi:[0,1,1]
	v_cvt_f32_ubyte2_e32 v102, v82
	v_cvt_f32_ubyte3_e32 v103, v82
	v_pk_fma_f32 v[92:93], v[56:57], v[98:99], v[92:93] op_sel:[1,0,0]
	v_cvt_f32_ubyte0_e32 v104, v83
	v_cvt_f32_ubyte1_e32 v105, v83
	v_pk_fma_f32 v[90:91], v[56:57], v[102:103], v[90:91] op_sel:[1,0,0]
	v_cvt_f32_ubyte2_e32 v146, v83
	v_cvt_f32_ubyte3_e32 v147, v83
	v_pk_fma_f32 v[86:87], v[66:67], v[104:105], v[86:87] op_sel:[1,0,0]
	v_cvt_f32_ubyte0_e32 v98, v88
	v_cvt_f32_ubyte1_e32 v99, v88
	v_pk_fma_f32 v[84:85], v[66:67], v[146:147], v[84:85] op_sel:[1,0,0]
	v_cvt_f32_ubyte2_e32 v102, v88
	v_cvt_f32_ubyte3_e32 v103, v88
	v_pk_fma_f32 v[80:81], v[56:57], v[98:99], v[80:81] op_sel:[1,0,0]
	v_cvt_f32_ubyte0_e32 v104, v89
	v_cvt_f32_ubyte1_e32 v105, v89
	v_pk_fma_f32 v[78:79], v[56:57], v[102:103], v[78:79] op_sel:[1,0,0]
	v_cvt_f32_ubyte2_e32 v146, v89
	v_cvt_f32_ubyte3_e32 v147, v89
	v_pk_fma_f32 v[70:71], v[66:67], v[104:105], v[70:71] op_sel:[1,0,0]
	v_pk_fma_f32 v[62:63], v[66:67], v[146:147], v[62:63] op_sel:[1,0,0]
	s_waitcnt lgkmcnt(0)
	v_lshl_add_u32 v72, v72, 9, v100
	v_lshl_add_u32 v73, v73, 9, v100
	v_lshl_add_u32 v74, v74, 9, v100
	v_lshl_add_u32 v75, v75, 9, v100
	v_lshl_add_u32 v94, v94, 9, v100
	v_lshl_add_u32 v95, v95, 9, v100
	v_lshl_add_u32 v96, v96, 9, v100
	v_lshl_add_u32 v97, v97, 9, v100
	global_load_dwordx2 v[212:213], v72, s[38:39]
	global_load_dwordx2 v[214:215], v73, s[38:39]
	global_load_dwordx2 v[216:217], v74, s[38:39]
	global_load_dwordx2 v[218:219], v75, s[38:39]
	global_load_dwordx2 v[220:221], v94, s[38:39]
	global_load_dwordx2 v[222:223], v95, s[38:39]
	global_load_dwordx2 v[224:225], v96, s[38:39]
	global_load_dwordx2 v[226:227], v97, s[38:39]
	ds_read_b128 v[50:53], v1 offset:864
	ds_read_b128 v[54:57], v1 offset:880
	ds_read_b128 v[58:61], v1 offset:1888
	ds_read_b128 v[64:67], v1 offset:1904
	s_waitcnt vmcnt(40)
	v_and_b32_e32 v68, s0, v2
	v_and_b32_e32 v69, s1, v2
	v_and_b32_e32 v76, s0, v3
	v_and_b32_e32 v77, s1, v3
	v_cvt_f32_ubyte0_e32 v98, v68
	v_cvt_f32_ubyte1_e32 v99, v68
	v_cvt_f32_ubyte2_e32 v102, v68
	v_cvt_f32_ubyte3_e32 v103, v68
	v_pk_fma_f32 v[92:93], v[34:35], v[98:99], v[92:93] op_sel_hi:[0,1,1]
	v_cvt_f32_ubyte0_e32 v104, v69
	v_cvt_f32_ubyte1_e32 v105, v69
	v_pk_fma_f32 v[90:91], v[34:35], v[102:103], v[90:91] op_sel_hi:[0,1,1]
	v_cvt_f32_ubyte2_e32 v146, v69
	v_cvt_f32_ubyte3_e32 v147, v69
	v_pk_fma_f32 v[86:87], v[42:43], v[104:105], v[86:87] op_sel_hi:[0,1,1]
	v_cvt_f32_ubyte0_e32 v98, v76
	v_cvt_f32_ubyte1_e32 v99, v76
	v_pk_fma_f32 v[84:85], v[42:43], v[146:147], v[84:85] op_sel_hi:[0,1,1]
	v_and_b32_e32 v82, s0, v4
	v_and_b32_e32 v83, s1, v4
	v_and_b32_e32 v88, s0, v5
	v_and_b32_e32 v89, s1, v5
	v_cvt_f32_ubyte2_e32 v102, v76
	v_cvt_f32_ubyte3_e32 v103, v76
	v_pk_fma_f32 v[80:81], v[34:35], v[98:99], v[80:81] op_sel_hi:[0,1,1]
	v_cvt_f32_ubyte0_e32 v104, v77
	v_cvt_f32_ubyte1_e32 v105, v77
	v_pk_fma_f32 v[78:79], v[34:35], v[102:103], v[78:79] op_sel_hi:[0,1,1]
	v_cvt_f32_ubyte2_e32 v146, v77
	v_cvt_f32_ubyte3_e32 v147, v77
	v_pk_fma_f32 v[70:71], v[42:43], v[104:105], v[70:71] op_sel_hi:[0,1,1]
	v_cvt_f32_ubyte0_e32 v98, v82
	v_cvt_f32_ubyte1_e32 v99, v82
	v_pk_fma_f32 v[62:63], v[42:43], v[146:147], v[62:63] op_sel_hi:[0,1,1]
	v_cvt_f32_ubyte2_e32 v102, v82
	v_cvt_f32_ubyte3_e32 v103, v82
	v_pk_fma_f32 v[92:93], v[34:35], v[98:99], v[92:93] op_sel:[1,0,0]
	v_cvt_f32_ubyte0_e32 v104, v83
	v_cvt_f32_ubyte1_e32 v105, v83
	v_pk_fma_f32 v[90:91], v[34:35], v[102:103], v[90:91] op_sel:[1,0,0]
	v_cvt_f32_ubyte2_e32 v146, v83
	v_cvt_f32_ubyte3_e32 v147, v83
	v_pk_fma_f32 v[86:87], v[42:43], v[104:105], v[86:87] op_sel:[1,0,0]
	v_cvt_f32_ubyte0_e32 v98, v88
	v_cvt_f32_ubyte1_e32 v99, v88
	v_pk_fma_f32 v[84:85], v[42:43], v[146:147], v[84:85] op_sel:[1,0,0]
	v_and_b32_e32 v68, s0, v6
	v_and_b32_e32 v69, s1, v6
	v_and_b32_e32 v76, s0, v7
	v_and_b32_e32 v77, s1, v7
	v_cvt_f32_ubyte2_e32 v102, v88
	v_cvt_f32_ubyte3_e32 v103, v88
	v_pk_fma_f32 v[80:81], v[34:35], v[98:99], v[80:81] op_sel:[1,0,0]
	v_cvt_f32_ubyte0_e32 v104, v89
	v_cvt_f32_ubyte1_e32 v105, v89
	v_pk_fma_f32 v[78:79], v[34:35], v[102:103], v[78:79] op_sel:[1,0,0]
	v_cvt_f32_ubyte2_e32 v146, v89
	v_cvt_f32_ubyte3_e32 v147, v89
	v_pk_fma_f32 v[70:71], v[42:43], v[104:105], v[70:71] op_sel:[1,0,0]
	v_cvt_f32_ubyte0_e32 v98, v68
	v_cvt_f32_ubyte1_e32 v99, v68
	v_pk_fma_f32 v[62:63], v[42:43], v[146:147], v[62:63] op_sel:[1,0,0]
	v_cvt_f32_ubyte2_e32 v102, v68
	v_cvt_f32_ubyte3_e32 v103, v68
	v_pk_fma_f32 v[92:93], v[36:37], v[98:99], v[92:93] op_sel_hi:[0,1,1]
	v_cvt_f32_ubyte0_e32 v104, v69
	v_cvt_f32_ubyte1_e32 v105, v69
	v_pk_fma_f32 v[90:91], v[36:37], v[102:103], v[90:91] op_sel_hi:[0,1,1]
	v_cvt_f32_ubyte2_e32 v146, v69
	v_cvt_f32_ubyte3_e32 v147, v69
	v_pk_fma_f32 v[86:87], v[44:45], v[104:105], v[86:87] op_sel_hi:[0,1,1]
	v_cvt_f32_ubyte0_e32 v98, v76
	v_cvt_f32_ubyte1_e32 v99, v76
	v_pk_fma_f32 v[84:85], v[44:45], v[146:147], v[84:85] op_sel_hi:[0,1,1]
	v_and_b32_e32 v82, s0, v8
	v_and_b32_e32 v83, s1, v8
	v_and_b32_e32 v88, s0, v9
	v_and_b32_e32 v89, s1, v9
	v_cvt_f32_ubyte2_e32 v102, v76
	v_cvt_f32_ubyte3_e32 v103, v76
	v_pk_fma_f32 v[80:81], v[36:37], v[98:99], v[80:81] op_sel_hi:[0,1,1]
	v_cvt_f32_ubyte0_e32 v104, v77
	v_cvt_f32_ubyte1_e32 v105, v77
	v_pk_fma_f32 v[78:79], v[36:37], v[102:103], v[78:79] op_sel_hi:[0,1,1]
	v_cvt_f32_ubyte2_e32 v146, v77
	v_cvt_f32_ubyte3_e32 v147, v77
	v_pk_fma_f32 v[70:71], v[44:45], v[104:105], v[70:71] op_sel_hi:[0,1,1]
	v_cvt_f32_ubyte0_e32 v98, v82
	v_cvt_f32_ubyte1_e32 v99, v82
	v_pk_fma_f32 v[62:63], v[44:45], v[146:147], v[62:63] op_sel_hi:[0,1,1]
	v_cvt_f32_ubyte2_e32 v102, v82
	v_cvt_f32_ubyte3_e32 v103, v82
	v_pk_fma_f32 v[92:93], v[36:37], v[98:99], v[92:93] op_sel:[1,0,0]
	v_cvt_f32_ubyte0_e32 v104, v83
	v_cvt_f32_ubyte1_e32 v105, v83
	v_pk_fma_f32 v[90:91], v[36:37], v[102:103], v[90:91] op_sel:[1,0,0]
	v_cvt_f32_ubyte2_e32 v146, v83
	v_cvt_f32_ubyte3_e32 v147, v83
	v_pk_fma_f32 v[86:87], v[44:45], v[104:105], v[86:87] op_sel:[1,0,0]
	v_cvt_f32_ubyte0_e32 v98, v88
	v_cvt_f32_ubyte1_e32 v99, v88
	v_pk_fma_f32 v[84:85], v[44:45], v[146:147], v[84:85] op_sel:[1,0,0]
	v_and_b32_e32 v68, s0, v10
	v_and_b32_e32 v69, s1, v10
	v_and_b32_e32 v76, s0, v11
	v_and_b32_e32 v77, s1, v11
	v_cvt_f32_ubyte2_e32 v102, v88
	v_cvt_f32_ubyte3_e32 v103, v88
	v_pk_fma_f32 v[80:81], v[36:37], v[98:99], v[80:81] op_sel:[1,0,0]
	v_cvt_f32_ubyte0_e32 v104, v89
	v_cvt_f32_ubyte1_e32 v105, v89
	v_pk_fma_f32 v[78:79], v[36:37], v[102:103], v[78:79] op_sel:[1,0,0]
	v_cvt_f32_ubyte2_e32 v146, v89
	v_cvt_f32_ubyte3_e32 v147, v89
	v_pk_fma_f32 v[70:71], v[44:45], v[104:105], v[70:71] op_sel:[1,0,0]
	v_cvt_f32_ubyte0_e32 v98, v68
	v_cvt_f32_ubyte1_e32 v99, v68
	v_pk_fma_f32 v[62:63], v[44:45], v[146:147], v[62:63] op_sel:[1,0,0]
	v_cvt_f32_ubyte2_e32 v102, v68
	v_cvt_f32_ubyte3_e32 v103, v68
	v_pk_fma_f32 v[92:93], v[38:39], v[98:99], v[92:93] op_sel_hi:[0,1,1]
	v_cvt_f32_ubyte0_e32 v104, v69
	v_cvt_f32_ubyte1_e32 v105, v69
	v_pk_fma_f32 v[90:91], v[38:39], v[102:103], v[90:91] op_sel_hi:[0,1,1]
	v_cvt_f32_ubyte2_e32 v146, v69
	v_cvt_f32_ubyte3_e32 v147, v69
	v_pk_fma_f32 v[86:87], v[46:47], v[104:105], v[86:87] op_sel_hi:[0,1,1]
	v_cvt_f32_ubyte0_e32 v98, v76
	v_cvt_f32_ubyte1_e32 v99, v76
	v_pk_fma_f32 v[84:85], v[46:47], v[146:147], v[84:85] op_sel_hi:[0,1,1]
	v_and_b32_e32 v82, s0, v12
	v_and_b32_e32 v83, s1, v12
	v_and_b32_e32 v88, s0, v13
	v_and_b32_e32 v89, s1, v13
	v_cvt_f32_ubyte2_e32 v102, v76
	v_cvt_f32_ubyte3_e32 v103, v76
	v_pk_fma_f32 v[80:81], v[38:39], v[98:99], v[80:81] op_sel_hi:[0,1,1]
	v_cvt_f32_ubyte0_e32 v104, v77
	v_cvt_f32_ubyte1_e32 v105, v77
	v_pk_fma_f32 v[78:79], v[38:39], v[102:103], v[78:79] op_sel_hi:[0,1,1]
	v_cvt_f32_ubyte2_e32 v146, v77
	v_cvt_f32_ubyte3_e32 v147, v77
	v_pk_fma_f32 v[70:71], v[46:47], v[104:105], v[70:71] op_sel_hi:[0,1,1]
	v_cvt_f32_ubyte0_e32 v98, v82
	v_cvt_f32_ubyte1_e32 v99, v82
	v_pk_fma_f32 v[62:63], v[46:47], v[146:147], v[62:63] op_sel_hi:[0,1,1]
	v_cvt_f32_ubyte2_e32 v102, v82
	v_cvt_f32_ubyte3_e32 v103, v82
	v_pk_fma_f32 v[92:93], v[38:39], v[98:99], v[92:93] op_sel:[1,0,0]
	v_cvt_f32_ubyte0_e32 v104, v83
	v_cvt_f32_ubyte1_e32 v105, v83
	v_pk_fma_f32 v[90:91], v[38:39], v[102:103], v[90:91] op_sel:[1,0,0]
	v_cvt_f32_ubyte2_e32 v146, v83
	v_cvt_f32_ubyte3_e32 v147, v83
	v_pk_fma_f32 v[86:87], v[46:47], v[104:105], v[86:87] op_sel:[1,0,0]
	v_cvt_f32_ubyte0_e32 v98, v88
	v_cvt_f32_ubyte1_e32 v99, v88
	v_pk_fma_f32 v[84:85], v[46:47], v[146:147], v[84:85] op_sel:[1,0,0]
	v_and_b32_e32 v68, s0, v14
	v_and_b32_e32 v69, s1, v14
	v_and_b32_e32 v76, s0, v15
	v_and_b32_e32 v77, s1, v15
	v_cvt_f32_ubyte2_e32 v102, v88
	v_cvt_f32_ubyte3_e32 v103, v88
	v_pk_fma_f32 v[80:81], v[38:39], v[98:99], v[80:81] op_sel:[1,0,0]
	v_cvt_f32_ubyte0_e32 v104, v89
	v_cvt_f32_ubyte1_e32 v105, v89
	v_pk_fma_f32 v[78:79], v[38:39], v[102:103], v[78:79] op_sel:[1,0,0]
	v_cvt_f32_ubyte2_e32 v146, v89
	v_cvt_f32_ubyte3_e32 v147, v89
	v_pk_fma_f32 v[70:71], v[46:47], v[104:105], v[70:71] op_sel:[1,0,0]
	v_cvt_f32_ubyte0_e32 v98, v68
	v_cvt_f32_ubyte1_e32 v99, v68
	v_pk_fma_f32 v[62:63], v[46:47], v[146:147], v[62:63] op_sel:[1,0,0]
	v_cvt_f32_ubyte2_e32 v102, v68
	v_cvt_f32_ubyte3_e32 v103, v68
	v_pk_fma_f32 v[92:93], v[40:41], v[98:99], v[92:93] op_sel_hi:[0,1,1]
	v_cvt_f32_ubyte0_e32 v104, v69
	v_cvt_f32_ubyte1_e32 v105, v69
	v_pk_fma_f32 v[90:91], v[40:41], v[102:103], v[90:91] op_sel_hi:[0,1,1]
	v_cvt_f32_ubyte2_e32 v146, v69
	v_cvt_f32_ubyte3_e32 v147, v69
	v_pk_fma_f32 v[86:87], v[48:49], v[104:105], v[86:87] op_sel_hi:[0,1,1]
	v_cvt_f32_ubyte0_e32 v98, v76
	v_cvt_f32_ubyte1_e32 v99, v76
	v_pk_fma_f32 v[84:85], v[48:49], v[146:147], v[84:85] op_sel_hi:[0,1,1]
	v_and_b32_e32 v82, s0, v16
	v_and_b32_e32 v83, s1, v16
	v_and_b32_e32 v88, s0, v17
	v_and_b32_e32 v89, s1, v17
	v_cvt_f32_ubyte2_e32 v102, v76
	v_cvt_f32_ubyte3_e32 v103, v76
	v_pk_fma_f32 v[80:81], v[40:41], v[98:99], v[80:81] op_sel_hi:[0,1,1]
	v_cvt_f32_ubyte0_e32 v104, v77
	v_cvt_f32_ubyte1_e32 v105, v77
	v_pk_fma_f32 v[78:79], v[40:41], v[102:103], v[78:79] op_sel_hi:[0,1,1]
	v_cvt_f32_ubyte2_e32 v146, v77
	v_cvt_f32_ubyte3_e32 v147, v77
	v_pk_fma_f32 v[70:71], v[48:49], v[104:105], v[70:71] op_sel_hi:[0,1,1]
	v_cvt_f32_ubyte0_e32 v98, v82
	v_cvt_f32_ubyte1_e32 v99, v82
	v_pk_fma_f32 v[62:63], v[48:49], v[146:147], v[62:63] op_sel_hi:[0,1,1]
	v_cvt_f32_ubyte2_e32 v102, v82
	v_cvt_f32_ubyte3_e32 v103, v82
	v_pk_fma_f32 v[92:93], v[40:41], v[98:99], v[92:93] op_sel:[1,0,0]
	v_cvt_f32_ubyte0_e32 v104, v83
	v_cvt_f32_ubyte1_e32 v105, v83
	v_pk_fma_f32 v[90:91], v[40:41], v[102:103], v[90:91] op_sel:[1,0,0]
	v_cvt_f32_ubyte2_e32 v146, v83
	v_cvt_f32_ubyte3_e32 v147, v83
	v_pk_fma_f32 v[86:87], v[48:49], v[104:105], v[86:87] op_sel:[1,0,0]
	v_cvt_f32_ubyte0_e32 v98, v88
	v_cvt_f32_ubyte1_e32 v99, v88
	v_pk_fma_f32 v[84:85], v[48:49], v[146:147], v[84:85] op_sel:[1,0,0]
	v_cvt_f32_ubyte2_e32 v102, v88
	v_cvt_f32_ubyte3_e32 v103, v88
	v_pk_fma_f32 v[80:81], v[40:41], v[98:99], v[80:81] op_sel:[1,0,0]
	v_cvt_f32_ubyte0_e32 v104, v89
	v_cvt_f32_ubyte1_e32 v105, v89
	v_pk_fma_f32 v[78:79], v[40:41], v[102:103], v[78:79] op_sel:[1,0,0]
	v_cvt_f32_ubyte2_e32 v146, v89
	v_cvt_f32_ubyte3_e32 v147, v89
	v_pk_fma_f32 v[70:71], v[48:49], v[104:105], v[70:71] op_sel:[1,0,0]
	v_pk_fma_f32 v[62:63], v[48:49], v[146:147], v[62:63] op_sel:[1,0,0]
	s_waitcnt lgkmcnt(0)
	ds_read_b128 v[34:37], v1 offset:896
	ds_read_b128 v[38:41], v1 offset:912
	ds_read_b128 v[42:45], v1 offset:1920
	ds_read_b128 v[46:49], v1 offset:1936
	s_waitcnt vmcnt(32)
	v_and_b32_e32 v68, s0, v18
	v_and_b32_e32 v69, s1, v18
	v_and_b32_e32 v76, s0, v19
	v_and_b32_e32 v77, s1, v19
	v_cvt_f32_ubyte0_e32 v98, v68
	v_cvt_f32_ubyte1_e32 v99, v68
	v_cvt_f32_ubyte2_e32 v102, v68
	v_cvt_f32_ubyte3_e32 v103, v68
	v_pk_fma_f32 v[92:93], v[50:51], v[98:99], v[92:93] op_sel_hi:[0,1,1]
	v_cvt_f32_ubyte0_e32 v104, v69
	v_cvt_f32_ubyte1_e32 v105, v69
	v_pk_fma_f32 v[90:91], v[50:51], v[102:103], v[90:91] op_sel_hi:[0,1,1]
	v_cvt_f32_ubyte2_e32 v146, v69
	v_cvt_f32_ubyte3_e32 v147, v69
	v_pk_fma_f32 v[86:87], v[58:59], v[104:105], v[86:87] op_sel_hi:[0,1,1]
	v_cvt_f32_ubyte0_e32 v98, v76
	v_cvt_f32_ubyte1_e32 v99, v76
	v_pk_fma_f32 v[84:85], v[58:59], v[146:147], v[84:85] op_sel_hi:[0,1,1]
	v_and_b32_e32 v82, s0, v20
	v_and_b32_e32 v83, s1, v20
	v_and_b32_e32 v88, s0, v21
	v_and_b32_e32 v89, s1, v21
	v_cvt_f32_ubyte2_e32 v102, v76
	v_cvt_f32_ubyte3_e32 v103, v76
	v_pk_fma_f32 v[80:81], v[50:51], v[98:99], v[80:81] op_sel_hi:[0,1,1]
	v_cvt_f32_ubyte0_e32 v104, v77
	v_cvt_f32_ubyte1_e32 v105, v77
	v_pk_fma_f32 v[78:79], v[50:51], v[102:103], v[78:79] op_sel_hi:[0,1,1]
	v_cvt_f32_ubyte2_e32 v146, v77
	v_cvt_f32_ubyte3_e32 v147, v77
	v_pk_fma_f32 v[70:71], v[58:59], v[104:105], v[70:71] op_sel_hi:[0,1,1]
	v_cvt_f32_ubyte0_e32 v98, v82
	v_cvt_f32_ubyte1_e32 v99, v82
	v_pk_fma_f32 v[62:63], v[58:59], v[146:147], v[62:63] op_sel_hi:[0,1,1]
	v_cvt_f32_ubyte2_e32 v102, v82
	v_cvt_f32_ubyte3_e32 v103, v82
	v_pk_fma_f32 v[92:93], v[50:51], v[98:99], v[92:93] op_sel:[1,0,0]
	v_cvt_f32_ubyte0_e32 v104, v83
	v_cvt_f32_ubyte1_e32 v105, v83
	v_pk_fma_f32 v[90:91], v[50:51], v[102:103], v[90:91] op_sel:[1,0,0]
	v_cvt_f32_ubyte2_e32 v146, v83
	v_cvt_f32_ubyte3_e32 v147, v83
	v_pk_fma_f32 v[86:87], v[58:59], v[104:105], v[86:87] op_sel:[1,0,0]
	v_cvt_f32_ubyte0_e32 v98, v88
	v_cvt_f32_ubyte1_e32 v99, v88
	v_pk_fma_f32 v[84:85], v[58:59], v[146:147], v[84:85] op_sel:[1,0,0]
	v_and_b32_e32 v68, s0, v22
	v_and_b32_e32 v69, s1, v22
	v_and_b32_e32 v76, s0, v23
	v_and_b32_e32 v77, s1, v23
	v_cvt_f32_ubyte2_e32 v102, v88
	v_cvt_f32_ubyte3_e32 v103, v88
	v_pk_fma_f32 v[80:81], v[50:51], v[98:99], v[80:81] op_sel:[1,0,0]
	v_cvt_f32_ubyte0_e32 v104, v89
	v_cvt_f32_ubyte1_e32 v105, v89
	v_pk_fma_f32 v[78:79], v[50:51], v[102:103], v[78:79] op_sel:[1,0,0]
	v_cvt_f32_ubyte2_e32 v146, v89
	v_cvt_f32_ubyte3_e32 v147, v89
	v_pk_fma_f32 v[70:71], v[58:59], v[104:105], v[70:71] op_sel:[1,0,0]
	v_cvt_f32_ubyte0_e32 v98, v68
	v_cvt_f32_ubyte1_e32 v99, v68
	v_pk_fma_f32 v[62:63], v[58:59], v[146:147], v[62:63] op_sel:[1,0,0]
	v_cvt_f32_ubyte2_e32 v102, v68
	v_cvt_f32_ubyte3_e32 v103, v68
	v_pk_fma_f32 v[92:93], v[52:53], v[98:99], v[92:93] op_sel_hi:[0,1,1]
	v_cvt_f32_ubyte0_e32 v104, v69
	v_cvt_f32_ubyte1_e32 v105, v69
	v_pk_fma_f32 v[90:91], v[52:53], v[102:103], v[90:91] op_sel_hi:[0,1,1]
	v_cvt_f32_ubyte2_e32 v146, v69
	v_cvt_f32_ubyte3_e32 v147, v69
	v_pk_fma_f32 v[86:87], v[60:61], v[104:105], v[86:87] op_sel_hi:[0,1,1]
	v_cvt_f32_ubyte0_e32 v98, v76
	v_cvt_f32_ubyte1_e32 v99, v76
	v_pk_fma_f32 v[84:85], v[60:61], v[146:147], v[84:85] op_sel_hi:[0,1,1]
	v_and_b32_e32 v82, s0, v24
	v_and_b32_e32 v83, s1, v24
	v_and_b32_e32 v88, s0, v25
	v_and_b32_e32 v89, s1, v25
	v_cvt_f32_ubyte2_e32 v102, v76
	v_cvt_f32_ubyte3_e32 v103, v76
	v_pk_fma_f32 v[80:81], v[52:53], v[98:99], v[80:81] op_sel_hi:[0,1,1]
	v_cvt_f32_ubyte0_e32 v104, v77
	v_cvt_f32_ubyte1_e32 v105, v77
	v_pk_fma_f32 v[78:79], v[52:53], v[102:103], v[78:79] op_sel_hi:[0,1,1]
	v_cvt_f32_ubyte2_e32 v146, v77
	v_cvt_f32_ubyte3_e32 v147, v77
	v_pk_fma_f32 v[70:71], v[60:61], v[104:105], v[70:71] op_sel_hi:[0,1,1]
	v_cvt_f32_ubyte0_e32 v98, v82
	v_cvt_f32_ubyte1_e32 v99, v82
	v_pk_fma_f32 v[62:63], v[60:61], v[146:147], v[62:63] op_sel_hi:[0,1,1]
	v_cvt_f32_ubyte2_e32 v102, v82
	v_cvt_f32_ubyte3_e32 v103, v82
	v_pk_fma_f32 v[92:93], v[52:53], v[98:99], v[92:93] op_sel:[1,0,0]
	v_cvt_f32_ubyte0_e32 v104, v83
	v_cvt_f32_ubyte1_e32 v105, v83
	v_pk_fma_f32 v[90:91], v[52:53], v[102:103], v[90:91] op_sel:[1,0,0]
	v_cvt_f32_ubyte2_e32 v146, v83
	v_cvt_f32_ubyte3_e32 v147, v83
	v_pk_fma_f32 v[86:87], v[60:61], v[104:105], v[86:87] op_sel:[1,0,0]
	v_cvt_f32_ubyte0_e32 v98, v88
	v_cvt_f32_ubyte1_e32 v99, v88
	v_pk_fma_f32 v[84:85], v[60:61], v[146:147], v[84:85] op_sel:[1,0,0]
	v_and_b32_e32 v68, s0, v26
	v_and_b32_e32 v69, s1, v26
	v_and_b32_e32 v76, s0, v27
	v_and_b32_e32 v77, s1, v27
	v_cvt_f32_ubyte2_e32 v102, v88
	v_cvt_f32_ubyte3_e32 v103, v88
	v_pk_fma_f32 v[80:81], v[52:53], v[98:99], v[80:81] op_sel:[1,0,0]
	v_cvt_f32_ubyte0_e32 v104, v89
	v_cvt_f32_ubyte1_e32 v105, v89
	v_pk_fma_f32 v[78:79], v[52:53], v[102:103], v[78:79] op_sel:[1,0,0]
	v_cvt_f32_ubyte2_e32 v146, v89
	v_cvt_f32_ubyte3_e32 v147, v89
	v_pk_fma_f32 v[70:71], v[60:61], v[104:105], v[70:71] op_sel:[1,0,0]
	v_cvt_f32_ubyte0_e32 v98, v68
	v_cvt_f32_ubyte1_e32 v99, v68
	v_pk_fma_f32 v[62:63], v[60:61], v[146:147], v[62:63] op_sel:[1,0,0]
	v_cvt_f32_ubyte2_e32 v102, v68
	v_cvt_f32_ubyte3_e32 v103, v68
	v_pk_fma_f32 v[92:93], v[54:55], v[98:99], v[92:93] op_sel_hi:[0,1,1]
	v_cvt_f32_ubyte0_e32 v104, v69
	v_cvt_f32_ubyte1_e32 v105, v69
	v_pk_fma_f32 v[90:91], v[54:55], v[102:103], v[90:91] op_sel_hi:[0,1,1]
	v_cvt_f32_ubyte2_e32 v146, v69
	v_cvt_f32_ubyte3_e32 v147, v69
	v_pk_fma_f32 v[86:87], v[64:65], v[104:105], v[86:87] op_sel_hi:[0,1,1]
	v_cvt_f32_ubyte0_e32 v98, v76
	v_cvt_f32_ubyte1_e32 v99, v76
	v_pk_fma_f32 v[84:85], v[64:65], v[146:147], v[84:85] op_sel_hi:[0,1,1]
	v_and_b32_e32 v82, s0, v28
	v_and_b32_e32 v83, s1, v28
	v_and_b32_e32 v88, s0, v29
	v_and_b32_e32 v89, s1, v29
	v_cvt_f32_ubyte2_e32 v102, v76
	v_cvt_f32_ubyte3_e32 v103, v76
	v_pk_fma_f32 v[80:81], v[54:55], v[98:99], v[80:81] op_sel_hi:[0,1,1]
	v_cvt_f32_ubyte0_e32 v104, v77
	v_cvt_f32_ubyte1_e32 v105, v77
	v_pk_fma_f32 v[78:79], v[54:55], v[102:103], v[78:79] op_sel_hi:[0,1,1]
	v_cvt_f32_ubyte2_e32 v146, v77
	v_cvt_f32_ubyte3_e32 v147, v77
	v_pk_fma_f32 v[70:71], v[64:65], v[104:105], v[70:71] op_sel_hi:[0,1,1]
	v_cvt_f32_ubyte0_e32 v98, v82
	v_cvt_f32_ubyte1_e32 v99, v82
	v_pk_fma_f32 v[62:63], v[64:65], v[146:147], v[62:63] op_sel_hi:[0,1,1]
	v_cvt_f32_ubyte2_e32 v102, v82
	v_cvt_f32_ubyte3_e32 v103, v82
	v_pk_fma_f32 v[92:93], v[54:55], v[98:99], v[92:93] op_sel:[1,0,0]
	v_cvt_f32_ubyte0_e32 v104, v83
	v_cvt_f32_ubyte1_e32 v105, v83
	v_pk_fma_f32 v[90:91], v[54:55], v[102:103], v[90:91] op_sel:[1,0,0]
	v_cvt_f32_ubyte2_e32 v146, v83
	v_cvt_f32_ubyte3_e32 v147, v83
	v_pk_fma_f32 v[86:87], v[64:65], v[104:105], v[86:87] op_sel:[1,0,0]
	v_cvt_f32_ubyte0_e32 v98, v88
	v_cvt_f32_ubyte1_e32 v99, v88
	v_pk_fma_f32 v[84:85], v[64:65], v[146:147], v[84:85] op_sel:[1,0,0]
	v_and_b32_e32 v68, s0, v30
	v_and_b32_e32 v69, s1, v30
	v_and_b32_e32 v76, s0, v31
	v_and_b32_e32 v77, s1, v31
	v_cvt_f32_ubyte2_e32 v102, v88
	v_cvt_f32_ubyte3_e32 v103, v88
	v_pk_fma_f32 v[80:81], v[54:55], v[98:99], v[80:81] op_sel:[1,0,0]
	v_cvt_f32_ubyte0_e32 v104, v89
	v_cvt_f32_ubyte1_e32 v105, v89
	v_pk_fma_f32 v[78:79], v[54:55], v[102:103], v[78:79] op_sel:[1,0,0]
	v_cvt_f32_ubyte2_e32 v146, v89
	v_cvt_f32_ubyte3_e32 v147, v89
	v_pk_fma_f32 v[70:71], v[64:65], v[104:105], v[70:71] op_sel:[1,0,0]
	v_cvt_f32_ubyte0_e32 v98, v68
	v_cvt_f32_ubyte1_e32 v99, v68
	v_pk_fma_f32 v[62:63], v[64:65], v[146:147], v[62:63] op_sel:[1,0,0]
	v_cvt_f32_ubyte2_e32 v102, v68
	v_cvt_f32_ubyte3_e32 v103, v68
	v_pk_fma_f32 v[92:93], v[56:57], v[98:99], v[92:93] op_sel_hi:[0,1,1]
	v_cvt_f32_ubyte0_e32 v104, v69
	v_cvt_f32_ubyte1_e32 v105, v69
	v_pk_fma_f32 v[90:91], v[56:57], v[102:103], v[90:91] op_sel_hi:[0,1,1]
	v_cvt_f32_ubyte2_e32 v146, v69
	v_cvt_f32_ubyte3_e32 v147, v69
	v_pk_fma_f32 v[86:87], v[66:67], v[104:105], v[86:87] op_sel_hi:[0,1,1]
	v_cvt_f32_ubyte0_e32 v98, v76
	v_cvt_f32_ubyte1_e32 v99, v76
	v_pk_fma_f32 v[84:85], v[66:67], v[146:147], v[84:85] op_sel_hi:[0,1,1]
	v_and_b32_e32 v82, s0, v32
	v_and_b32_e32 v83, s1, v32
	v_and_b32_e32 v88, s0, v33
	v_and_b32_e32 v89, s1, v33
	v_cvt_f32_ubyte2_e32 v102, v76
	v_cvt_f32_ubyte3_e32 v103, v76
	v_pk_fma_f32 v[80:81], v[56:57], v[98:99], v[80:81] op_sel_hi:[0,1,1]
	v_cvt_f32_ubyte0_e32 v104, v77
	v_cvt_f32_ubyte1_e32 v105, v77
	v_pk_fma_f32 v[78:79], v[56:57], v[102:103], v[78:79] op_sel_hi:[0,1,1]
	v_cvt_f32_ubyte2_e32 v146, v77
	v_cvt_f32_ubyte3_e32 v147, v77
	v_pk_fma_f32 v[70:71], v[66:67], v[104:105], v[70:71] op_sel_hi:[0,1,1]
	v_cvt_f32_ubyte0_e32 v98, v82
	v_cvt_f32_ubyte1_e32 v99, v82
	v_pk_fma_f32 v[62:63], v[66:67], v[146:147], v[62:63] op_sel_hi:[0,1,1]
	v_cvt_f32_ubyte2_e32 v102, v82
	v_cvt_f32_ubyte3_e32 v103, v82
	v_pk_fma_f32 v[92:93], v[56:57], v[98:99], v[92:93] op_sel:[1,0,0]
	v_cvt_f32_ubyte0_e32 v104, v83
	v_cvt_f32_ubyte1_e32 v105, v83
	v_pk_fma_f32 v[90:91], v[56:57], v[102:103], v[90:91] op_sel:[1,0,0]
	v_cvt_f32_ubyte2_e32 v146, v83
	v_cvt_f32_ubyte3_e32 v147, v83
	v_pk_fma_f32 v[86:87], v[66:67], v[104:105], v[86:87] op_sel:[1,0,0]
	v_cvt_f32_ubyte0_e32 v98, v88
	v_cvt_f32_ubyte1_e32 v99, v88
	v_pk_fma_f32 v[84:85], v[66:67], v[146:147], v[84:85] op_sel:[1,0,0]
	v_cvt_f32_ubyte2_e32 v102, v88
	v_cvt_f32_ubyte3_e32 v103, v88
	v_pk_fma_f32 v[80:81], v[56:57], v[98:99], v[80:81] op_sel:[1,0,0]
	v_cvt_f32_ubyte0_e32 v104, v89
	v_cvt_f32_ubyte1_e32 v105, v89
	v_pk_fma_f32 v[78:79], v[56:57], v[102:103], v[78:79] op_sel:[1,0,0]
	v_cvt_f32_ubyte2_e32 v146, v89
	v_cvt_f32_ubyte3_e32 v147, v89
	v_pk_fma_f32 v[70:71], v[66:67], v[104:105], v[70:71] op_sel:[1,0,0]
	v_pk_fma_f32 v[62:63], v[66:67], v[146:147], v[62:63] op_sel:[1,0,0]
	s_waitcnt lgkmcnt(0)
	ds_read_b128 v[50:53], v1 offset:928
	ds_read_b128 v[54:57], v1 offset:944
	ds_read_b128 v[58:61], v1 offset:1952
	ds_read_b128 v[64:67], v1 offset:1968
	s_waitcnt vmcnt(24)
	v_and_b32_e32 v68, s0, v164
	v_and_b32_e32 v69, s1, v164
	v_and_b32_e32 v76, s0, v165
	v_and_b32_e32 v77, s1, v165
	v_cvt_f32_ubyte0_e32 v98, v68
	v_cvt_f32_ubyte1_e32 v99, v68
	v_cvt_f32_ubyte2_e32 v102, v68
	v_cvt_f32_ubyte3_e32 v103, v68
	v_pk_fma_f32 v[92:93], v[34:35], v[98:99], v[92:93] op_sel_hi:[0,1,1]
	v_cvt_f32_ubyte0_e32 v104, v69
	v_cvt_f32_ubyte1_e32 v105, v69
	v_pk_fma_f32 v[90:91], v[34:35], v[102:103], v[90:91] op_sel_hi:[0,1,1]
	v_cvt_f32_ubyte2_e32 v146, v69
	v_cvt_f32_ubyte3_e32 v147, v69
	v_pk_fma_f32 v[86:87], v[42:43], v[104:105], v[86:87] op_sel_hi:[0,1,1]
	v_cvt_f32_ubyte0_e32 v98, v76
	v_cvt_f32_ubyte1_e32 v99, v76
	v_pk_fma_f32 v[84:85], v[42:43], v[146:147], v[84:85] op_sel_hi:[0,1,1]
	v_and_b32_e32 v82, s0, v166
	v_and_b32_e32 v83, s1, v166
	v_and_b32_e32 v88, s0, v167
	v_and_b32_e32 v89, s1, v167
	v_cvt_f32_ubyte2_e32 v102, v76
	v_cvt_f32_ubyte3_e32 v103, v76
	v_pk_fma_f32 v[80:81], v[34:35], v[98:99], v[80:81] op_sel_hi:[0,1,1]
	v_cvt_f32_ubyte0_e32 v104, v77
	v_cvt_f32_ubyte1_e32 v105, v77
	v_pk_fma_f32 v[78:79], v[34:35], v[102:103], v[78:79] op_sel_hi:[0,1,1]
	v_cvt_f32_ubyte2_e32 v146, v77
	v_cvt_f32_ubyte3_e32 v147, v77
	v_pk_fma_f32 v[70:71], v[42:43], v[104:105], v[70:71] op_sel_hi:[0,1,1]
	v_cvt_f32_ubyte0_e32 v98, v82
	v_cvt_f32_ubyte1_e32 v99, v82
	v_pk_fma_f32 v[62:63], v[42:43], v[146:147], v[62:63] op_sel_hi:[0,1,1]
	v_cvt_f32_ubyte2_e32 v102, v82
	v_cvt_f32_ubyte3_e32 v103, v82
	v_pk_fma_f32 v[92:93], v[34:35], v[98:99], v[92:93] op_sel:[1,0,0]
	v_cvt_f32_ubyte0_e32 v104, v83
	v_cvt_f32_ubyte1_e32 v105, v83
	v_pk_fma_f32 v[90:91], v[34:35], v[102:103], v[90:91] op_sel:[1,0,0]
	v_cvt_f32_ubyte2_e32 v146, v83
	v_cvt_f32_ubyte3_e32 v147, v83
	v_pk_fma_f32 v[86:87], v[42:43], v[104:105], v[86:87] op_sel:[1,0,0]
	v_cvt_f32_ubyte0_e32 v98, v88
	v_cvt_f32_ubyte1_e32 v99, v88
	v_pk_fma_f32 v[84:85], v[42:43], v[146:147], v[84:85] op_sel:[1,0,0]
	v_and_b32_e32 v68, s0, v168
	v_and_b32_e32 v69, s1, v168
	v_and_b32_e32 v76, s0, v169
	v_and_b32_e32 v77, s1, v169
	v_cvt_f32_ubyte2_e32 v102, v88
	v_cvt_f32_ubyte3_e32 v103, v88
	v_pk_fma_f32 v[80:81], v[34:35], v[98:99], v[80:81] op_sel:[1,0,0]
	v_cvt_f32_ubyte0_e32 v104, v89
	v_cvt_f32_ubyte1_e32 v105, v89
	v_pk_fma_f32 v[78:79], v[34:35], v[102:103], v[78:79] op_sel:[1,0,0]
	v_cvt_f32_ubyte2_e32 v146, v89
	v_cvt_f32_ubyte3_e32 v147, v89
	v_pk_fma_f32 v[70:71], v[42:43], v[104:105], v[70:71] op_sel:[1,0,0]
	v_cvt_f32_ubyte0_e32 v98, v68
	v_cvt_f32_ubyte1_e32 v99, v68
	v_pk_fma_f32 v[62:63], v[42:43], v[146:147], v[62:63] op_sel:[1,0,0]
	v_cvt_f32_ubyte2_e32 v102, v68
	v_cvt_f32_ubyte3_e32 v103, v68
	v_pk_fma_f32 v[92:93], v[36:37], v[98:99], v[92:93] op_sel_hi:[0,1,1]
	v_cvt_f32_ubyte0_e32 v104, v69
	v_cvt_f32_ubyte1_e32 v105, v69
	v_pk_fma_f32 v[90:91], v[36:37], v[102:103], v[90:91] op_sel_hi:[0,1,1]
	v_cvt_f32_ubyte2_e32 v146, v69
	v_cvt_f32_ubyte3_e32 v147, v69
	v_pk_fma_f32 v[86:87], v[44:45], v[104:105], v[86:87] op_sel_hi:[0,1,1]
	v_cvt_f32_ubyte0_e32 v98, v76
	v_cvt_f32_ubyte1_e32 v99, v76
	v_pk_fma_f32 v[84:85], v[44:45], v[146:147], v[84:85] op_sel_hi:[0,1,1]
	v_and_b32_e32 v82, s0, v170
	v_and_b32_e32 v83, s1, v170
	v_and_b32_e32 v88, s0, v171
	v_and_b32_e32 v89, s1, v171
	v_cvt_f32_ubyte2_e32 v102, v76
	v_cvt_f32_ubyte3_e32 v103, v76
	v_pk_fma_f32 v[80:81], v[36:37], v[98:99], v[80:81] op_sel_hi:[0,1,1]
	v_cvt_f32_ubyte0_e32 v104, v77
	v_cvt_f32_ubyte1_e32 v105, v77
	v_pk_fma_f32 v[78:79], v[36:37], v[102:103], v[78:79] op_sel_hi:[0,1,1]
	v_cvt_f32_ubyte2_e32 v146, v77
	v_cvt_f32_ubyte3_e32 v147, v77
	v_pk_fma_f32 v[70:71], v[44:45], v[104:105], v[70:71] op_sel_hi:[0,1,1]
	v_cvt_f32_ubyte0_e32 v98, v82
	v_cvt_f32_ubyte1_e32 v99, v82
	v_pk_fma_f32 v[62:63], v[44:45], v[146:147], v[62:63] op_sel_hi:[0,1,1]
	v_cvt_f32_ubyte2_e32 v102, v82
	v_cvt_f32_ubyte3_e32 v103, v82
	v_pk_fma_f32 v[92:93], v[36:37], v[98:99], v[92:93] op_sel:[1,0,0]
	v_cvt_f32_ubyte0_e32 v104, v83
	v_cvt_f32_ubyte1_e32 v105, v83
	v_pk_fma_f32 v[90:91], v[36:37], v[102:103], v[90:91] op_sel:[1,0,0]
	v_cvt_f32_ubyte2_e32 v146, v83
	v_cvt_f32_ubyte3_e32 v147, v83
	v_pk_fma_f32 v[86:87], v[44:45], v[104:105], v[86:87] op_sel:[1,0,0]
	v_cvt_f32_ubyte0_e32 v98, v88
	v_cvt_f32_ubyte1_e32 v99, v88
	v_pk_fma_f32 v[84:85], v[44:45], v[146:147], v[84:85] op_sel:[1,0,0]
	v_and_b32_e32 v68, s0, v172
	v_and_b32_e32 v69, s1, v172
	v_and_b32_e32 v76, s0, v173
	v_and_b32_e32 v77, s1, v173
	v_cvt_f32_ubyte2_e32 v102, v88
	v_cvt_f32_ubyte3_e32 v103, v88
	v_pk_fma_f32 v[80:81], v[36:37], v[98:99], v[80:81] op_sel:[1,0,0]
	v_cvt_f32_ubyte0_e32 v104, v89
	v_cvt_f32_ubyte1_e32 v105, v89
	v_pk_fma_f32 v[78:79], v[36:37], v[102:103], v[78:79] op_sel:[1,0,0]
	v_cvt_f32_ubyte2_e32 v146, v89
	v_cvt_f32_ubyte3_e32 v147, v89
	v_pk_fma_f32 v[70:71], v[44:45], v[104:105], v[70:71] op_sel:[1,0,0]
	v_cvt_f32_ubyte0_e32 v98, v68
	v_cvt_f32_ubyte1_e32 v99, v68
	v_pk_fma_f32 v[62:63], v[44:45], v[146:147], v[62:63] op_sel:[1,0,0]
	v_cvt_f32_ubyte2_e32 v102, v68
	v_cvt_f32_ubyte3_e32 v103, v68
	v_pk_fma_f32 v[92:93], v[38:39], v[98:99], v[92:93] op_sel_hi:[0,1,1]
	v_cvt_f32_ubyte0_e32 v104, v69
	v_cvt_f32_ubyte1_e32 v105, v69
	v_pk_fma_f32 v[90:91], v[38:39], v[102:103], v[90:91] op_sel_hi:[0,1,1]
	v_cvt_f32_ubyte2_e32 v146, v69
	v_cvt_f32_ubyte3_e32 v147, v69
	v_pk_fma_f32 v[86:87], v[46:47], v[104:105], v[86:87] op_sel_hi:[0,1,1]
	v_cvt_f32_ubyte0_e32 v98, v76
	v_cvt_f32_ubyte1_e32 v99, v76
	v_pk_fma_f32 v[84:85], v[46:47], v[146:147], v[84:85] op_sel_hi:[0,1,1]
	v_and_b32_e32 v82, s0, v174
	v_and_b32_e32 v83, s1, v174
	v_and_b32_e32 v88, s0, v175
	v_and_b32_e32 v89, s1, v175
	v_cvt_f32_ubyte2_e32 v102, v76
	v_cvt_f32_ubyte3_e32 v103, v76
	v_pk_fma_f32 v[80:81], v[38:39], v[98:99], v[80:81] op_sel_hi:[0,1,1]
	v_cvt_f32_ubyte0_e32 v104, v77
	v_cvt_f32_ubyte1_e32 v105, v77
	v_pk_fma_f32 v[78:79], v[38:39], v[102:103], v[78:79] op_sel_hi:[0,1,1]
	v_cvt_f32_ubyte2_e32 v146, v77
	v_cvt_f32_ubyte3_e32 v147, v77
	v_pk_fma_f32 v[70:71], v[46:47], v[104:105], v[70:71] op_sel_hi:[0,1,1]
	v_cvt_f32_ubyte0_e32 v98, v82
	v_cvt_f32_ubyte1_e32 v99, v82
	v_pk_fma_f32 v[62:63], v[46:47], v[146:147], v[62:63] op_sel_hi:[0,1,1]
	v_cvt_f32_ubyte2_e32 v102, v82
	v_cvt_f32_ubyte3_e32 v103, v82
	v_pk_fma_f32 v[92:93], v[38:39], v[98:99], v[92:93] op_sel:[1,0,0]
	v_cvt_f32_ubyte0_e32 v104, v83
	v_cvt_f32_ubyte1_e32 v105, v83
	v_pk_fma_f32 v[90:91], v[38:39], v[102:103], v[90:91] op_sel:[1,0,0]
	v_cvt_f32_ubyte2_e32 v146, v83
	v_cvt_f32_ubyte3_e32 v147, v83
	v_pk_fma_f32 v[86:87], v[46:47], v[104:105], v[86:87] op_sel:[1,0,0]
	v_cvt_f32_ubyte0_e32 v98, v88
	v_cvt_f32_ubyte1_e32 v99, v88
	v_pk_fma_f32 v[84:85], v[46:47], v[146:147], v[84:85] op_sel:[1,0,0]
	v_and_b32_e32 v68, s0, v176
	v_and_b32_e32 v69, s1, v176
	v_and_b32_e32 v76, s0, v177
	v_and_b32_e32 v77, s1, v177
	v_cvt_f32_ubyte2_e32 v102, v88
	v_cvt_f32_ubyte3_e32 v103, v88
	v_pk_fma_f32 v[80:81], v[38:39], v[98:99], v[80:81] op_sel:[1,0,0]
	v_cvt_f32_ubyte0_e32 v104, v89
	v_cvt_f32_ubyte1_e32 v105, v89
	v_pk_fma_f32 v[78:79], v[38:39], v[102:103], v[78:79] op_sel:[1,0,0]
	v_cvt_f32_ubyte2_e32 v146, v89
	v_cvt_f32_ubyte3_e32 v147, v89
	v_pk_fma_f32 v[70:71], v[46:47], v[104:105], v[70:71] op_sel:[1,0,0]
	v_cvt_f32_ubyte0_e32 v98, v68
	v_cvt_f32_ubyte1_e32 v99, v68
	v_pk_fma_f32 v[62:63], v[46:47], v[146:147], v[62:63] op_sel:[1,0,0]
	v_cvt_f32_ubyte2_e32 v102, v68
	v_cvt_f32_ubyte3_e32 v103, v68
	v_pk_fma_f32 v[92:93], v[40:41], v[98:99], v[92:93] op_sel_hi:[0,1,1]
	v_cvt_f32_ubyte0_e32 v104, v69
	v_cvt_f32_ubyte1_e32 v105, v69
	v_pk_fma_f32 v[90:91], v[40:41], v[102:103], v[90:91] op_sel_hi:[0,1,1]
	v_cvt_f32_ubyte2_e32 v146, v69
	v_cvt_f32_ubyte3_e32 v147, v69
	v_pk_fma_f32 v[86:87], v[48:49], v[104:105], v[86:87] op_sel_hi:[0,1,1]
	v_cvt_f32_ubyte0_e32 v98, v76
	v_cvt_f32_ubyte1_e32 v99, v76
	v_pk_fma_f32 v[84:85], v[48:49], v[146:147], v[84:85] op_sel_hi:[0,1,1]
	v_and_b32_e32 v82, s0, v178
	v_and_b32_e32 v83, s1, v178
	v_and_b32_e32 v88, s0, v179
	v_and_b32_e32 v89, s1, v179
	v_cvt_f32_ubyte2_e32 v102, v76
	v_cvt_f32_ubyte3_e32 v103, v76
	v_pk_fma_f32 v[80:81], v[40:41], v[98:99], v[80:81] op_sel_hi:[0,1,1]
	v_cvt_f32_ubyte0_e32 v104, v77
	v_cvt_f32_ubyte1_e32 v105, v77
	v_pk_fma_f32 v[78:79], v[40:41], v[102:103], v[78:79] op_sel_hi:[0,1,1]
	v_cvt_f32_ubyte2_e32 v146, v77
	v_cvt_f32_ubyte3_e32 v147, v77
	v_pk_fma_f32 v[70:71], v[48:49], v[104:105], v[70:71] op_sel_hi:[0,1,1]
	v_cvt_f32_ubyte0_e32 v98, v82
	v_cvt_f32_ubyte1_e32 v99, v82
	v_pk_fma_f32 v[62:63], v[48:49], v[146:147], v[62:63] op_sel_hi:[0,1,1]
	v_cvt_f32_ubyte2_e32 v102, v82
	v_cvt_f32_ubyte3_e32 v103, v82
	v_pk_fma_f32 v[92:93], v[40:41], v[98:99], v[92:93] op_sel:[1,0,0]
	v_cvt_f32_ubyte0_e32 v104, v83
	v_cvt_f32_ubyte1_e32 v105, v83
	v_pk_fma_f32 v[90:91], v[40:41], v[102:103], v[90:91] op_sel:[1,0,0]
	v_cvt_f32_ubyte2_e32 v146, v83
	v_cvt_f32_ubyte3_e32 v147, v83
	v_pk_fma_f32 v[86:87], v[48:49], v[104:105], v[86:87] op_sel:[1,0,0]
	v_cvt_f32_ubyte0_e32 v98, v88
	v_cvt_f32_ubyte1_e32 v99, v88
	v_pk_fma_f32 v[84:85], v[48:49], v[146:147], v[84:85] op_sel:[1,0,0]
	v_cvt_f32_ubyte2_e32 v102, v88
	v_cvt_f32_ubyte3_e32 v103, v88
	v_pk_fma_f32 v[80:81], v[40:41], v[98:99], v[80:81] op_sel:[1,0,0]
	v_cvt_f32_ubyte0_e32 v104, v89
	v_cvt_f32_ubyte1_e32 v105, v89
	v_pk_fma_f32 v[78:79], v[40:41], v[102:103], v[78:79] op_sel:[1,0,0]
	v_cvt_f32_ubyte2_e32 v146, v89
	v_cvt_f32_ubyte3_e32 v147, v89
	v_pk_fma_f32 v[70:71], v[48:49], v[104:105], v[70:71] op_sel:[1,0,0]
	v_pk_fma_f32 v[62:63], v[48:49], v[146:147], v[62:63] op_sel:[1,0,0]
	s_waitcnt lgkmcnt(0)
	ds_read_b128 v[34:37], v1 offset:960
	ds_read_b128 v[38:41], v1 offset:976
	ds_read_b128 v[42:45], v1 offset:1984
	ds_read_b128 v[46:49], v1 offset:2000
	s_waitcnt vmcnt(16)
	v_and_b32_e32 v68, s0, v180
	v_and_b32_e32 v69, s1, v180
	v_and_b32_e32 v76, s0, v181
	v_and_b32_e32 v77, s1, v181
	v_cvt_f32_ubyte0_e32 v98, v68
	v_cvt_f32_ubyte1_e32 v99, v68
	v_cvt_f32_ubyte2_e32 v102, v68
	v_cvt_f32_ubyte3_e32 v103, v68
	v_pk_fma_f32 v[92:93], v[50:51], v[98:99], v[92:93] op_sel_hi:[0,1,1]
	v_cvt_f32_ubyte0_e32 v104, v69
	v_cvt_f32_ubyte1_e32 v105, v69
	v_pk_fma_f32 v[90:91], v[50:51], v[102:103], v[90:91] op_sel_hi:[0,1,1]
	v_cvt_f32_ubyte2_e32 v146, v69
	v_cvt_f32_ubyte3_e32 v147, v69
	v_pk_fma_f32 v[86:87], v[58:59], v[104:105], v[86:87] op_sel_hi:[0,1,1]
	v_cvt_f32_ubyte0_e32 v98, v76
	v_cvt_f32_ubyte1_e32 v99, v76
	v_pk_fma_f32 v[84:85], v[58:59], v[146:147], v[84:85] op_sel_hi:[0,1,1]
	v_and_b32_e32 v82, s0, v182
	v_and_b32_e32 v83, s1, v182
	v_and_b32_e32 v88, s0, v183
	v_and_b32_e32 v89, s1, v183
	v_cvt_f32_ubyte2_e32 v102, v76
	v_cvt_f32_ubyte3_e32 v103, v76
	v_pk_fma_f32 v[80:81], v[50:51], v[98:99], v[80:81] op_sel_hi:[0,1,1]
	v_cvt_f32_ubyte0_e32 v104, v77
	v_cvt_f32_ubyte1_e32 v105, v77
	v_pk_fma_f32 v[78:79], v[50:51], v[102:103], v[78:79] op_sel_hi:[0,1,1]
	v_cvt_f32_ubyte2_e32 v146, v77
	v_cvt_f32_ubyte3_e32 v147, v77
	v_pk_fma_f32 v[70:71], v[58:59], v[104:105], v[70:71] op_sel_hi:[0,1,1]
	v_cvt_f32_ubyte0_e32 v98, v82
	v_cvt_f32_ubyte1_e32 v99, v82
	v_pk_fma_f32 v[62:63], v[58:59], v[146:147], v[62:63] op_sel_hi:[0,1,1]
	v_cvt_f32_ubyte2_e32 v102, v82
	v_cvt_f32_ubyte3_e32 v103, v82
	v_pk_fma_f32 v[92:93], v[50:51], v[98:99], v[92:93] op_sel:[1,0,0]
	v_cvt_f32_ubyte0_e32 v104, v83
	v_cvt_f32_ubyte1_e32 v105, v83
	v_pk_fma_f32 v[90:91], v[50:51], v[102:103], v[90:91] op_sel:[1,0,0]
	v_cvt_f32_ubyte2_e32 v146, v83
	v_cvt_f32_ubyte3_e32 v147, v83
	v_pk_fma_f32 v[86:87], v[58:59], v[104:105], v[86:87] op_sel:[1,0,0]
	v_cvt_f32_ubyte0_e32 v98, v88
	v_cvt_f32_ubyte1_e32 v99, v88
	v_pk_fma_f32 v[84:85], v[58:59], v[146:147], v[84:85] op_sel:[1,0,0]
	v_and_b32_e32 v68, s0, v184
	v_and_b32_e32 v69, s1, v184
	v_and_b32_e32 v76, s0, v185
	v_and_b32_e32 v77, s1, v185
	v_cvt_f32_ubyte2_e32 v102, v88
	v_cvt_f32_ubyte3_e32 v103, v88
	v_pk_fma_f32 v[80:81], v[50:51], v[98:99], v[80:81] op_sel:[1,0,0]
	v_cvt_f32_ubyte0_e32 v104, v89
	v_cvt_f32_ubyte1_e32 v105, v89
	v_pk_fma_f32 v[78:79], v[50:51], v[102:103], v[78:79] op_sel:[1,0,0]
	v_cvt_f32_ubyte2_e32 v146, v89
	v_cvt_f32_ubyte3_e32 v147, v89
	v_pk_fma_f32 v[70:71], v[58:59], v[104:105], v[70:71] op_sel:[1,0,0]
	v_cvt_f32_ubyte0_e32 v98, v68
	v_cvt_f32_ubyte1_e32 v99, v68
	v_pk_fma_f32 v[62:63], v[58:59], v[146:147], v[62:63] op_sel:[1,0,0]
	v_cvt_f32_ubyte2_e32 v102, v68
	v_cvt_f32_ubyte3_e32 v103, v68
	v_pk_fma_f32 v[92:93], v[52:53], v[98:99], v[92:93] op_sel_hi:[0,1,1]
	v_cvt_f32_ubyte0_e32 v104, v69
	v_cvt_f32_ubyte1_e32 v105, v69
	v_pk_fma_f32 v[90:91], v[52:53], v[102:103], v[90:91] op_sel_hi:[0,1,1]
	v_cvt_f32_ubyte2_e32 v146, v69
	v_cvt_f32_ubyte3_e32 v147, v69
	v_pk_fma_f32 v[86:87], v[60:61], v[104:105], v[86:87] op_sel_hi:[0,1,1]
	v_cvt_f32_ubyte0_e32 v98, v76
	v_cvt_f32_ubyte1_e32 v99, v76
	v_pk_fma_f32 v[84:85], v[60:61], v[146:147], v[84:85] op_sel_hi:[0,1,1]
	v_and_b32_e32 v82, s0, v186
	v_and_b32_e32 v83, s1, v186
	v_and_b32_e32 v88, s0, v187
	v_and_b32_e32 v89, s1, v187
	v_cvt_f32_ubyte2_e32 v102, v76
	v_cvt_f32_ubyte3_e32 v103, v76
	v_pk_fma_f32 v[80:81], v[52:53], v[98:99], v[80:81] op_sel_hi:[0,1,1]
	v_cvt_f32_ubyte0_e32 v104, v77
	v_cvt_f32_ubyte1_e32 v105, v77
	v_pk_fma_f32 v[78:79], v[52:53], v[102:103], v[78:79] op_sel_hi:[0,1,1]
	v_cvt_f32_ubyte2_e32 v146, v77
	v_cvt_f32_ubyte3_e32 v147, v77
	v_pk_fma_f32 v[70:71], v[60:61], v[104:105], v[70:71] op_sel_hi:[0,1,1]
	v_cvt_f32_ubyte0_e32 v98, v82
	v_cvt_f32_ubyte1_e32 v99, v82
	v_pk_fma_f32 v[62:63], v[60:61], v[146:147], v[62:63] op_sel_hi:[0,1,1]
	v_cvt_f32_ubyte2_e32 v102, v82
	v_cvt_f32_ubyte3_e32 v103, v82
	v_pk_fma_f32 v[92:93], v[52:53], v[98:99], v[92:93] op_sel:[1,0,0]
	v_cvt_f32_ubyte0_e32 v104, v83
	v_cvt_f32_ubyte1_e32 v105, v83
	v_pk_fma_f32 v[90:91], v[52:53], v[102:103], v[90:91] op_sel:[1,0,0]
	v_cvt_f32_ubyte2_e32 v146, v83
	v_cvt_f32_ubyte3_e32 v147, v83
	v_pk_fma_f32 v[86:87], v[60:61], v[104:105], v[86:87] op_sel:[1,0,0]
	v_cvt_f32_ubyte0_e32 v98, v88
	v_cvt_f32_ubyte1_e32 v99, v88
	v_pk_fma_f32 v[84:85], v[60:61], v[146:147], v[84:85] op_sel:[1,0,0]
	v_and_b32_e32 v68, s0, v188
	v_and_b32_e32 v69, s1, v188
	v_and_b32_e32 v76, s0, v189
	v_and_b32_e32 v77, s1, v189
	v_cvt_f32_ubyte2_e32 v102, v88
	v_cvt_f32_ubyte3_e32 v103, v88
	v_pk_fma_f32 v[80:81], v[52:53], v[98:99], v[80:81] op_sel:[1,0,0]
	v_cvt_f32_ubyte0_e32 v104, v89
	v_cvt_f32_ubyte1_e32 v105, v89
	v_pk_fma_f32 v[78:79], v[52:53], v[102:103], v[78:79] op_sel:[1,0,0]
	v_cvt_f32_ubyte2_e32 v146, v89
	v_cvt_f32_ubyte3_e32 v147, v89
	v_pk_fma_f32 v[70:71], v[60:61], v[104:105], v[70:71] op_sel:[1,0,0]
	v_cvt_f32_ubyte0_e32 v98, v68
	v_cvt_f32_ubyte1_e32 v99, v68
	v_pk_fma_f32 v[62:63], v[60:61], v[146:147], v[62:63] op_sel:[1,0,0]
	v_cvt_f32_ubyte2_e32 v102, v68
	v_cvt_f32_ubyte3_e32 v103, v68
	v_pk_fma_f32 v[92:93], v[54:55], v[98:99], v[92:93] op_sel_hi:[0,1,1]
	v_cvt_f32_ubyte0_e32 v104, v69
	v_cvt_f32_ubyte1_e32 v105, v69
	v_pk_fma_f32 v[90:91], v[54:55], v[102:103], v[90:91] op_sel_hi:[0,1,1]
	v_cvt_f32_ubyte2_e32 v146, v69
	v_cvt_f32_ubyte3_e32 v147, v69
	v_pk_fma_f32 v[86:87], v[64:65], v[104:105], v[86:87] op_sel_hi:[0,1,1]
	v_cvt_f32_ubyte0_e32 v98, v76
	v_cvt_f32_ubyte1_e32 v99, v76
	v_pk_fma_f32 v[84:85], v[64:65], v[146:147], v[84:85] op_sel_hi:[0,1,1]
	v_and_b32_e32 v82, s0, v190
	v_and_b32_e32 v83, s1, v190
	v_and_b32_e32 v88, s0, v191
	v_and_b32_e32 v89, s1, v191
	v_cvt_f32_ubyte2_e32 v102, v76
	v_cvt_f32_ubyte3_e32 v103, v76
	v_pk_fma_f32 v[80:81], v[54:55], v[98:99], v[80:81] op_sel_hi:[0,1,1]
	v_cvt_f32_ubyte0_e32 v104, v77
	v_cvt_f32_ubyte1_e32 v105, v77
	v_pk_fma_f32 v[78:79], v[54:55], v[102:103], v[78:79] op_sel_hi:[0,1,1]
	v_cvt_f32_ubyte2_e32 v146, v77
	v_cvt_f32_ubyte3_e32 v147, v77
	v_pk_fma_f32 v[70:71], v[64:65], v[104:105], v[70:71] op_sel_hi:[0,1,1]
	v_cvt_f32_ubyte0_e32 v98, v82
	v_cvt_f32_ubyte1_e32 v99, v82
	v_pk_fma_f32 v[62:63], v[64:65], v[146:147], v[62:63] op_sel_hi:[0,1,1]
	v_cvt_f32_ubyte2_e32 v102, v82
	v_cvt_f32_ubyte3_e32 v103, v82
	v_pk_fma_f32 v[92:93], v[54:55], v[98:99], v[92:93] op_sel:[1,0,0]
	v_cvt_f32_ubyte0_e32 v104, v83
	v_cvt_f32_ubyte1_e32 v105, v83
	v_pk_fma_f32 v[90:91], v[54:55], v[102:103], v[90:91] op_sel:[1,0,0]
	v_cvt_f32_ubyte2_e32 v146, v83
	v_cvt_f32_ubyte3_e32 v147, v83
	v_pk_fma_f32 v[86:87], v[64:65], v[104:105], v[86:87] op_sel:[1,0,0]
	v_cvt_f32_ubyte0_e32 v98, v88
	v_cvt_f32_ubyte1_e32 v99, v88
	v_pk_fma_f32 v[84:85], v[64:65], v[146:147], v[84:85] op_sel:[1,0,0]
	v_and_b32_e32 v68, s0, v192
	v_and_b32_e32 v69, s1, v192
	v_and_b32_e32 v76, s0, v193
	v_and_b32_e32 v77, s1, v193
	v_cvt_f32_ubyte2_e32 v102, v88
	v_cvt_f32_ubyte3_e32 v103, v88
	v_pk_fma_f32 v[80:81], v[54:55], v[98:99], v[80:81] op_sel:[1,0,0]
	v_cvt_f32_ubyte0_e32 v104, v89
	v_cvt_f32_ubyte1_e32 v105, v89
	v_pk_fma_f32 v[78:79], v[54:55], v[102:103], v[78:79] op_sel:[1,0,0]
	v_cvt_f32_ubyte2_e32 v146, v89
	v_cvt_f32_ubyte3_e32 v147, v89
	v_pk_fma_f32 v[70:71], v[64:65], v[104:105], v[70:71] op_sel:[1,0,0]
	v_cvt_f32_ubyte0_e32 v98, v68
	v_cvt_f32_ubyte1_e32 v99, v68
	v_pk_fma_f32 v[62:63], v[64:65], v[146:147], v[62:63] op_sel:[1,0,0]
	v_cvt_f32_ubyte2_e32 v102, v68
	v_cvt_f32_ubyte3_e32 v103, v68
	v_pk_fma_f32 v[92:93], v[56:57], v[98:99], v[92:93] op_sel_hi:[0,1,1]
	v_cvt_f32_ubyte0_e32 v104, v69
	v_cvt_f32_ubyte1_e32 v105, v69
	v_pk_fma_f32 v[90:91], v[56:57], v[102:103], v[90:91] op_sel_hi:[0,1,1]
	v_cvt_f32_ubyte2_e32 v146, v69
	v_cvt_f32_ubyte3_e32 v147, v69
	v_pk_fma_f32 v[86:87], v[66:67], v[104:105], v[86:87] op_sel_hi:[0,1,1]
	v_cvt_f32_ubyte0_e32 v98, v76
	v_cvt_f32_ubyte1_e32 v99, v76
	v_pk_fma_f32 v[84:85], v[66:67], v[146:147], v[84:85] op_sel_hi:[0,1,1]
	v_and_b32_e32 v82, s0, v194
	v_and_b32_e32 v83, s1, v194
	v_and_b32_e32 v88, s0, v195
	v_and_b32_e32 v89, s1, v195
	v_cvt_f32_ubyte2_e32 v102, v76
	v_cvt_f32_ubyte3_e32 v103, v76
	v_pk_fma_f32 v[80:81], v[56:57], v[98:99], v[80:81] op_sel_hi:[0,1,1]
	v_cvt_f32_ubyte0_e32 v104, v77
	v_cvt_f32_ubyte1_e32 v105, v77
	v_pk_fma_f32 v[78:79], v[56:57], v[102:103], v[78:79] op_sel_hi:[0,1,1]
	v_cvt_f32_ubyte2_e32 v146, v77
	v_cvt_f32_ubyte3_e32 v147, v77
	v_pk_fma_f32 v[70:71], v[66:67], v[104:105], v[70:71] op_sel_hi:[0,1,1]
	v_cvt_f32_ubyte0_e32 v98, v82
	v_cvt_f32_ubyte1_e32 v99, v82
	v_pk_fma_f32 v[62:63], v[66:67], v[146:147], v[62:63] op_sel_hi:[0,1,1]
	v_cvt_f32_ubyte2_e32 v102, v82
	v_cvt_f32_ubyte3_e32 v103, v82
	v_pk_fma_f32 v[92:93], v[56:57], v[98:99], v[92:93] op_sel:[1,0,0]
	v_cvt_f32_ubyte0_e32 v104, v83
	v_cvt_f32_ubyte1_e32 v105, v83
	v_pk_fma_f32 v[90:91], v[56:57], v[102:103], v[90:91] op_sel:[1,0,0]
	v_cvt_f32_ubyte2_e32 v146, v83
	v_cvt_f32_ubyte3_e32 v147, v83
	v_pk_fma_f32 v[86:87], v[66:67], v[104:105], v[86:87] op_sel:[1,0,0]
	v_cvt_f32_ubyte0_e32 v98, v88
	v_cvt_f32_ubyte1_e32 v99, v88
	v_pk_fma_f32 v[84:85], v[66:67], v[146:147], v[84:85] op_sel:[1,0,0]
	v_cvt_f32_ubyte2_e32 v102, v88
	v_cvt_f32_ubyte3_e32 v103, v88
	v_pk_fma_f32 v[80:81], v[56:57], v[98:99], v[80:81] op_sel:[1,0,0]
	v_cvt_f32_ubyte0_e32 v104, v89
	v_cvt_f32_ubyte1_e32 v105, v89
	v_pk_fma_f32 v[78:79], v[56:57], v[102:103], v[78:79] op_sel:[1,0,0]
	v_cvt_f32_ubyte2_e32 v146, v89
	v_cvt_f32_ubyte3_e32 v147, v89
	v_pk_fma_f32 v[70:71], v[66:67], v[104:105], v[70:71] op_sel:[1,0,0]
	v_pk_fma_f32 v[62:63], v[66:67], v[146:147], v[62:63] op_sel:[1,0,0]
	s_waitcnt lgkmcnt(0)
	ds_read_b128 v[50:53], v1 offset:992
	ds_read_b128 v[54:57], v1 offset:1008
	ds_read_b128 v[58:61], v1 offset:2016
	ds_read_b128 v[64:67], v1 offset:2032
	s_waitcnt vmcnt(8)
	v_and_b32_e32 v68, s0, v196
	v_and_b32_e32 v69, s1, v196
	v_and_b32_e32 v76, s0, v197
	v_and_b32_e32 v77, s1, v197
	v_cvt_f32_ubyte0_e32 v98, v68
	v_cvt_f32_ubyte1_e32 v99, v68
	v_cvt_f32_ubyte2_e32 v102, v68
	v_cvt_f32_ubyte3_e32 v103, v68
	v_pk_fma_f32 v[92:93], v[34:35], v[98:99], v[92:93] op_sel_hi:[0,1,1]
	v_cvt_f32_ubyte0_e32 v104, v69
	v_cvt_f32_ubyte1_e32 v105, v69
	v_pk_fma_f32 v[90:91], v[34:35], v[102:103], v[90:91] op_sel_hi:[0,1,1]
	v_cvt_f32_ubyte2_e32 v146, v69
	v_cvt_f32_ubyte3_e32 v147, v69
	v_pk_fma_f32 v[86:87], v[42:43], v[104:105], v[86:87] op_sel_hi:[0,1,1]
	v_cvt_f32_ubyte0_e32 v98, v76
	v_cvt_f32_ubyte1_e32 v99, v76
	v_pk_fma_f32 v[84:85], v[42:43], v[146:147], v[84:85] op_sel_hi:[0,1,1]
	v_and_b32_e32 v82, s0, v198
	v_and_b32_e32 v83, s1, v198
	v_and_b32_e32 v88, s0, v199
	v_and_b32_e32 v89, s1, v199
	v_cvt_f32_ubyte2_e32 v102, v76
	v_cvt_f32_ubyte3_e32 v103, v76
	v_pk_fma_f32 v[80:81], v[34:35], v[98:99], v[80:81] op_sel_hi:[0,1,1]
	v_cvt_f32_ubyte0_e32 v104, v77
	v_cvt_f32_ubyte1_e32 v105, v77
	v_pk_fma_f32 v[78:79], v[34:35], v[102:103], v[78:79] op_sel_hi:[0,1,1]
	v_cvt_f32_ubyte2_e32 v146, v77
	v_cvt_f32_ubyte3_e32 v147, v77
	v_pk_fma_f32 v[70:71], v[42:43], v[104:105], v[70:71] op_sel_hi:[0,1,1]
	v_cvt_f32_ubyte0_e32 v98, v82
	v_cvt_f32_ubyte1_e32 v99, v82
	v_pk_fma_f32 v[62:63], v[42:43], v[146:147], v[62:63] op_sel_hi:[0,1,1]
	v_cvt_f32_ubyte2_e32 v102, v82
	v_cvt_f32_ubyte3_e32 v103, v82
	v_pk_fma_f32 v[92:93], v[34:35], v[98:99], v[92:93] op_sel:[1,0,0]
	v_cvt_f32_ubyte0_e32 v104, v83
	v_cvt_f32_ubyte1_e32 v105, v83
	v_pk_fma_f32 v[90:91], v[34:35], v[102:103], v[90:91] op_sel:[1,0,0]
	v_cvt_f32_ubyte2_e32 v146, v83
	v_cvt_f32_ubyte3_e32 v147, v83
	v_pk_fma_f32 v[86:87], v[42:43], v[104:105], v[86:87] op_sel:[1,0,0]
	v_cvt_f32_ubyte0_e32 v98, v88
	v_cvt_f32_ubyte1_e32 v99, v88
	v_pk_fma_f32 v[84:85], v[42:43], v[146:147], v[84:85] op_sel:[1,0,0]
	v_and_b32_e32 v68, s0, v200
	v_and_b32_e32 v69, s1, v200
	v_and_b32_e32 v76, s0, v201
	v_and_b32_e32 v77, s1, v201
	v_cvt_f32_ubyte2_e32 v102, v88
	v_cvt_f32_ubyte3_e32 v103, v88
	v_pk_fma_f32 v[80:81], v[34:35], v[98:99], v[80:81] op_sel:[1,0,0]
	v_cvt_f32_ubyte0_e32 v104, v89
	v_cvt_f32_ubyte1_e32 v105, v89
	v_pk_fma_f32 v[78:79], v[34:35], v[102:103], v[78:79] op_sel:[1,0,0]
	v_cvt_f32_ubyte2_e32 v146, v89
	v_cvt_f32_ubyte3_e32 v147, v89
	v_pk_fma_f32 v[70:71], v[42:43], v[104:105], v[70:71] op_sel:[1,0,0]
	v_cvt_f32_ubyte0_e32 v98, v68
	v_cvt_f32_ubyte1_e32 v99, v68
	v_pk_fma_f32 v[62:63], v[42:43], v[146:147], v[62:63] op_sel:[1,0,0]
	v_cvt_f32_ubyte2_e32 v102, v68
	v_cvt_f32_ubyte3_e32 v103, v68
	v_pk_fma_f32 v[92:93], v[36:37], v[98:99], v[92:93] op_sel_hi:[0,1,1]
	v_cvt_f32_ubyte0_e32 v104, v69
	v_cvt_f32_ubyte1_e32 v105, v69
	v_pk_fma_f32 v[90:91], v[36:37], v[102:103], v[90:91] op_sel_hi:[0,1,1]
	v_cvt_f32_ubyte2_e32 v146, v69
	v_cvt_f32_ubyte3_e32 v147, v69
	v_pk_fma_f32 v[86:87], v[44:45], v[104:105], v[86:87] op_sel_hi:[0,1,1]
	v_cvt_f32_ubyte0_e32 v98, v76
	v_cvt_f32_ubyte1_e32 v99, v76
	v_pk_fma_f32 v[84:85], v[44:45], v[146:147], v[84:85] op_sel_hi:[0,1,1]
	v_and_b32_e32 v82, s0, v202
	v_and_b32_e32 v83, s1, v202
	v_and_b32_e32 v88, s0, v203
	v_and_b32_e32 v89, s1, v203
	v_cvt_f32_ubyte2_e32 v102, v76
	v_cvt_f32_ubyte3_e32 v103, v76
	v_pk_fma_f32 v[80:81], v[36:37], v[98:99], v[80:81] op_sel_hi:[0,1,1]
	v_cvt_f32_ubyte0_e32 v104, v77
	v_cvt_f32_ubyte1_e32 v105, v77
	v_pk_fma_f32 v[78:79], v[36:37], v[102:103], v[78:79] op_sel_hi:[0,1,1]
	v_cvt_f32_ubyte2_e32 v146, v77
	v_cvt_f32_ubyte3_e32 v147, v77
	v_pk_fma_f32 v[70:71], v[44:45], v[104:105], v[70:71] op_sel_hi:[0,1,1]
	v_cvt_f32_ubyte0_e32 v98, v82
	v_cvt_f32_ubyte1_e32 v99, v82
	v_pk_fma_f32 v[62:63], v[44:45], v[146:147], v[62:63] op_sel_hi:[0,1,1]
	v_cvt_f32_ubyte2_e32 v102, v82
	v_cvt_f32_ubyte3_e32 v103, v82
	v_pk_fma_f32 v[92:93], v[36:37], v[98:99], v[92:93] op_sel:[1,0,0]
	v_cvt_f32_ubyte0_e32 v104, v83
	v_cvt_f32_ubyte1_e32 v105, v83
	v_pk_fma_f32 v[90:91], v[36:37], v[102:103], v[90:91] op_sel:[1,0,0]
	v_cvt_f32_ubyte2_e32 v146, v83
	v_cvt_f32_ubyte3_e32 v147, v83
	v_pk_fma_f32 v[86:87], v[44:45], v[104:105], v[86:87] op_sel:[1,0,0]
	v_cvt_f32_ubyte0_e32 v98, v88
	v_cvt_f32_ubyte1_e32 v99, v88
	v_pk_fma_f32 v[84:85], v[44:45], v[146:147], v[84:85] op_sel:[1,0,0]
	v_and_b32_e32 v68, s0, v204
	v_and_b32_e32 v69, s1, v204
	v_and_b32_e32 v76, s0, v205
	v_and_b32_e32 v77, s1, v205
	v_cvt_f32_ubyte2_e32 v102, v88
	v_cvt_f32_ubyte3_e32 v103, v88
	v_pk_fma_f32 v[80:81], v[36:37], v[98:99], v[80:81] op_sel:[1,0,0]
	v_cvt_f32_ubyte0_e32 v104, v89
	v_cvt_f32_ubyte1_e32 v105, v89
	v_pk_fma_f32 v[78:79], v[36:37], v[102:103], v[78:79] op_sel:[1,0,0]
	v_cvt_f32_ubyte2_e32 v146, v89
	v_cvt_f32_ubyte3_e32 v147, v89
	v_pk_fma_f32 v[70:71], v[44:45], v[104:105], v[70:71] op_sel:[1,0,0]
	v_cvt_f32_ubyte0_e32 v98, v68
	v_cvt_f32_ubyte1_e32 v99, v68
	v_pk_fma_f32 v[62:63], v[44:45], v[146:147], v[62:63] op_sel:[1,0,0]
	v_cvt_f32_ubyte2_e32 v102, v68
	v_cvt_f32_ubyte3_e32 v103, v68
	v_pk_fma_f32 v[92:93], v[38:39], v[98:99], v[92:93] op_sel_hi:[0,1,1]
	v_cvt_f32_ubyte0_e32 v104, v69
	v_cvt_f32_ubyte1_e32 v105, v69
	v_pk_fma_f32 v[90:91], v[38:39], v[102:103], v[90:91] op_sel_hi:[0,1,1]
	v_cvt_f32_ubyte2_e32 v146, v69
	v_cvt_f32_ubyte3_e32 v147, v69
	v_pk_fma_f32 v[86:87], v[46:47], v[104:105], v[86:87] op_sel_hi:[0,1,1]
	v_cvt_f32_ubyte0_e32 v98, v76
	v_cvt_f32_ubyte1_e32 v99, v76
	v_pk_fma_f32 v[84:85], v[46:47], v[146:147], v[84:85] op_sel_hi:[0,1,1]
	v_and_b32_e32 v82, s0, v206
	v_and_b32_e32 v83, s1, v206
	v_and_b32_e32 v88, s0, v207
	v_and_b32_e32 v89, s1, v207
	v_cvt_f32_ubyte2_e32 v102, v76
	v_cvt_f32_ubyte3_e32 v103, v76
	v_pk_fma_f32 v[80:81], v[38:39], v[98:99], v[80:81] op_sel_hi:[0,1,1]
	v_cvt_f32_ubyte0_e32 v104, v77
	v_cvt_f32_ubyte1_e32 v105, v77
	v_pk_fma_f32 v[78:79], v[38:39], v[102:103], v[78:79] op_sel_hi:[0,1,1]
	v_cvt_f32_ubyte2_e32 v146, v77
	v_cvt_f32_ubyte3_e32 v147, v77
	v_pk_fma_f32 v[70:71], v[46:47], v[104:105], v[70:71] op_sel_hi:[0,1,1]
	v_cvt_f32_ubyte0_e32 v98, v82
	v_cvt_f32_ubyte1_e32 v99, v82
	v_pk_fma_f32 v[62:63], v[46:47], v[146:147], v[62:63] op_sel_hi:[0,1,1]
	v_cvt_f32_ubyte2_e32 v102, v82
	v_cvt_f32_ubyte3_e32 v103, v82
	v_pk_fma_f32 v[92:93], v[38:39], v[98:99], v[92:93] op_sel:[1,0,0]
	v_cvt_f32_ubyte0_e32 v104, v83
	v_cvt_f32_ubyte1_e32 v105, v83
	v_pk_fma_f32 v[90:91], v[38:39], v[102:103], v[90:91] op_sel:[1,0,0]
	v_cvt_f32_ubyte2_e32 v146, v83
	v_cvt_f32_ubyte3_e32 v147, v83
	v_pk_fma_f32 v[86:87], v[46:47], v[104:105], v[86:87] op_sel:[1,0,0]
	v_cvt_f32_ubyte0_e32 v98, v88
	v_cvt_f32_ubyte1_e32 v99, v88
	v_pk_fma_f32 v[84:85], v[46:47], v[146:147], v[84:85] op_sel:[1,0,0]
	v_and_b32_e32 v68, s0, v208
	v_and_b32_e32 v69, s1, v208
	v_and_b32_e32 v76, s0, v209
	v_and_b32_e32 v77, s1, v209
	v_cvt_f32_ubyte2_e32 v102, v88
	v_cvt_f32_ubyte3_e32 v103, v88
	v_pk_fma_f32 v[80:81], v[38:39], v[98:99], v[80:81] op_sel:[1,0,0]
	v_cvt_f32_ubyte0_e32 v104, v89
	v_cvt_f32_ubyte1_e32 v105, v89
	v_pk_fma_f32 v[78:79], v[38:39], v[102:103], v[78:79] op_sel:[1,0,0]
	v_cvt_f32_ubyte2_e32 v146, v89
	v_cvt_f32_ubyte3_e32 v147, v89
	v_pk_fma_f32 v[70:71], v[46:47], v[104:105], v[70:71] op_sel:[1,0,0]
	v_cvt_f32_ubyte0_e32 v98, v68
	v_cvt_f32_ubyte1_e32 v99, v68
	v_pk_fma_f32 v[62:63], v[46:47], v[146:147], v[62:63] op_sel:[1,0,0]
	v_cvt_f32_ubyte2_e32 v102, v68
	v_cvt_f32_ubyte3_e32 v103, v68
	v_pk_fma_f32 v[92:93], v[40:41], v[98:99], v[92:93] op_sel_hi:[0,1,1]
	v_cvt_f32_ubyte0_e32 v104, v69
	v_cvt_f32_ubyte1_e32 v105, v69
	v_pk_fma_f32 v[90:91], v[40:41], v[102:103], v[90:91] op_sel_hi:[0,1,1]
	v_cvt_f32_ubyte2_e32 v146, v69
	v_cvt_f32_ubyte3_e32 v147, v69
	v_pk_fma_f32 v[86:87], v[48:49], v[104:105], v[86:87] op_sel_hi:[0,1,1]
	v_cvt_f32_ubyte0_e32 v98, v76
	v_cvt_f32_ubyte1_e32 v99, v76
	v_pk_fma_f32 v[84:85], v[48:49], v[146:147], v[84:85] op_sel_hi:[0,1,1]
	v_and_b32_e32 v82, s0, v210
	v_and_b32_e32 v83, s1, v210
	v_and_b32_e32 v88, s0, v211
	v_and_b32_e32 v89, s1, v211
	v_cvt_f32_ubyte2_e32 v102, v76
	v_cvt_f32_ubyte3_e32 v103, v76
	v_pk_fma_f32 v[80:81], v[40:41], v[98:99], v[80:81] op_sel_hi:[0,1,1]
	v_cvt_f32_ubyte0_e32 v104, v77
	v_cvt_f32_ubyte1_e32 v105, v77
	v_pk_fma_f32 v[78:79], v[40:41], v[102:103], v[78:79] op_sel_hi:[0,1,1]
	v_cvt_f32_ubyte2_e32 v146, v77
	v_cvt_f32_ubyte3_e32 v147, v77
	v_pk_fma_f32 v[70:71], v[48:49], v[104:105], v[70:71] op_sel_hi:[0,1,1]
	v_cvt_f32_ubyte0_e32 v98, v82
	v_cvt_f32_ubyte1_e32 v99, v82
	v_pk_fma_f32 v[62:63], v[48:49], v[146:147], v[62:63] op_sel_hi:[0,1,1]
	v_cvt_f32_ubyte2_e32 v102, v82
	v_cvt_f32_ubyte3_e32 v103, v82
	v_pk_fma_f32 v[92:93], v[40:41], v[98:99], v[92:93] op_sel:[1,0,0]
	v_cvt_f32_ubyte0_e32 v104, v83
	v_cvt_f32_ubyte1_e32 v105, v83
	v_pk_fma_f32 v[90:91], v[40:41], v[102:103], v[90:91] op_sel:[1,0,0]
	v_cvt_f32_ubyte2_e32 v146, v83
	v_cvt_f32_ubyte3_e32 v147, v83
	v_pk_fma_f32 v[86:87], v[48:49], v[104:105], v[86:87] op_sel:[1,0,0]
	v_cvt_f32_ubyte0_e32 v98, v88
	v_cvt_f32_ubyte1_e32 v99, v88
	v_pk_fma_f32 v[84:85], v[48:49], v[146:147], v[84:85] op_sel:[1,0,0]
	v_cvt_f32_ubyte2_e32 v102, v88
	v_cvt_f32_ubyte3_e32 v103, v88
	v_pk_fma_f32 v[80:81], v[40:41], v[98:99], v[80:81] op_sel:[1,0,0]
	v_cvt_f32_ubyte0_e32 v104, v89
	v_cvt_f32_ubyte1_e32 v105, v89
	v_pk_fma_f32 v[78:79], v[40:41], v[102:103], v[78:79] op_sel:[1,0,0]
	v_cvt_f32_ubyte2_e32 v146, v89
	v_cvt_f32_ubyte3_e32 v147, v89
	v_pk_fma_f32 v[70:71], v[48:49], v[104:105], v[70:71] op_sel:[1,0,0]
	v_pk_fma_f32 v[62:63], v[48:49], v[146:147], v[62:63] op_sel:[1,0,0]
	s_waitcnt lgkmcnt(0)
	s_waitcnt vmcnt(0)
	v_and_b32_e32 v68, s0, v212
	v_and_b32_e32 v69, s1, v212
	v_and_b32_e32 v76, s0, v213
	v_and_b32_e32 v77, s1, v213
	v_cvt_f32_ubyte0_e32 v98, v68
	v_cvt_f32_ubyte1_e32 v99, v68
	v_cvt_f32_ubyte2_e32 v102, v68
	v_cvt_f32_ubyte3_e32 v103, v68
	v_pk_fma_f32 v[92:93], v[50:51], v[98:99], v[92:93] op_sel_hi:[0,1,1]
	v_cvt_f32_ubyte0_e32 v104, v69
	v_cvt_f32_ubyte1_e32 v105, v69
	v_pk_fma_f32 v[90:91], v[50:51], v[102:103], v[90:91] op_sel_hi:[0,1,1]
	v_cvt_f32_ubyte2_e32 v146, v69
	v_cvt_f32_ubyte3_e32 v147, v69
	v_pk_fma_f32 v[86:87], v[58:59], v[104:105], v[86:87] op_sel_hi:[0,1,1]
	v_cvt_f32_ubyte0_e32 v98, v76
	v_cvt_f32_ubyte1_e32 v99, v76
	v_pk_fma_f32 v[84:85], v[58:59], v[146:147], v[84:85] op_sel_hi:[0,1,1]
	v_and_b32_e32 v82, s0, v214
	v_and_b32_e32 v83, s1, v214
	v_and_b32_e32 v88, s0, v215
	v_and_b32_e32 v89, s1, v215
	v_cvt_f32_ubyte2_e32 v102, v76
	v_cvt_f32_ubyte3_e32 v103, v76
	v_pk_fma_f32 v[80:81], v[50:51], v[98:99], v[80:81] op_sel_hi:[0,1,1]
	v_cvt_f32_ubyte0_e32 v104, v77
	v_cvt_f32_ubyte1_e32 v105, v77
	v_pk_fma_f32 v[78:79], v[50:51], v[102:103], v[78:79] op_sel_hi:[0,1,1]
	v_cvt_f32_ubyte2_e32 v146, v77
	v_cvt_f32_ubyte3_e32 v147, v77
	v_pk_fma_f32 v[70:71], v[58:59], v[104:105], v[70:71] op_sel_hi:[0,1,1]
	v_cvt_f32_ubyte0_e32 v98, v82
	v_cvt_f32_ubyte1_e32 v99, v82
	v_pk_fma_f32 v[62:63], v[58:59], v[146:147], v[62:63] op_sel_hi:[0,1,1]
	v_cvt_f32_ubyte2_e32 v102, v82
	v_cvt_f32_ubyte3_e32 v103, v82
	v_pk_fma_f32 v[92:93], v[50:51], v[98:99], v[92:93] op_sel:[1,0,0]
	v_cvt_f32_ubyte0_e32 v104, v83
	v_cvt_f32_ubyte1_e32 v105, v83
	v_pk_fma_f32 v[90:91], v[50:51], v[102:103], v[90:91] op_sel:[1,0,0]
	v_cvt_f32_ubyte2_e32 v146, v83
	v_cvt_f32_ubyte3_e32 v147, v83
	v_pk_fma_f32 v[86:87], v[58:59], v[104:105], v[86:87] op_sel:[1,0,0]
	v_cvt_f32_ubyte0_e32 v98, v88
	v_cvt_f32_ubyte1_e32 v99, v88
	v_pk_fma_f32 v[84:85], v[58:59], v[146:147], v[84:85] op_sel:[1,0,0]
	v_and_b32_e32 v68, s0, v216
	v_and_b32_e32 v69, s1, v216
	v_and_b32_e32 v76, s0, v217
	v_and_b32_e32 v77, s1, v217
	v_cvt_f32_ubyte2_e32 v102, v88
	v_cvt_f32_ubyte3_e32 v103, v88
	v_pk_fma_f32 v[80:81], v[50:51], v[98:99], v[80:81] op_sel:[1,0,0]
	v_cvt_f32_ubyte0_e32 v104, v89
	v_cvt_f32_ubyte1_e32 v105, v89
	v_pk_fma_f32 v[78:79], v[50:51], v[102:103], v[78:79] op_sel:[1,0,0]
	v_cvt_f32_ubyte2_e32 v146, v89
	v_cvt_f32_ubyte3_e32 v147, v89
	v_pk_fma_f32 v[70:71], v[58:59], v[104:105], v[70:71] op_sel:[1,0,0]
	v_cvt_f32_ubyte0_e32 v98, v68
	v_cvt_f32_ubyte1_e32 v99, v68
	v_pk_fma_f32 v[62:63], v[58:59], v[146:147], v[62:63] op_sel:[1,0,0]
	v_cvt_f32_ubyte2_e32 v102, v68
	v_cvt_f32_ubyte3_e32 v103, v68
	v_pk_fma_f32 v[92:93], v[52:53], v[98:99], v[92:93] op_sel_hi:[0,1,1]
	v_cvt_f32_ubyte0_e32 v104, v69
	v_cvt_f32_ubyte1_e32 v105, v69
	v_pk_fma_f32 v[90:91], v[52:53], v[102:103], v[90:91] op_sel_hi:[0,1,1]
	v_cvt_f32_ubyte2_e32 v146, v69
	v_cvt_f32_ubyte3_e32 v147, v69
	v_pk_fma_f32 v[86:87], v[60:61], v[104:105], v[86:87] op_sel_hi:[0,1,1]
	v_cvt_f32_ubyte0_e32 v98, v76
	v_cvt_f32_ubyte1_e32 v99, v76
	v_pk_fma_f32 v[84:85], v[60:61], v[146:147], v[84:85] op_sel_hi:[0,1,1]
	v_and_b32_e32 v82, s0, v218
	v_and_b32_e32 v83, s1, v218
	v_and_b32_e32 v88, s0, v219
	v_and_b32_e32 v89, s1, v219
	v_cvt_f32_ubyte2_e32 v102, v76
	v_cvt_f32_ubyte3_e32 v103, v76
	v_pk_fma_f32 v[80:81], v[52:53], v[98:99], v[80:81] op_sel_hi:[0,1,1]
	v_cvt_f32_ubyte0_e32 v104, v77
	v_cvt_f32_ubyte1_e32 v105, v77
	v_pk_fma_f32 v[78:79], v[52:53], v[102:103], v[78:79] op_sel_hi:[0,1,1]
	v_cvt_f32_ubyte2_e32 v146, v77
	v_cvt_f32_ubyte3_e32 v147, v77
	v_pk_fma_f32 v[70:71], v[60:61], v[104:105], v[70:71] op_sel_hi:[0,1,1]
	v_cvt_f32_ubyte0_e32 v98, v82
	v_cvt_f32_ubyte1_e32 v99, v82
	v_pk_fma_f32 v[62:63], v[60:61], v[146:147], v[62:63] op_sel_hi:[0,1,1]
	v_cvt_f32_ubyte2_e32 v102, v82
	v_cvt_f32_ubyte3_e32 v103, v82
	v_pk_fma_f32 v[92:93], v[52:53], v[98:99], v[92:93] op_sel:[1,0,0]
	v_cvt_f32_ubyte0_e32 v104, v83
	v_cvt_f32_ubyte1_e32 v105, v83
	v_pk_fma_f32 v[90:91], v[52:53], v[102:103], v[90:91] op_sel:[1,0,0]
	v_cvt_f32_ubyte2_e32 v146, v83
	v_cvt_f32_ubyte3_e32 v147, v83
	v_pk_fma_f32 v[86:87], v[60:61], v[104:105], v[86:87] op_sel:[1,0,0]
	v_cvt_f32_ubyte0_e32 v98, v88
	v_cvt_f32_ubyte1_e32 v99, v88
	v_pk_fma_f32 v[84:85], v[60:61], v[146:147], v[84:85] op_sel:[1,0,0]
	v_and_b32_e32 v68, s0, v220
	v_and_b32_e32 v69, s1, v220
	v_and_b32_e32 v76, s0, v221
	v_and_b32_e32 v77, s1, v221
	v_cvt_f32_ubyte2_e32 v102, v88
	v_cvt_f32_ubyte3_e32 v103, v88
	v_pk_fma_f32 v[80:81], v[52:53], v[98:99], v[80:81] op_sel:[1,0,0]
	v_cvt_f32_ubyte0_e32 v104, v89
	v_cvt_f32_ubyte1_e32 v105, v89
	v_pk_fma_f32 v[78:79], v[52:53], v[102:103], v[78:79] op_sel:[1,0,0]
	v_cvt_f32_ubyte2_e32 v146, v89
	v_cvt_f32_ubyte3_e32 v147, v89
	v_pk_fma_f32 v[70:71], v[60:61], v[104:105], v[70:71] op_sel:[1,0,0]
	v_cvt_f32_ubyte0_e32 v98, v68
	v_cvt_f32_ubyte1_e32 v99, v68
	v_pk_fma_f32 v[62:63], v[60:61], v[146:147], v[62:63] op_sel:[1,0,0]
	v_cvt_f32_ubyte2_e32 v102, v68
	v_cvt_f32_ubyte3_e32 v103, v68
	v_pk_fma_f32 v[92:93], v[54:55], v[98:99], v[92:93] op_sel_hi:[0,1,1]
	v_cvt_f32_ubyte0_e32 v104, v69
	v_cvt_f32_ubyte1_e32 v105, v69
	v_pk_fma_f32 v[90:91], v[54:55], v[102:103], v[90:91] op_sel_hi:[0,1,1]
	v_cvt_f32_ubyte2_e32 v146, v69
	v_cvt_f32_ubyte3_e32 v147, v69
	v_pk_fma_f32 v[86:87], v[64:65], v[104:105], v[86:87] op_sel_hi:[0,1,1]
	v_cvt_f32_ubyte0_e32 v98, v76
	v_cvt_f32_ubyte1_e32 v99, v76
	v_pk_fma_f32 v[84:85], v[64:65], v[146:147], v[84:85] op_sel_hi:[0,1,1]
	v_and_b32_e32 v82, s0, v222
	v_and_b32_e32 v83, s1, v222
	v_and_b32_e32 v88, s0, v223
	v_and_b32_e32 v89, s1, v223
	v_cvt_f32_ubyte2_e32 v102, v76
	v_cvt_f32_ubyte3_e32 v103, v76
	v_pk_fma_f32 v[80:81], v[54:55], v[98:99], v[80:81] op_sel_hi:[0,1,1]
	v_cvt_f32_ubyte0_e32 v104, v77
	v_cvt_f32_ubyte1_e32 v105, v77
	v_pk_fma_f32 v[78:79], v[54:55], v[102:103], v[78:79] op_sel_hi:[0,1,1]
	v_cvt_f32_ubyte2_e32 v146, v77
	v_cvt_f32_ubyte3_e32 v147, v77
	v_pk_fma_f32 v[70:71], v[64:65], v[104:105], v[70:71] op_sel_hi:[0,1,1]
	v_cvt_f32_ubyte0_e32 v98, v82
	v_cvt_f32_ubyte1_e32 v99, v82
	v_pk_fma_f32 v[62:63], v[64:65], v[146:147], v[62:63] op_sel_hi:[0,1,1]
	v_cvt_f32_ubyte2_e32 v102, v82
	v_cvt_f32_ubyte3_e32 v103, v82
	v_pk_fma_f32 v[92:93], v[54:55], v[98:99], v[92:93] op_sel:[1,0,0]
	v_cvt_f32_ubyte0_e32 v104, v83
	v_cvt_f32_ubyte1_e32 v105, v83
	v_pk_fma_f32 v[90:91], v[54:55], v[102:103], v[90:91] op_sel:[1,0,0]
	v_cvt_f32_ubyte2_e32 v146, v83
	v_cvt_f32_ubyte3_e32 v147, v83
	v_pk_fma_f32 v[86:87], v[64:65], v[104:105], v[86:87] op_sel:[1,0,0]
	v_cvt_f32_ubyte0_e32 v98, v88
	v_cvt_f32_ubyte1_e32 v99, v88
	v_pk_fma_f32 v[84:85], v[64:65], v[146:147], v[84:85] op_sel:[1,0,0]
	v_and_b32_e32 v68, s0, v224
	v_and_b32_e32 v69, s1, v224
	v_and_b32_e32 v76, s0, v225
	v_and_b32_e32 v77, s1, v225
	v_cvt_f32_ubyte2_e32 v102, v88
	v_cvt_f32_ubyte3_e32 v103, v88
	v_pk_fma_f32 v[80:81], v[54:55], v[98:99], v[80:81] op_sel:[1,0,0]
	v_cvt_f32_ubyte0_e32 v104, v89
	v_cvt_f32_ubyte1_e32 v105, v89
	v_pk_fma_f32 v[78:79], v[54:55], v[102:103], v[78:79] op_sel:[1,0,0]
	v_cvt_f32_ubyte2_e32 v146, v89
	v_cvt_f32_ubyte3_e32 v147, v89
	v_pk_fma_f32 v[70:71], v[64:65], v[104:105], v[70:71] op_sel:[1,0,0]
	v_cvt_f32_ubyte0_e32 v98, v68
	v_cvt_f32_ubyte1_e32 v99, v68
	v_pk_fma_f32 v[62:63], v[64:65], v[146:147], v[62:63] op_sel:[1,0,0]
	v_cvt_f32_ubyte2_e32 v102, v68
	v_cvt_f32_ubyte3_e32 v103, v68
	v_pk_fma_f32 v[92:93], v[56:57], v[98:99], v[92:93] op_sel_hi:[0,1,1]
	v_cvt_f32_ubyte0_e32 v104, v69
	v_cvt_f32_ubyte1_e32 v105, v69
	v_pk_fma_f32 v[90:91], v[56:57], v[102:103], v[90:91] op_sel_hi:[0,1,1]
	v_cvt_f32_ubyte2_e32 v146, v69
	v_cvt_f32_ubyte3_e32 v147, v69
	v_pk_fma_f32 v[86:87], v[66:67], v[104:105], v[86:87] op_sel_hi:[0,1,1]
	v_cvt_f32_ubyte0_e32 v98, v76
	v_cvt_f32_ubyte1_e32 v99, v76
	v_pk_fma_f32 v[84:85], v[66:67], v[146:147], v[84:85] op_sel_hi:[0,1,1]
	v_and_b32_e32 v82, s0, v226
	v_and_b32_e32 v83, s1, v226
	v_and_b32_e32 v88, s0, v227
	v_and_b32_e32 v89, s1, v227
	v_cvt_f32_ubyte2_e32 v102, v76
	v_cvt_f32_ubyte3_e32 v103, v76
	v_pk_fma_f32 v[80:81], v[56:57], v[98:99], v[80:81] op_sel_hi:[0,1,1]
	v_cvt_f32_ubyte0_e32 v104, v77
	v_cvt_f32_ubyte1_e32 v105, v77
	v_pk_fma_f32 v[78:79], v[56:57], v[102:103], v[78:79] op_sel_hi:[0,1,1]
	v_cvt_f32_ubyte2_e32 v146, v77
	v_cvt_f32_ubyte3_e32 v147, v77
	v_pk_fma_f32 v[70:71], v[66:67], v[104:105], v[70:71] op_sel_hi:[0,1,1]
	v_cvt_f32_ubyte0_e32 v98, v82
	v_cvt_f32_ubyte1_e32 v99, v82
	v_pk_fma_f32 v[62:63], v[66:67], v[146:147], v[62:63] op_sel_hi:[0,1,1]
	v_cvt_f32_ubyte2_e32 v102, v82
	v_cvt_f32_ubyte3_e32 v103, v82
	v_pk_fma_f32 v[92:93], v[56:57], v[98:99], v[92:93] op_sel:[1,0,0]
	v_cvt_f32_ubyte0_e32 v104, v83
	v_cvt_f32_ubyte1_e32 v105, v83
	v_pk_fma_f32 v[90:91], v[56:57], v[102:103], v[90:91] op_sel:[1,0,0]
	v_cvt_f32_ubyte2_e32 v146, v83
	v_cvt_f32_ubyte3_e32 v147, v83
	v_pk_fma_f32 v[86:87], v[66:67], v[104:105], v[86:87] op_sel:[1,0,0]
	v_cvt_f32_ubyte0_e32 v98, v88
	v_cvt_f32_ubyte1_e32 v99, v88
	v_pk_fma_f32 v[84:85], v[66:67], v[146:147], v[84:85] op_sel:[1,0,0]
	v_cvt_f32_ubyte2_e32 v102, v88
	v_cvt_f32_ubyte3_e32 v103, v88
	v_pk_fma_f32 v[80:81], v[56:57], v[98:99], v[80:81] op_sel:[1,0,0]
	v_cvt_f32_ubyte0_e32 v104, v89
	v_cvt_f32_ubyte1_e32 v105, v89
	v_pk_fma_f32 v[78:79], v[56:57], v[102:103], v[78:79] op_sel:[1,0,0]
	v_cvt_f32_ubyte2_e32 v146, v89
	v_cvt_f32_ubyte3_e32 v147, v89
	v_pk_fma_f32 v[70:71], v[66:67], v[104:105], v[70:71] op_sel:[1,0,0]
	v_pk_fma_f32 v[62:63], v[66:67], v[146:147], v[62:63] op_sel:[1,0,0]
	s_waitcnt lgkmcnt(0)
	s_branch .LBB0_608

.LBB0_980:
	s_setprio 1
	v_ashrrev_i32_e32 v105, 31, v104
	v_lshlrev_b64 v[124:125], 10, v[104:105]
	v_mov_b32_e32 v126, v236
	v_mov_b32_e32 v127, v237
	ds_write2st64_b32 v129, v230, v231 offset1:1
	ds_write_b128 v139, v[232:235] offset:1024
	ds_read2_b32 v[0:1], v130 offset1:8
	s_waitcnt lgkmcnt(0)
	v_ashrrev_i32_e32 v3, 31, v0
	v_mov_b32_e32 v2, v0
	v_lshlrev_b64 v[2:3], 9, v[2:3]
	v_lshl_add_u64 v[2:3], v[106:107], 0, v[2:3]
	global_load_dwordx4 v[84:87], v[2:3], off
	global_load_dwordx4 v[88:91], v[2:3], off offset:128
	global_load_dwordx4 v[92:95], v[2:3], off offset:256
	global_load_dwordx4 v[96:99], v[2:3], off offset:384
	v_ashrrev_i32_e32 v3, 31, v1
	v_mov_b32_e32 v2, v1
	v_lshlrev_b64 v[0:1], 9, v[2:3]
	v_lshl_add_u64 v[24:25], v[106:107], 0, v[0:1]
	global_load_dwordx4 v[100:103], v[24:25], off
	global_load_dwordx4 v[76:79], v[24:25], off offset:128
	ds_read2_b32 v[32:33], v130 offset0:16 offset1:24
	ds_read2_b32 v[80:81], v130 offset0:32 offset1:40
	ds_read_b128 v[4:7], v140 offset:1024
	ds_read_b128 v[0:3], v140 offset:1040
	global_load_dwordx4 v[146:149], v[24:25], off offset:256
	s_waitcnt lgkmcnt(3)
	v_ashrrev_i32_e32 v27, 31, v32
	v_mov_b32_e32 v26, v32
	v_lshlrev_b64 v[26:27], 9, v[26:27]
	ds_read_b128 v[12:15], v140 offset:1280
	ds_read_b128 v[8:11], v140 offset:1296
	ds_read_b128 v[20:23], v140 offset:1536
	ds_read_b128 v[16:19], v140 offset:1552
	v_lshl_add_u64 v[34:35], v[106:107], 0, v[26:27]
	global_load_dwordx4 v[72:75], v[24:25], off offset:384
	global_load_dwordx4 v[150:153], v[34:35], off
	v_ashrrev_i32_e32 v37, 31, v33
	v_mov_b32_e32 v36, v33
	s_waitcnt lgkmcnt(6)
	v_ashrrev_i32_e32 v33, 31, v80
	v_mov_b32_e32 v32, v80
	v_lshlrev_b64 v[36:37], 9, v[36:37]
	v_lshlrev_b64 v[32:33], 9, v[32:33]
	v_lshl_add_u64 v[36:37], v[106:107], 0, v[36:37]
	v_lshl_add_u64 v[32:33], v[106:107], 0, v[32:33]
	ds_read_b128 v[28:31], v140 offset:1792
	ds_read_b128 v[24:27], v140 offset:1808
	global_load_dwordx4 v[154:157], v[34:35], off offset:128
	global_load_dwordx4 v[68:71], v[34:35], off offset:256
	global_load_dwordx4 v[64:67], v[34:35], off offset:384
	global_load_dwordx4 v[60:63], v[36:37], off
	global_load_dwordx4 v[52:55], v[36:37], off offset:128
	global_load_dwordx4 v[56:59], v[36:37], off offset:256
	global_load_dwordx4 v[48:51], v[36:37], off offset:384
	global_load_dwordx4 v[44:47], v[32:33], off
	global_load_dwordx4 v[40:43], v[32:33], off offset:128
	s_nop 0
	global_load_dwordx4 v[36:39], v[32:33], off offset:256
	s_nop 0
	global_load_dwordx4 v[32:35], v[32:33], off offset:384
	v_ashrrev_i32_e32 v83, 31, v81
	s_waitcnt vmcnt(19)
	v_lshrrev_b32_e32 v80, 4, v84
	v_lshrrev_b32_e32 v82, 4, v85
	v_and_b32_e32 v158, 0xf0f0f0f, v84
	v_and_b32_e32 v160, 0xf0f0f0f, v85
	v_and_b32_e32 v159, 0xf0f0f0f, v80
	v_and_b32_e32 v161, 0xf0f0f0f, v82
	v_and_b32_e32 v84, 0xf0f0f0f, v86
	s_waitcnt vmcnt(15)
	v_lshrrev_b32_e32 v165, 4, v100
	v_and_b32_e32 v176, 0xf0f0f0f, v101
	v_lshrrev_b32_e32 v101, 4, v101
	v_and_b32_e32 v174, 0xf0f0f0f, v100
	v_and_b32_e32 v175, 0xf0f0f0f, v165
	v_and_b32_e32 v177, 0xf0f0f0f, v101
	v_and_b32_e32 v100, 0xf0f0f0f, v102
	v_lshrrev_b32_e32 v179, 4, v102
	v_and_b32_e32 v102, 0xf0f0f0f, v103
	v_lshrrev_b32_e32 v103, 4, v103
	v_and_b32_e32 v101, 0xf0f0f0f, v179
	v_and_b32_e32 v103, 0xf0f0f0f, v103
	s_waitcnt lgkmcnt(7)
	v_mfma_i32_16x16x64_i8 v[174:177], v[174:177], v[4:7], 0
	v_lshrrev_b32_e32 v85, 4, v86
	v_and_b32_e32 v86, 0xf0f0f0f, v87
	v_lshrrev_b32_e32 v87, 4, v87
	s_waitcnt vmcnt(14)
	v_lshrrev_b32_e32 v181, 4, v76
	v_and_b32_e32 v180, 0xf0f0f0f, v77
	v_lshrrev_b32_e32 v77, 4, v77
	v_and_b32_e32 v85, 0xf0f0f0f, v85
	v_and_b32_e32 v87, 0xf0f0f0f, v87
	v_and_b32_e32 v178, 0xf0f0f0f, v76
	v_mfma_i32_16x16x64_i8 v[158:161], v[158:161], v[4:7], 0
	v_and_b32_e32 v179, 0xf0f0f0f, v181
	v_and_b32_e32 v181, 0xf0f0f0f, v77
	v_and_b32_e32 v76, 0xf0f0f0f, v78
	s_waitcnt lgkmcnt(6)
	v_mfma_i32_16x16x64_i8 v[100:103], v[100:103], v[0:3], v[174:177]
	v_lshrrev_b32_e32 v183, 4, v78
	v_and_b32_e32 v78, 0xf0f0f0f, v79
	v_lshrrev_b32_e32 v79, 4, v79
	s_waitcnt vmcnt(10)
	v_lshrrev_b32_e32 v77, 4, v155
	v_mfma_i32_16x16x64_i8 v[84:87], v[84:87], v[0:3], v[158:161]
	v_and_b32_e32 v79, 0xf0f0f0f, v79
	v_lshrrev_b32_e32 v189, 4, v150
	v_lshrrev_b32_e32 v80, 4, v151
	v_and_b32_e32 v161, 0xf0f0f0f, v77
	v_and_b32_e32 v77, 0xf0f0f0f, v183
	s_waitcnt lgkmcnt(5)
	v_mfma_i32_16x16x64_i8 v[100:103], v[178:181], v[12:15], v[100:103]
	v_and_b32_e32 v188, 0xf0f0f0f, v150
	v_and_b32_e32 v190, 0xf0f0f0f, v151
	v_and_b32_e32 v189, 0xf0f0f0f, v189
	v_and_b32_e32 v191, 0xf0f0f0f, v80
	v_lshrrev_b32_e32 v163, 4, v88
	v_and_b32_e32 v164, 0xf0f0f0f, v89
	v_lshrrev_b32_e32 v89, 4, v89
	v_lshrrev_b32_e32 v185, 4, v146
	v_and_b32_e32 v184, 0xf0f0f0f, v147
	v_lshrrev_b32_e32 v147, 4, v147
	v_and_b32_e32 v162, 0xf0f0f0f, v88
	v_and_b32_e32 v182, 0xf0f0f0f, v146
	v_and_b32_e32 v163, 0xf0f0f0f, v163
	v_and_b32_e32 v165, 0xf0f0f0f, v89
	v_and_b32_e32 v183, 0xf0f0f0f, v185
	v_and_b32_e32 v185, 0xf0f0f0f, v147
	v_lshrrev_b32_e32 v82, 4, v152
	v_lshrrev_b32_e32 v80, 4, v153
	s_waitcnt lgkmcnt(4)
	v_mfma_i32_16x16x64_i8 v[76:79], v[76:79], v[8:11], v[100:103]
	v_and_b32_e32 v150, 0xf0f0f0f, v152
	v_and_b32_e32 v152, 0xf0f0f0f, v153
	v_and_b32_e32 v151, 0xf0f0f0f, v82
	v_and_b32_e32 v153, 0xf0f0f0f, v80
	v_and_b32_e32 v88, 0xf0f0f0f, v90
	v_lshrrev_b32_e32 v167, 4, v90
	v_and_b32_e32 v90, 0xf0f0f0f, v91
	v_lshrrev_b32_e32 v91, 4, v91
	v_and_b32_e32 v146, 0xf0f0f0f, v148
	v_lshrrev_b32_e32 v187, 4, v148
	v_and_b32_e32 v148, 0xf0f0f0f, v149
	v_lshrrev_b32_e32 v149, 4, v149
	v_mfma_i32_16x16x64_i8 v[188:191], v[188:191], v[4:7], 0
	v_and_b32_e32 v89, 0xf0f0f0f, v167
	v_and_b32_e32 v91, 0xf0f0f0f, v91
	v_and_b32_e32 v147, 0xf0f0f0f, v187
	v_and_b32_e32 v149, 0xf0f0f0f, v149
	v_mfma_i32_16x16x64_i8 v[84:87], v[162:165], v[12:15], v[84:87]
	v_lshrrev_b32_e32 v80, 4, v154
	v_lshrrev_b32_e32 v169, 4, v92
	v_and_b32_e32 v168, 0xf0f0f0f, v93
	s_waitcnt lgkmcnt(3)
	v_mfma_i32_16x16x64_i8 v[76:79], v[182:185], v[20:23], v[76:79]
	v_lshrrev_b32_e32 v93, 4, v93
	v_and_b32_e32 v159, 0xf0f0f0f, v80
	v_lshrrev_b32_e32 v80, 4, v72
	v_mfma_i32_16x16x64_i8 v[150:153], v[150:153], v[0:3], v[188:191]
	v_and_b32_e32 v166, 0xf0f0f0f, v92
	v_and_b32_e32 v186, 0xf0f0f0f, v72
	v_and_b32_e32 v167, 0xf0f0f0f, v169
	v_and_b32_e32 v188, 0xf0f0f0f, v73
	v_lshrrev_b32_e32 v73, 4, v73
	v_and_b32_e32 v169, 0xf0f0f0f, v93
	v_and_b32_e32 v187, 0xf0f0f0f, v80
	v_and_b32_e32 v189, 0xf0f0f0f, v73
	v_mfma_i32_16x16x64_i8 v[84:87], v[88:91], v[8:11], v[84:87]
	v_and_b32_e32 v92, 0xf0f0f0f, v94
	v_lshrrev_b32_e32 v171, 4, v94
	v_and_b32_e32 v94, 0xf0f0f0f, v95
	s_waitcnt lgkmcnt(2)
	v_mfma_i32_16x16x64_i8 v[76:79], v[146:149], v[16:19], v[76:79]
	v_lshrrev_b32_e32 v95, 4, v95
	v_and_b32_e32 v158, 0xf0f0f0f, v154
	v_and_b32_e32 v160, 0xf0f0f0f, v155
	v_and_b32_e32 v72, 0xf0f0f0f, v74
	v_lshrrev_b32_e32 v82, 4, v74
	v_and_b32_e32 v74, 0xf0f0f0f, v75
	v_lshrrev_b32_e32 v75, 4, v75
	v_and_b32_e32 v93, 0xf0f0f0f, v171
	v_and_b32_e32 v95, 0xf0f0f0f, v95
	v_and_b32_e32 v73, 0xf0f0f0f, v82
	v_and_b32_e32 v75, 0xf0f0f0f, v75
	v_mfma_i32_16x16x64_i8 v[84:87], v[166:169], v[20:23], v[84:87]
	v_lshrrev_b32_e32 v80, 4, v156
	v_lshrrev_b32_e32 v82, 4, v157
	v_and_b32_e32 v88, 0xf0f0f0f, v156
	s_waitcnt lgkmcnt(1)
	v_mfma_i32_16x16x64_i8 v[76:79], v[186:189], v[28:31], v[76:79]
	v_and_b32_e32 v90, 0xf0f0f0f, v157
	v_and_b32_e32 v89, 0xf0f0f0f, v80
	v_and_b32_e32 v91, 0xf0f0f0f, v82
	v_mfma_i32_16x16x64_i8 v[150:153], v[158:161], v[12:15], v[150:153]
	v_mov_b32_e32 v82, v81
	v_lshrrev_b32_e32 v173, 4, v96
	v_and_b32_e32 v172, 0xf0f0f0f, v97
	v_mfma_i32_16x16x64_i8 v[84:87], v[92:95], v[16:19], v[84:87]
	v_lshrrev_b32_e32 v97, 4, v97
	v_and_b32_e32 v170, 0xf0f0f0f, v96
	v_and_b32_e32 v171, 0xf0f0f0f, v173
	s_waitcnt lgkmcnt(0)
	v_mfma_i32_16x16x64_i8 v[92:95], v[72:75], v[24:27], v[76:79]
	v_lshlrev_b64 v[72:73], 9, v[82:83]
	v_lshl_add_u64 v[80:81], v[106:107], 0, v[72:73]
	v_and_b32_e32 v173, 0xf0f0f0f, v97
	s_waitcnt vmcnt(9)
	v_and_b32_e32 v76, 0xf0f0f0f, v68
	v_lshrrev_b32_e32 v68, 4, v68
	v_and_b32_e32 v77, 0xf0f0f0f, v68
	v_lshrrev_b32_e32 v68, 4, v69
	v_and_b32_e32 v78, 0xf0f0f0f, v69
	v_and_b32_e32 v79, 0xf0f0f0f, v68
	v_mfma_i32_16x16x64_i8 v[72:75], v[88:91], v[8:11], v[150:153]
	v_and_b32_e32 v68, 0xf0f0f0f, v70
	v_lshrrev_b32_e32 v69, 4, v70
	v_and_b32_e32 v70, 0xf0f0f0f, v71
	v_lshrrev_b32_e32 v71, 4, v71
	v_and_b32_e32 v69, 0xf0f0f0f, v69
	v_and_b32_e32 v71, 0xf0f0f0f, v71
	v_mfma_i32_16x16x64_i8 v[72:75], v[76:79], v[20:23], v[72:75]
	v_and_b32_e32 v96, 0xf0f0f0f, v98
	v_lshrrev_b32_e32 v192, 4, v98
	v_and_b32_e32 v98, 0xf0f0f0f, v99
	v_mfma_i32_16x16x64_i8 v[68:71], v[68:71], v[16:19], v[72:75]
	v_lshrrev_b32_e32 v99, 4, v99
	v_and_b32_e32 v97, 0xf0f0f0f, v192
	v_and_b32_e32 v99, 0xf0f0f0f, v99
	s_waitcnt vmcnt(8)
	v_and_b32_e32 v72, 0xf0f0f0f, v64
	v_lshrrev_b32_e32 v64, 4, v64
	v_and_b32_e32 v73, 0xf0f0f0f, v64
	v_lshrrev_b32_e32 v64, 4, v65
	v_and_b32_e32 v74, 0xf0f0f0f, v65
	v_and_b32_e32 v75, 0xf0f0f0f, v64
	v_and_b32_e32 v64, 0xf0f0f0f, v66
	v_lshrrev_b32_e32 v65, 4, v66
	v_and_b32_e32 v66, 0xf0f0f0f, v67
	v_lshrrev_b32_e32 v67, 4, v67
	v_and_b32_e32 v65, 0xf0f0f0f, v65
	v_and_b32_e32 v67, 0xf0f0f0f, v67
	v_mfma_i32_16x16x64_i8 v[84:87], v[170:173], v[28:31], v[84:87]
	s_waitcnt vmcnt(6)
	v_and_b32_e32 v146, 0xf0f0f0f, v54
	v_and_b32_e32 v148, 0xf0f0f0f, v55
	v_cndmask_b32_e32 v92, v93, v92, vcc
	v_mfma_i32_16x16x64_i8 v[72:75], v[72:75], v[28:31], v[68:71]
	v_mfma_i32_16x16x64_i8 v[100:103], v[96:99], v[24:27], v[84:87]
	global_load_dwordx4 v[88:91], v[80:81], off
	s_nop 1
	global_load_dwordx4 v[84:87], v[80:81], off offset:128
	ds_read2_b32 v[150:151], v130 offset0:48 offset1:56
	global_load_dwordx4 v[76:79], v[80:81], off offset:256
	global_load_dwordx4 v[68:71], v[80:81], off offset:384
	v_mfma_i32_16x16x64_i8 v[96:99], v[64:67], v[24:27], v[72:75]
	v_and_b32_e32 v64, 0xf0f0f0f, v60
	v_lshrrev_b32_e32 v60, 4, v60
	v_and_b32_e32 v65, 0xf0f0f0f, v60
	v_lshrrev_b32_e32 v60, 4, v61
	v_and_b32_e32 v66, 0xf0f0f0f, v61
	v_and_b32_e32 v67, 0xf0f0f0f, v60
	v_and_b32_e32 v60, 0xf0f0f0f, v62
	v_lshrrev_b32_e32 v61, 4, v62
	v_and_b32_e32 v62, 0xf0f0f0f, v63
	v_lshrrev_b32_e32 v63, 4, v63
	v_and_b32_e32 v61, 0xf0f0f0f, v61
	v_and_b32_e32 v63, 0xf0f0f0f, v63
	v_mfma_i32_16x16x64_i8 v[64:67], v[64:67], v[4:7], 0
	s_waitcnt lgkmcnt(0)
	v_ashrrev_i32_e32 v81, 31, v150
	v_mov_b32_e32 v80, v150
	v_lshlrev_b64 v[72:73], 9, v[80:81]
	v_mfma_i32_16x16x64_i8 v[60:63], v[60:63], v[0:3], v[64:67]
	v_lshl_add_u64 v[152:153], v[106:107], 0, v[72:73]
	v_cndmask_b32_e32 v100, v101, v100, vcc
	s_nop 0
	v_and_b32_e32 v64, 0xf0f0f0f, v52
	v_lshrrev_b32_e32 v52, 4, v52
	v_and_b32_e32 v65, 0xf0f0f0f, v52
	v_lshrrev_b32_e32 v52, 4, v53
	v_and_b32_e32 v66, 0xf0f0f0f, v53
	v_and_b32_e32 v67, 0xf0f0f0f, v52
	v_lshrrev_b32_e32 v52, 4, v54
	v_and_b32_e32 v147, 0xf0f0f0f, v52
	v_lshrrev_b32_e32 v52, 4, v55
	v_and_b32_e32 v149, 0xf0f0f0f, v52
	v_mfma_i32_16x16x64_i8 v[64:67], v[64:67], v[12:15], v[60:63]
	global_load_dwordx4 v[80:83], v[152:153], off
	global_load_dwordx4 v[72:75], v[152:153], off offset:128
	s_nop 0
	global_load_dwordx4 v[60:63], v[152:153], off offset:256
	global_load_dwordx4 v[52:55], v[152:153], off offset:384
	v_mfma_i32_16x16x64_i8 v[64:67], v[146:149], v[8:11], v[64:67]
	s_waitcnt vmcnt(13)
	v_and_b32_e32 v146, 0xf0f0f0f, v56
	v_lshrrev_b32_e32 v56, 4, v56
	v_and_b32_e32 v147, 0xf0f0f0f, v56
	v_lshrrev_b32_e32 v56, 4, v57
	v_and_b32_e32 v148, 0xf0f0f0f, v57
	v_and_b32_e32 v149, 0xf0f0f0f, v56
	v_and_b32_e32 v56, 0xf0f0f0f, v58
	v_lshrrev_b32_e32 v57, 4, v58
	v_and_b32_e32 v58, 0xf0f0f0f, v59
	v_lshrrev_b32_e32 v59, 4, v59
	v_and_b32_e32 v57, 0xf0f0f0f, v57
	v_and_b32_e32 v59, 0xf0f0f0f, v59
	v_mfma_i32_16x16x64_i8 v[64:67], v[146:149], v[20:23], v[64:67]
	v_ashrrev_i32_e32 v147, 31, v151
	v_mov_b32_e32 v146, v151
	v_lshlrev_b64 v[150:151], 9, v[146:147]
	v_mfma_i32_16x16x64_i8 v[56:59], v[56:59], v[16:19], v[64:67]
	s_waitcnt vmcnt(12)
	v_and_b32_e32 v146, 0xf0f0f0f, v50
	v_and_b32_e32 v148, 0xf0f0f0f, v51
	v_lshl_add_u64 v[150:151], v[106:107], 0, v[150:151]
	v_and_b32_e32 v64, 0xf0f0f0f, v48
	v_lshrrev_b32_e32 v48, 4, v48
	v_and_b32_e32 v65, 0xf0f0f0f, v48
	v_lshrrev_b32_e32 v48, 4, v49
	v_and_b32_e32 v66, 0xf0f0f0f, v49
	v_and_b32_e32 v67, 0xf0f0f0f, v48
	v_lshrrev_b32_e32 v48, 4, v50
	v_and_b32_e32 v147, 0xf0f0f0f, v48
	v_lshrrev_b32_e32 v48, 4, v51
	v_and_b32_e32 v149, 0xf0f0f0f, v48
	v_mfma_i32_16x16x64_i8 v[64:67], v[64:67], v[28:31], v[56:59]
	s_nop 2
	global_load_dwordx4 v[56:59], v[150:151], off
	global_load_dwordx4 v[48:51], v[150:151], off offset:128
	v_mfma_i32_16x16x64_i8 v[152:155], v[146:149], v[24:27], v[64:67]
	s_waitcnt vmcnt(13)
	v_and_b32_e32 v146, 0xf0f0f0f, v46
	v_and_b32_e32 v148, 0xf0f0f0f, v47
	v_and_b32_e32 v64, 0xf0f0f0f, v44
	v_lshrrev_b32_e32 v44, 4, v44
	v_and_b32_e32 v65, 0xf0f0f0f, v44
	v_lshrrev_b32_e32 v44, 4, v45
	v_and_b32_e32 v66, 0xf0f0f0f, v45
	v_and_b32_e32 v67, 0xf0f0f0f, v44
	v_lshrrev_b32_e32 v44, 4, v46
	v_and_b32_e32 v147, 0xf0f0f0f, v44
	v_lshrrev_b32_e32 v44, 4, v47
	v_and_b32_e32 v149, 0xf0f0f0f, v44
	v_mfma_i32_16x16x64_i8 v[156:159], v[64:67], v[4:7], 0
	global_load_dwordx4 v[64:67], v[150:151], off offset:256
	global_load_dwordx4 v[44:47], v[150:151], off offset:384
	v_mfma_i32_16x16x64_i8 v[146:149], v[146:149], v[0:3], v[156:159]
	s_waitcnt vmcnt(14)
	s_nop 3
	v_and_b32_e32 v156, 0xf0f0f0f, v40
	v_lshrrev_b32_e32 v40, 4, v40
	v_and_b32_e32 v157, 0xf0f0f0f, v40
	v_lshrrev_b32_e32 v40, 4, v41
	v_and_b32_e32 v158, 0xf0f0f0f, v41
	v_and_b32_e32 v159, 0xf0f0f0f, v40
	v_and_b32_e32 v40, 0xf0f0f0f, v42
	v_lshrrev_b32_e32 v41, 4, v42
	v_and_b32_e32 v42, 0xf0f0f0f, v43
	v_lshrrev_b32_e32 v43, 4, v43
	v_and_b32_e32 v41, 0xf0f0f0f, v41
	v_and_b32_e32 v43, 0xf0f0f0f, v43
	v_mfma_i32_16x16x64_i8 v[148:151], v[156:159], v[12:15], v[146:149]
	v_add_u32_dpp v156, v100, v100 quad_perm:[1,0,3,2] row_mask:0xf bank_mask:0xf bound_ctrl:1
	s_waitcnt vmcnt(13)
	v_and_b32_e32 v100, 0xf0f0f0f, v36
	v_lshrrev_b32_e32 v36, 4, v36
	v_and_b32_e32 v101, 0xf0f0f0f, v36
	v_lshrrev_b32_e32 v36, 4, v37
	v_cndmask_b32_e32 v146, v103, v102, vcc
	v_and_b32_e32 v102, 0xf0f0f0f, v37
	v_and_b32_e32 v103, 0xf0f0f0f, v36
	v_mfma_i32_16x16x64_i8 v[40:43], v[40:43], v[8:11], v[148:151]
	v_and_b32_e32 v36, 0xf0f0f0f, v38
	v_lshrrev_b32_e32 v37, 4, v38
	v_and_b32_e32 v38, 0xf0f0f0f, v39
	v_lshrrev_b32_e32 v39, 4, v39
	v_and_b32_e32 v37, 0xf0f0f0f, v37
	v_and_b32_e32 v39, 0xf0f0f0f, v39
	v_mfma_i32_16x16x64_i8 v[40:43], v[100:103], v[20:23], v[40:43]
	v_cndmask_b32_e64 v100, 0, v156, s[0:1]
	v_cndmask_b32_e32 v148, v95, v94, vcc
	v_cndmask_b32_e32 v150, v99, v98, vcc
	v_mfma_i32_16x16x64_i8 v[36:39], v[36:39], v[16:19], v[40:43]
	v_mov_b32_dpp v147, v146 quad_perm:[1,0,3,2] row_mask:0xf bank_mask:0xf bound_ctrl:1
	v_mov_b32_dpp v149, v148 quad_perm:[1,0,3,2] row_mask:0xf bank_mask:0xf bound_ctrl:1
	v_mov_b32_dpp v151, v150 quad_perm:[1,0,3,2] row_mask:0xf bank_mask:0xf bound_ctrl:1
	s_waitcnt vmcnt(12)
	v_and_b32_e32 v40, 0xf0f0f0f, v32
	v_lshrrev_b32_e32 v32, 4, v32
	v_and_b32_e32 v41, 0xf0f0f0f, v32
	v_lshrrev_b32_e32 v32, 4, v33
	v_and_b32_e32 v42, 0xf0f0f0f, v33
	v_and_b32_e32 v43, 0xf0f0f0f, v32
	v_and_b32_e32 v32, 0xf0f0f0f, v34
	v_lshrrev_b32_e32 v33, 4, v34
	v_and_b32_e32 v34, 0xf0f0f0f, v35
	v_lshrrev_b32_e32 v35, 4, v35
	v_and_b32_e32 v33, 0xf0f0f0f, v33
	v_and_b32_e32 v35, 0xf0f0f0f, v35
	v_mfma_i32_16x16x64_i8 v[36:39], v[40:43], v[28:31], v[36:39]
	v_add_u32_dpp v40, v92, v92 quad_perm:[1,0,3,2] row_mask:0xf bank_mask:0xf bound_ctrl:1
	s_waitcnt vmcnt(11)
	v_lshrrev_b32_e32 v41, 4, v90
	v_lshrrev_b32_e32 v43, 4, v91
	v_mfma_i32_16x16x64_i8 v[32:35], v[32:35], v[24:27], v[36:39]
	v_cndmask_b32_e64 v92, v100, v40, s[2:3]
	v_and_b32_e32 v40, 0xf0f0f0f, v90
	v_and_b32_e32 v41, 0xf0f0f0f, v41
	v_lshrrev_b32_e32 v37, 4, v88
	v_lshrrev_b32_e32 v39, 4, v89
	v_and_b32_e32 v36, 0xf0f0f0f, v88
	v_and_b32_e32 v37, 0xf0f0f0f, v37
	v_and_b32_e32 v38, 0xf0f0f0f, v89
	v_and_b32_e32 v39, 0xf0f0f0f, v39
	v_and_b32_e32 v42, 0xf0f0f0f, v91
	v_and_b32_e32 v43, 0xf0f0f0f, v43
	v_mfma_i32_16x16x64_i8 v[36:39], v[36:39], v[4:7], 0
	v_cndmask_b32_e32 v88, v97, v96, vcc
	v_cndmask_b32_e32 v89, v153, v152, vcc
	v_cndmask_b32_e32 v152, v155, v154, vcc
	v_mfma_i32_16x16x64_i8 v[36:39], v[40:43], v[0:3], v[36:39]
	s_waitcnt vmcnt(10)
	v_lshrrev_b32_e32 v41, 4, v84
	v_lshrrev_b32_e32 v43, 4, v85
	v_and_b32_e32 v40, 0xf0f0f0f, v84
	v_and_b32_e32 v41, 0xf0f0f0f, v41
	v_and_b32_e32 v42, 0xf0f0f0f, v85
	v_and_b32_e32 v43, 0xf0f0f0f, v43
	v_and_b32_e32 v84, 0xf0f0f0f, v86
	v_lshrrev_b32_e32 v85, 4, v86
	v_and_b32_e32 v86, 0xf0f0f0f, v87
	v_lshrrev_b32_e32 v87, 4, v87
	v_and_b32_e32 v85, 0xf0f0f0f, v85
	v_and_b32_e32 v87, 0xf0f0f0f, v87
	v_mfma_i32_16x16x64_i8 v[36:39], v[40:43], v[12:15], v[36:39]
	v_add_u32_dpp v40, v88, v88 quad_perm:[1,0,3,2] row_mask:0xf bank_mask:0xf bound_ctrl:1
	s_waitcnt vmcnt(9)
	v_lshrrev_b32_e32 v41, 4, v76
	v_lshrrev_b32_e32 v43, 4, v77
	v_cndmask_b32_e64 v88, v92, v40, s[4:5]
	v_and_b32_e32 v40, 0xf0f0f0f, v76
	v_and_b32_e32 v41, 0xf0f0f0f, v41
	v_and_b32_e32 v42, 0xf0f0f0f, v77
	v_and_b32_e32 v43, 0xf0f0f0f, v43
	v_mfma_i32_16x16x64_i8 v[36:39], v[84:87], v[8:11], v[36:39]
	v_and_b32_e32 v76, 0xf0f0f0f, v78
	v_lshrrev_b32_e32 v77, 4, v78
	v_and_b32_e32 v78, 0xf0f0f0f, v79
	v_lshrrev_b32_e32 v79, 4, v79
	v_and_b32_e32 v77, 0xf0f0f0f, v77
	v_and_b32_e32 v79, 0xf0f0f0f, v79
	v_mfma_i32_16x16x64_i8 v[36:39], v[40:43], v[20:23], v[36:39]
	ds_read2_b32 v[84:85], v130 offset0:64 offset1:72
	s_waitcnt vmcnt(8)
	v_lshrrev_b32_e32 v41, 4, v68
	v_lshrrev_b32_e32 v43, 4, v69
	v_and_b32_e32 v40, 0xf0f0f0f, v68
	v_and_b32_e32 v41, 0xf0f0f0f, v41
	v_and_b32_e32 v42, 0xf0f0f0f, v69
	v_and_b32_e32 v43, 0xf0f0f0f, v43
	v_mfma_i32_16x16x64_i8 v[36:39], v[76:79], v[16:19], v[36:39]
	v_and_b32_e32 v68, 0xf0f0f0f, v70
	v_lshrrev_b32_e32 v69, 4, v70
	v_and_b32_e32 v70, 0xf0f0f0f, v71
	v_lshrrev_b32_e32 v71, 4, v71
	s_waitcnt lgkmcnt(0)
	v_ashrrev_i32_e32 v77, 31, v84
	v_mov_b32_e32 v76, v84
	v_and_b32_e32 v69, 0xf0f0f0f, v69
	v_and_b32_e32 v71, 0xf0f0f0f, v71
	v_lshlrev_b64 v[76:77], 9, v[76:77]
	v_mfma_i32_16x16x64_i8 v[36:39], v[40:43], v[28:31], v[36:39]
	v_add_u32_dpp v40, v89, v89 quad_perm:[1,0,3,2] row_mask:0xf bank_mask:0xf bound_ctrl:1
	s_waitcnt vmcnt(7)
	v_lshrrev_b32_e32 v41, 4, v80
	v_lshrrev_b32_e32 v43, 4, v81
	v_lshl_add_u64 v[76:77], v[106:107], 0, v[76:77]
	v_cndmask_b32_e64 v166, v88, v40, s[6:7]
	v_and_b32_e32 v40, 0xf0f0f0f, v80
	v_and_b32_e32 v41, 0xf0f0f0f, v41
	v_and_b32_e32 v42, 0xf0f0f0f, v81
	v_and_b32_e32 v43, 0xf0f0f0f, v43
	global_load_dwordx4 v[92:95], v[76:77], off
	global_load_dwordx4 v[154:157], v[76:77], off offset:128
	global_load_dwordx4 v[100:103], v[76:77], off offset:256
	global_load_dwordx4 v[88:91], v[76:77], off offset:384
	v_mfma_i32_16x16x64_i8 v[36:39], v[68:71], v[24:27], v[36:39]
	v_lshrrev_b32_e32 v69, 4, v82
	v_lshrrev_b32_e32 v71, 4, v83
	v_and_b32_e32 v68, 0xf0f0f0f, v82
	v_and_b32_e32 v69, 0xf0f0f0f, v69
	v_and_b32_e32 v70, 0xf0f0f0f, v83
	v_and_b32_e32 v71, 0xf0f0f0f, v71
	v_mfma_i32_16x16x64_i8 v[40:43], v[40:43], v[4:7], 0
	s_nop 0
	v_cndmask_b32_e32 v36, v37, v36, vcc
	v_mov_b32_dpp v153, v152 quad_perm:[1,0,3,2] row_mask:0xf bank_mask:0xf bound_ctrl:1
	s_waitcnt vmcnt(1)
	v_and_b32_e32 v164, 0xf0f0f0f, v103
	v_mfma_i32_16x16x64_i8 v[40:43], v[68:71], v[0:3], v[40:43]
	v_lshrrev_b32_e32 v69, 4, v72
	v_lshrrev_b32_e32 v71, 4, v73
	v_and_b32_e32 v68, 0xf0f0f0f, v72
	v_and_b32_e32 v69, 0xf0f0f0f, v69
	v_and_b32_e32 v70, 0xf0f0f0f, v73
	v_and_b32_e32 v71, 0xf0f0f0f, v71
	v_and_b32_e32 v72, 0xf0f0f0f, v74
	v_lshrrev_b32_e32 v73, 4, v74
	v_and_b32_e32 v74, 0xf0f0f0f, v75
	v_lshrrev_b32_e32 v75, 4, v75
	v_and_b32_e32 v73, 0xf0f0f0f, v73
	v_and_b32_e32 v75, 0xf0f0f0f, v75
	v_mfma_i32_16x16x64_i8 v[40:43], v[68:71], v[12:15], v[40:43]
	v_and_b32_e32 v68, 0xf0f0f0f, v60
	v_lshrrev_b32_e32 v60, 4, v60
	v_and_b32_e32 v69, 0xf0f0f0f, v60
	v_lshrrev_b32_e32 v60, 4, v61
	v_and_b32_e32 v70, 0xf0f0f0f, v61
	v_and_b32_e32 v71, 0xf0f0f0f, v60
	v_mfma_i32_16x16x64_i8 v[40:43], v[72:75], v[8:11], v[40:43]
	v_and_b32_e32 v60, 0xf0f0f0f, v62
	v_lshrrev_b32_e32 v61, 4, v62
	v_and_b32_e32 v62, 0xf0f0f0f, v63
	v_lshrrev_b32_e32 v63, 4, v63
	v_and_b32_e32 v61, 0xf0f0f0f, v61
	v_and_b32_e32 v63, 0xf0f0f0f, v63
	v_mfma_i32_16x16x64_i8 v[40:43], v[68:71], v[20:23], v[40:43]
	v_ashrrev_i32_e32 v69, 31, v85
	v_mov_b32_e32 v68, v85
	v_lshlrev_b64 v[68:69], 9, v[68:69]
	v_mfma_i32_16x16x64_i8 v[40:43], v[60:63], v[16:19], v[40:43]
	v_and_b32_e32 v60, 0xf0f0f0f, v52
	v_lshrrev_b32_e32 v52, 4, v52
	v_and_b32_e32 v61, 0xf0f0f0f, v52
	v_lshrrev_b32_e32 v52, 4, v53
	v_and_b32_e32 v62, 0xf0f0f0f, v53
	v_and_b32_e32 v63, 0xf0f0f0f, v52
	v_and_b32_e32 v52, 0xf0f0f0f, v54
	v_lshrrev_b32_e32 v53, 4, v54
	v_and_b32_e32 v54, 0xf0f0f0f, v55
	v_lshrrev_b32_e32 v55, 4, v55
	v_and_b32_e32 v53, 0xf0f0f0f, v53
	v_and_b32_e32 v55, 0xf0f0f0f, v55
	v_mfma_i32_16x16x64_i8 v[40:43], v[60:63], v[28:31], v[40:43]
	v_lshl_add_u64 v[60:61], v[106:107], 0, v[68:69]
	global_load_dwordx4 v[96:99], v[60:61], off
	global_load_dwordx4 v[76:79], v[60:61], off offset:128
	global_load_dwordx4 v[84:87], v[60:61], off offset:256
	global_load_dwordx4 v[68:71], v[60:61], off offset:384
	v_mfma_i32_16x16x64_i8 v[72:75], v[52:55], v[24:27], v[40:43]
	v_lshrrev_b32_e32 v53, 4, v58
	v_lshrrev_b32_e32 v55, 4, v59
	v_and_b32_e32 v52, 0xf0f0f0f, v58
	v_lshrrev_b32_e32 v41, 4, v56
	v_lshrrev_b32_e32 v43, 4, v57
	v_and_b32_e32 v40, 0xf0f0f0f, v56
	v_and_b32_e32 v41, 0xf0f0f0f, v41
	v_and_b32_e32 v42, 0xf0f0f0f, v57
	v_and_b32_e32 v43, 0xf0f0f0f, v43
	v_and_b32_e32 v53, 0xf0f0f0f, v53
	v_and_b32_e32 v54, 0xf0f0f0f, v59
	v_and_b32_e32 v55, 0xf0f0f0f, v55
	v_mfma_i32_16x16x64_i8 v[40:43], v[40:43], v[4:7], 0
	ds_read2_b32 v[158:159], v130 offset0:80 offset1:88
	s_waitcnt vmcnt(3)
	v_lshrrev_b32_e32 v37, 4, v96
	v_mfma_i32_16x16x64_i8 v[40:43], v[52:55], v[0:3], v[40:43]
	v_and_b32_e32 v52, 0xf0f0f0f, v48
	v_lshrrev_b32_e32 v48, 4, v48
	v_and_b32_e32 v53, 0xf0f0f0f, v48
	v_lshrrev_b32_e32 v48, 4, v49
	v_and_b32_e32 v54, 0xf0f0f0f, v49
	v_and_b32_e32 v55, 0xf0f0f0f, v48
	v_and_b32_e32 v48, 0xf0f0f0f, v50
	v_lshrrev_b32_e32 v49, 4, v50
	v_and_b32_e32 v50, 0xf0f0f0f, v51
	v_lshrrev_b32_e32 v51, 4, v51
	v_and_b32_e32 v49, 0xf0f0f0f, v49
	v_and_b32_e32 v51, 0xf0f0f0f, v51
	v_mfma_i32_16x16x64_i8 v[40:43], v[52:55], v[12:15], v[40:43]
	s_waitcnt lgkmcnt(0)
	v_ashrrev_i32_e32 v53, 31, v158
	v_mov_b32_e32 v52, v158
	v_lshlrev_b64 v[56:57], 9, v[52:53]
	v_mfma_i32_16x16x64_i8 v[40:43], v[48:51], v[8:11], v[40:43]
	v_lshrrev_b32_e32 v49, 4, v64
	v_lshrrev_b32_e32 v51, 4, v65
	v_and_b32_e32 v48, 0xf0f0f0f, v64
	v_and_b32_e32 v49, 0xf0f0f0f, v49
	v_and_b32_e32 v50, 0xf0f0f0f, v65
	v_and_b32_e32 v51, 0xf0f0f0f, v51
	v_lshrrev_b32_e32 v53, 4, v66
	v_lshrrev_b32_e32 v55, 4, v67
	v_and_b32_e32 v52, 0xf0f0f0f, v66
	v_and_b32_e32 v53, 0xf0f0f0f, v53
	v_and_b32_e32 v54, 0xf0f0f0f, v67
	v_and_b32_e32 v55, 0xf0f0f0f, v55
	v_mfma_i32_16x16x64_i8 v[40:43], v[48:51], v[20:23], v[40:43]
	v_and_b32_e32 v48, 0xf0f0f0f, v44
	v_lshrrev_b32_e32 v44, 4, v44
	v_and_b32_e32 v49, 0xf0f0f0f, v44
	v_lshrrev_b32_e32 v44, 4, v45
	v_and_b32_e32 v50, 0xf0f0f0f, v45
	v_and_b32_e32 v51, 0xf0f0f0f, v44
	v_mfma_i32_16x16x64_i8 v[40:43], v[52:55], v[16:19], v[40:43]
	v_lshrrev_b32_e32 v44, 4, v46
	v_and_b32_e32 v53, 0xf0f0f0f, v44
	v_lshrrev_b32_e32 v44, 4, v47
	v_and_b32_e32 v52, 0xf0f0f0f, v46
	v_and_b32_e32 v54, 0xf0f0f0f, v47
	v_and_b32_e32 v55, 0xf0f0f0f, v44
	v_mfma_i32_16x16x64_i8 v[40:43], v[48:51], v[28:31], v[40:43]
	v_lshl_add_u64 v[64:65], v[106:107], 0, v[56:57]
	global_load_dwordx4 v[80:83], v[64:65], off
	global_load_dwordx4 v[60:63], v[64:65], off offset:128
	global_load_dwordx4 v[56:59], v[64:65], off offset:256
	global_load_dwordx4 v[44:47], v[64:65], off offset:384
	v_mfma_i32_16x16x64_i8 v[48:51], v[52:55], v[24:27], v[40:43]
	v_lshrrev_b32_e32 v53, 4, v94
	v_lshrrev_b32_e32 v55, 4, v95
	v_and_b32_e32 v52, 0xf0f0f0f, v94
	v_lshrrev_b32_e32 v41, 4, v92
	v_lshrrev_b32_e32 v43, 4, v93
	v_and_b32_e32 v40, 0xf0f0f0f, v92
	v_and_b32_e32 v41, 0xf0f0f0f, v41
	v_and_b32_e32 v42, 0xf0f0f0f, v93
	v_and_b32_e32 v43, 0xf0f0f0f, v43
	v_and_b32_e32 v53, 0xf0f0f0f, v53
	v_and_b32_e32 v54, 0xf0f0f0f, v95
	v_and_b32_e32 v55, 0xf0f0f0f, v55
	v_mfma_i32_16x16x64_i8 v[40:43], v[40:43], v[4:7], 0
	v_ashrrev_i32_e32 v65, 31, v159
	v_mov_b32_e32 v64, v159
	v_lshlrev_b64 v[64:65], 9, v[64:65]
	v_mfma_i32_16x16x64_i8 v[40:43], v[52:55], v[0:3], v[40:43]
	v_lshrrev_b32_e32 v53, 4, v154
	v_lshrrev_b32_e32 v55, 4, v155
	v_and_b32_e32 v52, 0xf0f0f0f, v154
	v_and_b32_e32 v53, 0xf0f0f0f, v53
	v_and_b32_e32 v54, 0xf0f0f0f, v155
	v_and_b32_e32 v55, 0xf0f0f0f, v55
	v_lshl_add_u64 v[162:163], v[106:107], 0, v[64:65]
	v_lshrrev_b32_e32 v64, 4, v156
	v_and_b32_e32 v155, 0xf0f0f0f, v64
	v_lshrrev_b32_e32 v64, 4, v157
	v_and_b32_e32 v154, 0xf0f0f0f, v156
	v_and_b32_e32 v156, 0xf0f0f0f, v157
	v_and_b32_e32 v157, 0xf0f0f0f, v64
	v_mfma_i32_16x16x64_i8 v[158:161], v[52:55], v[12:15], v[40:43]
	global_load_dwordx4 v[92:95], v[162:163], off
	global_load_dwordx4 v[64:67], v[162:163], off offset:128
	global_load_dwordx4 v[52:55], v[162:163], off offset:256
	global_load_dwordx4 v[40:43], v[162:163], off offset:384
	v_and_b32_e32 v162, 0xf0f0f0f, v102
	v_mfma_i32_16x16x64_i8 v[154:157], v[154:157], v[8:11], v[158:161]
	s_nop 2
	v_and_b32_e32 v158, 0xf0f0f0f, v100
	v_lshrrev_b32_e32 v100, 4, v100
	v_and_b32_e32 v159, 0xf0f0f0f, v100
	v_lshrrev_b32_e32 v100, 4, v101
	v_and_b32_e32 v160, 0xf0f0f0f, v101
	v_and_b32_e32 v161, 0xf0f0f0f, v100
	v_lshrrev_b32_e32 v100, 4, v102
	v_and_b32_e32 v163, 0xf0f0f0f, v100
	v_lshrrev_b32_e32 v100, 4, v103
	v_and_b32_e32 v165, 0xf0f0f0f, v100
	v_mfma_i32_16x16x64_i8 v[154:157], v[158:161], v[20:23], v[154:157]
	v_cndmask_b32_e32 v102, v33, v32, vcc
	v_cndmask_b32_e32 v100, v35, v34, vcc
	v_mfma_i32_16x16x64_i8 v[32:35], v[162:165], v[16:19], v[154:157]
	v_add_u32_dpp v102, v102, v102 quad_perm:[1,0,3,2] row_mask:0xf bank_mask:0xf bound_ctrl:1
	v_cndmask_b32_e64 v102, v166, v102, s[8:9]
	v_mov_b32_dpp v101, v100 quad_perm:[1,0,3,2] row_mask:0xf bank_mask:0xf bound_ctrl:1
	s_nop 1
	v_and_b32_e32 v154, 0xf0f0f0f, v88
	v_lshrrev_b32_e32 v88, 4, v88
	v_and_b32_e32 v155, 0xf0f0f0f, v88
	v_lshrrev_b32_e32 v88, 4, v89
	v_and_b32_e32 v156, 0xf0f0f0f, v89
	v_and_b32_e32 v157, 0xf0f0f0f, v88
	v_and_b32_e32 v88, 0xf0f0f0f, v90
	v_lshrrev_b32_e32 v89, 4, v90
	v_and_b32_e32 v90, 0xf0f0f0f, v91
	v_lshrrev_b32_e32 v91, 4, v91
	v_and_b32_e32 v89, 0xf0f0f0f, v89
	v_and_b32_e32 v91, 0xf0f0f0f, v91
	v_mfma_i32_16x16x64_i8 v[32:35], v[154:157], v[28:31], v[32:35]
	s_nop 0
	v_mfma_i32_16x16x64_i8 v[32:35], v[88:91], v[24:27], v[32:35]
	v_and_b32_e32 v89, 0xf0f0f0f, v37
	v_lshrrev_b32_e32 v37, 4, v97
	v_and_b32_e32 v88, 0xf0f0f0f, v96
	v_and_b32_e32 v90, 0xf0f0f0f, v97
	v_and_b32_e32 v91, 0xf0f0f0f, v37
	v_lshrrev_b32_e32 v37, 4, v98
	v_and_b32_e32 v97, 0xf0f0f0f, v37
	v_lshrrev_b32_e32 v37, 4, v99
	v_and_b32_e32 v96, 0xf0f0f0f, v98
	v_and_b32_e32 v98, 0xf0f0f0f, v99
	v_and_b32_e32 v99, 0xf0f0f0f, v37
	v_mfma_i32_16x16x64_i8 v[154:157], v[88:91], v[4:7], 0
	v_cndmask_b32_e32 v88, v39, v38, vcc
	v_add_u32_dpp v90, v36, v36 quad_perm:[1,0,3,2] row_mask:0xf bank_mask:0xf bound_ctrl:1
	v_cndmask_b32_e32 v91, v73, v72, vcc
	v_mfma_i32_16x16x64_i8 v[36:39], v[96:99], v[0:3], v[154:157]
	s_waitcnt vmcnt(10)
	v_and_b32_e32 v96, 0xf0f0f0f, v76
	v_lshrrev_b32_e32 v76, 4, v76
	v_and_b32_e32 v97, 0xf0f0f0f, v76
	v_lshrrev_b32_e32 v76, 4, v77
	v_and_b32_e32 v98, 0xf0f0f0f, v77
	v_and_b32_e32 v99, 0xf0f0f0f, v76
	v_and_b32_e32 v76, 0xf0f0f0f, v78
	v_lshrrev_b32_e32 v77, 4, v78
	v_and_b32_e32 v78, 0xf0f0f0f, v79
	v_lshrrev_b32_e32 v79, 4, v79
	v_and_b32_e32 v77, 0xf0f0f0f, v77
	v_and_b32_e32 v79, 0xf0f0f0f, v79
	v_mfma_i32_16x16x64_i8 v[36:39], v[96:99], v[12:15], v[36:39]
	s_waitcnt vmcnt(9)
	v_lshrrev_b32_e32 v73, 4, v84
	v_cndmask_b32_e32 v72, v75, v74, vcc
	v_and_b32_e32 v75, 0xf0f0f0f, v73
	v_lshrrev_b32_e32 v73, 4, v85
	v_mfma_i32_16x16x64_i8 v[36:39], v[76:79], v[8:11], v[36:39]
	v_and_b32_e32 v74, 0xf0f0f0f, v84
	v_and_b32_e32 v76, 0xf0f0f0f, v85
	v_and_b32_e32 v77, 0xf0f0f0f, v73
	v_lshrrev_b32_e32 v73, 4, v86
	v_and_b32_e32 v85, 0xf0f0f0f, v73
	v_lshrrev_b32_e32 v73, 4, v87
	v_and_b32_e32 v84, 0xf0f0f0f, v86
	v_and_b32_e32 v86, 0xf0f0f0f, v87
	v_and_b32_e32 v87, 0xf0f0f0f, v73
	v_cndmask_b32_e64 v90, v102, v90, s[10:11]
	v_mfma_i32_16x16x64_i8 v[36:39], v[74:77], v[20:23], v[36:39]
	v_add_u32_dpp v74, v91, v91 quad_perm:[1,0,3,2] row_mask:0xf bank_mask:0xf bound_ctrl:1
	v_cndmask_b32_e64 v78, v90, v74, s[12:13]
	s_waitcnt vmcnt(8)
	v_and_b32_e32 v74, 0xf0f0f0f, v68
	v_lshrrev_b32_e32 v68, 4, v68
	v_and_b32_e32 v75, 0xf0f0f0f, v68
	v_lshrrev_b32_e32 v68, 4, v69
	v_and_b32_e32 v76, 0xf0f0f0f, v69
	v_and_b32_e32 v77, 0xf0f0f0f, v68
	v_mfma_i32_16x16x64_i8 v[36:39], v[84:87], v[16:19], v[36:39]
	v_lshrrev_b32_e32 v68, 4, v70
	v_and_b32_e32 v85, 0xf0f0f0f, v68
	v_lshrrev_b32_e32 v68, 4, v71
	v_and_b32_e32 v84, 0xf0f0f0f, v70
	v_and_b32_e32 v86, 0xf0f0f0f, v71
	v_and_b32_e32 v87, 0xf0f0f0f, v68
	v_mfma_i32_16x16x64_i8 v[36:39], v[74:77], v[28:31], v[36:39]
	v_cndmask_b32_e32 v70, v49, v48, vcc
	v_cndmask_b32_e32 v68, v51, v50, vcc
	s_waitcnt vmcnt(7)
	v_lshrrev_b32_e32 v71, 4, v82
	v_mfma_i32_16x16x64_i8 v[48:51], v[84:87], v[24:27], v[36:39]
	v_and_b32_e32 v75, 0xf0f0f0f, v71
	v_lshrrev_b32_e32 v71, 4, v83
	v_and_b32_e32 v74, 0xf0f0f0f, v82
	v_lshrrev_b32_e32 v37, 4, v80
	v_lshrrev_b32_e32 v39, 4, v81
	v_and_b32_e32 v36, 0xf0f0f0f, v80
	v_and_b32_e32 v37, 0xf0f0f0f, v37
	v_and_b32_e32 v38, 0xf0f0f0f, v81
	v_and_b32_e32 v39, 0xf0f0f0f, v39
	v_and_b32_e32 v76, 0xf0f0f0f, v83
	v_and_b32_e32 v77, 0xf0f0f0f, v71
	v_mfma_i32_16x16x64_i8 v[36:39], v[36:39], v[4:7], 0
	v_add_u32_dpp v70, v70, v70 quad_perm:[1,0,3,2] row_mask:0xf bank_mask:0xf bound_ctrl:1
	v_cndmask_b32_e64 v98, v78, v70, s[14:15]
	ds_read2_b32 v[70:71], v130 offset0:96 offset1:104
	v_mfma_i32_16x16x64_i8 v[36:39], v[74:77], v[0:3], v[36:39]
	s_waitcnt vmcnt(6)
	v_and_b32_e32 v74, 0xf0f0f0f, v60
	v_lshrrev_b32_e32 v60, 4, v60
	v_and_b32_e32 v75, 0xf0f0f0f, v60
	v_lshrrev_b32_e32 v60, 4, v61
	v_and_b32_e32 v76, 0xf0f0f0f, v61
	v_and_b32_e32 v77, 0xf0f0f0f, v60
	v_and_b32_e32 v60, 0xf0f0f0f, v62
	v_lshrrev_b32_e32 v61, 4, v62
	v_and_b32_e32 v62, 0xf0f0f0f, v63
	v_lshrrev_b32_e32 v63, 4, v63
	v_and_b32_e32 v61, 0xf0f0f0f, v61
	v_and_b32_e32 v63, 0xf0f0f0f, v63
	v_mfma_i32_16x16x64_i8 v[36:39], v[74:77], v[12:15], v[36:39]
	s_waitcnt lgkmcnt(0)
	v_ashrrev_i32_e32 v75, 31, v70
	v_mov_b32_e32 v74, v70
	v_lshlrev_b64 v[74:75], 9, v[74:75]
	v_mfma_i32_16x16x64_i8 v[36:39], v[60:63], v[8:11], v[36:39]
	s_waitcnt vmcnt(5)
	v_and_b32_e32 v60, 0xf0f0f0f, v56
	v_lshrrev_b32_e32 v56, 4, v56
	v_and_b32_e32 v61, 0xf0f0f0f, v56
	v_lshrrev_b32_e32 v56, 4, v57
	v_and_b32_e32 v62, 0xf0f0f0f, v57
	v_and_b32_e32 v63, 0xf0f0f0f, v56
	v_lshl_add_u64 v[82:83], v[106:107], 0, v[74:75]
	v_and_b32_e32 v56, 0xf0f0f0f, v58
	v_mfma_i32_16x16x64_i8 v[36:39], v[60:63], v[20:23], v[36:39]
	global_load_dwordx4 v[60:63], v[82:83], off
	global_load_dwordx4 v[74:77], v[82:83], off offset:128
	global_load_dwordx4 v[78:81], v[82:83], off offset:256
	s_nop 0
	global_load_dwordx4 v[82:85], v[82:83], off offset:384
	v_lshrrev_b32_e32 v57, 4, v58
	v_and_b32_e32 v58, 0xf0f0f0f, v59
	v_lshrrev_b32_e32 v59, 4, v59
	v_and_b32_e32 v57, 0xf0f0f0f, v57
	v_and_b32_e32 v59, 0xf0f0f0f, v59
	v_ashrrev_i32_e32 v87, 31, v71
	v_mov_b32_e32 v86, v71
	v_mfma_i32_16x16x64_i8 v[36:39], v[56:59], v[16:19], v[36:39]
	s_waitcnt vmcnt(8)
	v_and_b32_e32 v56, 0xf0f0f0f, v44
	v_lshrrev_b32_e32 v44, 4, v44
	v_and_b32_e32 v57, 0xf0f0f0f, v44
	v_lshrrev_b32_e32 v44, 4, v45
	v_and_b32_e32 v58, 0xf0f0f0f, v45
	v_and_b32_e32 v59, 0xf0f0f0f, v44
	v_and_b32_e32 v44, 0xf0f0f0f, v46
	v_lshrrev_b32_e32 v45, 4, v46
	v_and_b32_e32 v46, 0xf0f0f0f, v47
	v_lshrrev_b32_e32 v47, 4, v47
	v_and_b32_e32 v45, 0xf0f0f0f, v45
	v_and_b32_e32 v47, 0xf0f0f0f, v47
	v_mfma_i32_16x16x64_i8 v[36:39], v[56:59], v[28:31], v[36:39]
	v_lshlrev_b64 v[70:71], 9, v[86:87]
	v_lshl_add_u64 v[70:71], v[106:107], 0, v[70:71]
	v_mov_b32_dpp v89, v88 quad_perm:[1,0,3,2] row_mask:0xf bank_mask:0xf bound_ctrl:1
	v_mfma_i32_16x16x64_i8 v[56:59], v[44:47], v[24:27], v[36:39]
	s_waitcnt vmcnt(7)
	v_and_b32_e32 v44, 0xf0f0f0f, v94
	v_lshrrev_b32_e32 v45, 4, v94
	v_and_b32_e32 v46, 0xf0f0f0f, v95
	v_and_b32_e32 v36, 0xf0f0f0f, v92
	v_lshrrev_b32_e32 v37, 4, v92
	v_and_b32_e32 v38, 0xf0f0f0f, v93
	v_lshrrev_b32_e32 v39, 4, v93
	v_lshrrev_b32_e32 v47, 4, v95
	global_load_dwordx4 v[90:93], v[70:71], off
	global_load_dwordx4 v[94:97], v[70:71], off offset:128
	v_and_b32_e32 v37, 0xf0f0f0f, v37
	v_and_b32_e32 v39, 0xf0f0f0f, v39
	v_and_b32_e32 v45, 0xf0f0f0f, v45
	v_and_b32_e32 v47, 0xf0f0f0f, v47
	v_mfma_i32_16x16x64_i8 v[36:39], v[36:39], v[4:7], 0
	ds_read2_b32 v[86:87], v130 offset0:112 offset1:120
	global_load_dwordx4 v[154:157], v[70:71], off offset:256
	global_load_dwordx4 v[158:161], v[70:71], off offset:384
	v_mov_b32_dpp v73, v72 quad_perm:[1,0,3,2] row_mask:0xf bank_mask:0xf bound_ctrl:1
	v_mfma_i32_16x16x64_i8 v[36:39], v[44:47], v[0:3], v[36:39]
	s_waitcnt vmcnt(10)
	v_lshrrev_b32_e32 v45, 4, v64
	v_lshrrev_b32_e32 v47, 4, v65
	v_and_b32_e32 v44, 0xf0f0f0f, v64
	v_and_b32_e32 v45, 0xf0f0f0f, v45
	v_and_b32_e32 v46, 0xf0f0f0f, v65
	v_and_b32_e32 v47, 0xf0f0f0f, v47
	v_and_b32_e32 v64, 0xf0f0f0f, v66
	v_lshrrev_b32_e32 v65, 4, v66
	v_and_b32_e32 v66, 0xf0f0f0f, v67
	v_lshrrev_b32_e32 v67, 4, v67
	v_and_b32_e32 v65, 0xf0f0f0f, v65
	v_and_b32_e32 v67, 0xf0f0f0f, v67
	v_mfma_i32_16x16x64_i8 v[36:39], v[44:47], v[12:15], v[36:39]
	s_waitcnt vmcnt(9)
	v_lshrrev_b32_e32 v45, 4, v52
	v_lshrrev_b32_e32 v47, 4, v53
	v_and_b32_e32 v44, 0xf0f0f0f, v52
	v_and_b32_e32 v45, 0xf0f0f0f, v45
	v_and_b32_e32 v46, 0xf0f0f0f, v53
	v_and_b32_e32 v47, 0xf0f0f0f, v47
	v_mfma_i32_16x16x64_i8 v[36:39], v[64:67], v[8:11], v[36:39]
	v_and_b32_e32 v52, 0xf0f0f0f, v54
	v_lshrrev_b32_e32 v53, 4, v54
	v_and_b32_e32 v54, 0xf0f0f0f, v55
	v_lshrrev_b32_e32 v55, 4, v55
	v_and_b32_e32 v53, 0xf0f0f0f, v53
	v_and_b32_e32 v55, 0xf0f0f0f, v55
	v_mfma_i32_16x16x64_i8 v[36:39], v[44:47], v[20:23], v[36:39]
	s_waitcnt vmcnt(8)
	v_and_b32_e32 v44, 0xf0f0f0f, v40
	v_lshrrev_b32_e32 v40, 4, v40
	v_and_b32_e32 v45, 0xf0f0f0f, v40
	v_lshrrev_b32_e32 v40, 4, v41
	v_and_b32_e32 v46, 0xf0f0f0f, v41
	v_and_b32_e32 v47, 0xf0f0f0f, v40
	v_mfma_i32_16x16x64_i8 v[36:39], v[52:55], v[16:19], v[36:39]
	v_and_b32_e32 v40, 0xf0f0f0f, v42
	v_lshrrev_b32_e32 v41, 4, v42
	v_and_b32_e32 v42, 0xf0f0f0f, v43
	v_lshrrev_b32_e32 v43, 4, v43
	v_and_b32_e32 v41, 0xf0f0f0f, v41
	v_and_b32_e32 v43, 0xf0f0f0f, v43
	v_mfma_i32_16x16x64_i8 v[36:39], v[44:47], v[28:31], v[36:39]
	s_waitcnt lgkmcnt(0)
	v_ashrrev_i32_e32 v65, 31, v86
	v_mov_b32_e32 v64, v86
	v_lshlrev_b64 v[44:45], 9, v[64:65]
	v_lshl_add_u64 v[44:45], v[106:107], 0, v[44:45]
	v_mfma_i32_16x16x64_i8 v[162:165], v[40:43], v[24:27], v[36:39]
	s_waitcnt vmcnt(7)
	v_and_b32_e32 v40, 0xf0f0f0f, v62
	v_lshrrev_b32_e32 v41, 4, v62
	v_and_b32_e32 v42, 0xf0f0f0f, v63
	v_and_b32_e32 v36, 0xf0f0f0f, v60
	v_lshrrev_b32_e32 v37, 4, v60
	v_and_b32_e32 v38, 0xf0f0f0f, v61
	v_lshrrev_b32_e32 v39, 4, v61
	v_lshrrev_b32_e32 v43, 4, v63
	global_load_dwordx4 v[166:169], v[44:45], off
	global_load_dwordx4 v[170:173], v[44:45], off offset:128
	global_load_dwordx4 v[174:177], v[44:45], off offset:256
	global_load_dwordx4 v[60:63], v[44:45], off offset:384
	v_and_b32_e32 v37, 0xf0f0f0f, v37
	v_and_b32_e32 v39, 0xf0f0f0f, v39
	v_and_b32_e32 v41, 0xf0f0f0f, v41
	v_and_b32_e32 v43, 0xf0f0f0f, v43
	v_mfma_i32_16x16x64_i8 v[36:39], v[36:39], v[4:7], 0
	s_waitcnt vmcnt(10)
	v_lshrrev_b32_e32 v45, 4, v76
	v_lshrrev_b32_e32 v47, 4, v77
	v_and_b32_e32 v44, 0xf0f0f0f, v76
	v_mfma_i32_16x16x64_i8 v[36:39], v[40:43], v[0:3], v[36:39]
	v_lshrrev_b32_e32 v41, 4, v74
	v_lshrrev_b32_e32 v43, 4, v75
	v_and_b32_e32 v40, 0xf0f0f0f, v74
	v_and_b32_e32 v41, 0xf0f0f0f, v41
	v_and_b32_e32 v42, 0xf0f0f0f, v75
	v_and_b32_e32 v43, 0xf0f0f0f, v43
	v_and_b32_e32 v45, 0xf0f0f0f, v45
	v_and_b32_e32 v46, 0xf0f0f0f, v77
	v_and_b32_e32 v47, 0xf0f0f0f, v47
	v_mfma_i32_16x16x64_i8 v[36:39], v[40:43], v[12:15], v[36:39]
	v_ashrrev_i32_e32 v41, 31, v87
	v_mov_b32_e32 v40, v87
	v_lshlrev_b64 v[52:53], 9, v[40:41]
	s_waitcnt vmcnt(9)
	v_lshrrev_b32_e32 v41, 4, v78
	v_lshrrev_b32_e32 v43, 4, v79
	v_and_b32_e32 v40, 0xf0f0f0f, v78
	v_and_b32_e32 v41, 0xf0f0f0f, v41
	v_and_b32_e32 v42, 0xf0f0f0f, v79
	v_and_b32_e32 v43, 0xf0f0f0f, v43
	v_mfma_i32_16x16x64_i8 v[36:39], v[44:47], v[8:11], v[36:39]
	v_lshrrev_b32_e32 v45, 4, v80
	v_lshrrev_b32_e32 v47, 4, v81
	v_and_b32_e32 v44, 0xf0f0f0f, v80
	v_and_b32_e32 v45, 0xf0f0f0f, v45
	v_and_b32_e32 v46, 0xf0f0f0f, v81
	v_and_b32_e32 v47, 0xf0f0f0f, v47
	v_mfma_i32_16x16x64_i8 v[36:39], v[40:43], v[20:23], v[36:39]
	v_lshl_add_u64 v[70:71], v[106:107], 0, v[52:53]
	global_load_dwordx4 v[52:55], v[70:71], off
	global_load_dwordx4 v[40:43], v[70:71], off offset:128
	s_waitcnt vmcnt(10)
	v_lshrrev_b32_e32 v65, 4, v84
	v_mfma_i32_16x16x64_i8 v[36:39], v[44:47], v[16:19], v[36:39]
	v_lshrrev_b32_e32 v45, 4, v82
	v_lshrrev_b32_e32 v47, 4, v83
	v_and_b32_e32 v44, 0xf0f0f0f, v82
	v_and_b32_e32 v45, 0xf0f0f0f, v45
	v_and_b32_e32 v46, 0xf0f0f0f, v83
	v_and_b32_e32 v47, 0xf0f0f0f, v47
	v_lshrrev_b32_e32 v67, 4, v85
	v_and_b32_e32 v64, 0xf0f0f0f, v84
	v_and_b32_e32 v65, 0xf0f0f0f, v65
	v_and_b32_e32 v66, 0xf0f0f0f, v85
	v_and_b32_e32 v67, 0xf0f0f0f, v67
	v_mfma_i32_16x16x64_i8 v[74:77], v[44:47], v[28:31], v[36:39]
	global_load_dwordx4 v[44:47], v[70:71], off offset:256
	s_nop 1
	global_load_dwordx4 v[36:39], v[70:71], off offset:384
	v_cndmask_b32_e32 v70, v33, v32, vcc
	s_waitcnt vmcnt(11)
	v_lshrrev_b32_e32 v32, 4, v90
	v_mfma_i32_16x16x64_i8 v[74:77], v[64:67], v[24:27], v[74:77]
	v_and_b32_e32 v65, 0xf0f0f0f, v32
	v_lshrrev_b32_e32 v32, 4, v91
	v_and_b32_e32 v64, 0xf0f0f0f, v90
	v_and_b32_e32 v66, 0xf0f0f0f, v91
	v_and_b32_e32 v67, 0xf0f0f0f, v32
	v_lshrrev_b32_e32 v32, 4, v92
	v_and_b32_e32 v79, 0xf0f0f0f, v32
	v_lshrrev_b32_e32 v32, 4, v93
	v_and_b32_e32 v78, 0xf0f0f0f, v92
	v_and_b32_e32 v80, 0xf0f0f0f, v93
	v_and_b32_e32 v81, 0xf0f0f0f, v32
	v_mfma_i32_16x16x64_i8 v[82:85], v[64:67], v[4:7], 0
	s_waitcnt vmcnt(10)
	v_lshrrev_b32_e32 v67, 4, v94
	v_cndmask_b32_e32 v64, v35, v34, vcc
	v_cndmask_b32_e32 v86, v57, v56, vcc
	v_mfma_i32_16x16x64_i8 v[32:35], v[78:81], v[0:3], v[82:85]
	v_and_b32_e32 v79, 0xf0f0f0f, v67
	v_lshrrev_b32_e32 v67, 4, v95
	v_and_b32_e32 v78, 0xf0f0f0f, v94
	v_and_b32_e32 v80, 0xf0f0f0f, v95
	v_and_b32_e32 v81, 0xf0f0f0f, v67
	v_lshrrev_b32_e32 v67, 4, v96
	v_and_b32_e32 v83, 0xf0f0f0f, v67
	v_lshrrev_b32_e32 v67, 4, v97
	v_and_b32_e32 v82, 0xf0f0f0f, v96
	v_and_b32_e32 v84, 0xf0f0f0f, v97
	v_and_b32_e32 v85, 0xf0f0f0f, v67
	v_mfma_i32_16x16x64_i8 v[32:35], v[78:81], v[12:15], v[32:35]
	v_cndmask_b32_e32 v67, v49, v48, vcc
	s_waitcnt vmcnt(9)
	v_lshrrev_b32_e32 v49, 4, v154
	v_and_b32_e32 v79, 0xf0f0f0f, v49
	v_lshrrev_b32_e32 v49, 4, v155
	v_and_b32_e32 v78, 0xf0f0f0f, v154
	v_and_b32_e32 v80, 0xf0f0f0f, v155
	v_and_b32_e32 v81, 0xf0f0f0f, v49
	v_mfma_i32_16x16x64_i8 v[32:35], v[82:85], v[8:11], v[32:35]
	v_lshrrev_b32_e32 v49, 4, v156
	v_and_b32_e32 v83, 0xf0f0f0f, v49
	v_lshrrev_b32_e32 v49, 4, v157
	v_and_b32_e32 v82, 0xf0f0f0f, v156
	v_and_b32_e32 v84, 0xf0f0f0f, v157
	v_and_b32_e32 v85, 0xf0f0f0f, v49
	v_mfma_i32_16x16x64_i8 v[32:35], v[78:81], v[20:23], v[32:35]
	v_cndmask_b32_e32 v48, v51, v50, vcc
	s_waitcnt vmcnt(8)
	v_lshrrev_b32_e32 v51, 4, v158
	v_and_b32_e32 v57, 0xf0f0f0f, v51
	v_lshrrev_b32_e32 v51, 4, v159
	v_cndmask_b32_e32 v50, v59, v58, vcc
	v_and_b32_e32 v56, 0xf0f0f0f, v158
	v_and_b32_e32 v58, 0xf0f0f0f, v159
	v_and_b32_e32 v59, 0xf0f0f0f, v51
	v_mfma_i32_16x16x64_i8 v[32:35], v[82:85], v[16:19], v[32:35]
	v_lshrrev_b32_e32 v51, 4, v160
	v_and_b32_e32 v79, 0xf0f0f0f, v51
	v_lshrrev_b32_e32 v51, 4, v161
	v_and_b32_e32 v78, 0xf0f0f0f, v160
	v_and_b32_e32 v80, 0xf0f0f0f, v161
	v_and_b32_e32 v81, 0xf0f0f0f, v51
	v_mfma_i32_16x16x64_i8 v[32:35], v[56:59], v[28:31], v[32:35]
	s_waitcnt vmcnt(7)
	v_lshrrev_b32_e32 v56, 4, v168
	v_and_b32_e32 v83, 0xf0f0f0f, v56
	v_lshrrev_b32_e32 v56, 4, v169
	v_mfma_i32_16x16x64_i8 v[78:81], v[78:81], v[24:27], v[32:35]
	v_and_b32_e32 v82, 0xf0f0f0f, v168
	v_and_b32_e32 v84, 0xf0f0f0f, v169
	v_and_b32_e32 v85, 0xf0f0f0f, v56
	v_lshrrev_b32_e32 v33, 4, v166
	v_lshrrev_b32_e32 v35, 4, v167
	v_and_b32_e32 v32, 0xf0f0f0f, v166
	v_and_b32_e32 v33, 0xf0f0f0f, v33
	v_and_b32_e32 v34, 0xf0f0f0f, v167
	v_and_b32_e32 v35, 0xf0f0f0f, v35
	v_cndmask_b32_e32 v59, v163, v162, vcc
	s_waitcnt vmcnt(6)
	v_and_b32_e32 v90, 0xf0f0f0f, v172
	v_mfma_i32_16x16x64_i8 v[32:35], v[32:35], v[4:7], 0
	v_add_u32_dpp v87, v59, v59 quad_perm:[1,0,3,2] row_mask:0xf bank_mask:0xf bound_ctrl:1
	v_lshrrev_b32_e32 v59, 4, v170
	v_and_b32_e32 v92, 0xf0f0f0f, v173
	v_mfma_i32_16x16x64_i8 v[32:35], v[82:85], v[0:3], v[32:35]
	v_and_b32_e32 v83, 0xf0f0f0f, v59
	v_lshrrev_b32_e32 v59, 4, v171
	v_and_b32_e32 v82, 0xf0f0f0f, v170
	v_and_b32_e32 v84, 0xf0f0f0f, v171
	v_and_b32_e32 v85, 0xf0f0f0f, v59
	v_lshrrev_b32_e32 v59, 4, v172
	v_and_b32_e32 v91, 0xf0f0f0f, v59
	v_lshrrev_b32_e32 v59, 4, v173
	v_and_b32_e32 v93, 0xf0f0f0f, v59
	v_mov_b32_dpp v71, v67 quad_perm:[1,0,3,2] row_mask:0xf bank_mask:0xf bound_ctrl:1
	v_mfma_i32_16x16x64_i8 v[32:35], v[82:85], v[12:15], v[32:35]
	v_add_u32_e32 v59, v67, v71
	s_waitcnt vmcnt(5)
	v_lshrrev_b32_e32 v67, 4, v174
	v_and_b32_e32 v83, 0xf0f0f0f, v67
	v_lshrrev_b32_e32 v67, 4, v175
	v_and_b32_e32 v82, 0xf0f0f0f, v174
	v_and_b32_e32 v84, 0xf0f0f0f, v175
	v_and_b32_e32 v85, 0xf0f0f0f, v67
	v_mfma_i32_16x16x64_i8 v[32:35], v[90:93], v[8:11], v[32:35]
	v_lshrrev_b32_e32 v67, 4, v176
	v_mov_b32_dpp v66, v70 quad_perm:[1,0,3,2] row_mask:0xf bank_mask:0xf bound_ctrl:1
	v_and_b32_e32 v91, 0xf0f0f0f, v67
	v_lshrrev_b32_e32 v67, 4, v177
	v_add_u32_e32 v66, v70, v66
	v_and_b32_e32 v90, 0xf0f0f0f, v176
	v_and_b32_e32 v92, 0xf0f0f0f, v177
	v_and_b32_e32 v93, 0xf0f0f0f, v67
	v_mov_b32_dpp v58, v86 quad_perm:[1,0,3,2] row_mask:0xf bank_mask:0xf bound_ctrl:1
	v_mfma_i32_16x16x64_i8 v[32:35], v[82:85], v[20:23], v[32:35]
	v_cndmask_b32_e64 v66, v98, v66, s[22:23]
	v_add_u32_e32 v58, v86, v58
	v_cndmask_b32_e64 v59, v66, v59, s[20:21]
	v_cndmask_b32_e64 v66, v59, v58, s[18:19]
	s_waitcnt vmcnt(4)
	v_and_b32_e32 v58, 0xf0f0f0f, v60
	v_lshrrev_b32_e32 v59, 4, v60
	v_and_b32_e32 v60, 0xf0f0f0f, v61
	v_lshrrev_b32_e32 v61, 4, v61
	v_and_b32_e32 v59, 0xf0f0f0f, v59
	v_and_b32_e32 v61, 0xf0f0f0f, v61
	v_mfma_i32_16x16x64_i8 v[32:35], v[90:93], v[16:19], v[32:35]
	v_and_b32_e32 v82, 0xf0f0f0f, v62
	v_lshrrev_b32_e32 v62, 4, v62
	v_and_b32_e32 v83, 0xf0f0f0f, v62
	v_lshrrev_b32_e32 v62, 4, v63
	v_and_b32_e32 v84, 0xf0f0f0f, v63
	v_and_b32_e32 v85, 0xf0f0f0f, v62
	v_mfma_i32_16x16x64_i8 v[32:35], v[58:61], v[28:31], v[32:35]
	v_cndmask_b32_e64 v59, v66, v87, s[16:17]
	ds_read_b64 v[66:67], v131
	v_cndmask_b32_e32 v70, v75, v74, vcc
	v_mfma_i32_16x16x64_i8 v[60:63], v[82:85], v[24:27], v[32:35]
	s_waitcnt vmcnt(3)
	v_and_b32_e32 v74, 0xf0f0f0f, v52
	v_cndmask_b32_e32 v58, v77, v76, vcc
	v_and_b32_e32 v76, 0xf0f0f0f, v53
	v_lshrrev_b32_e32 v32, 4, v52
	v_and_b32_e32 v75, 0xf0f0f0f, v32
	s_waitcnt lgkmcnt(0)
	v_ashrrev_i32_e32 v33, 31, v66
	v_mov_b32_e32 v32, v66
	v_lshl_add_u64 v[34:35], v[32:33], 2, s[38:39]
	global_load_dword v71, v[34:35], off
	v_ashrrev_i32_e32 v35, 31, v67
	v_mov_b32_e32 v34, v67
	v_lshl_add_u64 v[66:67], v[34:35], 2, s[38:39]
	global_load_dword v52, v[66:67], off
	v_lshrrev_b32_e32 v53, 4, v53
	v_and_b32_e32 v77, 0xf0f0f0f, v53
	v_lshrrev_b32_e32 v53, 4, v54
	v_and_b32_e32 v83, 0xf0f0f0f, v53
	v_lshrrev_b32_e32 v53, 4, v55
	v_and_b32_e32 v82, 0xf0f0f0f, v54
	v_and_b32_e32 v84, 0xf0f0f0f, v55
	v_and_b32_e32 v85, 0xf0f0f0f, v53
	v_mfma_i32_16x16x64_i8 v[74:77], v[74:77], v[4:7], 0
	v_add_u32_dpp v5, v70, v70 quad_perm:[1,0,3,2] row_mask:0xf bank_mask:0xf bound_ctrl:1
	v_cndmask_b32_e64 v53, v59, v5, s[24:25]
	s_waitcnt vmcnt(4)
	v_lshrrev_b32_e32 v5, 4, v40
	v_mfma_i32_16x16x64_i8 v[0:3], v[82:85], v[0:3], v[74:77]
	v_cndmask_b32_e32 v56, v165, v164, vcc
	v_mov_b32_dpp v69, v68 quad_perm:[1,0,3,2] row_mask:0xf bank_mask:0xf bound_ctrl:1
	v_mov_b32_dpp v65, v64 quad_perm:[1,0,3,2] row_mask:0xf bank_mask:0xf bound_ctrl:1
	v_and_b32_e32 v75, 0xf0f0f0f, v5
	v_lshrrev_b32_e32 v5, 4, v41
	v_and_b32_e32 v74, 0xf0f0f0f, v40
	v_and_b32_e32 v76, 0xf0f0f0f, v41
	v_and_b32_e32 v77, 0xf0f0f0f, v5
	v_lshrrev_b32_e32 v5, 4, v42
	v_and_b32_e32 v41, 0xf0f0f0f, v5
	v_lshrrev_b32_e32 v5, 4, v43
	v_and_b32_e32 v40, 0xf0f0f0f, v42
	v_and_b32_e32 v42, 0xf0f0f0f, v43
	v_and_b32_e32 v43, 0xf0f0f0f, v5
	v_mfma_i32_16x16x64_i8 v[12:15], v[74:77], v[12:15], v[0:3]
	v_mov_b32_dpp v49, v48 quad_perm:[1,0,3,2] row_mask:0xf bank_mask:0xf bound_ctrl:1
	v_mov_b32_dpp v51, v50 quad_perm:[1,0,3,2] row_mask:0xf bank_mask:0xf bound_ctrl:1
	v_mov_b32_dpp v57, v56 quad_perm:[1,0,3,2] row_mask:0xf bank_mask:0xf bound_ctrl:1
	s_waitcnt vmcnt(3)
	v_lshrrev_b32_e32 v1, 4, v44
	v_mfma_i32_16x16x64_i8 v[6:9], v[40:43], v[8:11], v[12:15]
	v_and_b32_e32 v11, 0xf0f0f0f, v1
	v_lshrrev_b32_e32 v1, 4, v45
	v_and_b32_e32 v10, 0xf0f0f0f, v44
	v_and_b32_e32 v12, 0xf0f0f0f, v45
	v_and_b32_e32 v13, 0xf0f0f0f, v1
	v_lshrrev_b32_e32 v1, 4, v46
	v_and_b32_e32 v41, 0xf0f0f0f, v1
	v_lshrrev_b32_e32 v1, 4, v47
	v_and_b32_e32 v40, 0xf0f0f0f, v46
	v_and_b32_e32 v42, 0xf0f0f0f, v47
	v_and_b32_e32 v43, 0xf0f0f0f, v1
	v_mfma_i32_16x16x64_i8 v[6:9], v[10:13], v[20:23], v[6:9]
	s_waitcnt vmcnt(2)
	v_lshrrev_b32_e32 v2, 4, v36
	v_and_b32_e32 v11, 0xf0f0f0f, v2
	v_lshrrev_b32_e32 v2, 4, v37
	v_and_b32_e32 v10, 0xf0f0f0f, v36
	v_and_b32_e32 v12, 0xf0f0f0f, v37
	v_and_b32_e32 v13, 0xf0f0f0f, v2
	v_mfma_i32_16x16x64_i8 v[6:9], v[40:43], v[16:19], v[6:9]
	v_lshrrev_b32_e32 v2, 4, v38
	v_and_b32_e32 v15, 0xf0f0f0f, v2
	v_lshrrev_b32_e32 v2, 4, v39
	v_and_b32_e32 v14, 0xf0f0f0f, v38
	v_and_b32_e32 v16, 0xf0f0f0f, v39
	v_and_b32_e32 v17, 0xf0f0f0f, v2
	v_mfma_i32_16x16x64_i8 v[8:11], v[10:13], v[28:31], v[6:9]
	v_cndmask_b32_e32 v0, v79, v78, vcc
	v_cndmask_b32_e32 v1, v61, v60, vcc
	v_cndmask_b32_e32 v3, v81, v80, vcc
	v_mfma_i32_16x16x64_i8 v[8:11], v[14:17], v[24:27], v[8:11]
	v_add_u32_dpp v0, v0, v0 quad_perm:[1,0,3,2] row_mask:0xf bank_mask:0xf bound_ctrl:1
	v_cndmask_b32_e64 v0, v53, v0, s[26:27]
	v_add_u32_dpp v1, v1, v1 quad_perm:[1,0,3,2] row_mask:0xf bank_mask:0xf bound_ctrl:1
	v_cndmask_b32_e64 v0, v0, v1, s[28:29]
	v_cndmask_b32_e32 v6, v63, v62, vcc
	s_nop 2
	v_cndmask_b32_e32 v1, v9, v8, vcc
	v_cndmask_b32_e32 v7, v11, v10, vcc
	v_mov_b32_dpp v4, v58 quad_perm:[1,0,3,2] row_mask:0xf bank_mask:0xf bound_ctrl:1
	v_add_u32_dpp v1, v1, v1 quad_perm:[1,0,3,2] row_mask:0xf bank_mask:0xf bound_ctrl:1
	v_cndmask_b32_e64 v0, v0, v1, s[30:31]
	v_cvt_f32_i32_e32 v0, v0
	v_mov_b32_dpp v5, v3 quad_perm:[1,0,3,2] row_mask:0xf bank_mask:0xf bound_ctrl:1
	v_mov_b32_dpp v8, v6 quad_perm:[1,0,3,2] row_mask:0xf bank_mask:0xf bound_ctrl:1
	v_mov_b32_dpp v9, v7 quad_perm:[1,0,3,2] row_mask:0xf bank_mask:0xf bound_ctrl:1
	v_fmac_f32_e32 v0, 0xc0f00000, v127
	s_waitcnt vmcnt(1)
	v_mul_f32_e32 v0, v71, v0
	v_mul_f32_e32 v0, v126, v0
	v_mul_f32_e32 v1, 0x3f3504f3, v0
	v_cmp_nlt_f32_e64 s[34:35], |v1|, 1.0
	s_and_saveexec_b64 s[36:37], s[34:35]
	s_xor_b64 s[36:37], exec, s[36:37]
	s_cbranch_execz .LBB0_982
	v_fma_f32 v2, |v1|, s45, v143
	v_fma_f32 v2, |v1|, v2, s46
	v_fma_f32 v2, |v1|, v2, s47
	v_fma_f32 v2, |v1|, v2, s48
	v_fma_f32 v2, |v1|, v2, s49
	v_fma_f32 v2, |v1|, v2, s50
	v_fma_f32 v2, |v1|, v2, |v1|
	v_mul_f32_e32 v10, 0xbfb8aa3b, v2
	v_fma_f32 v11, v2, s51, -v10
	v_rndne_f32_e32 v12, v10
	v_fmac_f32_e32 v11, 0xb2a5705f, v2
	v_sub_f32_e32 v10, v10, v12
	v_add_f32_e32 v10, v10, v11
	v_cvt_i32_f32_e32 v11, v12
	v_exp_f32_e32 v10, v10
	v_cmp_nlt_f32_e64 s[34:35], s52, v2
	v_ldexp_f32 v10, v10, v11
	s_nop 0
	v_cndmask_b32_e64 v10, 0, v10, s[34:35]
	v_cmp_ngt_f32_e64 s[34:35], s53, v2
	s_nop 1
	v_cndmask_b32_e64 v2, v144, v10, s[34:35]
	v_sub_f32_e32 v2, 1.0, v2

.LBB0_986:
	s_andn2_saveexec_b64 s[34:35], s[36:37]
	v_mul_f32_e32 v5, v4, v4
	v_fmamk_f32 v6, v5, 0xba1345e1, v141
	v_fmaak_f32 v6, v5, v6, 0xbcdac9b8
	v_fmaak_f32 v6, v5, v6, 0x3de703be
	v_fmaak_f32 v6, v5, v6, 0xbec09330
	v_fmaak_f32 v5, v5, v6, 0x3e0375d0
	v_fma_f32 v5, |v4|, v5, |v4|
	s_or_b64 exec, exec, s[34:35]
	v_lshlrev_b64 v[6:7], 7, v[104:105]
	v_lshl_add_u64 v[6:7], v[6:7], 2, v[120:121]
	v_lshl_add_u64 v[8:9], v[32:33], 2, s[40:41]
	v_lshl_add_u64 v[10:11], v[34:35], 2, s[40:41]
	global_load_dwordx2 v[6:7], v[6:7], off
	s_nop 0
	global_load_dword v8, v[8:9], off
	s_nop 0
	global_load_dword v9, v[10:11], off
	v_bfi_b32 v1, s54, v2, v1
	v_mul_f32_e32 v2, 0.5, v3
	v_bfi_b32 v3, s54, v5, v4
	v_mul_f32_e32 v0, 0.5, v0
	v_add_f32_e32 v1, 1.0, v1
	v_add_f32_e32 v3, 1.0, v3
	v_mul_f32_e32 v0, v0, v1
	v_mul_f32_e32 v1, v2, v3
	v_mov_b32_e32 v90, 0
	s_mov_b32 s34, 0
	v_mov_b32_e32 v91, v90
	v_mov_b32_e32 v88, v90
	v_mov_b32_e32 v89, v90
	v_mov_b32_e32 v84, v90
	v_mov_b32_e32 v85, v90
	v_mov_b32_e32 v80, v90
	v_mov_b32_e32 v81, v90
	v_mov_b32_e32 v76, v90
	v_mov_b32_e32 v77, v90
	v_mov_b32_e32 v68, v90
	v_mov_b32_e32 v69, v90
	v_mov_b32_e32 v62, v90
	v_mov_b32_e32 v63, v90
	v_mov_b32_e32 v60, v90
	v_mov_b32_e32 v61, v90
	s_waitcnt vmcnt(2)
	v_pk_mul_f32 v[0:1], v[0:1], v[6:7]
	s_waitcnt vmcnt(0)
	v_pk_mul_f32 v[22:23], v[0:1], v[8:9]
	ds_write_b64 v131, v[22:23] offset:512
	s_setprio 0
	v_lshl_add_u64 v[228:229], v[124:125], 2, v[118:119]
	global_load_dwordx4 v[212:215], v[228:229], off
	global_load_dwordx4 v[216:219], v[228:229], off offset:16
	global_load_dwordx4 v[220:223], v[228:229], off offset:32
	global_load_dwordx4 v[224:227], v[228:229], off offset:48
	v_add_u32_e32 v32, s33, v104
	v_min_u32_e32 v32, 0x7fff, v32
	v_mov_b32_e32 v33, 0
	v_lshlrev_b64 v[34:35], 9, v[32:33]
	v_lshlrev_b64 v[36:37], 10, v[32:33]
	v_lshlrev_b64 v[38:39], 2, v[32:33]
	v_lshl_add_u64 v[34:35], v[114:115], 0, v[34:35]
	v_lshl_add_u64 v[36:37], v[116:117], 0, v[36:37]
	v_lshl_add_u64 v[40:41], s[68:69], 0, v[38:39]
	v_lshl_add_u64 v[38:39], s[70:71], 0, v[38:39]
	global_load_dword v230, v[34:35], off
	global_load_dword v231, v[34:35], off offset:256
	global_load_dwordx4 v[232:235], v[36:37], off
	global_load_dword v236, v[40:41], off
	global_load_dword v237, v[38:39], off
	s_mov_b32 s34, 0x0f0f0f0f
	s_mov_b32 s35, 0xf0f0f0f0
	v_readfirstlane_b32 s36, v108
	v_readfirstlane_b32 s37, v109
	v_mul_f32_e32 v210, 0x3d800000, v22
	v_mul_f32_e32 v211, 0x3d800000, v23
	v_subrev_u32_e32 v98, s36, v108
	ds_write_b64 v131, v[210:211] offset:1536
	ds_read_b128 v[70:73], v128 offset:0
	ds_read_b128 v[92:95], v128 offset:16
	ds_read_b128 v[48:51], v128 offset:32
	ds_read_b128 v[52:55], v128 offset:48
	s_waitcnt lgkmcnt(2)
	v_lshl_add_u32 v70, v70, 9, v98
	v_lshl_add_u32 v71, v71, 9, v98
	v_lshl_add_u32 v72, v72, 9, v98
	v_lshl_add_u32 v73, v73, 9, v98
	v_lshl_add_u32 v92, v92, 9, v98
	v_lshl_add_u32 v93, v93, 9, v98
	v_lshl_add_u32 v94, v94, 9, v98
	v_lshl_add_u32 v95, v95, 9, v98
	global_load_dwordx2 v[146:147], v70, s[36:37]
	global_load_dwordx2 v[148:149], v71, s[36:37]
	global_load_dwordx2 v[150:151], v72, s[36:37]
	global_load_dwordx2 v[152:153], v73, s[36:37]
	global_load_dwordx2 v[154:155], v92, s[36:37]
	global_load_dwordx2 v[156:157], v93, s[36:37]
	global_load_dwordx2 v[158:159], v94, s[36:37]
	global_load_dwordx2 v[160:161], v95, s[36:37]
	ds_read_b128 v[70:73], v128 offset:64
	ds_read_b128 v[92:95], v128 offset:80
	s_waitcnt lgkmcnt(2)
	v_lshl_add_u32 v48, v48, 9, v98
	v_lshl_add_u32 v49, v49, 9, v98
	v_lshl_add_u32 v50, v50, 9, v98
	v_lshl_add_u32 v51, v51, 9, v98
	v_lshl_add_u32 v52, v52, 9, v98
	v_lshl_add_u32 v53, v53, 9, v98
	v_lshl_add_u32 v54, v54, 9, v98
	v_lshl_add_u32 v55, v55, 9, v98
	global_load_dwordx2 v[162:163], v48, s[36:37]
	global_load_dwordx2 v[164:165], v49, s[36:37]
	global_load_dwordx2 v[166:167], v50, s[36:37]
	global_load_dwordx2 v[168:169], v51, s[36:37]
	global_load_dwordx2 v[170:171], v52, s[36:37]
	global_load_dwordx2 v[172:173], v53, s[36:37]
	global_load_dwordx2 v[174:175], v54, s[36:37]
	global_load_dwordx2 v[176:177], v55, s[36:37]
	ds_read_b128 v[48:51], v128 offset:96
	ds_read_b128 v[52:55], v128 offset:112
	s_waitcnt lgkmcnt(2)
	v_lshl_add_u32 v70, v70, 9, v98
	v_lshl_add_u32 v71, v71, 9, v98
	v_lshl_add_u32 v72, v72, 9, v98
	v_lshl_add_u32 v73, v73, 9, v98
	v_lshl_add_u32 v92, v92, 9, v98
	v_lshl_add_u32 v93, v93, 9, v98
	v_lshl_add_u32 v94, v94, 9, v98
	v_lshl_add_u32 v95, v95, 9, v98
	global_load_dwordx2 v[178:179], v70, s[36:37]
	global_load_dwordx2 v[180:181], v71, s[36:37]
	global_load_dwordx2 v[182:183], v72, s[36:37]
	global_load_dwordx2 v[184:185], v73, s[36:37]
	global_load_dwordx2 v[186:187], v92, s[36:37]
	global_load_dwordx2 v[188:189], v93, s[36:37]
	global_load_dwordx2 v[190:191], v94, s[36:37]
	global_load_dwordx2 v[192:193], v95, s[36:37]
	ds_read_b128 v[70:73], v128 offset:128
	ds_read_b128 v[92:95], v128 offset:144
	s_waitcnt lgkmcnt(2)
	v_lshl_add_u32 v48, v48, 9, v98
	v_lshl_add_u32 v49, v49, 9, v98
	v_lshl_add_u32 v50, v50, 9, v98
	v_lshl_add_u32 v51, v51, 9, v98
	v_lshl_add_u32 v52, v52, 9, v98
	v_lshl_add_u32 v53, v53, 9, v98
	v_lshl_add_u32 v54, v54, 9, v98
	v_lshl_add_u32 v55, v55, 9, v98
	global_load_dwordx2 v[194:195], v48, s[36:37]
	global_load_dwordx2 v[196:197], v49, s[36:37]
	global_load_dwordx2 v[198:199], v50, s[36:37]
	global_load_dwordx2 v[200:201], v51, s[36:37]
	global_load_dwordx2 v[202:203], v52, s[36:37]
	global_load_dwordx2 v[204:205], v53, s[36:37]
	global_load_dwordx2 v[206:207], v54, s[36:37]
	global_load_dwordx2 v[208:209], v55, s[36:37]
	s_waitcnt lgkmcnt(0)
	v_lshl_add_u32 v70, v70, 9, v98
	v_lshl_add_u32 v71, v71, 9, v98
	v_lshl_add_u32 v72, v72, 9, v98
	v_lshl_add_u32 v73, v73, 9, v98
	v_lshl_add_u32 v92, v92, 9, v98
	v_lshl_add_u32 v93, v93, 9, v98
	v_lshl_add_u32 v94, v94, 9, v98
	v_lshl_add_u32 v95, v95, 9, v98
	global_load_dwordx2 v[0:1], v70, s[36:37]
	global_load_dwordx2 v[2:3], v71, s[36:37]
	global_load_dwordx2 v[4:5], v72, s[36:37]
	global_load_dwordx2 v[6:7], v73, s[36:37]
	global_load_dwordx2 v[8:9], v92, s[36:37]
	global_load_dwordx2 v[10:11], v93, s[36:37]
	global_load_dwordx2 v[12:13], v94, s[36:37]
	global_load_dwordx2 v[14:15], v95, s[36:37]
	v_add_f32_e32 v210, v22, v23
	ds_bpermute_b32 v211, v132, v210
	s_waitcnt lgkmcnt(0)
	v_add_f32_e32 v210, v210, v211
	ds_bpermute_b32 v211, v133, v210
	s_waitcnt lgkmcnt(0)
	v_add_f32_e32 v210, v210, v211
	ds_bpermute_b32 v211, v134, v210
	s_waitcnt lgkmcnt(0)
	v_add_f32_e32 v210, v210, v211
	ds_bpermute_b32 v211, v135, v210
	s_waitcnt lgkmcnt(0)
	v_add_f32_e32 v210, v210, v211
	ds_bpermute_b32 v211, v136, v210
	s_waitcnt lgkmcnt(0)
	v_add_f32_e32 v99, v210, v211
	ds_bpermute_b32 v105, v137, v99
	ds_read_b128 v[70:73], v128 offset:160
	ds_read_b128 v[92:95], v128 offset:176
	ds_read_b128 v[32:35], v128 offset:512
	ds_read_b128 v[36:39], v128 offset:528
	ds_read_b128 v[40:43], v128 offset:1536
	ds_read_b128 v[44:47], v128 offset:1552
	s_waitcnt lgkmcnt(0)
	v_lshl_add_u32 v70, v70, 9, v98
	v_lshl_add_u32 v71, v71, 9, v98
	v_lshl_add_u32 v72, v72, 9, v98
	v_lshl_add_u32 v73, v73, 9, v98
	v_lshl_add_u32 v92, v92, 9, v98
	v_lshl_add_u32 v93, v93, 9, v98
	v_lshl_add_u32 v94, v94, 9, v98
	v_lshl_add_u32 v95, v95, 9, v98
	global_load_dwordx2 v[16:17], v70, s[36:37]
	global_load_dwordx2 v[18:19], v71, s[36:37]
	global_load_dwordx2 v[20:21], v72, s[36:37]
	global_load_dwordx2 v[22:23], v73, s[36:37]
	global_load_dwordx2 v[24:25], v92, s[36:37]
	global_load_dwordx2 v[26:27], v93, s[36:37]
	global_load_dwordx2 v[28:29], v94, s[36:37]
	global_load_dwordx2 v[30:31], v95, s[36:37]
	ds_read_b128 v[70:73], v128 offset:192
	ds_read_b128 v[92:95], v128 offset:208
	ds_read_b128 v[48:51], v128 offset:544
	ds_read_b128 v[52:55], v128 offset:560
	ds_read_b128 v[56:59], v128 offset:1568
	ds_read_b128 v[64:67], v128 offset:1584
	s_waitcnt vmcnt(40)
	v_and_b32_e32 v74, s34, v146
	v_and_b32_e32 v75, s35, v146
	v_and_b32_e32 v78, s34, v147
	v_and_b32_e32 v79, s35, v147
	v_cvt_f32_ubyte0_e32 v96, v74
	v_cvt_f32_ubyte1_e32 v97, v74
	v_cvt_f32_ubyte2_e32 v100, v74
	v_cvt_f32_ubyte3_e32 v101, v74
	v_pk_fma_f32 v[90:91], v[32:33], v[96:97], v[90:91] op_sel_hi:[0,1,1]
	v_cvt_f32_ubyte0_e32 v102, v75
	v_cvt_f32_ubyte1_e32 v103, v75
	v_pk_fma_f32 v[88:89], v[32:33], v[100:101], v[88:89] op_sel_hi:[0,1,1]
	v_cvt_f32_ubyte2_e32 v126, v75
	v_cvt_f32_ubyte3_e32 v127, v75
	v_pk_fma_f32 v[84:85], v[40:41], v[102:103], v[84:85] op_sel_hi:[0,1,1]
	v_cvt_f32_ubyte0_e32 v96, v78
	v_cvt_f32_ubyte1_e32 v97, v78
	v_pk_fma_f32 v[80:81], v[40:41], v[126:127], v[80:81] op_sel_hi:[0,1,1]
	v_and_b32_e32 v82, s34, v148
	v_and_b32_e32 v83, s35, v148
	v_and_b32_e32 v86, s34, v149
	v_and_b32_e32 v87, s35, v149
	v_cvt_f32_ubyte2_e32 v100, v78
	v_cvt_f32_ubyte3_e32 v101, v78
	v_pk_fma_f32 v[76:77], v[32:33], v[96:97], v[76:77] op_sel_hi:[0,1,1]
	v_cvt_f32_ubyte0_e32 v102, v79
	v_cvt_f32_ubyte1_e32 v103, v79
	v_pk_fma_f32 v[68:69], v[32:33], v[100:101], v[68:69] op_sel_hi:[0,1,1]
	v_cvt_f32_ubyte2_e32 v126, v79
	v_cvt_f32_ubyte3_e32 v127, v79
	v_pk_fma_f32 v[62:63], v[40:41], v[102:103], v[62:63] op_sel_hi:[0,1,1]
	v_cvt_f32_ubyte0_e32 v96, v82
	v_cvt_f32_ubyte1_e32 v97, v82
	v_pk_fma_f32 v[60:61], v[40:41], v[126:127], v[60:61] op_sel_hi:[0,1,1]
	v_cvt_f32_ubyte2_e32 v100, v82
	v_cvt_f32_ubyte3_e32 v101, v82
	v_pk_fma_f32 v[90:91], v[32:33], v[96:97], v[90:91] op_sel:[1,0,0]
	v_cvt_f32_ubyte0_e32 v102, v83
	v_cvt_f32_ubyte1_e32 v103, v83
	v_pk_fma_f32 v[88:89], v[32:33], v[100:101], v[88:89] op_sel:[1,0,0]
	v_cvt_f32_ubyte2_e32 v126, v83
	v_cvt_f32_ubyte3_e32 v127, v83
	v_pk_fma_f32 v[84:85], v[40:41], v[102:103], v[84:85] op_sel:[1,0,0]
	v_cvt_f32_ubyte0_e32 v96, v86
	v_cvt_f32_ubyte1_e32 v97, v86
	v_pk_fma_f32 v[80:81], v[40:41], v[126:127], v[80:81] op_sel:[1,0,0]
	v_and_b32_e32 v74, s34, v150
	v_and_b32_e32 v75, s35, v150
	v_and_b32_e32 v78, s34, v151
	v_and_b32_e32 v79, s35, v151
	v_cvt_f32_ubyte2_e32 v100, v86
	v_cvt_f32_ubyte3_e32 v101, v86
	v_pk_fma_f32 v[76:77], v[32:33], v[96:97], v[76:77] op_sel:[1,0,0]
	v_cvt_f32_ubyte0_e32 v102, v87
	v_cvt_f32_ubyte1_e32 v103, v87
	v_pk_fma_f32 v[68:69], v[32:33], v[100:101], v[68:69] op_sel:[1,0,0]
	v_cvt_f32_ubyte2_e32 v126, v87
	v_cvt_f32_ubyte3_e32 v127, v87
	v_pk_fma_f32 v[62:63], v[40:41], v[102:103], v[62:63] op_sel:[1,0,0]
	v_cvt_f32_ubyte0_e32 v96, v74
	v_cvt_f32_ubyte1_e32 v97, v74
	v_pk_fma_f32 v[60:61], v[40:41], v[126:127], v[60:61] op_sel:[1,0,0]
	v_cvt_f32_ubyte2_e32 v100, v74
	v_cvt_f32_ubyte3_e32 v101, v74
	v_pk_fma_f32 v[90:91], v[34:35], v[96:97], v[90:91] op_sel_hi:[0,1,1]
	v_cvt_f32_ubyte0_e32 v102, v75
	v_cvt_f32_ubyte1_e32 v103, v75
	v_pk_fma_f32 v[88:89], v[34:35], v[100:101], v[88:89] op_sel_hi:[0,1,1]
	v_cvt_f32_ubyte2_e32 v126, v75
	v_cvt_f32_ubyte3_e32 v127, v75
	v_pk_fma_f32 v[84:85], v[42:43], v[102:103], v[84:85] op_sel_hi:[0,1,1]
	v_cvt_f32_ubyte0_e32 v96, v78
	v_cvt_f32_ubyte1_e32 v97, v78
	v_pk_fma_f32 v[80:81], v[42:43], v[126:127], v[80:81] op_sel_hi:[0,1,1]
	v_and_b32_e32 v82, s34, v152
	v_and_b32_e32 v83, s35, v152
	v_and_b32_e32 v86, s34, v153
	v_and_b32_e32 v87, s35, v153
	v_cvt_f32_ubyte2_e32 v100, v78
	v_cvt_f32_ubyte3_e32 v101, v78
	v_pk_fma_f32 v[76:77], v[34:35], v[96:97], v[76:77] op_sel_hi:[0,1,1]
	v_cvt_f32_ubyte0_e32 v102, v79
	v_cvt_f32_ubyte1_e32 v103, v79
	v_pk_fma_f32 v[68:69], v[34:35], v[100:101], v[68:69] op_sel_hi:[0,1,1]
	v_cvt_f32_ubyte2_e32 v126, v79
	v_cvt_f32_ubyte3_e32 v127, v79
	v_pk_fma_f32 v[62:63], v[42:43], v[102:103], v[62:63] op_sel_hi:[0,1,1]
	v_cvt_f32_ubyte0_e32 v96, v82
	v_cvt_f32_ubyte1_e32 v97, v82
	v_pk_fma_f32 v[60:61], v[42:43], v[126:127], v[60:61] op_sel_hi:[0,1,1]
	v_cvt_f32_ubyte2_e32 v100, v82
	v_cvt_f32_ubyte3_e32 v101, v82
	v_pk_fma_f32 v[90:91], v[34:35], v[96:97], v[90:91] op_sel:[1,0,0]
	v_cvt_f32_ubyte0_e32 v102, v83
	v_cvt_f32_ubyte1_e32 v103, v83
	v_pk_fma_f32 v[88:89], v[34:35], v[100:101], v[88:89] op_sel:[1,0,0]
	v_cvt_f32_ubyte2_e32 v126, v83
	v_cvt_f32_ubyte3_e32 v127, v83
	v_pk_fma_f32 v[84:85], v[42:43], v[102:103], v[84:85] op_sel:[1,0,0]
	v_cvt_f32_ubyte0_e32 v96, v86
	v_cvt_f32_ubyte1_e32 v97, v86
	v_pk_fma_f32 v[80:81], v[42:43], v[126:127], v[80:81] op_sel:[1,0,0]
	v_and_b32_e32 v74, s34, v154
	v_and_b32_e32 v75, s35, v154
	v_and_b32_e32 v78, s34, v155
	v_and_b32_e32 v79, s35, v155
	v_cvt_f32_ubyte2_e32 v100, v86
	v_cvt_f32_ubyte3_e32 v101, v86
	v_pk_fma_f32 v[76:77], v[34:35], v[96:97], v[76:77] op_sel:[1,0,0]
	v_cvt_f32_ubyte0_e32 v102, v87
	v_cvt_f32_ubyte1_e32 v103, v87
	v_pk_fma_f32 v[68:69], v[34:35], v[100:101], v[68:69] op_sel:[1,0,0]
	v_cvt_f32_ubyte2_e32 v126, v87
	v_cvt_f32_ubyte3_e32 v127, v87
	v_pk_fma_f32 v[62:63], v[42:43], v[102:103], v[62:63] op_sel:[1,0,0]
	v_cvt_f32_ubyte0_e32 v96, v74
	v_cvt_f32_ubyte1_e32 v97, v74
	v_pk_fma_f32 v[60:61], v[42:43], v[126:127], v[60:61] op_sel:[1,0,0]
	v_cvt_f32_ubyte2_e32 v100, v74
	v_cvt_f32_ubyte3_e32 v101, v74
	v_pk_fma_f32 v[90:91], v[36:37], v[96:97], v[90:91] op_sel_hi:[0,1,1]
	v_cvt_f32_ubyte0_e32 v102, v75
	v_cvt_f32_ubyte1_e32 v103, v75
	v_pk_fma_f32 v[88:89], v[36:37], v[100:101], v[88:89] op_sel_hi:[0,1,1]
	v_cvt_f32_ubyte2_e32 v126, v75
	v_cvt_f32_ubyte3_e32 v127, v75
	v_pk_fma_f32 v[84:85], v[44:45], v[102:103], v[84:85] op_sel_hi:[0,1,1]
	v_cvt_f32_ubyte0_e32 v96, v78
	v_cvt_f32_ubyte1_e32 v97, v78
	v_pk_fma_f32 v[80:81], v[44:45], v[126:127], v[80:81] op_sel_hi:[0,1,1]
	v_and_b32_e32 v82, s34, v156
	v_and_b32_e32 v83, s35, v156
	v_and_b32_e32 v86, s34, v157
	v_and_b32_e32 v87, s35, v157
	v_cvt_f32_ubyte2_e32 v100, v78
	v_cvt_f32_ubyte3_e32 v101, v78
	v_pk_fma_f32 v[76:77], v[36:37], v[96:97], v[76:77] op_sel_hi:[0,1,1]
	v_cvt_f32_ubyte0_e32 v102, v79
	v_cvt_f32_ubyte1_e32 v103, v79
	v_pk_fma_f32 v[68:69], v[36:37], v[100:101], v[68:69] op_sel_hi:[0,1,1]
	v_cvt_f32_ubyte2_e32 v126, v79
	v_cvt_f32_ubyte3_e32 v127, v79
	v_pk_fma_f32 v[62:63], v[44:45], v[102:103], v[62:63] op_sel_hi:[0,1,1]
	v_cvt_f32_ubyte0_e32 v96, v82
	v_cvt_f32_ubyte1_e32 v97, v82
	v_pk_fma_f32 v[60:61], v[44:45], v[126:127], v[60:61] op_sel_hi:[0,1,1]
	v_cvt_f32_ubyte2_e32 v100, v82
	v_cvt_f32_ubyte3_e32 v101, v82
	v_pk_fma_f32 v[90:91], v[36:37], v[96:97], v[90:91] op_sel:[1,0,0]
	v_cvt_f32_ubyte0_e32 v102, v83
	v_cvt_f32_ubyte1_e32 v103, v83
	v_pk_fma_f32 v[88:89], v[36:37], v[100:101], v[88:89] op_sel:[1,0,0]
	v_cvt_f32_ubyte2_e32 v126, v83
	v_cvt_f32_ubyte3_e32 v127, v83
	v_pk_fma_f32 v[84:85], v[44:45], v[102:103], v[84:85] op_sel:[1,0,0]
	v_cvt_f32_ubyte0_e32 v96, v86
	v_cvt_f32_ubyte1_e32 v97, v86
	v_pk_fma_f32 v[80:81], v[44:45], v[126:127], v[80:81] op_sel:[1,0,0]
	v_and_b32_e32 v74, s34, v158
	v_and_b32_e32 v75, s35, v158
	v_and_b32_e32 v78, s34, v159
	v_and_b32_e32 v79, s35, v159
	v_cvt_f32_ubyte2_e32 v100, v86
	v_cvt_f32_ubyte3_e32 v101, v86
	v_pk_fma_f32 v[76:77], v[36:37], v[96:97], v[76:77] op_sel:[1,0,0]
	v_cvt_f32_ubyte0_e32 v102, v87
	v_cvt_f32_ubyte1_e32 v103, v87
	v_pk_fma_f32 v[68:69], v[36:37], v[100:101], v[68:69] op_sel:[1,0,0]
	v_cvt_f32_ubyte2_e32 v126, v87
	v_cvt_f32_ubyte3_e32 v127, v87
	v_pk_fma_f32 v[62:63], v[44:45], v[102:103], v[62:63] op_sel:[1,0,0]
	v_cvt_f32_ubyte0_e32 v96, v74
	v_cvt_f32_ubyte1_e32 v97, v74
	v_pk_fma_f32 v[60:61], v[44:45], v[126:127], v[60:61] op_sel:[1,0,0]
	v_cvt_f32_ubyte2_e32 v100, v74
	v_cvt_f32_ubyte3_e32 v101, v74
	v_pk_fma_f32 v[90:91], v[38:39], v[96:97], v[90:91] op_sel_hi:[0,1,1]
	v_cvt_f32_ubyte0_e32 v102, v75
	v_cvt_f32_ubyte1_e32 v103, v75
	v_pk_fma_f32 v[88:89], v[38:39], v[100:101], v[88:89] op_sel_hi:[0,1,1]
	v_cvt_f32_ubyte2_e32 v126, v75
	v_cvt_f32_ubyte3_e32 v127, v75
	v_pk_fma_f32 v[84:85], v[46:47], v[102:103], v[84:85] op_sel_hi:[0,1,1]
	v_cvt_f32_ubyte0_e32 v96, v78
	v_cvt_f32_ubyte1_e32 v97, v78
	v_pk_fma_f32 v[80:81], v[46:47], v[126:127], v[80:81] op_sel_hi:[0,1,1]
	v_and_b32_e32 v82, s34, v160
	v_and_b32_e32 v83, s35, v160
	v_and_b32_e32 v86, s34, v161
	v_and_b32_e32 v87, s35, v161
	v_cvt_f32_ubyte2_e32 v100, v78
	v_cvt_f32_ubyte3_e32 v101, v78
	v_pk_fma_f32 v[76:77], v[38:39], v[96:97], v[76:77] op_sel_hi:[0,1,1]
	v_cvt_f32_ubyte0_e32 v102, v79
	v_cvt_f32_ubyte1_e32 v103, v79
	v_pk_fma_f32 v[68:69], v[38:39], v[100:101], v[68:69] op_sel_hi:[0,1,1]
	v_cvt_f32_ubyte2_e32 v126, v79
	v_cvt_f32_ubyte3_e32 v127, v79
	v_pk_fma_f32 v[62:63], v[46:47], v[102:103], v[62:63] op_sel_hi:[0,1,1]
	v_cvt_f32_ubyte0_e32 v96, v82
	v_cvt_f32_ubyte1_e32 v97, v82
	v_pk_fma_f32 v[60:61], v[46:47], v[126:127], v[60:61] op_sel_hi:[0,1,1]
	v_cvt_f32_ubyte2_e32 v100, v82
	v_cvt_f32_ubyte3_e32 v101, v82
	v_pk_fma_f32 v[90:91], v[38:39], v[96:97], v[90:91] op_sel:[1,0,0]
	v_cvt_f32_ubyte0_e32 v102, v83
	v_cvt_f32_ubyte1_e32 v103, v83
	v_pk_fma_f32 v[88:89], v[38:39], v[100:101], v[88:89] op_sel:[1,0,0]
	v_cvt_f32_ubyte2_e32 v126, v83
	v_cvt_f32_ubyte3_e32 v127, v83
	v_pk_fma_f32 v[84:85], v[46:47], v[102:103], v[84:85] op_sel:[1,0,0]
	v_cvt_f32_ubyte0_e32 v96, v86
	v_cvt_f32_ubyte1_e32 v97, v86
	v_pk_fma_f32 v[80:81], v[46:47], v[126:127], v[80:81] op_sel:[1,0,0]
	v_cvt_f32_ubyte2_e32 v100, v86
	v_cvt_f32_ubyte3_e32 v101, v86
	v_pk_fma_f32 v[76:77], v[38:39], v[96:97], v[76:77] op_sel:[1,0,0]
	v_cvt_f32_ubyte0_e32 v102, v87
	v_cvt_f32_ubyte1_e32 v103, v87
	v_pk_fma_f32 v[68:69], v[38:39], v[100:101], v[68:69] op_sel:[1,0,0]
	v_cvt_f32_ubyte2_e32 v126, v87
	v_cvt_f32_ubyte3_e32 v127, v87
	v_pk_fma_f32 v[62:63], v[46:47], v[102:103], v[62:63] op_sel:[1,0,0]
	v_pk_fma_f32 v[60:61], v[46:47], v[126:127], v[60:61] op_sel:[1,0,0]
	s_waitcnt lgkmcnt(0)
	v_lshl_add_u32 v70, v70, 9, v98
	v_lshl_add_u32 v71, v71, 9, v98
	v_lshl_add_u32 v72, v72, 9, v98
	v_lshl_add_u32 v73, v73, 9, v98
	v_lshl_add_u32 v92, v92, 9, v98
	v_lshl_add_u32 v93, v93, 9, v98
	v_lshl_add_u32 v94, v94, 9, v98
	v_lshl_add_u32 v95, v95, 9, v98
	global_load_dwordx2 v[146:147], v70, s[36:37]
	global_load_dwordx2 v[148:149], v71, s[36:37]
	global_load_dwordx2 v[150:151], v72, s[36:37]
	global_load_dwordx2 v[152:153], v73, s[36:37]
	global_load_dwordx2 v[154:155], v92, s[36:37]
	global_load_dwordx2 v[156:157], v93, s[36:37]
	global_load_dwordx2 v[158:159], v94, s[36:37]
	global_load_dwordx2 v[160:161], v95, s[36:37]
	ds_read_b128 v[70:73], v128 offset:224
	ds_read_b128 v[92:95], v128 offset:240
	ds_read_b128 v[32:35], v128 offset:576
	ds_read_b128 v[36:39], v128 offset:592
	ds_read_b128 v[40:43], v128 offset:1600
	ds_read_b128 v[44:47], v128 offset:1616
	s_waitcnt vmcnt(40)
	v_and_b32_e32 v74, s34, v162
	v_and_b32_e32 v75, s35, v162
	v_and_b32_e32 v78, s34, v163
	v_and_b32_e32 v79, s35, v163
	v_cvt_f32_ubyte0_e32 v96, v74
	v_cvt_f32_ubyte1_e32 v97, v74
	v_cvt_f32_ubyte2_e32 v100, v74
	v_cvt_f32_ubyte3_e32 v101, v74
	v_pk_fma_f32 v[90:91], v[48:49], v[96:97], v[90:91] op_sel_hi:[0,1,1]
	v_cvt_f32_ubyte0_e32 v102, v75
	v_cvt_f32_ubyte1_e32 v103, v75
	v_pk_fma_f32 v[88:89], v[48:49], v[100:101], v[88:89] op_sel_hi:[0,1,1]
	v_cvt_f32_ubyte2_e32 v126, v75
	v_cvt_f32_ubyte3_e32 v127, v75
	v_pk_fma_f32 v[84:85], v[56:57], v[102:103], v[84:85] op_sel_hi:[0,1,1]
	v_cvt_f32_ubyte0_e32 v96, v78
	v_cvt_f32_ubyte1_e32 v97, v78
	v_pk_fma_f32 v[80:81], v[56:57], v[126:127], v[80:81] op_sel_hi:[0,1,1]
	v_and_b32_e32 v82, s34, v164
	v_and_b32_e32 v83, s35, v164
	v_and_b32_e32 v86, s34, v165
	v_and_b32_e32 v87, s35, v165
	v_cvt_f32_ubyte2_e32 v100, v78
	v_cvt_f32_ubyte3_e32 v101, v78
	v_pk_fma_f32 v[76:77], v[48:49], v[96:97], v[76:77] op_sel_hi:[0,1,1]
	v_cvt_f32_ubyte0_e32 v102, v79
	v_cvt_f32_ubyte1_e32 v103, v79
	v_pk_fma_f32 v[68:69], v[48:49], v[100:101], v[68:69] op_sel_hi:[0,1,1]
	v_cvt_f32_ubyte2_e32 v126, v79
	v_cvt_f32_ubyte3_e32 v127, v79
	v_pk_fma_f32 v[62:63], v[56:57], v[102:103], v[62:63] op_sel_hi:[0,1,1]
	v_cvt_f32_ubyte0_e32 v96, v82
	v_cvt_f32_ubyte1_e32 v97, v82
	v_pk_fma_f32 v[60:61], v[56:57], v[126:127], v[60:61] op_sel_hi:[0,1,1]
	v_cvt_f32_ubyte2_e32 v100, v82
	v_cvt_f32_ubyte3_e32 v101, v82
	v_pk_fma_f32 v[90:91], v[48:49], v[96:97], v[90:91] op_sel:[1,0,0]
	v_cvt_f32_ubyte0_e32 v102, v83
	v_cvt_f32_ubyte1_e32 v103, v83
	v_pk_fma_f32 v[88:89], v[48:49], v[100:101], v[88:89] op_sel:[1,0,0]
	v_cvt_f32_ubyte2_e32 v126, v83
	v_cvt_f32_ubyte3_e32 v127, v83
	v_pk_fma_f32 v[84:85], v[56:57], v[102:103], v[84:85] op_sel:[1,0,0]
	v_cvt_f32_ubyte0_e32 v96, v86
	v_cvt_f32_ubyte1_e32 v97, v86
	v_pk_fma_f32 v[80:81], v[56:57], v[126:127], v[80:81] op_sel:[1,0,0]
	v_and_b32_e32 v74, s34, v166
	v_and_b32_e32 v75, s35, v166
	v_and_b32_e32 v78, s34, v167
	v_and_b32_e32 v79, s35, v167
	v_cvt_f32_ubyte2_e32 v100, v86
	v_cvt_f32_ubyte3_e32 v101, v86
	v_pk_fma_f32 v[76:77], v[48:49], v[96:97], v[76:77] op_sel:[1,0,0]
	v_cvt_f32_ubyte0_e32 v102, v87
	v_cvt_f32_ubyte1_e32 v103, v87
	v_pk_fma_f32 v[68:69], v[48:49], v[100:101], v[68:69] op_sel:[1,0,0]
	v_cvt_f32_ubyte2_e32 v126, v87
	v_cvt_f32_ubyte3_e32 v127, v87
	v_pk_fma_f32 v[62:63], v[56:57], v[102:103], v[62:63] op_sel:[1,0,0]
	v_cvt_f32_ubyte0_e32 v96, v74
	v_cvt_f32_ubyte1_e32 v97, v74
	v_pk_fma_f32 v[60:61], v[56:57], v[126:127], v[60:61] op_sel:[1,0,0]
	v_cvt_f32_ubyte2_e32 v100, v74
	v_cvt_f32_ubyte3_e32 v101, v74
	v_pk_fma_f32 v[90:91], v[50:51], v[96:97], v[90:91] op_sel_hi:[0,1,1]
	v_cvt_f32_ubyte0_e32 v102, v75
	v_cvt_f32_ubyte1_e32 v103, v75
	v_pk_fma_f32 v[88:89], v[50:51], v[100:101], v[88:89] op_sel_hi:[0,1,1]
	v_cvt_f32_ubyte2_e32 v126, v75
	v_cvt_f32_ubyte3_e32 v127, v75
	v_pk_fma_f32 v[84:85], v[58:59], v[102:103], v[84:85] op_sel_hi:[0,1,1]
	v_cvt_f32_ubyte0_e32 v96, v78
	v_cvt_f32_ubyte1_e32 v97, v78
	v_pk_fma_f32 v[80:81], v[58:59], v[126:127], v[80:81] op_sel_hi:[0,1,1]
	v_and_b32_e32 v82, s34, v168
	v_and_b32_e32 v83, s35, v168
	v_and_b32_e32 v86, s34, v169
	v_and_b32_e32 v87, s35, v169
	v_cvt_f32_ubyte2_e32 v100, v78
	v_cvt_f32_ubyte3_e32 v101, v78
	v_pk_fma_f32 v[76:77], v[50:51], v[96:97], v[76:77] op_sel_hi:[0,1,1]
	v_cvt_f32_ubyte0_e32 v102, v79
	v_cvt_f32_ubyte1_e32 v103, v79
	v_pk_fma_f32 v[68:69], v[50:51], v[100:101], v[68:69] op_sel_hi:[0,1,1]
	v_cvt_f32_ubyte2_e32 v126, v79
	v_cvt_f32_ubyte3_e32 v127, v79
	v_pk_fma_f32 v[62:63], v[58:59], v[102:103], v[62:63] op_sel_hi:[0,1,1]
	v_cvt_f32_ubyte0_e32 v96, v82
	v_cvt_f32_ubyte1_e32 v97, v82
	v_pk_fma_f32 v[60:61], v[58:59], v[126:127], v[60:61] op_sel_hi:[0,1,1]
	v_cvt_f32_ubyte2_e32 v100, v82
	v_cvt_f32_ubyte3_e32 v101, v82
	v_pk_fma_f32 v[90:91], v[50:51], v[96:97], v[90:91] op_sel:[1,0,0]
	v_cvt_f32_ubyte0_e32 v102, v83
	v_cvt_f32_ubyte1_e32 v103, v83
	v_pk_fma_f32 v[88:89], v[50:51], v[100:101], v[88:89] op_sel:[1,0,0]
	v_cvt_f32_ubyte2_e32 v126, v83
	v_cvt_f32_ubyte3_e32 v127, v83
	v_pk_fma_f32 v[84:85], v[58:59], v[102:103], v[84:85] op_sel:[1,0,0]
	v_cvt_f32_ubyte0_e32 v96, v86
	v_cvt_f32_ubyte1_e32 v97, v86
	v_pk_fma_f32 v[80:81], v[58:59], v[126:127], v[80:81] op_sel:[1,0,0]
	v_and_b32_e32 v74, s34, v170
	v_and_b32_e32 v75, s35, v170
	v_and_b32_e32 v78, s34, v171
	v_and_b32_e32 v79, s35, v171
	v_cvt_f32_ubyte2_e32 v100, v86
	v_cvt_f32_ubyte3_e32 v101, v86
	v_pk_fma_f32 v[76:77], v[50:51], v[96:97], v[76:77] op_sel:[1,0,0]
	v_cvt_f32_ubyte0_e32 v102, v87
	v_cvt_f32_ubyte1_e32 v103, v87
	v_pk_fma_f32 v[68:69], v[50:51], v[100:101], v[68:69] op_sel:[1,0,0]
	v_cvt_f32_ubyte2_e32 v126, v87
	v_cvt_f32_ubyte3_e32 v127, v87
	v_pk_fma_f32 v[62:63], v[58:59], v[102:103], v[62:63] op_sel:[1,0,0]
	v_cvt_f32_ubyte0_e32 v96, v74
	v_cvt_f32_ubyte1_e32 v97, v74
	v_pk_fma_f32 v[60:61], v[58:59], v[126:127], v[60:61] op_sel:[1,0,0]
	v_cvt_f32_ubyte2_e32 v100, v74
	v_cvt_f32_ubyte3_e32 v101, v74
	v_pk_fma_f32 v[90:91], v[52:53], v[96:97], v[90:91] op_sel_hi:[0,1,1]
	v_cvt_f32_ubyte0_e32 v102, v75
	v_cvt_f32_ubyte1_e32 v103, v75
	v_pk_fma_f32 v[88:89], v[52:53], v[100:101], v[88:89] op_sel_hi:[0,1,1]
	v_cvt_f32_ubyte2_e32 v126, v75
	v_cvt_f32_ubyte3_e32 v127, v75
	v_pk_fma_f32 v[84:85], v[64:65], v[102:103], v[84:85] op_sel_hi:[0,1,1]
	v_cvt_f32_ubyte0_e32 v96, v78
	v_cvt_f32_ubyte1_e32 v97, v78
	v_pk_fma_f32 v[80:81], v[64:65], v[126:127], v[80:81] op_sel_hi:[0,1,1]
	v_and_b32_e32 v82, s34, v172
	v_and_b32_e32 v83, s35, v172
	v_and_b32_e32 v86, s34, v173
	v_and_b32_e32 v87, s35, v173
	v_cvt_f32_ubyte2_e32 v100, v78
	v_cvt_f32_ubyte3_e32 v101, v78
	v_pk_fma_f32 v[76:77], v[52:53], v[96:97], v[76:77] op_sel_hi:[0,1,1]
	v_cvt_f32_ubyte0_e32 v102, v79
	v_cvt_f32_ubyte1_e32 v103, v79
	v_pk_fma_f32 v[68:69], v[52:53], v[100:101], v[68:69] op_sel_hi:[0,1,1]
	v_cvt_f32_ubyte2_e32 v126, v79
	v_cvt_f32_ubyte3_e32 v127, v79
	v_pk_fma_f32 v[62:63], v[64:65], v[102:103], v[62:63] op_sel_hi:[0,1,1]
	v_cvt_f32_ubyte0_e32 v96, v82
	v_cvt_f32_ubyte1_e32 v97, v82
	v_pk_fma_f32 v[60:61], v[64:65], v[126:127], v[60:61] op_sel_hi:[0,1,1]
	v_cvt_f32_ubyte2_e32 v100, v82
	v_cvt_f32_ubyte3_e32 v101, v82
	v_pk_fma_f32 v[90:91], v[52:53], v[96:97], v[90:91] op_sel:[1,0,0]
	v_cvt_f32_ubyte0_e32 v102, v83
	v_cvt_f32_ubyte1_e32 v103, v83
	v_pk_fma_f32 v[88:89], v[52:53], v[100:101], v[88:89] op_sel:[1,0,0]
	v_cvt_f32_ubyte2_e32 v126, v83
	v_cvt_f32_ubyte3_e32 v127, v83
	v_pk_fma_f32 v[84:85], v[64:65], v[102:103], v[84:85] op_sel:[1,0,0]
	v_cvt_f32_ubyte0_e32 v96, v86
	v_cvt_f32_ubyte1_e32 v97, v86
	v_pk_fma_f32 v[80:81], v[64:65], v[126:127], v[80:81] op_sel:[1,0,0]
	v_and_b32_e32 v74, s34, v174
	v_and_b32_e32 v75, s35, v174
	v_and_b32_e32 v78, s34, v175
	v_and_b32_e32 v79, s35, v175
	v_cvt_f32_ubyte2_e32 v100, v86
	v_cvt_f32_ubyte3_e32 v101, v86
	v_pk_fma_f32 v[76:77], v[52:53], v[96:97], v[76:77] op_sel:[1,0,0]
	v_cvt_f32_ubyte0_e32 v102, v87
	v_cvt_f32_ubyte1_e32 v103, v87
	v_pk_fma_f32 v[68:69], v[52:53], v[100:101], v[68:69] op_sel:[1,0,0]
	v_cvt_f32_ubyte2_e32 v126, v87
	v_cvt_f32_ubyte3_e32 v127, v87
	v_pk_fma_f32 v[62:63], v[64:65], v[102:103], v[62:63] op_sel:[1,0,0]
	v_cvt_f32_ubyte0_e32 v96, v74
	v_cvt_f32_ubyte1_e32 v97, v74
	v_pk_fma_f32 v[60:61], v[64:65], v[126:127], v[60:61] op_sel:[1,0,0]
	v_cvt_f32_ubyte2_e32 v100, v74
	v_cvt_f32_ubyte3_e32 v101, v74
	v_pk_fma_f32 v[90:91], v[54:55], v[96:97], v[90:91] op_sel_hi:[0,1,1]
	v_cvt_f32_ubyte0_e32 v102, v75
	v_cvt_f32_ubyte1_e32 v103, v75
	v_pk_fma_f32 v[88:89], v[54:55], v[100:101], v[88:89] op_sel_hi:[0,1,1]
	v_cvt_f32_ubyte2_e32 v126, v75
	v_cvt_f32_ubyte3_e32 v127, v75
	v_pk_fma_f32 v[84:85], v[66:67], v[102:103], v[84:85] op_sel_hi:[0,1,1]
	v_cvt_f32_ubyte0_e32 v96, v78
	v_cvt_f32_ubyte1_e32 v97, v78
	v_pk_fma_f32 v[80:81], v[66:67], v[126:127], v[80:81] op_sel_hi:[0,1,1]
	v_and_b32_e32 v82, s34, v176
	v_and_b32_e32 v83, s35, v176
	v_and_b32_e32 v86, s34, v177
	v_and_b32_e32 v87, s35, v177
	v_cvt_f32_ubyte2_e32 v100, v78
	v_cvt_f32_ubyte3_e32 v101, v78
	v_pk_fma_f32 v[76:77], v[54:55], v[96:97], v[76:77] op_sel_hi:[0,1,1]
	v_cvt_f32_ubyte0_e32 v102, v79
	v_cvt_f32_ubyte1_e32 v103, v79
	v_pk_fma_f32 v[68:69], v[54:55], v[100:101], v[68:69] op_sel_hi:[0,1,1]
	v_cvt_f32_ubyte2_e32 v126, v79
	v_cvt_f32_ubyte3_e32 v127, v79
	v_pk_fma_f32 v[62:63], v[66:67], v[102:103], v[62:63] op_sel_hi:[0,1,1]
	v_cvt_f32_ubyte0_e32 v96, v82
	v_cvt_f32_ubyte1_e32 v97, v82
	v_pk_fma_f32 v[60:61], v[66:67], v[126:127], v[60:61] op_sel_hi:[0,1,1]
	v_cvt_f32_ubyte2_e32 v100, v82
	v_cvt_f32_ubyte3_e32 v101, v82
	v_pk_fma_f32 v[90:91], v[54:55], v[96:97], v[90:91] op_sel:[1,0,0]
	v_cvt_f32_ubyte0_e32 v102, v83
	v_cvt_f32_ubyte1_e32 v103, v83
	v_pk_fma_f32 v[88:89], v[54:55], v[100:101], v[88:89] op_sel:[1,0,0]
	v_cvt_f32_ubyte2_e32 v126, v83
	v_cvt_f32_ubyte3_e32 v127, v83
	v_pk_fma_f32 v[84:85], v[66:67], v[102:103], v[84:85] op_sel:[1,0,0]
	v_cvt_f32_ubyte0_e32 v96, v86
	v_cvt_f32_ubyte1_e32 v97, v86
	v_pk_fma_f32 v[80:81], v[66:67], v[126:127], v[80:81] op_sel:[1,0,0]
	v_cvt_f32_ubyte2_e32 v100, v86
	v_cvt_f32_ubyte3_e32 v101, v86
	v_pk_fma_f32 v[76:77], v[54:55], v[96:97], v[76:77] op_sel:[1,0,0]
	v_cvt_f32_ubyte0_e32 v102, v87
	v_cvt_f32_ubyte1_e32 v103, v87
	v_pk_fma_f32 v[68:69], v[54:55], v[100:101], v[68:69] op_sel:[1,0,0]
	v_cvt_f32_ubyte2_e32 v126, v87
	v_cvt_f32_ubyte3_e32 v127, v87
	v_pk_fma_f32 v[62:63], v[66:67], v[102:103], v[62:63] op_sel:[1,0,0]
	v_pk_fma_f32 v[60:61], v[66:67], v[126:127], v[60:61] op_sel:[1,0,0]
	s_waitcnt lgkmcnt(0)
	v_lshl_add_u32 v70, v70, 9, v98
	v_lshl_add_u32 v71, v71, 9, v98
	v_lshl_add_u32 v72, v72, 9, v98
	v_lshl_add_u32 v73, v73, 9, v98
	v_lshl_add_u32 v92, v92, 9, v98
	v_lshl_add_u32 v93, v93, 9, v98
	v_lshl_add_u32 v94, v94, 9, v98
	v_lshl_add_u32 v95, v95, 9, v98
	global_load_dwordx2 v[162:163], v70, s[36:37]
	global_load_dwordx2 v[164:165], v71, s[36:37]
	global_load_dwordx2 v[166:167], v72, s[36:37]
	global_load_dwordx2 v[168:169], v73, s[36:37]
	global_load_dwordx2 v[170:171], v92, s[36:37]
	global_load_dwordx2 v[172:173], v93, s[36:37]
	global_load_dwordx2 v[174:175], v94, s[36:37]
	global_load_dwordx2 v[176:177], v95, s[36:37]
	ds_read_b128 v[70:73], v128 offset:256
	ds_read_b128 v[92:95], v128 offset:272
	ds_read_b128 v[48:51], v128 offset:608
	ds_read_b128 v[52:55], v128 offset:624
	ds_read_b128 v[56:59], v128 offset:1632
	ds_read_b128 v[64:67], v128 offset:1648
	s_waitcnt vmcnt(40)
	v_and_b32_e32 v74, s34, v178
	v_and_b32_e32 v75, s35, v178
	v_and_b32_e32 v78, s34, v179
	v_and_b32_e32 v79, s35, v179
	v_cvt_f32_ubyte0_e32 v96, v74
	v_cvt_f32_ubyte1_e32 v97, v74
	v_cvt_f32_ubyte2_e32 v100, v74
	v_cvt_f32_ubyte3_e32 v101, v74
	v_pk_fma_f32 v[90:91], v[32:33], v[96:97], v[90:91] op_sel_hi:[0,1,1]
	v_cvt_f32_ubyte0_e32 v102, v75
	v_cvt_f32_ubyte1_e32 v103, v75
	v_pk_fma_f32 v[88:89], v[32:33], v[100:101], v[88:89] op_sel_hi:[0,1,1]
	v_cvt_f32_ubyte2_e32 v126, v75
	v_cvt_f32_ubyte3_e32 v127, v75
	v_pk_fma_f32 v[84:85], v[40:41], v[102:103], v[84:85] op_sel_hi:[0,1,1]
	v_cvt_f32_ubyte0_e32 v96, v78
	v_cvt_f32_ubyte1_e32 v97, v78
	v_pk_fma_f32 v[80:81], v[40:41], v[126:127], v[80:81] op_sel_hi:[0,1,1]
	v_and_b32_e32 v82, s34, v180
	v_and_b32_e32 v83, s35, v180
	v_and_b32_e32 v86, s34, v181
	v_and_b32_e32 v87, s35, v181
	v_cvt_f32_ubyte2_e32 v100, v78
	v_cvt_f32_ubyte3_e32 v101, v78
	v_pk_fma_f32 v[76:77], v[32:33], v[96:97], v[76:77] op_sel_hi:[0,1,1]
	v_cvt_f32_ubyte0_e32 v102, v79
	v_cvt_f32_ubyte1_e32 v103, v79
	v_pk_fma_f32 v[68:69], v[32:33], v[100:101], v[68:69] op_sel_hi:[0,1,1]
	v_cvt_f32_ubyte2_e32 v126, v79
	v_cvt_f32_ubyte3_e32 v127, v79
	v_pk_fma_f32 v[62:63], v[40:41], v[102:103], v[62:63] op_sel_hi:[0,1,1]
	v_cvt_f32_ubyte0_e32 v96, v82
	v_cvt_f32_ubyte1_e32 v97, v82
	v_pk_fma_f32 v[60:61], v[40:41], v[126:127], v[60:61] op_sel_hi:[0,1,1]
	v_cvt_f32_ubyte2_e32 v100, v82
	v_cvt_f32_ubyte3_e32 v101, v82
	v_pk_fma_f32 v[90:91], v[32:33], v[96:97], v[90:91] op_sel:[1,0,0]
	v_cvt_f32_ubyte0_e32 v102, v83
	v_cvt_f32_ubyte1_e32 v103, v83
	v_pk_fma_f32 v[88:89], v[32:33], v[100:101], v[88:89] op_sel:[1,0,0]
	v_cvt_f32_ubyte2_e32 v126, v83
	v_cvt_f32_ubyte3_e32 v127, v83
	v_pk_fma_f32 v[84:85], v[40:41], v[102:103], v[84:85] op_sel:[1,0,0]
	v_cvt_f32_ubyte0_e32 v96, v86
	v_cvt_f32_ubyte1_e32 v97, v86
	v_pk_fma_f32 v[80:81], v[40:41], v[126:127], v[80:81] op_sel:[1,0,0]
	v_and_b32_e32 v74, s34, v182
	v_and_b32_e32 v75, s35, v182
	v_and_b32_e32 v78, s34, v183
	v_and_b32_e32 v79, s35, v183
	v_cvt_f32_ubyte2_e32 v100, v86
	v_cvt_f32_ubyte3_e32 v101, v86
	v_pk_fma_f32 v[76:77], v[32:33], v[96:97], v[76:77] op_sel:[1,0,0]
	v_cvt_f32_ubyte0_e32 v102, v87
	v_cvt_f32_ubyte1_e32 v103, v87
	v_pk_fma_f32 v[68:69], v[32:33], v[100:101], v[68:69] op_sel:[1,0,0]
	v_cvt_f32_ubyte2_e32 v126, v87
	v_cvt_f32_ubyte3_e32 v127, v87
	v_pk_fma_f32 v[62:63], v[40:41], v[102:103], v[62:63] op_sel:[1,0,0]
	v_cvt_f32_ubyte0_e32 v96, v74
	v_cvt_f32_ubyte1_e32 v97, v74
	v_pk_fma_f32 v[60:61], v[40:41], v[126:127], v[60:61] op_sel:[1,0,0]
	v_cvt_f32_ubyte2_e32 v100, v74
	v_cvt_f32_ubyte3_e32 v101, v74
	v_pk_fma_f32 v[90:91], v[34:35], v[96:97], v[90:91] op_sel_hi:[0,1,1]
	v_cvt_f32_ubyte0_e32 v102, v75
	v_cvt_f32_ubyte1_e32 v103, v75
	v_pk_fma_f32 v[88:89], v[34:35], v[100:101], v[88:89] op_sel_hi:[0,1,1]
	v_cvt_f32_ubyte2_e32 v126, v75
	v_cvt_f32_ubyte3_e32 v127, v75
	v_pk_fma_f32 v[84:85], v[42:43], v[102:103], v[84:85] op_sel_hi:[0,1,1]
	v_cvt_f32_ubyte0_e32 v96, v78
	v_cvt_f32_ubyte1_e32 v97, v78
	v_pk_fma_f32 v[80:81], v[42:43], v[126:127], v[80:81] op_sel_hi:[0,1,1]
	v_and_b32_e32 v82, s34, v184
	v_and_b32_e32 v83, s35, v184
	v_and_b32_e32 v86, s34, v185
	v_and_b32_e32 v87, s35, v185
	v_cvt_f32_ubyte2_e32 v100, v78
	v_cvt_f32_ubyte3_e32 v101, v78
	v_pk_fma_f32 v[76:77], v[34:35], v[96:97], v[76:77] op_sel_hi:[0,1,1]
	v_cvt_f32_ubyte0_e32 v102, v79
	v_cvt_f32_ubyte1_e32 v103, v79
	v_pk_fma_f32 v[68:69], v[34:35], v[100:101], v[68:69] op_sel_hi:[0,1,1]
	v_cvt_f32_ubyte2_e32 v126, v79
	v_cvt_f32_ubyte3_e32 v127, v79
	v_pk_fma_f32 v[62:63], v[42:43], v[102:103], v[62:63] op_sel_hi:[0,1,1]
	v_cvt_f32_ubyte0_e32 v96, v82
	v_cvt_f32_ubyte1_e32 v97, v82
	v_pk_fma_f32 v[60:61], v[42:43], v[126:127], v[60:61] op_sel_hi:[0,1,1]
	v_cvt_f32_ubyte2_e32 v100, v82
	v_cvt_f32_ubyte3_e32 v101, v82
	v_pk_fma_f32 v[90:91], v[34:35], v[96:97], v[90:91] op_sel:[1,0,0]
	v_cvt_f32_ubyte0_e32 v102, v83
	v_cvt_f32_ubyte1_e32 v103, v83
	v_pk_fma_f32 v[88:89], v[34:35], v[100:101], v[88:89] op_sel:[1,0,0]
	v_cvt_f32_ubyte2_e32 v126, v83
	v_cvt_f32_ubyte3_e32 v127, v83
	v_pk_fma_f32 v[84:85], v[42:43], v[102:103], v[84:85] op_sel:[1,0,0]
	v_cvt_f32_ubyte0_e32 v96, v86
	v_cvt_f32_ubyte1_e32 v97, v86
	v_pk_fma_f32 v[80:81], v[42:43], v[126:127], v[80:81] op_sel:[1,0,0]
	v_and_b32_e32 v74, s34, v186
	v_and_b32_e32 v75, s35, v186
	v_and_b32_e32 v78, s34, v187
	v_and_b32_e32 v79, s35, v187
	v_cvt_f32_ubyte2_e32 v100, v86
	v_cvt_f32_ubyte3_e32 v101, v86
	v_pk_fma_f32 v[76:77], v[34:35], v[96:97], v[76:77] op_sel:[1,0,0]
	v_cvt_f32_ubyte0_e32 v102, v87
	v_cvt_f32_ubyte1_e32 v103, v87
	v_pk_fma_f32 v[68:69], v[34:35], v[100:101], v[68:69] op_sel:[1,0,0]
	v_cvt_f32_ubyte2_e32 v126, v87
	v_cvt_f32_ubyte3_e32 v127, v87
	v_pk_fma_f32 v[62:63], v[42:43], v[102:103], v[62:63] op_sel:[1,0,0]
	v_cvt_f32_ubyte0_e32 v96, v74
	v_cvt_f32_ubyte1_e32 v97, v74
	v_pk_fma_f32 v[60:61], v[42:43], v[126:127], v[60:61] op_sel:[1,0,0]
	v_cvt_f32_ubyte2_e32 v100, v74
	v_cvt_f32_ubyte3_e32 v101, v74
	v_pk_fma_f32 v[90:91], v[36:37], v[96:97], v[90:91] op_sel_hi:[0,1,1]
	v_cvt_f32_ubyte0_e32 v102, v75
	v_cvt_f32_ubyte1_e32 v103, v75
	v_pk_fma_f32 v[88:89], v[36:37], v[100:101], v[88:89] op_sel_hi:[0,1,1]
	v_cvt_f32_ubyte2_e32 v126, v75
	v_cvt_f32_ubyte3_e32 v127, v75
	v_pk_fma_f32 v[84:85], v[44:45], v[102:103], v[84:85] op_sel_hi:[0,1,1]
	v_cvt_f32_ubyte0_e32 v96, v78
	v_cvt_f32_ubyte1_e32 v97, v78
	v_pk_fma_f32 v[80:81], v[44:45], v[126:127], v[80:81] op_sel_hi:[0,1,1]
	v_and_b32_e32 v82, s34, v188
	v_and_b32_e32 v83, s35, v188
	v_and_b32_e32 v86, s34, v189
	v_and_b32_e32 v87, s35, v189
	v_cvt_f32_ubyte2_e32 v100, v78
	v_cvt_f32_ubyte3_e32 v101, v78
	v_pk_fma_f32 v[76:77], v[36:37], v[96:97], v[76:77] op_sel_hi:[0,1,1]
	v_cvt_f32_ubyte0_e32 v102, v79
	v_cvt_f32_ubyte1_e32 v103, v79
	v_pk_fma_f32 v[68:69], v[36:37], v[100:101], v[68:69] op_sel_hi:[0,1,1]
	v_cvt_f32_ubyte2_e32 v126, v79
	v_cvt_f32_ubyte3_e32 v127, v79
	v_pk_fma_f32 v[62:63], v[44:45], v[102:103], v[62:63] op_sel_hi:[0,1,1]
	v_cvt_f32_ubyte0_e32 v96, v82
	v_cvt_f32_ubyte1_e32 v97, v82
	v_pk_fma_f32 v[60:61], v[44:45], v[126:127], v[60:61] op_sel_hi:[0,1,1]
	v_cvt_f32_ubyte2_e32 v100, v82
	v_cvt_f32_ubyte3_e32 v101, v82
	v_pk_fma_f32 v[90:91], v[36:37], v[96:97], v[90:91] op_sel:[1,0,0]
	v_cvt_f32_ubyte0_e32 v102, v83
	v_cvt_f32_ubyte1_e32 v103, v83
	v_pk_fma_f32 v[88:89], v[36:37], v[100:101], v[88:89] op_sel:[1,0,0]
	v_cvt_f32_ubyte2_e32 v126, v83
	v_cvt_f32_ubyte3_e32 v127, v83
	v_pk_fma_f32 v[84:85], v[44:45], v[102:103], v[84:85] op_sel:[1,0,0]
	v_cvt_f32_ubyte0_e32 v96, v86
	v_cvt_f32_ubyte1_e32 v97, v86
	v_pk_fma_f32 v[80:81], v[44:45], v[126:127], v[80:81] op_sel:[1,0,0]
	v_and_b32_e32 v74, s34, v190
	v_and_b32_e32 v75, s35, v190
	v_and_b32_e32 v78, s34, v191
	v_and_b32_e32 v79, s35, v191
	v_cvt_f32_ubyte2_e32 v100, v86
	v_cvt_f32_ubyte3_e32 v101, v86
	v_pk_fma_f32 v[76:77], v[36:37], v[96:97], v[76:77] op_sel:[1,0,0]
	v_cvt_f32_ubyte0_e32 v102, v87
	v_cvt_f32_ubyte1_e32 v103, v87
	v_pk_fma_f32 v[68:69], v[36:37], v[100:101], v[68:69] op_sel:[1,0,0]
	v_cvt_f32_ubyte2_e32 v126, v87
	v_cvt_f32_ubyte3_e32 v127, v87
	v_pk_fma_f32 v[62:63], v[44:45], v[102:103], v[62:63] op_sel:[1,0,0]
	v_cvt_f32_ubyte0_e32 v96, v74
	v_cvt_f32_ubyte1_e32 v97, v74
	v_pk_fma_f32 v[60:61], v[44:45], v[126:127], v[60:61] op_sel:[1,0,0]
	v_cvt_f32_ubyte2_e32 v100, v74
	v_cvt_f32_ubyte3_e32 v101, v74
	v_pk_fma_f32 v[90:91], v[38:39], v[96:97], v[90:91] op_sel_hi:[0,1,1]
	v_cvt_f32_ubyte0_e32 v102, v75
	v_cvt_f32_ubyte1_e32 v103, v75
	v_pk_fma_f32 v[88:89], v[38:39], v[100:101], v[88:89] op_sel_hi:[0,1,1]
	v_cvt_f32_ubyte2_e32 v126, v75
	v_cvt_f32_ubyte3_e32 v127, v75
	v_pk_fma_f32 v[84:85], v[46:47], v[102:103], v[84:85] op_sel_hi:[0,1,1]
	v_cvt_f32_ubyte0_e32 v96, v78
	v_cvt_f32_ubyte1_e32 v97, v78
	v_pk_fma_f32 v[80:81], v[46:47], v[126:127], v[80:81] op_sel_hi:[0,1,1]
	v_and_b32_e32 v82, s34, v192
	v_and_b32_e32 v83, s35, v192
	v_and_b32_e32 v86, s34, v193
	v_and_b32_e32 v87, s35, v193
	v_cvt_f32_ubyte2_e32 v100, v78
	v_cvt_f32_ubyte3_e32 v101, v78
	v_pk_fma_f32 v[76:77], v[38:39], v[96:97], v[76:77] op_sel_hi:[0,1,1]
	v_cvt_f32_ubyte0_e32 v102, v79
	v_cvt_f32_ubyte1_e32 v103, v79
	v_pk_fma_f32 v[68:69], v[38:39], v[100:101], v[68:69] op_sel_hi:[0,1,1]
	v_cvt_f32_ubyte2_e32 v126, v79
	v_cvt_f32_ubyte3_e32 v127, v79
	v_pk_fma_f32 v[62:63], v[46:47], v[102:103], v[62:63] op_sel_hi:[0,1,1]
	v_cvt_f32_ubyte0_e32 v96, v82
	v_cvt_f32_ubyte1_e32 v97, v82
	v_pk_fma_f32 v[60:61], v[46:47], v[126:127], v[60:61] op_sel_hi:[0,1,1]
	v_cvt_f32_ubyte2_e32 v100, v82
	v_cvt_f32_ubyte3_e32 v101, v82
	v_pk_fma_f32 v[90:91], v[38:39], v[96:97], v[90:91] op_sel:[1,0,0]
	v_cvt_f32_ubyte0_e32 v102, v83
	v_cvt_f32_ubyte1_e32 v103, v83
	v_pk_fma_f32 v[88:89], v[38:39], v[100:101], v[88:89] op_sel:[1,0,0]
	v_cvt_f32_ubyte2_e32 v126, v83
	v_cvt_f32_ubyte3_e32 v127, v83
	v_pk_fma_f32 v[84:85], v[46:47], v[102:103], v[84:85] op_sel:[1,0,0]
	v_cvt_f32_ubyte0_e32 v96, v86
	v_cvt_f32_ubyte1_e32 v97, v86
	v_pk_fma_f32 v[80:81], v[46:47], v[126:127], v[80:81] op_sel:[1,0,0]
	v_cvt_f32_ubyte2_e32 v100, v86
	v_cvt_f32_ubyte3_e32 v101, v86
	v_pk_fma_f32 v[76:77], v[38:39], v[96:97], v[76:77] op_sel:[1,0,0]
	v_cvt_f32_ubyte0_e32 v102, v87
	v_cvt_f32_ubyte1_e32 v103, v87
	v_pk_fma_f32 v[68:69], v[38:39], v[100:101], v[68:69] op_sel:[1,0,0]
	v_cvt_f32_ubyte2_e32 v126, v87
	v_cvt_f32_ubyte3_e32 v127, v87
	v_pk_fma_f32 v[62:63], v[46:47], v[102:103], v[62:63] op_sel:[1,0,0]
	v_pk_fma_f32 v[60:61], v[46:47], v[126:127], v[60:61] op_sel:[1,0,0]
	s_waitcnt lgkmcnt(0)
	v_lshl_add_u32 v70, v70, 9, v98
	v_lshl_add_u32 v71, v71, 9, v98
	v_lshl_add_u32 v72, v72, 9, v98
	v_lshl_add_u32 v73, v73, 9, v98
	v_lshl_add_u32 v92, v92, 9, v98
	v_lshl_add_u32 v93, v93, 9, v98
	v_lshl_add_u32 v94, v94, 9, v98
	v_lshl_add_u32 v95, v95, 9, v98
	global_load_dwordx2 v[178:179], v70, s[36:37]
	global_load_dwordx2 v[180:181], v71, s[36:37]
	global_load_dwordx2 v[182:183], v72, s[36:37]
	global_load_dwordx2 v[184:185], v73, s[36:37]
	global_load_dwordx2 v[186:187], v92, s[36:37]
	global_load_dwordx2 v[188:189], v93, s[36:37]
	global_load_dwordx2 v[190:191], v94, s[36:37]
	global_load_dwordx2 v[192:193], v95, s[36:37]
	ds_read_b128 v[70:73], v128 offset:288
	ds_read_b128 v[92:95], v128 offset:304
	ds_read_b128 v[32:35], v128 offset:640
	ds_read_b128 v[36:39], v128 offset:656
	ds_read_b128 v[40:43], v128 offset:1664
	ds_read_b128 v[44:47], v128 offset:1680
	s_waitcnt vmcnt(40)
	v_and_b32_e32 v74, s34, v194
	v_and_b32_e32 v75, s35, v194
	v_and_b32_e32 v78, s34, v195
	v_and_b32_e32 v79, s35, v195
	v_cvt_f32_ubyte0_e32 v96, v74
	v_cvt_f32_ubyte1_e32 v97, v74
	v_cvt_f32_ubyte2_e32 v100, v74
	v_cvt_f32_ubyte3_e32 v101, v74
	v_pk_fma_f32 v[90:91], v[48:49], v[96:97], v[90:91] op_sel_hi:[0,1,1]
	v_cvt_f32_ubyte0_e32 v102, v75
	v_cvt_f32_ubyte1_e32 v103, v75
	v_pk_fma_f32 v[88:89], v[48:49], v[100:101], v[88:89] op_sel_hi:[0,1,1]
	v_cvt_f32_ubyte2_e32 v126, v75
	v_cvt_f32_ubyte3_e32 v127, v75
	v_pk_fma_f32 v[84:85], v[56:57], v[102:103], v[84:85] op_sel_hi:[0,1,1]
	v_cvt_f32_ubyte0_e32 v96, v78
	v_cvt_f32_ubyte1_e32 v97, v78
	v_pk_fma_f32 v[80:81], v[56:57], v[126:127], v[80:81] op_sel_hi:[0,1,1]
	v_and_b32_e32 v82, s34, v196
	v_and_b32_e32 v83, s35, v196
	v_and_b32_e32 v86, s34, v197
	v_and_b32_e32 v87, s35, v197
	v_cvt_f32_ubyte2_e32 v100, v78
	v_cvt_f32_ubyte3_e32 v101, v78
	v_pk_fma_f32 v[76:77], v[48:49], v[96:97], v[76:77] op_sel_hi:[0,1,1]
	v_cvt_f32_ubyte0_e32 v102, v79
	v_cvt_f32_ubyte1_e32 v103, v79
	v_pk_fma_f32 v[68:69], v[48:49], v[100:101], v[68:69] op_sel_hi:[0,1,1]
	v_cvt_f32_ubyte2_e32 v126, v79
	v_cvt_f32_ubyte3_e32 v127, v79
	v_pk_fma_f32 v[62:63], v[56:57], v[102:103], v[62:63] op_sel_hi:[0,1,1]
	v_cvt_f32_ubyte0_e32 v96, v82
	v_cvt_f32_ubyte1_e32 v97, v82
	v_pk_fma_f32 v[60:61], v[56:57], v[126:127], v[60:61] op_sel_hi:[0,1,1]
	v_cvt_f32_ubyte2_e32 v100, v82
	v_cvt_f32_ubyte3_e32 v101, v82
	v_pk_fma_f32 v[90:91], v[48:49], v[96:97], v[90:91] op_sel:[1,0,0]
	v_cvt_f32_ubyte0_e32 v102, v83
	v_cvt_f32_ubyte1_e32 v103, v83
	v_pk_fma_f32 v[88:89], v[48:49], v[100:101], v[88:89] op_sel:[1,0,0]
	v_cvt_f32_ubyte2_e32 v126, v83
	v_cvt_f32_ubyte3_e32 v127, v83
	v_pk_fma_f32 v[84:85], v[56:57], v[102:103], v[84:85] op_sel:[1,0,0]
	v_cvt_f32_ubyte0_e32 v96, v86
	v_cvt_f32_ubyte1_e32 v97, v86
	v_pk_fma_f32 v[80:81], v[56:57], v[126:127], v[80:81] op_sel:[1,0,0]
	v_and_b32_e32 v74, s34, v198
	v_and_b32_e32 v75, s35, v198
	v_and_b32_e32 v78, s34, v199
	v_and_b32_e32 v79, s35, v199
	v_cvt_f32_ubyte2_e32 v100, v86
	v_cvt_f32_ubyte3_e32 v101, v86
	v_pk_fma_f32 v[76:77], v[48:49], v[96:97], v[76:77] op_sel:[1,0,0]
	v_cvt_f32_ubyte0_e32 v102, v87
	v_cvt_f32_ubyte1_e32 v103, v87
	v_pk_fma_f32 v[68:69], v[48:49], v[100:101], v[68:69] op_sel:[1,0,0]
	v_cvt_f32_ubyte2_e32 v126, v87
	v_cvt_f32_ubyte3_e32 v127, v87
	v_pk_fma_f32 v[62:63], v[56:57], v[102:103], v[62:63] op_sel:[1,0,0]
	v_cvt_f32_ubyte0_e32 v96, v74
	v_cvt_f32_ubyte1_e32 v97, v74
	v_pk_fma_f32 v[60:61], v[56:57], v[126:127], v[60:61] op_sel:[1,0,0]
	v_cvt_f32_ubyte2_e32 v100, v74
	v_cvt_f32_ubyte3_e32 v101, v74
	v_pk_fma_f32 v[90:91], v[50:51], v[96:97], v[90:91] op_sel_hi:[0,1,1]
	v_cvt_f32_ubyte0_e32 v102, v75
	v_cvt_f32_ubyte1_e32 v103, v75
	v_pk_fma_f32 v[88:89], v[50:51], v[100:101], v[88:89] op_sel_hi:[0,1,1]
	v_cvt_f32_ubyte2_e32 v126, v75
	v_cvt_f32_ubyte3_e32 v127, v75
	v_pk_fma_f32 v[84:85], v[58:59], v[102:103], v[84:85] op_sel_hi:[0,1,1]
	v_cvt_f32_ubyte0_e32 v96, v78
	v_cvt_f32_ubyte1_e32 v97, v78
	v_pk_fma_f32 v[80:81], v[58:59], v[126:127], v[80:81] op_sel_hi:[0,1,1]
	v_and_b32_e32 v82, s34, v200
	v_and_b32_e32 v83, s35, v200
	v_and_b32_e32 v86, s34, v201
	v_and_b32_e32 v87, s35, v201
	v_cvt_f32_ubyte2_e32 v100, v78
	v_cvt_f32_ubyte3_e32 v101, v78
	v_pk_fma_f32 v[76:77], v[50:51], v[96:97], v[76:77] op_sel_hi:[0,1,1]
	v_cvt_f32_ubyte0_e32 v102, v79
	v_cvt_f32_ubyte1_e32 v103, v79
	v_pk_fma_f32 v[68:69], v[50:51], v[100:101], v[68:69] op_sel_hi:[0,1,1]
	v_cvt_f32_ubyte2_e32 v126, v79
	v_cvt_f32_ubyte3_e32 v127, v79
	v_pk_fma_f32 v[62:63], v[58:59], v[102:103], v[62:63] op_sel_hi:[0,1,1]
	v_cvt_f32_ubyte0_e32 v96, v82
	v_cvt_f32_ubyte1_e32 v97, v82
	v_pk_fma_f32 v[60:61], v[58:59], v[126:127], v[60:61] op_sel_hi:[0,1,1]
	v_cvt_f32_ubyte2_e32 v100, v82
	v_cvt_f32_ubyte3_e32 v101, v82
	v_pk_fma_f32 v[90:91], v[50:51], v[96:97], v[90:91] op_sel:[1,0,0]
	v_cvt_f32_ubyte0_e32 v102, v83
	v_cvt_f32_ubyte1_e32 v103, v83
	v_pk_fma_f32 v[88:89], v[50:51], v[100:101], v[88:89] op_sel:[1,0,0]
	v_cvt_f32_ubyte2_e32 v126, v83
	v_cvt_f32_ubyte3_e32 v127, v83
	v_pk_fma_f32 v[84:85], v[58:59], v[102:103], v[84:85] op_sel:[1,0,0]
	v_cvt_f32_ubyte0_e32 v96, v86
	v_cvt_f32_ubyte1_e32 v97, v86
	v_pk_fma_f32 v[80:81], v[58:59], v[126:127], v[80:81] op_sel:[1,0,0]
	v_and_b32_e32 v74, s34, v202
	v_and_b32_e32 v75, s35, v202
	v_and_b32_e32 v78, s34, v203
	v_and_b32_e32 v79, s35, v203
	v_cvt_f32_ubyte2_e32 v100, v86
	v_cvt_f32_ubyte3_e32 v101, v86
	v_pk_fma_f32 v[76:77], v[50:51], v[96:97], v[76:77] op_sel:[1,0,0]
	v_cvt_f32_ubyte0_e32 v102, v87
	v_cvt_f32_ubyte1_e32 v103, v87
	v_pk_fma_f32 v[68:69], v[50:51], v[100:101], v[68:69] op_sel:[1,0,0]
	v_cvt_f32_ubyte2_e32 v126, v87
	v_cvt_f32_ubyte3_e32 v127, v87
	v_pk_fma_f32 v[62:63], v[58:59], v[102:103], v[62:63] op_sel:[1,0,0]
	v_cvt_f32_ubyte0_e32 v96, v74
	v_cvt_f32_ubyte1_e32 v97, v74
	v_pk_fma_f32 v[60:61], v[58:59], v[126:127], v[60:61] op_sel:[1,0,0]
	v_cvt_f32_ubyte2_e32 v100, v74
	v_cvt_f32_ubyte3_e32 v101, v74
	v_pk_fma_f32 v[90:91], v[52:53], v[96:97], v[90:91] op_sel_hi:[0,1,1]
	v_cvt_f32_ubyte0_e32 v102, v75
	v_cvt_f32_ubyte1_e32 v103, v75
	v_pk_fma_f32 v[88:89], v[52:53], v[100:101], v[88:89] op_sel_hi:[0,1,1]
	v_cvt_f32_ubyte2_e32 v126, v75
	v_cvt_f32_ubyte3_e32 v127, v75
	v_pk_fma_f32 v[84:85], v[64:65], v[102:103], v[84:85] op_sel_hi:[0,1,1]
	v_cvt_f32_ubyte0_e32 v96, v78
	v_cvt_f32_ubyte1_e32 v97, v78
	v_pk_fma_f32 v[80:81], v[64:65], v[126:127], v[80:81] op_sel_hi:[0,1,1]
	v_and_b32_e32 v82, s34, v204
	v_and_b32_e32 v83, s35, v204
	v_and_b32_e32 v86, s34, v205
	v_and_b32_e32 v87, s35, v205
	v_cvt_f32_ubyte2_e32 v100, v78
	v_cvt_f32_ubyte3_e32 v101, v78
	v_pk_fma_f32 v[76:77], v[52:53], v[96:97], v[76:77] op_sel_hi:[0,1,1]
	v_cvt_f32_ubyte0_e32 v102, v79
	v_cvt_f32_ubyte1_e32 v103, v79
	v_pk_fma_f32 v[68:69], v[52:53], v[100:101], v[68:69] op_sel_hi:[0,1,1]
	v_cvt_f32_ubyte2_e32 v126, v79
	v_cvt_f32_ubyte3_e32 v127, v79
	v_pk_fma_f32 v[62:63], v[64:65], v[102:103], v[62:63] op_sel_hi:[0,1,1]
	v_cvt_f32_ubyte0_e32 v96, v82
	v_cvt_f32_ubyte1_e32 v97, v82
	v_pk_fma_f32 v[60:61], v[64:65], v[126:127], v[60:61] op_sel_hi:[0,1,1]
	v_cvt_f32_ubyte2_e32 v100, v82
	v_cvt_f32_ubyte3_e32 v101, v82
	v_pk_fma_f32 v[90:91], v[52:53], v[96:97], v[90:91] op_sel:[1,0,0]
	v_cvt_f32_ubyte0_e32 v102, v83
	v_cvt_f32_ubyte1_e32 v103, v83
	v_pk_fma_f32 v[88:89], v[52:53], v[100:101], v[88:89] op_sel:[1,0,0]
	v_cvt_f32_ubyte2_e32 v126, v83
	v_cvt_f32_ubyte3_e32 v127, v83
	v_pk_fma_f32 v[84:85], v[64:65], v[102:103], v[84:85] op_sel:[1,0,0]
	v_cvt_f32_ubyte0_e32 v96, v86
	v_cvt_f32_ubyte1_e32 v97, v86
	v_pk_fma_f32 v[80:81], v[64:65], v[126:127], v[80:81] op_sel:[1,0,0]
	v_and_b32_e32 v74, s34, v206
	v_and_b32_e32 v75, s35, v206
	v_and_b32_e32 v78, s34, v207
	v_and_b32_e32 v79, s35, v207
	v_cvt_f32_ubyte2_e32 v100, v86
	v_cvt_f32_ubyte3_e32 v101, v86
	v_pk_fma_f32 v[76:77], v[52:53], v[96:97], v[76:77] op_sel:[1,0,0]
	v_cvt_f32_ubyte0_e32 v102, v87
	v_cvt_f32_ubyte1_e32 v103, v87
	v_pk_fma_f32 v[68:69], v[52:53], v[100:101], v[68:69] op_sel:[1,0,0]
	v_cvt_f32_ubyte2_e32 v126, v87
	v_cvt_f32_ubyte3_e32 v127, v87
	v_pk_fma_f32 v[62:63], v[64:65], v[102:103], v[62:63] op_sel:[1,0,0]
	v_cvt_f32_ubyte0_e32 v96, v74
	v_cvt_f32_ubyte1_e32 v97, v74
	v_pk_fma_f32 v[60:61], v[64:65], v[126:127], v[60:61] op_sel:[1,0,0]
	v_cvt_f32_ubyte2_e32 v100, v74
	v_cvt_f32_ubyte3_e32 v101, v74
	v_pk_fma_f32 v[90:91], v[54:55], v[96:97], v[90:91] op_sel_hi:[0,1,1]
	v_cvt_f32_ubyte0_e32 v102, v75
	v_cvt_f32_ubyte1_e32 v103, v75
	v_pk_fma_f32 v[88:89], v[54:55], v[100:101], v[88:89] op_sel_hi:[0,1,1]
	v_cvt_f32_ubyte2_e32 v126, v75
	v_cvt_f32_ubyte3_e32 v127, v75
	v_pk_fma_f32 v[84:85], v[66:67], v[102:103], v[84:85] op_sel_hi:[0,1,1]
	v_cvt_f32_ubyte0_e32 v96, v78
	v_cvt_f32_ubyte1_e32 v97, v78
	v_pk_fma_f32 v[80:81], v[66:67], v[126:127], v[80:81] op_sel_hi:[0,1,1]
	v_and_b32_e32 v82, s34, v208
	v_and_b32_e32 v83, s35, v208
	v_and_b32_e32 v86, s34, v209
	v_and_b32_e32 v87, s35, v209
	v_cvt_f32_ubyte2_e32 v100, v78
	v_cvt_f32_ubyte3_e32 v101, v78
	v_pk_fma_f32 v[76:77], v[54:55], v[96:97], v[76:77] op_sel_hi:[0,1,1]
	v_cvt_f32_ubyte0_e32 v102, v79
	v_cvt_f32_ubyte1_e32 v103, v79
	v_pk_fma_f32 v[68:69], v[54:55], v[100:101], v[68:69] op_sel_hi:[0,1,1]
	v_cvt_f32_ubyte2_e32 v126, v79
	v_cvt_f32_ubyte3_e32 v127, v79
	v_pk_fma_f32 v[62:63], v[66:67], v[102:103], v[62:63] op_sel_hi:[0,1,1]
	v_cvt_f32_ubyte0_e32 v96, v82
	v_cvt_f32_ubyte1_e32 v97, v82
	v_pk_fma_f32 v[60:61], v[66:67], v[126:127], v[60:61] op_sel_hi:[0,1,1]
	v_cvt_f32_ubyte2_e32 v100, v82
	v_cvt_f32_ubyte3_e32 v101, v82
	v_pk_fma_f32 v[90:91], v[54:55], v[96:97], v[90:91] op_sel:[1,0,0]
	v_cvt_f32_ubyte0_e32 v102, v83
	v_cvt_f32_ubyte1_e32 v103, v83
	v_pk_fma_f32 v[88:89], v[54:55], v[100:101], v[88:89] op_sel:[1,0,0]
	v_cvt_f32_ubyte2_e32 v126, v83
	v_cvt_f32_ubyte3_e32 v127, v83
	v_pk_fma_f32 v[84:85], v[66:67], v[102:103], v[84:85] op_sel:[1,0,0]
	v_cvt_f32_ubyte0_e32 v96, v86
	v_cvt_f32_ubyte1_e32 v97, v86
	v_pk_fma_f32 v[80:81], v[66:67], v[126:127], v[80:81] op_sel:[1,0,0]
	v_cvt_f32_ubyte2_e32 v100, v86
	v_cvt_f32_ubyte3_e32 v101, v86
	v_pk_fma_f32 v[76:77], v[54:55], v[96:97], v[76:77] op_sel:[1,0,0]
	v_cvt_f32_ubyte0_e32 v102, v87
	v_cvt_f32_ubyte1_e32 v103, v87
	v_pk_fma_f32 v[68:69], v[54:55], v[100:101], v[68:69] op_sel:[1,0,0]
	v_cvt_f32_ubyte2_e32 v126, v87
	v_cvt_f32_ubyte3_e32 v127, v87
	v_pk_fma_f32 v[62:63], v[66:67], v[102:103], v[62:63] op_sel:[1,0,0]
	v_pk_fma_f32 v[60:61], v[66:67], v[126:127], v[60:61] op_sel:[1,0,0]
	s_waitcnt lgkmcnt(0)
	v_lshl_add_u32 v70, v70, 9, v98
	v_lshl_add_u32 v71, v71, 9, v98
	v_lshl_add_u32 v72, v72, 9, v98
	v_lshl_add_u32 v73, v73, 9, v98
	v_lshl_add_u32 v92, v92, 9, v98
	v_lshl_add_u32 v93, v93, 9, v98
	v_lshl_add_u32 v94, v94, 9, v98
	v_lshl_add_u32 v95, v95, 9, v98
	global_load_dwordx2 v[194:195], v70, s[36:37]
	global_load_dwordx2 v[196:197], v71, s[36:37]
	global_load_dwordx2 v[198:199], v72, s[36:37]
	global_load_dwordx2 v[200:201], v73, s[36:37]
	global_load_dwordx2 v[202:203], v92, s[36:37]
	global_load_dwordx2 v[204:205], v93, s[36:37]
	global_load_dwordx2 v[206:207], v94, s[36:37]
	global_load_dwordx2 v[208:209], v95, s[36:37]
	ds_read_b128 v[70:73], v128 offset:320
	ds_read_b128 v[92:95], v128 offset:336
	ds_read_b128 v[48:51], v128 offset:672
	ds_read_b128 v[52:55], v128 offset:688
	ds_read_b128 v[56:59], v128 offset:1696
	ds_read_b128 v[64:67], v128 offset:1712
	s_waitcnt vmcnt(40)
	v_and_b32_e32 v74, s34, v0
	v_and_b32_e32 v75, s35, v0
	v_and_b32_e32 v78, s34, v1
	v_and_b32_e32 v79, s35, v1
	v_cvt_f32_ubyte0_e32 v96, v74
	v_cvt_f32_ubyte1_e32 v97, v74
	v_cvt_f32_ubyte2_e32 v100, v74
	v_cvt_f32_ubyte3_e32 v101, v74
	v_pk_fma_f32 v[90:91], v[32:33], v[96:97], v[90:91] op_sel_hi:[0,1,1]
	v_cvt_f32_ubyte0_e32 v102, v75
	v_cvt_f32_ubyte1_e32 v103, v75
	v_pk_fma_f32 v[88:89], v[32:33], v[100:101], v[88:89] op_sel_hi:[0,1,1]
	v_cvt_f32_ubyte2_e32 v126, v75
	v_cvt_f32_ubyte3_e32 v127, v75
	v_pk_fma_f32 v[84:85], v[40:41], v[102:103], v[84:85] op_sel_hi:[0,1,1]
	v_cvt_f32_ubyte0_e32 v96, v78
	v_cvt_f32_ubyte1_e32 v97, v78
	v_pk_fma_f32 v[80:81], v[40:41], v[126:127], v[80:81] op_sel_hi:[0,1,1]
	v_and_b32_e32 v82, s34, v2
	v_and_b32_e32 v83, s35, v2
	v_and_b32_e32 v86, s34, v3
	v_and_b32_e32 v87, s35, v3
	v_cvt_f32_ubyte2_e32 v100, v78
	v_cvt_f32_ubyte3_e32 v101, v78
	v_pk_fma_f32 v[76:77], v[32:33], v[96:97], v[76:77] op_sel_hi:[0,1,1]
	v_cvt_f32_ubyte0_e32 v102, v79
	v_cvt_f32_ubyte1_e32 v103, v79
	v_pk_fma_f32 v[68:69], v[32:33], v[100:101], v[68:69] op_sel_hi:[0,1,1]
	v_cvt_f32_ubyte2_e32 v126, v79
	v_cvt_f32_ubyte3_e32 v127, v79
	v_pk_fma_f32 v[62:63], v[40:41], v[102:103], v[62:63] op_sel_hi:[0,1,1]
	v_cvt_f32_ubyte0_e32 v96, v82
	v_cvt_f32_ubyte1_e32 v97, v82
	v_pk_fma_f32 v[60:61], v[40:41], v[126:127], v[60:61] op_sel_hi:[0,1,1]
	v_cvt_f32_ubyte2_e32 v100, v82
	v_cvt_f32_ubyte3_e32 v101, v82
	v_pk_fma_f32 v[90:91], v[32:33], v[96:97], v[90:91] op_sel:[1,0,0]
	v_cvt_f32_ubyte0_e32 v102, v83
	v_cvt_f32_ubyte1_e32 v103, v83
	v_pk_fma_f32 v[88:89], v[32:33], v[100:101], v[88:89] op_sel:[1,0,0]
	v_cvt_f32_ubyte2_e32 v126, v83
	v_cvt_f32_ubyte3_e32 v127, v83
	v_pk_fma_f32 v[84:85], v[40:41], v[102:103], v[84:85] op_sel:[1,0,0]
	v_cvt_f32_ubyte0_e32 v96, v86
	v_cvt_f32_ubyte1_e32 v97, v86
	v_pk_fma_f32 v[80:81], v[40:41], v[126:127], v[80:81] op_sel:[1,0,0]
	v_and_b32_e32 v74, s34, v4
	v_and_b32_e32 v75, s35, v4
	v_and_b32_e32 v78, s34, v5
	v_and_b32_e32 v79, s35, v5
	v_cvt_f32_ubyte2_e32 v100, v86
	v_cvt_f32_ubyte3_e32 v101, v86
	v_pk_fma_f32 v[76:77], v[32:33], v[96:97], v[76:77] op_sel:[1,0,0]
	v_cvt_f32_ubyte0_e32 v102, v87
	v_cvt_f32_ubyte1_e32 v103, v87
	v_pk_fma_f32 v[68:69], v[32:33], v[100:101], v[68:69] op_sel:[1,0,0]
	v_cvt_f32_ubyte2_e32 v126, v87
	v_cvt_f32_ubyte3_e32 v127, v87
	v_pk_fma_f32 v[62:63], v[40:41], v[102:103], v[62:63] op_sel:[1,0,0]
	v_cvt_f32_ubyte0_e32 v96, v74
	v_cvt_f32_ubyte1_e32 v97, v74
	v_pk_fma_f32 v[60:61], v[40:41], v[126:127], v[60:61] op_sel:[1,0,0]
	v_cvt_f32_ubyte2_e32 v100, v74
	v_cvt_f32_ubyte3_e32 v101, v74
	v_pk_fma_f32 v[90:91], v[34:35], v[96:97], v[90:91] op_sel_hi:[0,1,1]
	v_cvt_f32_ubyte0_e32 v102, v75
	v_cvt_f32_ubyte1_e32 v103, v75
	v_pk_fma_f32 v[88:89], v[34:35], v[100:101], v[88:89] op_sel_hi:[0,1,1]
	v_cvt_f32_ubyte2_e32 v126, v75
	v_cvt_f32_ubyte3_e32 v127, v75
	v_pk_fma_f32 v[84:85], v[42:43], v[102:103], v[84:85] op_sel_hi:[0,1,1]
	v_cvt_f32_ubyte0_e32 v96, v78
	v_cvt_f32_ubyte1_e32 v97, v78
	v_pk_fma_f32 v[80:81], v[42:43], v[126:127], v[80:81] op_sel_hi:[0,1,1]
	v_and_b32_e32 v82, s34, v6
	v_and_b32_e32 v83, s35, v6
	v_and_b32_e32 v86, s34, v7
	v_and_b32_e32 v87, s35, v7
	v_cvt_f32_ubyte2_e32 v100, v78
	v_cvt_f32_ubyte3_e32 v101, v78
	v_pk_fma_f32 v[76:77], v[34:35], v[96:97], v[76:77] op_sel_hi:[0,1,1]
	v_cvt_f32_ubyte0_e32 v102, v79
	v_cvt_f32_ubyte1_e32 v103, v79
	v_pk_fma_f32 v[68:69], v[34:35], v[100:101], v[68:69] op_sel_hi:[0,1,1]
	v_cvt_f32_ubyte2_e32 v126, v79
	v_cvt_f32_ubyte3_e32 v127, v79
	v_pk_fma_f32 v[62:63], v[42:43], v[102:103], v[62:63] op_sel_hi:[0,1,1]
	v_cvt_f32_ubyte0_e32 v96, v82
	v_cvt_f32_ubyte1_e32 v97, v82
	v_pk_fma_f32 v[60:61], v[42:43], v[126:127], v[60:61] op_sel_hi:[0,1,1]
	v_cvt_f32_ubyte2_e32 v100, v82
	v_cvt_f32_ubyte3_e32 v101, v82
	v_pk_fma_f32 v[90:91], v[34:35], v[96:97], v[90:91] op_sel:[1,0,0]
	v_cvt_f32_ubyte0_e32 v102, v83
	v_cvt_f32_ubyte1_e32 v103, v83
	v_pk_fma_f32 v[88:89], v[34:35], v[100:101], v[88:89] op_sel:[1,0,0]
	v_cvt_f32_ubyte2_e32 v126, v83
	v_cvt_f32_ubyte3_e32 v127, v83
	v_pk_fma_f32 v[84:85], v[42:43], v[102:103], v[84:85] op_sel:[1,0,0]
	v_cvt_f32_ubyte0_e32 v96, v86
	v_cvt_f32_ubyte1_e32 v97, v86
	v_pk_fma_f32 v[80:81], v[42:43], v[126:127], v[80:81] op_sel:[1,0,0]
	v_and_b32_e32 v74, s34, v8
	v_and_b32_e32 v75, s35, v8
	v_and_b32_e32 v78, s34, v9
	v_and_b32_e32 v79, s35, v9
	v_cvt_f32_ubyte2_e32 v100, v86
	v_cvt_f32_ubyte3_e32 v101, v86
	v_pk_fma_f32 v[76:77], v[34:35], v[96:97], v[76:77] op_sel:[1,0,0]
	v_cvt_f32_ubyte0_e32 v102, v87
	v_cvt_f32_ubyte1_e32 v103, v87
	v_pk_fma_f32 v[68:69], v[34:35], v[100:101], v[68:69] op_sel:[1,0,0]
	v_cvt_f32_ubyte2_e32 v126, v87
	v_cvt_f32_ubyte3_e32 v127, v87
	v_pk_fma_f32 v[62:63], v[42:43], v[102:103], v[62:63] op_sel:[1,0,0]
	v_cvt_f32_ubyte0_e32 v96, v74
	v_cvt_f32_ubyte1_e32 v97, v74
	v_pk_fma_f32 v[60:61], v[42:43], v[126:127], v[60:61] op_sel:[1,0,0]
	v_cvt_f32_ubyte2_e32 v100, v74
	v_cvt_f32_ubyte3_e32 v101, v74
	v_pk_fma_f32 v[90:91], v[36:37], v[96:97], v[90:91] op_sel_hi:[0,1,1]
	v_cvt_f32_ubyte0_e32 v102, v75
	v_cvt_f32_ubyte1_e32 v103, v75
	v_pk_fma_f32 v[88:89], v[36:37], v[100:101], v[88:89] op_sel_hi:[0,1,1]
	v_cvt_f32_ubyte2_e32 v126, v75
	v_cvt_f32_ubyte3_e32 v127, v75
	v_pk_fma_f32 v[84:85], v[44:45], v[102:103], v[84:85] op_sel_hi:[0,1,1]
	v_cvt_f32_ubyte0_e32 v96, v78
	v_cvt_f32_ubyte1_e32 v97, v78
	v_pk_fma_f32 v[80:81], v[44:45], v[126:127], v[80:81] op_sel_hi:[0,1,1]
	v_and_b32_e32 v82, s34, v10
	v_and_b32_e32 v83, s35, v10
	v_and_b32_e32 v86, s34, v11
	v_and_b32_e32 v87, s35, v11
	v_cvt_f32_ubyte2_e32 v100, v78
	v_cvt_f32_ubyte3_e32 v101, v78
	v_pk_fma_f32 v[76:77], v[36:37], v[96:97], v[76:77] op_sel_hi:[0,1,1]
	v_cvt_f32_ubyte0_e32 v102, v79
	v_cvt_f32_ubyte1_e32 v103, v79
	v_pk_fma_f32 v[68:69], v[36:37], v[100:101], v[68:69] op_sel_hi:[0,1,1]
	v_cvt_f32_ubyte2_e32 v126, v79
	v_cvt_f32_ubyte3_e32 v127, v79
	v_pk_fma_f32 v[62:63], v[44:45], v[102:103], v[62:63] op_sel_hi:[0,1,1]
	v_cvt_f32_ubyte0_e32 v96, v82
	v_cvt_f32_ubyte1_e32 v97, v82
	v_pk_fma_f32 v[60:61], v[44:45], v[126:127], v[60:61] op_sel_hi:[0,1,1]
	v_cvt_f32_ubyte2_e32 v100, v82
	v_cvt_f32_ubyte3_e32 v101, v82
	v_pk_fma_f32 v[90:91], v[36:37], v[96:97], v[90:91] op_sel:[1,0,0]
	v_cvt_f32_ubyte0_e32 v102, v83
	v_cvt_f32_ubyte1_e32 v103, v83
	v_pk_fma_f32 v[88:89], v[36:37], v[100:101], v[88:89] op_sel:[1,0,0]
	v_cvt_f32_ubyte2_e32 v126, v83
	v_cvt_f32_ubyte3_e32 v127, v83
	v_pk_fma_f32 v[84:85], v[44:45], v[102:103], v[84:85] op_sel:[1,0,0]
	v_cvt_f32_ubyte0_e32 v96, v86
	v_cvt_f32_ubyte1_e32 v97, v86
	v_pk_fma_f32 v[80:81], v[44:45], v[126:127], v[80:81] op_sel:[1,0,0]
	v_and_b32_e32 v74, s34, v12
	v_and_b32_e32 v75, s35, v12
	v_and_b32_e32 v78, s34, v13
	v_and_b32_e32 v79, s35, v13
	v_cvt_f32_ubyte2_e32 v100, v86
	v_cvt_f32_ubyte3_e32 v101, v86
	v_pk_fma_f32 v[76:77], v[36:37], v[96:97], v[76:77] op_sel:[1,0,0]
	v_cvt_f32_ubyte0_e32 v102, v87
	v_cvt_f32_ubyte1_e32 v103, v87
	v_pk_fma_f32 v[68:69], v[36:37], v[100:101], v[68:69] op_sel:[1,0,0]
	v_cvt_f32_ubyte2_e32 v126, v87
	v_cvt_f32_ubyte3_e32 v127, v87
	v_pk_fma_f32 v[62:63], v[44:45], v[102:103], v[62:63] op_sel:[1,0,0]
	v_cvt_f32_ubyte0_e32 v96, v74
	v_cvt_f32_ubyte1_e32 v97, v74
	v_pk_fma_f32 v[60:61], v[44:45], v[126:127], v[60:61] op_sel:[1,0,0]
	v_cvt_f32_ubyte2_e32 v100, v74
	v_cvt_f32_ubyte3_e32 v101, v74
	v_pk_fma_f32 v[90:91], v[38:39], v[96:97], v[90:91] op_sel_hi:[0,1,1]
	v_cvt_f32_ubyte0_e32 v102, v75
	v_cvt_f32_ubyte1_e32 v103, v75
	v_pk_fma_f32 v[88:89], v[38:39], v[100:101], v[88:89] op_sel_hi:[0,1,1]
	v_cvt_f32_ubyte2_e32 v126, v75
	v_cvt_f32_ubyte3_e32 v127, v75
	v_pk_fma_f32 v[84:85], v[46:47], v[102:103], v[84:85] op_sel_hi:[0,1,1]
	v_cvt_f32_ubyte0_e32 v96, v78
	v_cvt_f32_ubyte1_e32 v97, v78
	v_pk_fma_f32 v[80:81], v[46:47], v[126:127], v[80:81] op_sel_hi:[0,1,1]
	v_and_b32_e32 v82, s34, v14
	v_and_b32_e32 v83, s35, v14
	v_and_b32_e32 v86, s34, v15
	v_and_b32_e32 v87, s35, v15
	v_cvt_f32_ubyte2_e32 v100, v78
	v_cvt_f32_ubyte3_e32 v101, v78
	v_pk_fma_f32 v[76:77], v[38:39], v[96:97], v[76:77] op_sel_hi:[0,1,1]
	v_cvt_f32_ubyte0_e32 v102, v79
	v_cvt_f32_ubyte1_e32 v103, v79
	v_pk_fma_f32 v[68:69], v[38:39], v[100:101], v[68:69] op_sel_hi:[0,1,1]
	v_cvt_f32_ubyte2_e32 v126, v79
	v_cvt_f32_ubyte3_e32 v127, v79
	v_pk_fma_f32 v[62:63], v[46:47], v[102:103], v[62:63] op_sel_hi:[0,1,1]
	v_cvt_f32_ubyte0_e32 v96, v82
	v_cvt_f32_ubyte1_e32 v97, v82
	v_pk_fma_f32 v[60:61], v[46:47], v[126:127], v[60:61] op_sel_hi:[0,1,1]
	v_cvt_f32_ubyte2_e32 v100, v82
	v_cvt_f32_ubyte3_e32 v101, v82
	v_pk_fma_f32 v[90:91], v[38:39], v[96:97], v[90:91] op_sel:[1,0,0]
	v_cvt_f32_ubyte0_e32 v102, v83
	v_cvt_f32_ubyte1_e32 v103, v83
	v_pk_fma_f32 v[88:89], v[38:39], v[100:101], v[88:89] op_sel:[1,0,0]
	v_cvt_f32_ubyte2_e32 v126, v83
	v_cvt_f32_ubyte3_e32 v127, v83
	v_pk_fma_f32 v[84:85], v[46:47], v[102:103], v[84:85] op_sel:[1,0,0]
	v_cvt_f32_ubyte0_e32 v96, v86
	v_cvt_f32_ubyte1_e32 v97, v86
	v_pk_fma_f32 v[80:81], v[46:47], v[126:127], v[80:81] op_sel:[1,0,0]
	v_cvt_f32_ubyte2_e32 v100, v86
	v_cvt_f32_ubyte3_e32 v101, v86
	v_pk_fma_f32 v[76:77], v[38:39], v[96:97], v[76:77] op_sel:[1,0,0]
	v_cvt_f32_ubyte0_e32 v102, v87
	v_cvt_f32_ubyte1_e32 v103, v87
	v_pk_fma_f32 v[68:69], v[38:39], v[100:101], v[68:69] op_sel:[1,0,0]
	v_cvt_f32_ubyte2_e32 v126, v87
	v_cvt_f32_ubyte3_e32 v127, v87
	v_pk_fma_f32 v[62:63], v[46:47], v[102:103], v[62:63] op_sel:[1,0,0]
	v_pk_fma_f32 v[60:61], v[46:47], v[126:127], v[60:61] op_sel:[1,0,0]
	s_waitcnt lgkmcnt(0)
	v_lshl_add_u32 v70, v70, 9, v98
	v_lshl_add_u32 v71, v71, 9, v98
	v_lshl_add_u32 v72, v72, 9, v98
	v_lshl_add_u32 v73, v73, 9, v98
	v_lshl_add_u32 v92, v92, 9, v98
	v_lshl_add_u32 v93, v93, 9, v98
	v_lshl_add_u32 v94, v94, 9, v98
	v_lshl_add_u32 v95, v95, 9, v98
	global_load_dwordx2 v[0:1], v70, s[36:37]
	global_load_dwordx2 v[2:3], v71, s[36:37]
	global_load_dwordx2 v[4:5], v72, s[36:37]
	global_load_dwordx2 v[6:7], v73, s[36:37]
	global_load_dwordx2 v[8:9], v92, s[36:37]
	global_load_dwordx2 v[10:11], v93, s[36:37]
	global_load_dwordx2 v[12:13], v94, s[36:37]
	global_load_dwordx2 v[14:15], v95, s[36:37]
	ds_read_b128 v[70:73], v128 offset:352
	ds_read_b128 v[92:95], v128 offset:368
	ds_read_b128 v[32:35], v128 offset:704
	ds_read_b128 v[36:39], v128 offset:720
	ds_read_b128 v[40:43], v128 offset:1728
	ds_read_b128 v[44:47], v128 offset:1744
	s_waitcnt vmcnt(40)
	v_and_b32_e32 v74, s34, v16
	v_and_b32_e32 v75, s35, v16
	v_and_b32_e32 v78, s34, v17
	v_and_b32_e32 v79, s35, v17
	v_cvt_f32_ubyte0_e32 v96, v74
	v_cvt_f32_ubyte1_e32 v97, v74
	v_cvt_f32_ubyte2_e32 v100, v74
	v_cvt_f32_ubyte3_e32 v101, v74
	v_pk_fma_f32 v[90:91], v[48:49], v[96:97], v[90:91] op_sel_hi:[0,1,1]
	v_cvt_f32_ubyte0_e32 v102, v75
	v_cvt_f32_ubyte1_e32 v103, v75
	v_pk_fma_f32 v[88:89], v[48:49], v[100:101], v[88:89] op_sel_hi:[0,1,1]
	v_cvt_f32_ubyte2_e32 v126, v75
	v_cvt_f32_ubyte3_e32 v127, v75
	v_pk_fma_f32 v[84:85], v[56:57], v[102:103], v[84:85] op_sel_hi:[0,1,1]
	v_cvt_f32_ubyte0_e32 v96, v78
	v_cvt_f32_ubyte1_e32 v97, v78
	v_pk_fma_f32 v[80:81], v[56:57], v[126:127], v[80:81] op_sel_hi:[0,1,1]
	v_and_b32_e32 v82, s34, v18
	v_and_b32_e32 v83, s35, v18
	v_and_b32_e32 v86, s34, v19
	v_and_b32_e32 v87, s35, v19
	v_cvt_f32_ubyte2_e32 v100, v78
	v_cvt_f32_ubyte3_e32 v101, v78
	v_pk_fma_f32 v[76:77], v[48:49], v[96:97], v[76:77] op_sel_hi:[0,1,1]
	v_cvt_f32_ubyte0_e32 v102, v79
	v_cvt_f32_ubyte1_e32 v103, v79
	v_pk_fma_f32 v[68:69], v[48:49], v[100:101], v[68:69] op_sel_hi:[0,1,1]
	v_cvt_f32_ubyte2_e32 v126, v79
	v_cvt_f32_ubyte3_e32 v127, v79
	v_pk_fma_f32 v[62:63], v[56:57], v[102:103], v[62:63] op_sel_hi:[0,1,1]
	v_cvt_f32_ubyte0_e32 v96, v82
	v_cvt_f32_ubyte1_e32 v97, v82
	v_pk_fma_f32 v[60:61], v[56:57], v[126:127], v[60:61] op_sel_hi:[0,1,1]
	v_cvt_f32_ubyte2_e32 v100, v82
	v_cvt_f32_ubyte3_e32 v101, v82
	v_pk_fma_f32 v[90:91], v[48:49], v[96:97], v[90:91] op_sel:[1,0,0]
	v_cvt_f32_ubyte0_e32 v102, v83
	v_cvt_f32_ubyte1_e32 v103, v83
	v_pk_fma_f32 v[88:89], v[48:49], v[100:101], v[88:89] op_sel:[1,0,0]
	v_cvt_f32_ubyte2_e32 v126, v83
	v_cvt_f32_ubyte3_e32 v127, v83
	v_pk_fma_f32 v[84:85], v[56:57], v[102:103], v[84:85] op_sel:[1,0,0]
	v_cvt_f32_ubyte0_e32 v96, v86
	v_cvt_f32_ubyte1_e32 v97, v86
	v_pk_fma_f32 v[80:81], v[56:57], v[126:127], v[80:81] op_sel:[1,0,0]
	v_and_b32_e32 v74, s34, v20
	v_and_b32_e32 v75, s35, v20
	v_and_b32_e32 v78, s34, v21
	v_and_b32_e32 v79, s35, v21
	v_cvt_f32_ubyte2_e32 v100, v86
	v_cvt_f32_ubyte3_e32 v101, v86
	v_pk_fma_f32 v[76:77], v[48:49], v[96:97], v[76:77] op_sel:[1,0,0]
	v_cvt_f32_ubyte0_e32 v102, v87
	v_cvt_f32_ubyte1_e32 v103, v87
	v_pk_fma_f32 v[68:69], v[48:49], v[100:101], v[68:69] op_sel:[1,0,0]
	v_cvt_f32_ubyte2_e32 v126, v87
	v_cvt_f32_ubyte3_e32 v127, v87
	v_pk_fma_f32 v[62:63], v[56:57], v[102:103], v[62:63] op_sel:[1,0,0]
	v_cvt_f32_ubyte0_e32 v96, v74
	v_cvt_f32_ubyte1_e32 v97, v74
	v_pk_fma_f32 v[60:61], v[56:57], v[126:127], v[60:61] op_sel:[1,0,0]
	v_cvt_f32_ubyte2_e32 v100, v74
	v_cvt_f32_ubyte3_e32 v101, v74
	v_pk_fma_f32 v[90:91], v[50:51], v[96:97], v[90:91] op_sel_hi:[0,1,1]
	v_cvt_f32_ubyte0_e32 v102, v75
	v_cvt_f32_ubyte1_e32 v103, v75
	v_pk_fma_f32 v[88:89], v[50:51], v[100:101], v[88:89] op_sel_hi:[0,1,1]
	v_cvt_f32_ubyte2_e32 v126, v75
	v_cvt_f32_ubyte3_e32 v127, v75
	v_pk_fma_f32 v[84:85], v[58:59], v[102:103], v[84:85] op_sel_hi:[0,1,1]
	v_cvt_f32_ubyte0_e32 v96, v78
	v_cvt_f32_ubyte1_e32 v97, v78
	v_pk_fma_f32 v[80:81], v[58:59], v[126:127], v[80:81] op_sel_hi:[0,1,1]
	v_and_b32_e32 v82, s34, v22
	v_and_b32_e32 v83, s35, v22
	v_and_b32_e32 v86, s34, v23
	v_and_b32_e32 v87, s35, v23
	v_cvt_f32_ubyte2_e32 v100, v78
	v_cvt_f32_ubyte3_e32 v101, v78
	v_pk_fma_f32 v[76:77], v[50:51], v[96:97], v[76:77] op_sel_hi:[0,1,1]
	v_cvt_f32_ubyte0_e32 v102, v79
	v_cvt_f32_ubyte1_e32 v103, v79
	v_pk_fma_f32 v[68:69], v[50:51], v[100:101], v[68:69] op_sel_hi:[0,1,1]
	v_cvt_f32_ubyte2_e32 v126, v79
	v_cvt_f32_ubyte3_e32 v127, v79
	v_pk_fma_f32 v[62:63], v[58:59], v[102:103], v[62:63] op_sel_hi:[0,1,1]
	v_cvt_f32_ubyte0_e32 v96, v82
	v_cvt_f32_ubyte1_e32 v97, v82
	v_pk_fma_f32 v[60:61], v[58:59], v[126:127], v[60:61] op_sel_hi:[0,1,1]
	v_cvt_f32_ubyte2_e32 v100, v82
	v_cvt_f32_ubyte3_e32 v101, v82
	v_pk_fma_f32 v[90:91], v[50:51], v[96:97], v[90:91] op_sel:[1,0,0]
	v_cvt_f32_ubyte0_e32 v102, v83
	v_cvt_f32_ubyte1_e32 v103, v83
	v_pk_fma_f32 v[88:89], v[50:51], v[100:101], v[88:89] op_sel:[1,0,0]
	v_cvt_f32_ubyte2_e32 v126, v83
	v_cvt_f32_ubyte3_e32 v127, v83
	v_pk_fma_f32 v[84:85], v[58:59], v[102:103], v[84:85] op_sel:[1,0,0]
	v_cvt_f32_ubyte0_e32 v96, v86
	v_cvt_f32_ubyte1_e32 v97, v86
	v_pk_fma_f32 v[80:81], v[58:59], v[126:127], v[80:81] op_sel:[1,0,0]
	v_and_b32_e32 v74, s34, v24
	v_and_b32_e32 v75, s35, v24
	v_and_b32_e32 v78, s34, v25
	v_and_b32_e32 v79, s35, v25
	v_cvt_f32_ubyte2_e32 v100, v86
	v_cvt_f32_ubyte3_e32 v101, v86
	v_pk_fma_f32 v[76:77], v[50:51], v[96:97], v[76:77] op_sel:[1,0,0]
	v_cvt_f32_ubyte0_e32 v102, v87
	v_cvt_f32_ubyte1_e32 v103, v87
	v_pk_fma_f32 v[68:69], v[50:51], v[100:101], v[68:69] op_sel:[1,0,0]
	v_cvt_f32_ubyte2_e32 v126, v87
	v_cvt_f32_ubyte3_e32 v127, v87
	v_pk_fma_f32 v[62:63], v[58:59], v[102:103], v[62:63] op_sel:[1,0,0]
	v_cvt_f32_ubyte0_e32 v96, v74
	v_cvt_f32_ubyte1_e32 v97, v74
	v_pk_fma_f32 v[60:61], v[58:59], v[126:127], v[60:61] op_sel:[1,0,0]
	v_cvt_f32_ubyte2_e32 v100, v74
	v_cvt_f32_ubyte3_e32 v101, v74
	v_pk_fma_f32 v[90:91], v[52:53], v[96:97], v[90:91] op_sel_hi:[0,1,1]
	v_cvt_f32_ubyte0_e32 v102, v75
	v_cvt_f32_ubyte1_e32 v103, v75
	v_pk_fma_f32 v[88:89], v[52:53], v[100:101], v[88:89] op_sel_hi:[0,1,1]
	v_cvt_f32_ubyte2_e32 v126, v75
	v_cvt_f32_ubyte3_e32 v127, v75
	v_pk_fma_f32 v[84:85], v[64:65], v[102:103], v[84:85] op_sel_hi:[0,1,1]
	v_cvt_f32_ubyte0_e32 v96, v78
	v_cvt_f32_ubyte1_e32 v97, v78
	v_pk_fma_f32 v[80:81], v[64:65], v[126:127], v[80:81] op_sel_hi:[0,1,1]
	v_and_b32_e32 v82, s34, v26
	v_and_b32_e32 v83, s35, v26
	v_and_b32_e32 v86, s34, v27
	v_and_b32_e32 v87, s35, v27
	v_cvt_f32_ubyte2_e32 v100, v78
	v_cvt_f32_ubyte3_e32 v101, v78
	v_pk_fma_f32 v[76:77], v[52:53], v[96:97], v[76:77] op_sel_hi:[0,1,1]
	v_cvt_f32_ubyte0_e32 v102, v79
	v_cvt_f32_ubyte1_e32 v103, v79
	v_pk_fma_f32 v[68:69], v[52:53], v[100:101], v[68:69] op_sel_hi:[0,1,1]
	v_cvt_f32_ubyte2_e32 v126, v79
	v_cvt_f32_ubyte3_e32 v127, v79
	v_pk_fma_f32 v[62:63], v[64:65], v[102:103], v[62:63] op_sel_hi:[0,1,1]
	v_cvt_f32_ubyte0_e32 v96, v82
	v_cvt_f32_ubyte1_e32 v97, v82
	v_pk_fma_f32 v[60:61], v[64:65], v[126:127], v[60:61] op_sel_hi:[0,1,1]
	v_cvt_f32_ubyte2_e32 v100, v82
	v_cvt_f32_ubyte3_e32 v101, v82
	v_pk_fma_f32 v[90:91], v[52:53], v[96:97], v[90:91] op_sel:[1,0,0]
	v_cvt_f32_ubyte0_e32 v102, v83
	v_cvt_f32_ubyte1_e32 v103, v83
	v_pk_fma_f32 v[88:89], v[52:53], v[100:101], v[88:89] op_sel:[1,0,0]
	v_cvt_f32_ubyte2_e32 v126, v83
	v_cvt_f32_ubyte3_e32 v127, v83
	v_pk_fma_f32 v[84:85], v[64:65], v[102:103], v[84:85] op_sel:[1,0,0]
	v_cvt_f32_ubyte0_e32 v96, v86
	v_cvt_f32_ubyte1_e32 v97, v86
	v_pk_fma_f32 v[80:81], v[64:65], v[126:127], v[80:81] op_sel:[1,0,0]
	v_and_b32_e32 v74, s34, v28
	v_and_b32_e32 v75, s35, v28
	v_and_b32_e32 v78, s34, v29
	v_and_b32_e32 v79, s35, v29
	v_cvt_f32_ubyte2_e32 v100, v86
	v_cvt_f32_ubyte3_e32 v101, v86
	v_pk_fma_f32 v[76:77], v[52:53], v[96:97], v[76:77] op_sel:[1,0,0]
	v_cvt_f32_ubyte0_e32 v102, v87
	v_cvt_f32_ubyte1_e32 v103, v87
	v_pk_fma_f32 v[68:69], v[52:53], v[100:101], v[68:69] op_sel:[1,0,0]
	v_cvt_f32_ubyte2_e32 v126, v87
	v_cvt_f32_ubyte3_e32 v127, v87
	v_pk_fma_f32 v[62:63], v[64:65], v[102:103], v[62:63] op_sel:[1,0,0]
	v_cvt_f32_ubyte0_e32 v96, v74
	v_cvt_f32_ubyte1_e32 v97, v74
	v_pk_fma_f32 v[60:61], v[64:65], v[126:127], v[60:61] op_sel:[1,0,0]
	v_cvt_f32_ubyte2_e32 v100, v74
	v_cvt_f32_ubyte3_e32 v101, v74
	v_pk_fma_f32 v[90:91], v[54:55], v[96:97], v[90:91] op_sel_hi:[0,1,1]
	v_cvt_f32_ubyte0_e32 v102, v75
	v_cvt_f32_ubyte1_e32 v103, v75
	v_pk_fma_f32 v[88:89], v[54:55], v[100:101], v[88:89] op_sel_hi:[0,1,1]
	v_cvt_f32_ubyte2_e32 v126, v75
	v_cvt_f32_ubyte3_e32 v127, v75
	v_pk_fma_f32 v[84:85], v[66:67], v[102:103], v[84:85] op_sel_hi:[0,1,1]
	v_cvt_f32_ubyte0_e32 v96, v78
	v_cvt_f32_ubyte1_e32 v97, v78
	v_pk_fma_f32 v[80:81], v[66:67], v[126:127], v[80:81] op_sel_hi:[0,1,1]
	v_and_b32_e32 v82, s34, v30
	v_and_b32_e32 v83, s35, v30
	v_and_b32_e32 v86, s34, v31
	v_and_b32_e32 v87, s35, v31
	v_cvt_f32_ubyte2_e32 v100, v78
	v_cvt_f32_ubyte3_e32 v101, v78
	v_pk_fma_f32 v[76:77], v[54:55], v[96:97], v[76:77] op_sel_hi:[0,1,1]
	v_cvt_f32_ubyte0_e32 v102, v79
	v_cvt_f32_ubyte1_e32 v103, v79
	v_pk_fma_f32 v[68:69], v[54:55], v[100:101], v[68:69] op_sel_hi:[0,1,1]
	v_cvt_f32_ubyte2_e32 v126, v79
	v_cvt_f32_ubyte3_e32 v127, v79
	v_pk_fma_f32 v[62:63], v[66:67], v[102:103], v[62:63] op_sel_hi:[0,1,1]
	v_cvt_f32_ubyte0_e32 v96, v82
	v_cvt_f32_ubyte1_e32 v97, v82
	v_pk_fma_f32 v[60:61], v[66:67], v[126:127], v[60:61] op_sel_hi:[0,1,1]
	v_cvt_f32_ubyte2_e32 v100, v82
	v_cvt_f32_ubyte3_e32 v101, v82
	v_pk_fma_f32 v[90:91], v[54:55], v[96:97], v[90:91] op_sel:[1,0,0]
	v_cvt_f32_ubyte0_e32 v102, v83
	v_cvt_f32_ubyte1_e32 v103, v83
	v_pk_fma_f32 v[88:89], v[54:55], v[100:101], v[88:89] op_sel:[1,0,0]
	v_cvt_f32_ubyte2_e32 v126, v83
	v_cvt_f32_ubyte3_e32 v127, v83
	v_pk_fma_f32 v[84:85], v[66:67], v[102:103], v[84:85] op_sel:[1,0,0]
	v_cvt_f32_ubyte0_e32 v96, v86
	v_cvt_f32_ubyte1_e32 v97, v86
	v_pk_fma_f32 v[80:81], v[66:67], v[126:127], v[80:81] op_sel:[1,0,0]
	v_cvt_f32_ubyte2_e32 v100, v86
	v_cvt_f32_ubyte3_e32 v101, v86
	v_pk_fma_f32 v[76:77], v[54:55], v[96:97], v[76:77] op_sel:[1,0,0]
	v_cvt_f32_ubyte0_e32 v102, v87
	v_cvt_f32_ubyte1_e32 v103, v87
	v_pk_fma_f32 v[68:69], v[54:55], v[100:101], v[68:69] op_sel:[1,0,0]
	v_cvt_f32_ubyte2_e32 v126, v87
	v_cvt_f32_ubyte3_e32 v127, v87
	v_pk_fma_f32 v[62:63], v[66:67], v[102:103], v[62:63] op_sel:[1,0,0]
	v_pk_fma_f32 v[60:61], v[66:67], v[126:127], v[60:61] op_sel:[1,0,0]
	s_waitcnt lgkmcnt(0)
	v_lshl_add_u32 v70, v70, 9, v98
	v_lshl_add_u32 v71, v71, 9, v98
	v_lshl_add_u32 v72, v72, 9, v98
	v_lshl_add_u32 v73, v73, 9, v98
	v_lshl_add_u32 v92, v92, 9, v98
	v_lshl_add_u32 v93, v93, 9, v98
	v_lshl_add_u32 v94, v94, 9, v98
	v_lshl_add_u32 v95, v95, 9, v98
	global_load_dwordx2 v[16:17], v70, s[36:37]
	global_load_dwordx2 v[18:19], v71, s[36:37]
	global_load_dwordx2 v[20:21], v72, s[36:37]
	global_load_dwordx2 v[22:23], v73, s[36:37]
	global_load_dwordx2 v[24:25], v92, s[36:37]
	global_load_dwordx2 v[26:27], v93, s[36:37]
	global_load_dwordx2 v[28:29], v94, s[36:37]
	global_load_dwordx2 v[30:31], v95, s[36:37]
	ds_read_b128 v[70:73], v128 offset:384
	ds_read_b128 v[92:95], v128 offset:400
	ds_read_b128 v[48:51], v128 offset:736
	ds_read_b128 v[52:55], v128 offset:752
	ds_read_b128 v[56:59], v128 offset:1760
	ds_read_b128 v[64:67], v128 offset:1776
	s_waitcnt vmcnt(40)
	v_and_b32_e32 v74, s34, v146
	v_and_b32_e32 v75, s35, v146
	v_and_b32_e32 v78, s34, v147
	v_and_b32_e32 v79, s35, v147
	v_cvt_f32_ubyte0_e32 v96, v74
	v_cvt_f32_ubyte1_e32 v97, v74
	v_cvt_f32_ubyte2_e32 v100, v74
	v_cvt_f32_ubyte3_e32 v101, v74
	v_pk_fma_f32 v[90:91], v[32:33], v[96:97], v[90:91] op_sel_hi:[0,1,1]
	v_cvt_f32_ubyte0_e32 v102, v75
	v_cvt_f32_ubyte1_e32 v103, v75
	v_pk_fma_f32 v[88:89], v[32:33], v[100:101], v[88:89] op_sel_hi:[0,1,1]
	v_cvt_f32_ubyte2_e32 v126, v75
	v_cvt_f32_ubyte3_e32 v127, v75
	v_pk_fma_f32 v[84:85], v[40:41], v[102:103], v[84:85] op_sel_hi:[0,1,1]
	v_cvt_f32_ubyte0_e32 v96, v78
	v_cvt_f32_ubyte1_e32 v97, v78
	v_pk_fma_f32 v[80:81], v[40:41], v[126:127], v[80:81] op_sel_hi:[0,1,1]
	v_and_b32_e32 v82, s34, v148
	v_and_b32_e32 v83, s35, v148
	v_and_b32_e32 v86, s34, v149
	v_and_b32_e32 v87, s35, v149
	v_cvt_f32_ubyte2_e32 v100, v78
	v_cvt_f32_ubyte3_e32 v101, v78
	v_pk_fma_f32 v[76:77], v[32:33], v[96:97], v[76:77] op_sel_hi:[0,1,1]
	v_cvt_f32_ubyte0_e32 v102, v79
	v_cvt_f32_ubyte1_e32 v103, v79
	v_pk_fma_f32 v[68:69], v[32:33], v[100:101], v[68:69] op_sel_hi:[0,1,1]
	v_cvt_f32_ubyte2_e32 v126, v79
	v_cvt_f32_ubyte3_e32 v127, v79
	v_pk_fma_f32 v[62:63], v[40:41], v[102:103], v[62:63] op_sel_hi:[0,1,1]
	v_cvt_f32_ubyte0_e32 v96, v82
	v_cvt_f32_ubyte1_e32 v97, v82
	v_pk_fma_f32 v[60:61], v[40:41], v[126:127], v[60:61] op_sel_hi:[0,1,1]
	v_cvt_f32_ubyte2_e32 v100, v82
	v_cvt_f32_ubyte3_e32 v101, v82
	v_pk_fma_f32 v[90:91], v[32:33], v[96:97], v[90:91] op_sel:[1,0,0]
	v_cvt_f32_ubyte0_e32 v102, v83
	v_cvt_f32_ubyte1_e32 v103, v83
	v_pk_fma_f32 v[88:89], v[32:33], v[100:101], v[88:89] op_sel:[1,0,0]
	v_cvt_f32_ubyte2_e32 v126, v83
	v_cvt_f32_ubyte3_e32 v127, v83
	v_pk_fma_f32 v[84:85], v[40:41], v[102:103], v[84:85] op_sel:[1,0,0]
	v_cvt_f32_ubyte0_e32 v96, v86
	v_cvt_f32_ubyte1_e32 v97, v86
	v_pk_fma_f32 v[80:81], v[40:41], v[126:127], v[80:81] op_sel:[1,0,0]
	v_and_b32_e32 v74, s34, v150
	v_and_b32_e32 v75, s35, v150
	v_and_b32_e32 v78, s34, v151
	v_and_b32_e32 v79, s35, v151
	v_cvt_f32_ubyte2_e32 v100, v86
	v_cvt_f32_ubyte3_e32 v101, v86
	v_pk_fma_f32 v[76:77], v[32:33], v[96:97], v[76:77] op_sel:[1,0,0]
	v_cvt_f32_ubyte0_e32 v102, v87
	v_cvt_f32_ubyte1_e32 v103, v87
	v_pk_fma_f32 v[68:69], v[32:33], v[100:101], v[68:69] op_sel:[1,0,0]
	v_cvt_f32_ubyte2_e32 v126, v87
	v_cvt_f32_ubyte3_e32 v127, v87
	v_pk_fma_f32 v[62:63], v[40:41], v[102:103], v[62:63] op_sel:[1,0,0]
	v_cvt_f32_ubyte0_e32 v96, v74
	v_cvt_f32_ubyte1_e32 v97, v74
	v_pk_fma_f32 v[60:61], v[40:41], v[126:127], v[60:61] op_sel:[1,0,0]
	v_cvt_f32_ubyte2_e32 v100, v74
	v_cvt_f32_ubyte3_e32 v101, v74
	v_pk_fma_f32 v[90:91], v[34:35], v[96:97], v[90:91] op_sel_hi:[0,1,1]
	v_cvt_f32_ubyte0_e32 v102, v75
	v_cvt_f32_ubyte1_e32 v103, v75
	v_pk_fma_f32 v[88:89], v[34:35], v[100:101], v[88:89] op_sel_hi:[0,1,1]
	v_cvt_f32_ubyte2_e32 v126, v75
	v_cvt_f32_ubyte3_e32 v127, v75
	v_pk_fma_f32 v[84:85], v[42:43], v[102:103], v[84:85] op_sel_hi:[0,1,1]
	v_cvt_f32_ubyte0_e32 v96, v78
	v_cvt_f32_ubyte1_e32 v97, v78
	v_pk_fma_f32 v[80:81], v[42:43], v[126:127], v[80:81] op_sel_hi:[0,1,1]
	v_and_b32_e32 v82, s34, v152
	v_and_b32_e32 v83, s35, v152
	v_and_b32_e32 v86, s34, v153
	v_and_b32_e32 v87, s35, v153
	v_cvt_f32_ubyte2_e32 v100, v78
	v_cvt_f32_ubyte3_e32 v101, v78
	v_pk_fma_f32 v[76:77], v[34:35], v[96:97], v[76:77] op_sel_hi:[0,1,1]
	v_cvt_f32_ubyte0_e32 v102, v79
	v_cvt_f32_ubyte1_e32 v103, v79
	v_pk_fma_f32 v[68:69], v[34:35], v[100:101], v[68:69] op_sel_hi:[0,1,1]
	v_cvt_f32_ubyte2_e32 v126, v79
	v_cvt_f32_ubyte3_e32 v127, v79
	v_pk_fma_f32 v[62:63], v[42:43], v[102:103], v[62:63] op_sel_hi:[0,1,1]
	v_cvt_f32_ubyte0_e32 v96, v82
	v_cvt_f32_ubyte1_e32 v97, v82
	v_pk_fma_f32 v[60:61], v[42:43], v[126:127], v[60:61] op_sel_hi:[0,1,1]
	v_cvt_f32_ubyte2_e32 v100, v82
	v_cvt_f32_ubyte3_e32 v101, v82
	v_pk_fma_f32 v[90:91], v[34:35], v[96:97], v[90:91] op_sel:[1,0,0]
	v_cvt_f32_ubyte0_e32 v102, v83
	v_cvt_f32_ubyte1_e32 v103, v83
	v_pk_fma_f32 v[88:89], v[34:35], v[100:101], v[88:89] op_sel:[1,0,0]
	v_cvt_f32_ubyte2_e32 v126, v83
	v_cvt_f32_ubyte3_e32 v127, v83
	v_pk_fma_f32 v[84:85], v[42:43], v[102:103], v[84:85] op_sel:[1,0,0]
	v_cvt_f32_ubyte0_e32 v96, v86
	v_cvt_f32_ubyte1_e32 v97, v86
	v_pk_fma_f32 v[80:81], v[42:43], v[126:127], v[80:81] op_sel:[1,0,0]
	v_and_b32_e32 v74, s34, v154
	v_and_b32_e32 v75, s35, v154
	v_and_b32_e32 v78, s34, v155
	v_and_b32_e32 v79, s35, v155
	v_cvt_f32_ubyte2_e32 v100, v86
	v_cvt_f32_ubyte3_e32 v101, v86
	v_pk_fma_f32 v[76:77], v[34:35], v[96:97], v[76:77] op_sel:[1,0,0]
	v_cvt_f32_ubyte0_e32 v102, v87
	v_cvt_f32_ubyte1_e32 v103, v87
	v_pk_fma_f32 v[68:69], v[34:35], v[100:101], v[68:69] op_sel:[1,0,0]
	v_cvt_f32_ubyte2_e32 v126, v87
	v_cvt_f32_ubyte3_e32 v127, v87
	v_pk_fma_f32 v[62:63], v[42:43], v[102:103], v[62:63] op_sel:[1,0,0]
	v_cvt_f32_ubyte0_e32 v96, v74
	v_cvt_f32_ubyte1_e32 v97, v74
	v_pk_fma_f32 v[60:61], v[42:43], v[126:127], v[60:61] op_sel:[1,0,0]
	v_cvt_f32_ubyte2_e32 v100, v74
	v_cvt_f32_ubyte3_e32 v101, v74
	v_pk_fma_f32 v[90:91], v[36:37], v[96:97], v[90:91] op_sel_hi:[0,1,1]
	v_cvt_f32_ubyte0_e32 v102, v75
	v_cvt_f32_ubyte1_e32 v103, v75
	v_pk_fma_f32 v[88:89], v[36:37], v[100:101], v[88:89] op_sel_hi:[0,1,1]
	v_cvt_f32_ubyte2_e32 v126, v75
	v_cvt_f32_ubyte3_e32 v127, v75
	v_pk_fma_f32 v[84:85], v[44:45], v[102:103], v[84:85] op_sel_hi:[0,1,1]
	v_cvt_f32_ubyte0_e32 v96, v78
	v_cvt_f32_ubyte1_e32 v97, v78
	v_pk_fma_f32 v[80:81], v[44:45], v[126:127], v[80:81] op_sel_hi:[0,1,1]
	v_and_b32_e32 v82, s34, v156
	v_and_b32_e32 v83, s35, v156
	v_and_b32_e32 v86, s34, v157
	v_and_b32_e32 v87, s35, v157
	v_cvt_f32_ubyte2_e32 v100, v78
	v_cvt_f32_ubyte3_e32 v101, v78
	v_pk_fma_f32 v[76:77], v[36:37], v[96:97], v[76:77] op_sel_hi:[0,1,1]
	v_cvt_f32_ubyte0_e32 v102, v79
	v_cvt_f32_ubyte1_e32 v103, v79
	v_pk_fma_f32 v[68:69], v[36:37], v[100:101], v[68:69] op_sel_hi:[0,1,1]
	v_cvt_f32_ubyte2_e32 v126, v79
	v_cvt_f32_ubyte3_e32 v127, v79
	v_pk_fma_f32 v[62:63], v[44:45], v[102:103], v[62:63] op_sel_hi:[0,1,1]
	v_cvt_f32_ubyte0_e32 v96, v82
	v_cvt_f32_ubyte1_e32 v97, v82
	v_pk_fma_f32 v[60:61], v[44:45], v[126:127], v[60:61] op_sel_hi:[0,1,1]
	v_cvt_f32_ubyte2_e32 v100, v82
	v_cvt_f32_ubyte3_e32 v101, v82
	v_pk_fma_f32 v[90:91], v[36:37], v[96:97], v[90:91] op_sel:[1,0,0]
	v_cvt_f32_ubyte0_e32 v102, v83
	v_cvt_f32_ubyte1_e32 v103, v83
	v_pk_fma_f32 v[88:89], v[36:37], v[100:101], v[88:89] op_sel:[1,0,0]
	v_cvt_f32_ubyte2_e32 v126, v83
	v_cvt_f32_ubyte3_e32 v127, v83
	v_pk_fma_f32 v[84:85], v[44:45], v[102:103], v[84:85] op_sel:[1,0,0]
	v_cvt_f32_ubyte0_e32 v96, v86
	v_cvt_f32_ubyte1_e32 v97, v86
	v_pk_fma_f32 v[80:81], v[44:45], v[126:127], v[80:81] op_sel:[1,0,0]
	v_and_b32_e32 v74, s34, v158
	v_and_b32_e32 v75, s35, v158
	v_and_b32_e32 v78, s34, v159
	v_and_b32_e32 v79, s35, v159
	v_cvt_f32_ubyte2_e32 v100, v86
	v_cvt_f32_ubyte3_e32 v101, v86
	v_pk_fma_f32 v[76:77], v[36:37], v[96:97], v[76:77] op_sel:[1,0,0]
	v_cvt_f32_ubyte0_e32 v102, v87
	v_cvt_f32_ubyte1_e32 v103, v87
	v_pk_fma_f32 v[68:69], v[36:37], v[100:101], v[68:69] op_sel:[1,0,0]
	v_cvt_f32_ubyte2_e32 v126, v87
	v_cvt_f32_ubyte3_e32 v127, v87
	v_pk_fma_f32 v[62:63], v[44:45], v[102:103], v[62:63] op_sel:[1,0,0]
	v_cvt_f32_ubyte0_e32 v96, v74
	v_cvt_f32_ubyte1_e32 v97, v74
	v_pk_fma_f32 v[60:61], v[44:45], v[126:127], v[60:61] op_sel:[1,0,0]
	v_cvt_f32_ubyte2_e32 v100, v74
	v_cvt_f32_ubyte3_e32 v101, v74
	v_pk_fma_f32 v[90:91], v[38:39], v[96:97], v[90:91] op_sel_hi:[0,1,1]
	v_cvt_f32_ubyte0_e32 v102, v75
	v_cvt_f32_ubyte1_e32 v103, v75
	v_pk_fma_f32 v[88:89], v[38:39], v[100:101], v[88:89] op_sel_hi:[0,1,1]
	v_cvt_f32_ubyte2_e32 v126, v75
	v_cvt_f32_ubyte3_e32 v127, v75
	v_pk_fma_f32 v[84:85], v[46:47], v[102:103], v[84:85] op_sel_hi:[0,1,1]
	v_cvt_f32_ubyte0_e32 v96, v78
	v_cvt_f32_ubyte1_e32 v97, v78
	v_pk_fma_f32 v[80:81], v[46:47], v[126:127], v[80:81] op_sel_hi:[0,1,1]
	v_and_b32_e32 v82, s34, v160
	v_and_b32_e32 v83, s35, v160
	v_and_b32_e32 v86, s34, v161
	v_and_b32_e32 v87, s35, v161
	v_cvt_f32_ubyte2_e32 v100, v78
	v_cvt_f32_ubyte3_e32 v101, v78
	v_pk_fma_f32 v[76:77], v[38:39], v[96:97], v[76:77] op_sel_hi:[0,1,1]
	v_cvt_f32_ubyte0_e32 v102, v79
	v_cvt_f32_ubyte1_e32 v103, v79
	v_pk_fma_f32 v[68:69], v[38:39], v[100:101], v[68:69] op_sel_hi:[0,1,1]
	v_cvt_f32_ubyte2_e32 v126, v79
	v_cvt_f32_ubyte3_e32 v127, v79
	v_pk_fma_f32 v[62:63], v[46:47], v[102:103], v[62:63] op_sel_hi:[0,1,1]
	v_cvt_f32_ubyte0_e32 v96, v82
	v_cvt_f32_ubyte1_e32 v97, v82
	v_pk_fma_f32 v[60:61], v[46:47], v[126:127], v[60:61] op_sel_hi:[0,1,1]
	v_cvt_f32_ubyte2_e32 v100, v82
	v_cvt_f32_ubyte3_e32 v101, v82
	v_pk_fma_f32 v[90:91], v[38:39], v[96:97], v[90:91] op_sel:[1,0,0]
	v_cvt_f32_ubyte0_e32 v102, v83
	v_cvt_f32_ubyte1_e32 v103, v83
	v_pk_fma_f32 v[88:89], v[38:39], v[100:101], v[88:89] op_sel:[1,0,0]
	v_cvt_f32_ubyte2_e32 v126, v83
	v_cvt_f32_ubyte3_e32 v127, v83
	v_pk_fma_f32 v[84:85], v[46:47], v[102:103], v[84:85] op_sel:[1,0,0]
	v_cvt_f32_ubyte0_e32 v96, v86
	v_cvt_f32_ubyte1_e32 v97, v86
	v_pk_fma_f32 v[80:81], v[46:47], v[126:127], v[80:81] op_sel:[1,0,0]
	v_cvt_f32_ubyte2_e32 v100, v86
	v_cvt_f32_ubyte3_e32 v101, v86
	v_pk_fma_f32 v[76:77], v[38:39], v[96:97], v[76:77] op_sel:[1,0,0]
	v_cvt_f32_ubyte0_e32 v102, v87
	v_cvt_f32_ubyte1_e32 v103, v87
	v_pk_fma_f32 v[68:69], v[38:39], v[100:101], v[68:69] op_sel:[1,0,0]
	v_cvt_f32_ubyte2_e32 v126, v87
	v_cvt_f32_ubyte3_e32 v127, v87
	v_pk_fma_f32 v[62:63], v[46:47], v[102:103], v[62:63] op_sel:[1,0,0]
	v_pk_fma_f32 v[60:61], v[46:47], v[126:127], v[60:61] op_sel:[1,0,0]
	s_waitcnt lgkmcnt(0)
	v_lshl_add_u32 v70, v70, 9, v98
	v_lshl_add_u32 v71, v71, 9, v98
	v_lshl_add_u32 v72, v72, 9, v98
	v_lshl_add_u32 v73, v73, 9, v98
	v_lshl_add_u32 v92, v92, 9, v98
	v_lshl_add_u32 v93, v93, 9, v98
	v_lshl_add_u32 v94, v94, 9, v98
	v_lshl_add_u32 v95, v95, 9, v98
	global_load_dwordx2 v[146:147], v70, s[36:37]
	global_load_dwordx2 v[148:149], v71, s[36:37]
	global_load_dwordx2 v[150:151], v72, s[36:37]
	global_load_dwordx2 v[152:153], v73, s[36:37]
	global_load_dwordx2 v[154:155], v92, s[36:37]
	global_load_dwordx2 v[156:157], v93, s[36:37]
	global_load_dwordx2 v[158:159], v94, s[36:37]
	global_load_dwordx2 v[160:161], v95, s[36:37]
	ds_read_b128 v[70:73], v128 offset:416
	ds_read_b128 v[92:95], v128 offset:432
	ds_read_b128 v[32:35], v128 offset:768
	ds_read_b128 v[36:39], v128 offset:784
	ds_read_b128 v[40:43], v128 offset:1792
	ds_read_b128 v[44:47], v128 offset:1808
	s_waitcnt vmcnt(40)
	v_and_b32_e32 v74, s34, v162
	v_and_b32_e32 v75, s35, v162
	v_and_b32_e32 v78, s34, v163
	v_and_b32_e32 v79, s35, v163
	v_cvt_f32_ubyte0_e32 v96, v74
	v_cvt_f32_ubyte1_e32 v97, v74
	v_cvt_f32_ubyte2_e32 v100, v74
	v_cvt_f32_ubyte3_e32 v101, v74
	v_pk_fma_f32 v[90:91], v[48:49], v[96:97], v[90:91] op_sel_hi:[0,1,1]
	v_cvt_f32_ubyte0_e32 v102, v75
	v_cvt_f32_ubyte1_e32 v103, v75
	v_pk_fma_f32 v[88:89], v[48:49], v[100:101], v[88:89] op_sel_hi:[0,1,1]
	v_cvt_f32_ubyte2_e32 v126, v75
	v_cvt_f32_ubyte3_e32 v127, v75
	v_pk_fma_f32 v[84:85], v[56:57], v[102:103], v[84:85] op_sel_hi:[0,1,1]
	v_cvt_f32_ubyte0_e32 v96, v78
	v_cvt_f32_ubyte1_e32 v97, v78
	v_pk_fma_f32 v[80:81], v[56:57], v[126:127], v[80:81] op_sel_hi:[0,1,1]
	v_and_b32_e32 v82, s34, v164
	v_and_b32_e32 v83, s35, v164
	v_and_b32_e32 v86, s34, v165
	v_and_b32_e32 v87, s35, v165
	v_cvt_f32_ubyte2_e32 v100, v78
	v_cvt_f32_ubyte3_e32 v101, v78
	v_pk_fma_f32 v[76:77], v[48:49], v[96:97], v[76:77] op_sel_hi:[0,1,1]
	v_cvt_f32_ubyte0_e32 v102, v79
	v_cvt_f32_ubyte1_e32 v103, v79
	v_pk_fma_f32 v[68:69], v[48:49], v[100:101], v[68:69] op_sel_hi:[0,1,1]
	v_cvt_f32_ubyte2_e32 v126, v79
	v_cvt_f32_ubyte3_e32 v127, v79
	v_pk_fma_f32 v[62:63], v[56:57], v[102:103], v[62:63] op_sel_hi:[0,1,1]
	v_cvt_f32_ubyte0_e32 v96, v82
	v_cvt_f32_ubyte1_e32 v97, v82
	v_pk_fma_f32 v[60:61], v[56:57], v[126:127], v[60:61] op_sel_hi:[0,1,1]
	v_cvt_f32_ubyte2_e32 v100, v82
	v_cvt_f32_ubyte3_e32 v101, v82
	v_pk_fma_f32 v[90:91], v[48:49], v[96:97], v[90:91] op_sel:[1,0,0]
	v_cvt_f32_ubyte0_e32 v102, v83
	v_cvt_f32_ubyte1_e32 v103, v83
	v_pk_fma_f32 v[88:89], v[48:49], v[100:101], v[88:89] op_sel:[1,0,0]
	v_cvt_f32_ubyte2_e32 v126, v83
	v_cvt_f32_ubyte3_e32 v127, v83
	v_pk_fma_f32 v[84:85], v[56:57], v[102:103], v[84:85] op_sel:[1,0,0]
	v_cvt_f32_ubyte0_e32 v96, v86
	v_cvt_f32_ubyte1_e32 v97, v86
	v_pk_fma_f32 v[80:81], v[56:57], v[126:127], v[80:81] op_sel:[1,0,0]
	v_and_b32_e32 v74, s34, v166
	v_and_b32_e32 v75, s35, v166
	v_and_b32_e32 v78, s34, v167
	v_and_b32_e32 v79, s35, v167
	v_cvt_f32_ubyte2_e32 v100, v86
	v_cvt_f32_ubyte3_e32 v101, v86
	v_pk_fma_f32 v[76:77], v[48:49], v[96:97], v[76:77] op_sel:[1,0,0]
	v_cvt_f32_ubyte0_e32 v102, v87
	v_cvt_f32_ubyte1_e32 v103, v87
	v_pk_fma_f32 v[68:69], v[48:49], v[100:101], v[68:69] op_sel:[1,0,0]
	v_cvt_f32_ubyte2_e32 v126, v87
	v_cvt_f32_ubyte3_e32 v127, v87
	v_pk_fma_f32 v[62:63], v[56:57], v[102:103], v[62:63] op_sel:[1,0,0]
	v_cvt_f32_ubyte0_e32 v96, v74
	v_cvt_f32_ubyte1_e32 v97, v74
	v_pk_fma_f32 v[60:61], v[56:57], v[126:127], v[60:61] op_sel:[1,0,0]
	v_cvt_f32_ubyte2_e32 v100, v74
	v_cvt_f32_ubyte3_e32 v101, v74
	v_pk_fma_f32 v[90:91], v[50:51], v[96:97], v[90:91] op_sel_hi:[0,1,1]
	v_cvt_f32_ubyte0_e32 v102, v75
	v_cvt_f32_ubyte1_e32 v103, v75
	v_pk_fma_f32 v[88:89], v[50:51], v[100:101], v[88:89] op_sel_hi:[0,1,1]
	v_cvt_f32_ubyte2_e32 v126, v75
	v_cvt_f32_ubyte3_e32 v127, v75
	v_pk_fma_f32 v[84:85], v[58:59], v[102:103], v[84:85] op_sel_hi:[0,1,1]
	v_cvt_f32_ubyte0_e32 v96, v78
	v_cvt_f32_ubyte1_e32 v97, v78
	v_pk_fma_f32 v[80:81], v[58:59], v[126:127], v[80:81] op_sel_hi:[0,1,1]
	v_and_b32_e32 v82, s34, v168
	v_and_b32_e32 v83, s35, v168
	v_and_b32_e32 v86, s34, v169
	v_and_b32_e32 v87, s35, v169
	v_cvt_f32_ubyte2_e32 v100, v78
	v_cvt_f32_ubyte3_e32 v101, v78
	v_pk_fma_f32 v[76:77], v[50:51], v[96:97], v[76:77] op_sel_hi:[0,1,1]
	v_cvt_f32_ubyte0_e32 v102, v79
	v_cvt_f32_ubyte1_e32 v103, v79
	v_pk_fma_f32 v[68:69], v[50:51], v[100:101], v[68:69] op_sel_hi:[0,1,1]
	v_cvt_f32_ubyte2_e32 v126, v79
	v_cvt_f32_ubyte3_e32 v127, v79
	v_pk_fma_f32 v[62:63], v[58:59], v[102:103], v[62:63] op_sel_hi:[0,1,1]
	v_cvt_f32_ubyte0_e32 v96, v82
	v_cvt_f32_ubyte1_e32 v97, v82
	v_pk_fma_f32 v[60:61], v[58:59], v[126:127], v[60:61] op_sel_hi:[0,1,1]
	v_cvt_f32_ubyte2_e32 v100, v82
	v_cvt_f32_ubyte3_e32 v101, v82
	v_pk_fma_f32 v[90:91], v[50:51], v[96:97], v[90:91] op_sel:[1,0,0]
	v_cvt_f32_ubyte0_e32 v102, v83
	v_cvt_f32_ubyte1_e32 v103, v83
	v_pk_fma_f32 v[88:89], v[50:51], v[100:101], v[88:89] op_sel:[1,0,0]
	v_cvt_f32_ubyte2_e32 v126, v83
	v_cvt_f32_ubyte3_e32 v127, v83
	v_pk_fma_f32 v[84:85], v[58:59], v[102:103], v[84:85] op_sel:[1,0,0]
	v_cvt_f32_ubyte0_e32 v96, v86
	v_cvt_f32_ubyte1_e32 v97, v86
	v_pk_fma_f32 v[80:81], v[58:59], v[126:127], v[80:81] op_sel:[1,0,0]
	v_and_b32_e32 v74, s34, v170
	v_and_b32_e32 v75, s35, v170
	v_and_b32_e32 v78, s34, v171
	v_and_b32_e32 v79, s35, v171
	v_cvt_f32_ubyte2_e32 v100, v86
	v_cvt_f32_ubyte3_e32 v101, v86
	v_pk_fma_f32 v[76:77], v[50:51], v[96:97], v[76:77] op_sel:[1,0,0]
	v_cvt_f32_ubyte0_e32 v102, v87
	v_cvt_f32_ubyte1_e32 v103, v87
	v_pk_fma_f32 v[68:69], v[50:51], v[100:101], v[68:69] op_sel:[1,0,0]
	v_cvt_f32_ubyte2_e32 v126, v87
	v_cvt_f32_ubyte3_e32 v127, v87
	v_pk_fma_f32 v[62:63], v[58:59], v[102:103], v[62:63] op_sel:[1,0,0]
	v_cvt_f32_ubyte0_e32 v96, v74
	v_cvt_f32_ubyte1_e32 v97, v74
	v_pk_fma_f32 v[60:61], v[58:59], v[126:127], v[60:61] op_sel:[1,0,0]
	v_cvt_f32_ubyte2_e32 v100, v74
	v_cvt_f32_ubyte3_e32 v101, v74
	v_pk_fma_f32 v[90:91], v[52:53], v[96:97], v[90:91] op_sel_hi:[0,1,1]
	v_cvt_f32_ubyte0_e32 v102, v75
	v_cvt_f32_ubyte1_e32 v103, v75
	v_pk_fma_f32 v[88:89], v[52:53], v[100:101], v[88:89] op_sel_hi:[0,1,1]
	v_cvt_f32_ubyte2_e32 v126, v75
	v_cvt_f32_ubyte3_e32 v127, v75
	v_pk_fma_f32 v[84:85], v[64:65], v[102:103], v[84:85] op_sel_hi:[0,1,1]
	v_cvt_f32_ubyte0_e32 v96, v78
	v_cvt_f32_ubyte1_e32 v97, v78
	v_pk_fma_f32 v[80:81], v[64:65], v[126:127], v[80:81] op_sel_hi:[0,1,1]
	v_and_b32_e32 v82, s34, v172
	v_and_b32_e32 v83, s35, v172
	v_and_b32_e32 v86, s34, v173
	v_and_b32_e32 v87, s35, v173
	v_cvt_f32_ubyte2_e32 v100, v78
	v_cvt_f32_ubyte3_e32 v101, v78
	v_pk_fma_f32 v[76:77], v[52:53], v[96:97], v[76:77] op_sel_hi:[0,1,1]
	v_cvt_f32_ubyte0_e32 v102, v79
	v_cvt_f32_ubyte1_e32 v103, v79
	v_pk_fma_f32 v[68:69], v[52:53], v[100:101], v[68:69] op_sel_hi:[0,1,1]
	v_cvt_f32_ubyte2_e32 v126, v79
	v_cvt_f32_ubyte3_e32 v127, v79
	v_pk_fma_f32 v[62:63], v[64:65], v[102:103], v[62:63] op_sel_hi:[0,1,1]
	v_cvt_f32_ubyte0_e32 v96, v82
	v_cvt_f32_ubyte1_e32 v97, v82
	v_pk_fma_f32 v[60:61], v[64:65], v[126:127], v[60:61] op_sel_hi:[0,1,1]
	v_cvt_f32_ubyte2_e32 v100, v82
	v_cvt_f32_ubyte3_e32 v101, v82
	v_pk_fma_f32 v[90:91], v[52:53], v[96:97], v[90:91] op_sel:[1,0,0]
	v_cvt_f32_ubyte0_e32 v102, v83
	v_cvt_f32_ubyte1_e32 v103, v83
	v_pk_fma_f32 v[88:89], v[52:53], v[100:101], v[88:89] op_sel:[1,0,0]
	v_cvt_f32_ubyte2_e32 v126, v83
	v_cvt_f32_ubyte3_e32 v127, v83
	v_pk_fma_f32 v[84:85], v[64:65], v[102:103], v[84:85] op_sel:[1,0,0]
	v_cvt_f32_ubyte0_e32 v96, v86
	v_cvt_f32_ubyte1_e32 v97, v86
	v_pk_fma_f32 v[80:81], v[64:65], v[126:127], v[80:81] op_sel:[1,0,0]
	v_and_b32_e32 v74, s34, v174
	v_and_b32_e32 v75, s35, v174
	v_and_b32_e32 v78, s34, v175
	v_and_b32_e32 v79, s35, v175
	v_cvt_f32_ubyte2_e32 v100, v86
	v_cvt_f32_ubyte3_e32 v101, v86
	v_pk_fma_f32 v[76:77], v[52:53], v[96:97], v[76:77] op_sel:[1,0,0]
	v_cvt_f32_ubyte0_e32 v102, v87
	v_cvt_f32_ubyte1_e32 v103, v87
	v_pk_fma_f32 v[68:69], v[52:53], v[100:101], v[68:69] op_sel:[1,0,0]
	v_cvt_f32_ubyte2_e32 v126, v87
	v_cvt_f32_ubyte3_e32 v127, v87
	v_pk_fma_f32 v[62:63], v[64:65], v[102:103], v[62:63] op_sel:[1,0,0]
	v_cvt_f32_ubyte0_e32 v96, v74
	v_cvt_f32_ubyte1_e32 v97, v74
	v_pk_fma_f32 v[60:61], v[64:65], v[126:127], v[60:61] op_sel:[1,0,0]
	v_cvt_f32_ubyte2_e32 v100, v74
	v_cvt_f32_ubyte3_e32 v101, v74
	v_pk_fma_f32 v[90:91], v[54:55], v[96:97], v[90:91] op_sel_hi:[0,1,1]
	v_cvt_f32_ubyte0_e32 v102, v75
	v_cvt_f32_ubyte1_e32 v103, v75
	v_pk_fma_f32 v[88:89], v[54:55], v[100:101], v[88:89] op_sel_hi:[0,1,1]
	v_cvt_f32_ubyte2_e32 v126, v75
	v_cvt_f32_ubyte3_e32 v127, v75
	v_pk_fma_f32 v[84:85], v[66:67], v[102:103], v[84:85] op_sel_hi:[0,1,1]
	v_cvt_f32_ubyte0_e32 v96, v78
	v_cvt_f32_ubyte1_e32 v97, v78
	v_pk_fma_f32 v[80:81], v[66:67], v[126:127], v[80:81] op_sel_hi:[0,1,1]
	v_and_b32_e32 v82, s34, v176
	v_and_b32_e32 v83, s35, v176
	v_and_b32_e32 v86, s34, v177
	v_and_b32_e32 v87, s35, v177
	v_cvt_f32_ubyte2_e32 v100, v78
	v_cvt_f32_ubyte3_e32 v101, v78
	v_pk_fma_f32 v[76:77], v[54:55], v[96:97], v[76:77] op_sel_hi:[0,1,1]
	v_cvt_f32_ubyte0_e32 v102, v79
	v_cvt_f32_ubyte1_e32 v103, v79
	v_pk_fma_f32 v[68:69], v[54:55], v[100:101], v[68:69] op_sel_hi:[0,1,1]
	v_cvt_f32_ubyte2_e32 v126, v79
	v_cvt_f32_ubyte3_e32 v127, v79
	v_pk_fma_f32 v[62:63], v[66:67], v[102:103], v[62:63] op_sel_hi:[0,1,1]
	v_cvt_f32_ubyte0_e32 v96, v82
	v_cvt_f32_ubyte1_e32 v97, v82
	v_pk_fma_f32 v[60:61], v[66:67], v[126:127], v[60:61] op_sel_hi:[0,1,1]
	v_cvt_f32_ubyte2_e32 v100, v82
	v_cvt_f32_ubyte3_e32 v101, v82
	v_pk_fma_f32 v[90:91], v[54:55], v[96:97], v[90:91] op_sel:[1,0,0]
	v_cvt_f32_ubyte0_e32 v102, v83
	v_cvt_f32_ubyte1_e32 v103, v83
	v_pk_fma_f32 v[88:89], v[54:55], v[100:101], v[88:89] op_sel:[1,0,0]
	v_cvt_f32_ubyte2_e32 v126, v83
	v_cvt_f32_ubyte3_e32 v127, v83
	v_pk_fma_f32 v[84:85], v[66:67], v[102:103], v[84:85] op_sel:[1,0,0]
	v_cvt_f32_ubyte0_e32 v96, v86
	v_cvt_f32_ubyte1_e32 v97, v86
	v_pk_fma_f32 v[80:81], v[66:67], v[126:127], v[80:81] op_sel:[1,0,0]
	v_cvt_f32_ubyte2_e32 v100, v86
	v_cvt_f32_ubyte3_e32 v101, v86
	v_pk_fma_f32 v[76:77], v[54:55], v[96:97], v[76:77] op_sel:[1,0,0]
	v_cvt_f32_ubyte0_e32 v102, v87
	v_cvt_f32_ubyte1_e32 v103, v87
	v_pk_fma_f32 v[68:69], v[54:55], v[100:101], v[68:69] op_sel:[1,0,0]
	v_cvt_f32_ubyte2_e32 v126, v87
	v_cvt_f32_ubyte3_e32 v127, v87
	v_pk_fma_f32 v[62:63], v[66:67], v[102:103], v[62:63] op_sel:[1,0,0]
	v_pk_fma_f32 v[60:61], v[66:67], v[126:127], v[60:61] op_sel:[1,0,0]
	s_waitcnt lgkmcnt(0)
	v_lshl_add_u32 v70, v70, 9, v98
	v_lshl_add_u32 v71, v71, 9, v98
	v_lshl_add_u32 v72, v72, 9, v98
	v_lshl_add_u32 v73, v73, 9, v98
	v_lshl_add_u32 v92, v92, 9, v98
	v_lshl_add_u32 v93, v93, 9, v98
	v_lshl_add_u32 v94, v94, 9, v98
	v_lshl_add_u32 v95, v95, 9, v98
	global_load_dwordx2 v[162:163], v70, s[36:37]
	global_load_dwordx2 v[164:165], v71, s[36:37]
	global_load_dwordx2 v[166:167], v72, s[36:37]
	global_load_dwordx2 v[168:169], v73, s[36:37]
	global_load_dwordx2 v[170:171], v92, s[36:37]
	global_load_dwordx2 v[172:173], v93, s[36:37]
	global_load_dwordx2 v[174:175], v94, s[36:37]
	global_load_dwordx2 v[176:177], v95, s[36:37]
	ds_read_b128 v[70:73], v128 offset:448
	ds_read_b128 v[92:95], v128 offset:464
	ds_read_b128 v[48:51], v128 offset:800
	ds_read_b128 v[52:55], v128 offset:816
	ds_read_b128 v[56:59], v128 offset:1824
	ds_read_b128 v[64:67], v128 offset:1840
	s_waitcnt vmcnt(40)
	v_and_b32_e32 v74, s34, v178
	v_and_b32_e32 v75, s35, v178
	v_and_b32_e32 v78, s34, v179
	v_and_b32_e32 v79, s35, v179
	v_cvt_f32_ubyte0_e32 v96, v74
	v_cvt_f32_ubyte1_e32 v97, v74
	v_cvt_f32_ubyte2_e32 v100, v74
	v_cvt_f32_ubyte3_e32 v101, v74
	v_pk_fma_f32 v[90:91], v[32:33], v[96:97], v[90:91] op_sel_hi:[0,1,1]
	v_cvt_f32_ubyte0_e32 v102, v75
	v_cvt_f32_ubyte1_e32 v103, v75
	v_pk_fma_f32 v[88:89], v[32:33], v[100:101], v[88:89] op_sel_hi:[0,1,1]
	v_cvt_f32_ubyte2_e32 v126, v75
	v_cvt_f32_ubyte3_e32 v127, v75
	v_pk_fma_f32 v[84:85], v[40:41], v[102:103], v[84:85] op_sel_hi:[0,1,1]
	v_cvt_f32_ubyte0_e32 v96, v78
	v_cvt_f32_ubyte1_e32 v97, v78
	v_pk_fma_f32 v[80:81], v[40:41], v[126:127], v[80:81] op_sel_hi:[0,1,1]
	v_and_b32_e32 v82, s34, v180
	v_and_b32_e32 v83, s35, v180
	v_and_b32_e32 v86, s34, v181
	v_and_b32_e32 v87, s35, v181
	v_cvt_f32_ubyte2_e32 v100, v78
	v_cvt_f32_ubyte3_e32 v101, v78
	v_pk_fma_f32 v[76:77], v[32:33], v[96:97], v[76:77] op_sel_hi:[0,1,1]
	v_cvt_f32_ubyte0_e32 v102, v79
	v_cvt_f32_ubyte1_e32 v103, v79
	v_pk_fma_f32 v[68:69], v[32:33], v[100:101], v[68:69] op_sel_hi:[0,1,1]
	v_cvt_f32_ubyte2_e32 v126, v79
	v_cvt_f32_ubyte3_e32 v127, v79
	v_pk_fma_f32 v[62:63], v[40:41], v[102:103], v[62:63] op_sel_hi:[0,1,1]
	v_cvt_f32_ubyte0_e32 v96, v82
	v_cvt_f32_ubyte1_e32 v97, v82
	v_pk_fma_f32 v[60:61], v[40:41], v[126:127], v[60:61] op_sel_hi:[0,1,1]
	v_cvt_f32_ubyte2_e32 v100, v82
	v_cvt_f32_ubyte3_e32 v101, v82
	v_pk_fma_f32 v[90:91], v[32:33], v[96:97], v[90:91] op_sel:[1,0,0]
	v_cvt_f32_ubyte0_e32 v102, v83
	v_cvt_f32_ubyte1_e32 v103, v83
	v_pk_fma_f32 v[88:89], v[32:33], v[100:101], v[88:89] op_sel:[1,0,0]
	v_cvt_f32_ubyte2_e32 v126, v83
	v_cvt_f32_ubyte3_e32 v127, v83
	v_pk_fma_f32 v[84:85], v[40:41], v[102:103], v[84:85] op_sel:[1,0,0]
	v_cvt_f32_ubyte0_e32 v96, v86
	v_cvt_f32_ubyte1_e32 v97, v86
	v_pk_fma_f32 v[80:81], v[40:41], v[126:127], v[80:81] op_sel:[1,0,0]
	v_and_b32_e32 v74, s34, v182
	v_and_b32_e32 v75, s35, v182
	v_and_b32_e32 v78, s34, v183
	v_and_b32_e32 v79, s35, v183
	v_cvt_f32_ubyte2_e32 v100, v86
	v_cvt_f32_ubyte3_e32 v101, v86
	v_pk_fma_f32 v[76:77], v[32:33], v[96:97], v[76:77] op_sel:[1,0,0]
	v_cvt_f32_ubyte0_e32 v102, v87
	v_cvt_f32_ubyte1_e32 v103, v87
	v_pk_fma_f32 v[68:69], v[32:33], v[100:101], v[68:69] op_sel:[1,0,0]
	v_cvt_f32_ubyte2_e32 v126, v87
	v_cvt_f32_ubyte3_e32 v127, v87
	v_pk_fma_f32 v[62:63], v[40:41], v[102:103], v[62:63] op_sel:[1,0,0]
	v_cvt_f32_ubyte0_e32 v96, v74
	v_cvt_f32_ubyte1_e32 v97, v74
	v_pk_fma_f32 v[60:61], v[40:41], v[126:127], v[60:61] op_sel:[1,0,0]
	v_cvt_f32_ubyte2_e32 v100, v74
	v_cvt_f32_ubyte3_e32 v101, v74
	v_pk_fma_f32 v[90:91], v[34:35], v[96:97], v[90:91] op_sel_hi:[0,1,1]
	v_cvt_f32_ubyte0_e32 v102, v75
	v_cvt_f32_ubyte1_e32 v103, v75
	v_pk_fma_f32 v[88:89], v[34:35], v[100:101], v[88:89] op_sel_hi:[0,1,1]
	v_cvt_f32_ubyte2_e32 v126, v75
	v_cvt_f32_ubyte3_e32 v127, v75
	v_pk_fma_f32 v[84:85], v[42:43], v[102:103], v[84:85] op_sel_hi:[0,1,1]
	v_cvt_f32_ubyte0_e32 v96, v78
	v_cvt_f32_ubyte1_e32 v97, v78
	v_pk_fma_f32 v[80:81], v[42:43], v[126:127], v[80:81] op_sel_hi:[0,1,1]
	v_and_b32_e32 v82, s34, v184
	v_and_b32_e32 v83, s35, v184
	v_and_b32_e32 v86, s34, v185
	v_and_b32_e32 v87, s35, v185
	v_cvt_f32_ubyte2_e32 v100, v78
	v_cvt_f32_ubyte3_e32 v101, v78
	v_pk_fma_f32 v[76:77], v[34:35], v[96:97], v[76:77] op_sel_hi:[0,1,1]
	v_cvt_f32_ubyte0_e32 v102, v79
	v_cvt_f32_ubyte1_e32 v103, v79
	v_pk_fma_f32 v[68:69], v[34:35], v[100:101], v[68:69] op_sel_hi:[0,1,1]
	v_cvt_f32_ubyte2_e32 v126, v79
	v_cvt_f32_ubyte3_e32 v127, v79
	v_pk_fma_f32 v[62:63], v[42:43], v[102:103], v[62:63] op_sel_hi:[0,1,1]
	v_cvt_f32_ubyte0_e32 v96, v82
	v_cvt_f32_ubyte1_e32 v97, v82
	v_pk_fma_f32 v[60:61], v[42:43], v[126:127], v[60:61] op_sel_hi:[0,1,1]
	v_cvt_f32_ubyte2_e32 v100, v82
	v_cvt_f32_ubyte3_e32 v101, v82
	v_pk_fma_f32 v[90:91], v[34:35], v[96:97], v[90:91] op_sel:[1,0,0]
	v_cvt_f32_ubyte0_e32 v102, v83
	v_cvt_f32_ubyte1_e32 v103, v83
	v_pk_fma_f32 v[88:89], v[34:35], v[100:101], v[88:89] op_sel:[1,0,0]
	v_cvt_f32_ubyte2_e32 v126, v83
	v_cvt_f32_ubyte3_e32 v127, v83
	v_pk_fma_f32 v[84:85], v[42:43], v[102:103], v[84:85] op_sel:[1,0,0]
	v_cvt_f32_ubyte0_e32 v96, v86
	v_cvt_f32_ubyte1_e32 v97, v86
	v_pk_fma_f32 v[80:81], v[42:43], v[126:127], v[80:81] op_sel:[1,0,0]
	v_and_b32_e32 v74, s34, v186
	v_and_b32_e32 v75, s35, v186
	v_and_b32_e32 v78, s34, v187
	v_and_b32_e32 v79, s35, v187
	v_cvt_f32_ubyte2_e32 v100, v86
	v_cvt_f32_ubyte3_e32 v101, v86
	v_pk_fma_f32 v[76:77], v[34:35], v[96:97], v[76:77] op_sel:[1,0,0]
	v_cvt_f32_ubyte0_e32 v102, v87
	v_cvt_f32_ubyte1_e32 v103, v87
	v_pk_fma_f32 v[68:69], v[34:35], v[100:101], v[68:69] op_sel:[1,0,0]
	v_cvt_f32_ubyte2_e32 v126, v87
	v_cvt_f32_ubyte3_e32 v127, v87
	v_pk_fma_f32 v[62:63], v[42:43], v[102:103], v[62:63] op_sel:[1,0,0]
	v_cvt_f32_ubyte0_e32 v96, v74
	v_cvt_f32_ubyte1_e32 v97, v74
	v_pk_fma_f32 v[60:61], v[42:43], v[126:127], v[60:61] op_sel:[1,0,0]
	v_cvt_f32_ubyte2_e32 v100, v74
	v_cvt_f32_ubyte3_e32 v101, v74
	v_pk_fma_f32 v[90:91], v[36:37], v[96:97], v[90:91] op_sel_hi:[0,1,1]
	v_cvt_f32_ubyte0_e32 v102, v75
	v_cvt_f32_ubyte1_e32 v103, v75
	v_pk_fma_f32 v[88:89], v[36:37], v[100:101], v[88:89] op_sel_hi:[0,1,1]
	v_cvt_f32_ubyte2_e32 v126, v75
	v_cvt_f32_ubyte3_e32 v127, v75
	v_pk_fma_f32 v[84:85], v[44:45], v[102:103], v[84:85] op_sel_hi:[0,1,1]
	v_cvt_f32_ubyte0_e32 v96, v78
	v_cvt_f32_ubyte1_e32 v97, v78
	v_pk_fma_f32 v[80:81], v[44:45], v[126:127], v[80:81] op_sel_hi:[0,1,1]
	v_and_b32_e32 v82, s34, v188
	v_and_b32_e32 v83, s35, v188
	v_and_b32_e32 v86, s34, v189
	v_and_b32_e32 v87, s35, v189
	v_cvt_f32_ubyte2_e32 v100, v78
	v_cvt_f32_ubyte3_e32 v101, v78
	v_pk_fma_f32 v[76:77], v[36:37], v[96:97], v[76:77] op_sel_hi:[0,1,1]
	v_cvt_f32_ubyte0_e32 v102, v79
	v_cvt_f32_ubyte1_e32 v103, v79
	v_pk_fma_f32 v[68:69], v[36:37], v[100:101], v[68:69] op_sel_hi:[0,1,1]
	v_cvt_f32_ubyte2_e32 v126, v79
	v_cvt_f32_ubyte3_e32 v127, v79
	v_pk_fma_f32 v[62:63], v[44:45], v[102:103], v[62:63] op_sel_hi:[0,1,1]
	v_cvt_f32_ubyte0_e32 v96, v82
	v_cvt_f32_ubyte1_e32 v97, v82
	v_pk_fma_f32 v[60:61], v[44:45], v[126:127], v[60:61] op_sel_hi:[0,1,1]
	v_cvt_f32_ubyte2_e32 v100, v82
	v_cvt_f32_ubyte3_e32 v101, v82
	v_pk_fma_f32 v[90:91], v[36:37], v[96:97], v[90:91] op_sel:[1,0,0]
	v_cvt_f32_ubyte0_e32 v102, v83
	v_cvt_f32_ubyte1_e32 v103, v83
	v_pk_fma_f32 v[88:89], v[36:37], v[100:101], v[88:89] op_sel:[1,0,0]
	v_cvt_f32_ubyte2_e32 v126, v83
	v_cvt_f32_ubyte3_e32 v127, v83
	v_pk_fma_f32 v[84:85], v[44:45], v[102:103], v[84:85] op_sel:[1,0,0]
	v_cvt_f32_ubyte0_e32 v96, v86
	v_cvt_f32_ubyte1_e32 v97, v86
	v_pk_fma_f32 v[80:81], v[44:45], v[126:127], v[80:81] op_sel:[1,0,0]
	v_and_b32_e32 v74, s34, v190
	v_and_b32_e32 v75, s35, v190
	v_and_b32_e32 v78, s34, v191
	v_and_b32_e32 v79, s35, v191
	v_cvt_f32_ubyte2_e32 v100, v86
	v_cvt_f32_ubyte3_e32 v101, v86
	v_pk_fma_f32 v[76:77], v[36:37], v[96:97], v[76:77] op_sel:[1,0,0]
	v_cvt_f32_ubyte0_e32 v102, v87
	v_cvt_f32_ubyte1_e32 v103, v87
	v_pk_fma_f32 v[68:69], v[36:37], v[100:101], v[68:69] op_sel:[1,0,0]
	v_cvt_f32_ubyte2_e32 v126, v87
	v_cvt_f32_ubyte3_e32 v127, v87
	v_pk_fma_f32 v[62:63], v[44:45], v[102:103], v[62:63] op_sel:[1,0,0]
	v_cvt_f32_ubyte0_e32 v96, v74
	v_cvt_f32_ubyte1_e32 v97, v74
	v_pk_fma_f32 v[60:61], v[44:45], v[126:127], v[60:61] op_sel:[1,0,0]
	v_cvt_f32_ubyte2_e32 v100, v74
	v_cvt_f32_ubyte3_e32 v101, v74
	v_pk_fma_f32 v[90:91], v[38:39], v[96:97], v[90:91] op_sel_hi:[0,1,1]
	v_cvt_f32_ubyte0_e32 v102, v75
	v_cvt_f32_ubyte1_e32 v103, v75
	v_pk_fma_f32 v[88:89], v[38:39], v[100:101], v[88:89] op_sel_hi:[0,1,1]
	v_cvt_f32_ubyte2_e32 v126, v75
	v_cvt_f32_ubyte3_e32 v127, v75
	v_pk_fma_f32 v[84:85], v[46:47], v[102:103], v[84:85] op_sel_hi:[0,1,1]
	v_cvt_f32_ubyte0_e32 v96, v78
	v_cvt_f32_ubyte1_e32 v97, v78
	v_pk_fma_f32 v[80:81], v[46:47], v[126:127], v[80:81] op_sel_hi:[0,1,1]
	v_and_b32_e32 v82, s34, v192
	v_and_b32_e32 v83, s35, v192
	v_and_b32_e32 v86, s34, v193
	v_and_b32_e32 v87, s35, v193
	v_cvt_f32_ubyte2_e32 v100, v78
	v_cvt_f32_ubyte3_e32 v101, v78
	v_pk_fma_f32 v[76:77], v[38:39], v[96:97], v[76:77] op_sel_hi:[0,1,1]
	v_cvt_f32_ubyte0_e32 v102, v79
	v_cvt_f32_ubyte1_e32 v103, v79
	v_pk_fma_f32 v[68:69], v[38:39], v[100:101], v[68:69] op_sel_hi:[0,1,1]
	v_cvt_f32_ubyte2_e32 v126, v79
	v_cvt_f32_ubyte3_e32 v127, v79
	v_pk_fma_f32 v[62:63], v[46:47], v[102:103], v[62:63] op_sel_hi:[0,1,1]
	v_cvt_f32_ubyte0_e32 v96, v82
	v_cvt_f32_ubyte1_e32 v97, v82
	v_pk_fma_f32 v[60:61], v[46:47], v[126:127], v[60:61] op_sel_hi:[0,1,1]
	v_cvt_f32_ubyte2_e32 v100, v82
	v_cvt_f32_ubyte3_e32 v101, v82
	v_pk_fma_f32 v[90:91], v[38:39], v[96:97], v[90:91] op_sel:[1,0,0]
	v_cvt_f32_ubyte0_e32 v102, v83
	v_cvt_f32_ubyte1_e32 v103, v83
	v_pk_fma_f32 v[88:89], v[38:39], v[100:101], v[88:89] op_sel:[1,0,0]
	v_cvt_f32_ubyte2_e32 v126, v83
	v_cvt_f32_ubyte3_e32 v127, v83
	v_pk_fma_f32 v[84:85], v[46:47], v[102:103], v[84:85] op_sel:[1,0,0]
	v_cvt_f32_ubyte0_e32 v96, v86
	v_cvt_f32_ubyte1_e32 v97, v86
	v_pk_fma_f32 v[80:81], v[46:47], v[126:127], v[80:81] op_sel:[1,0,0]
	v_cvt_f32_ubyte2_e32 v100, v86
	v_cvt_f32_ubyte3_e32 v101, v86
	v_pk_fma_f32 v[76:77], v[38:39], v[96:97], v[76:77] op_sel:[1,0,0]
	v_cvt_f32_ubyte0_e32 v102, v87
	v_cvt_f32_ubyte1_e32 v103, v87
	v_pk_fma_f32 v[68:69], v[38:39], v[100:101], v[68:69] op_sel:[1,0,0]
	v_cvt_f32_ubyte2_e32 v126, v87
	v_cvt_f32_ubyte3_e32 v127, v87
	v_pk_fma_f32 v[62:63], v[46:47], v[102:103], v[62:63] op_sel:[1,0,0]
	v_pk_fma_f32 v[60:61], v[46:47], v[126:127], v[60:61] op_sel:[1,0,0]
	s_waitcnt lgkmcnt(0)
	v_lshl_add_u32 v70, v70, 9, v98
	v_lshl_add_u32 v71, v71, 9, v98
	v_lshl_add_u32 v72, v72, 9, v98
	v_lshl_add_u32 v73, v73, 9, v98
	v_lshl_add_u32 v92, v92, 9, v98
	v_lshl_add_u32 v93, v93, 9, v98
	v_lshl_add_u32 v94, v94, 9, v98
	v_lshl_add_u32 v95, v95, 9, v98
	global_load_dwordx2 v[178:179], v70, s[36:37]
	global_load_dwordx2 v[180:181], v71, s[36:37]
	global_load_dwordx2 v[182:183], v72, s[36:37]
	global_load_dwordx2 v[184:185], v73, s[36:37]
	global_load_dwordx2 v[186:187], v92, s[36:37]
	global_load_dwordx2 v[188:189], v93, s[36:37]
	global_load_dwordx2 v[190:191], v94, s[36:37]
	global_load_dwordx2 v[192:193], v95, s[36:37]
	ds_read_b128 v[70:73], v128 offset:480
	ds_read_b128 v[92:95], v128 offset:496
	ds_read_b128 v[32:35], v128 offset:832
	ds_read_b128 v[36:39], v128 offset:848
	ds_read_b128 v[40:43], v128 offset:1856
	ds_read_b128 v[44:47], v128 offset:1872
	s_waitcnt vmcnt(40)
	v_and_b32_e32 v74, s34, v194
	v_and_b32_e32 v75, s35, v194
	v_and_b32_e32 v78, s34, v195
	v_and_b32_e32 v79, s35, v195
	v_cvt_f32_ubyte0_e32 v96, v74
	v_cvt_f32_ubyte1_e32 v97, v74
	v_cvt_f32_ubyte2_e32 v100, v74
	v_cvt_f32_ubyte3_e32 v101, v74
	v_pk_fma_f32 v[90:91], v[48:49], v[96:97], v[90:91] op_sel_hi:[0,1,1]
	v_cvt_f32_ubyte0_e32 v102, v75
	v_cvt_f32_ubyte1_e32 v103, v75
	v_pk_fma_f32 v[88:89], v[48:49], v[100:101], v[88:89] op_sel_hi:[0,1,1]
	v_cvt_f32_ubyte2_e32 v126, v75
	v_cvt_f32_ubyte3_e32 v127, v75
	v_pk_fma_f32 v[84:85], v[56:57], v[102:103], v[84:85] op_sel_hi:[0,1,1]
	v_cvt_f32_ubyte0_e32 v96, v78
	v_cvt_f32_ubyte1_e32 v97, v78
	v_pk_fma_f32 v[80:81], v[56:57], v[126:127], v[80:81] op_sel_hi:[0,1,1]
	v_and_b32_e32 v82, s34, v196
	v_and_b32_e32 v83, s35, v196
	v_and_b32_e32 v86, s34, v197
	v_and_b32_e32 v87, s35, v197
	v_cvt_f32_ubyte2_e32 v100, v78
	v_cvt_f32_ubyte3_e32 v101, v78
	v_pk_fma_f32 v[76:77], v[48:49], v[96:97], v[76:77] op_sel_hi:[0,1,1]
	v_cvt_f32_ubyte0_e32 v102, v79
	v_cvt_f32_ubyte1_e32 v103, v79
	v_pk_fma_f32 v[68:69], v[48:49], v[100:101], v[68:69] op_sel_hi:[0,1,1]
	v_cvt_f32_ubyte2_e32 v126, v79
	v_cvt_f32_ubyte3_e32 v127, v79
	v_pk_fma_f32 v[62:63], v[56:57], v[102:103], v[62:63] op_sel_hi:[0,1,1]
	v_cvt_f32_ubyte0_e32 v96, v82
	v_cvt_f32_ubyte1_e32 v97, v82
	v_pk_fma_f32 v[60:61], v[56:57], v[126:127], v[60:61] op_sel_hi:[0,1,1]
	v_cvt_f32_ubyte2_e32 v100, v82
	v_cvt_f32_ubyte3_e32 v101, v82
	v_pk_fma_f32 v[90:91], v[48:49], v[96:97], v[90:91] op_sel:[1,0,0]
	v_cvt_f32_ubyte0_e32 v102, v83
	v_cvt_f32_ubyte1_e32 v103, v83
	v_pk_fma_f32 v[88:89], v[48:49], v[100:101], v[88:89] op_sel:[1,0,0]
	v_cvt_f32_ubyte2_e32 v126, v83
	v_cvt_f32_ubyte3_e32 v127, v83
	v_pk_fma_f32 v[84:85], v[56:57], v[102:103], v[84:85] op_sel:[1,0,0]
	v_cvt_f32_ubyte0_e32 v96, v86
	v_cvt_f32_ubyte1_e32 v97, v86
	v_pk_fma_f32 v[80:81], v[56:57], v[126:127], v[80:81] op_sel:[1,0,0]
	v_and_b32_e32 v74, s34, v198
	v_and_b32_e32 v75, s35, v198
	v_and_b32_e32 v78, s34, v199
	v_and_b32_e32 v79, s35, v199
	v_cvt_f32_ubyte2_e32 v100, v86
	v_cvt_f32_ubyte3_e32 v101, v86
	v_pk_fma_f32 v[76:77], v[48:49], v[96:97], v[76:77] op_sel:[1,0,0]
	v_cvt_f32_ubyte0_e32 v102, v87
	v_cvt_f32_ubyte1_e32 v103, v87
	v_pk_fma_f32 v[68:69], v[48:49], v[100:101], v[68:69] op_sel:[1,0,0]
	v_cvt_f32_ubyte2_e32 v126, v87
	v_cvt_f32_ubyte3_e32 v127, v87
	v_pk_fma_f32 v[62:63], v[56:57], v[102:103], v[62:63] op_sel:[1,0,0]
	v_cvt_f32_ubyte0_e32 v96, v74
	v_cvt_f32_ubyte1_e32 v97, v74
	v_pk_fma_f32 v[60:61], v[56:57], v[126:127], v[60:61] op_sel:[1,0,0]
	v_cvt_f32_ubyte2_e32 v100, v74
	v_cvt_f32_ubyte3_e32 v101, v74
	v_pk_fma_f32 v[90:91], v[50:51], v[96:97], v[90:91] op_sel_hi:[0,1,1]
	v_cvt_f32_ubyte0_e32 v102, v75
	v_cvt_f32_ubyte1_e32 v103, v75
	v_pk_fma_f32 v[88:89], v[50:51], v[100:101], v[88:89] op_sel_hi:[0,1,1]
	v_cvt_f32_ubyte2_e32 v126, v75
	v_cvt_f32_ubyte3_e32 v127, v75
	v_pk_fma_f32 v[84:85], v[58:59], v[102:103], v[84:85] op_sel_hi:[0,1,1]
	v_cvt_f32_ubyte0_e32 v96, v78
	v_cvt_f32_ubyte1_e32 v97, v78
	v_pk_fma_f32 v[80:81], v[58:59], v[126:127], v[80:81] op_sel_hi:[0,1,1]
	v_and_b32_e32 v82, s34, v200
	v_and_b32_e32 v83, s35, v200
	v_and_b32_e32 v86, s34, v201
	v_and_b32_e32 v87, s35, v201
	v_cvt_f32_ubyte2_e32 v100, v78
	v_cvt_f32_ubyte3_e32 v101, v78
	v_pk_fma_f32 v[76:77], v[50:51], v[96:97], v[76:77] op_sel_hi:[0,1,1]
	v_cvt_f32_ubyte0_e32 v102, v79
	v_cvt_f32_ubyte1_e32 v103, v79
	v_pk_fma_f32 v[68:69], v[50:51], v[100:101], v[68:69] op_sel_hi:[0,1,1]
	v_cvt_f32_ubyte2_e32 v126, v79
	v_cvt_f32_ubyte3_e32 v127, v79
	v_pk_fma_f32 v[62:63], v[58:59], v[102:103], v[62:63] op_sel_hi:[0,1,1]
	v_cvt_f32_ubyte0_e32 v96, v82
	v_cvt_f32_ubyte1_e32 v97, v82
	v_pk_fma_f32 v[60:61], v[58:59], v[126:127], v[60:61] op_sel_hi:[0,1,1]
	v_cvt_f32_ubyte2_e32 v100, v82
	v_cvt_f32_ubyte3_e32 v101, v82
	v_pk_fma_f32 v[90:91], v[50:51], v[96:97], v[90:91] op_sel:[1,0,0]
	v_cvt_f32_ubyte0_e32 v102, v83
	v_cvt_f32_ubyte1_e32 v103, v83
	v_pk_fma_f32 v[88:89], v[50:51], v[100:101], v[88:89] op_sel:[1,0,0]
	v_cvt_f32_ubyte2_e32 v126, v83
	v_cvt_f32_ubyte3_e32 v127, v83
	v_pk_fma_f32 v[84:85], v[58:59], v[102:103], v[84:85] op_sel:[1,0,0]
	v_cvt_f32_ubyte0_e32 v96, v86
	v_cvt_f32_ubyte1_e32 v97, v86
	v_pk_fma_f32 v[80:81], v[58:59], v[126:127], v[80:81] op_sel:[1,0,0]
	v_and_b32_e32 v74, s34, v202
	v_and_b32_e32 v75, s35, v202
	v_and_b32_e32 v78, s34, v203
	v_and_b32_e32 v79, s35, v203
	v_cvt_f32_ubyte2_e32 v100, v86
	v_cvt_f32_ubyte3_e32 v101, v86
	v_pk_fma_f32 v[76:77], v[50:51], v[96:97], v[76:77] op_sel:[1,0,0]
	v_cvt_f32_ubyte0_e32 v102, v87
	v_cvt_f32_ubyte1_e32 v103, v87
	v_pk_fma_f32 v[68:69], v[50:51], v[100:101], v[68:69] op_sel:[1,0,0]
	v_cvt_f32_ubyte2_e32 v126, v87
	v_cvt_f32_ubyte3_e32 v127, v87
	v_pk_fma_f32 v[62:63], v[58:59], v[102:103], v[62:63] op_sel:[1,0,0]
	v_cvt_f32_ubyte0_e32 v96, v74
	v_cvt_f32_ubyte1_e32 v97, v74
	v_pk_fma_f32 v[60:61], v[58:59], v[126:127], v[60:61] op_sel:[1,0,0]
	v_cvt_f32_ubyte2_e32 v100, v74
	v_cvt_f32_ubyte3_e32 v101, v74
	v_pk_fma_f32 v[90:91], v[52:53], v[96:97], v[90:91] op_sel_hi:[0,1,1]
	v_cvt_f32_ubyte0_e32 v102, v75
	v_cvt_f32_ubyte1_e32 v103, v75
	v_pk_fma_f32 v[88:89], v[52:53], v[100:101], v[88:89] op_sel_hi:[0,1,1]
	v_cvt_f32_ubyte2_e32 v126, v75
	v_cvt_f32_ubyte3_e32 v127, v75
	v_pk_fma_f32 v[84:85], v[64:65], v[102:103], v[84:85] op_sel_hi:[0,1,1]
	v_cvt_f32_ubyte0_e32 v96, v78
	v_cvt_f32_ubyte1_e32 v97, v78
	v_pk_fma_f32 v[80:81], v[64:65], v[126:127], v[80:81] op_sel_hi:[0,1,1]
	v_and_b32_e32 v82, s34, v204
	v_and_b32_e32 v83, s35, v204
	v_and_b32_e32 v86, s34, v205
	v_and_b32_e32 v87, s35, v205
	v_cvt_f32_ubyte2_e32 v100, v78
	v_cvt_f32_ubyte3_e32 v101, v78
	v_pk_fma_f32 v[76:77], v[52:53], v[96:97], v[76:77] op_sel_hi:[0,1,1]
	v_cvt_f32_ubyte0_e32 v102, v79
	v_cvt_f32_ubyte1_e32 v103, v79
	v_pk_fma_f32 v[68:69], v[52:53], v[100:101], v[68:69] op_sel_hi:[0,1,1]
	v_cvt_f32_ubyte2_e32 v126, v79
	v_cvt_f32_ubyte3_e32 v127, v79
	v_pk_fma_f32 v[62:63], v[64:65], v[102:103], v[62:63] op_sel_hi:[0,1,1]
	v_cvt_f32_ubyte0_e32 v96, v82
	v_cvt_f32_ubyte1_e32 v97, v82
	v_pk_fma_f32 v[60:61], v[64:65], v[126:127], v[60:61] op_sel_hi:[0,1,1]
	v_cvt_f32_ubyte2_e32 v100, v82
	v_cvt_f32_ubyte3_e32 v101, v82
	v_pk_fma_f32 v[90:91], v[52:53], v[96:97], v[90:91] op_sel:[1,0,0]
	v_cvt_f32_ubyte0_e32 v102, v83
	v_cvt_f32_ubyte1_e32 v103, v83
	v_pk_fma_f32 v[88:89], v[52:53], v[100:101], v[88:89] op_sel:[1,0,0]
	v_cvt_f32_ubyte2_e32 v126, v83
	v_cvt_f32_ubyte3_e32 v127, v83
	v_pk_fma_f32 v[84:85], v[64:65], v[102:103], v[84:85] op_sel:[1,0,0]
	v_cvt_f32_ubyte0_e32 v96, v86
	v_cvt_f32_ubyte1_e32 v97, v86
	v_pk_fma_f32 v[80:81], v[64:65], v[126:127], v[80:81] op_sel:[1,0,0]
	v_and_b32_e32 v74, s34, v206
	v_and_b32_e32 v75, s35, v206
	v_and_b32_e32 v78, s34, v207
	v_and_b32_e32 v79, s35, v207
	v_cvt_f32_ubyte2_e32 v100, v86
	v_cvt_f32_ubyte3_e32 v101, v86
	v_pk_fma_f32 v[76:77], v[52:53], v[96:97], v[76:77] op_sel:[1,0,0]
	v_cvt_f32_ubyte0_e32 v102, v87
	v_cvt_f32_ubyte1_e32 v103, v87
	v_pk_fma_f32 v[68:69], v[52:53], v[100:101], v[68:69] op_sel:[1,0,0]
	v_cvt_f32_ubyte2_e32 v126, v87
	v_cvt_f32_ubyte3_e32 v127, v87
	v_pk_fma_f32 v[62:63], v[64:65], v[102:103], v[62:63] op_sel:[1,0,0]
	v_cvt_f32_ubyte0_e32 v96, v74
	v_cvt_f32_ubyte1_e32 v97, v74
	v_pk_fma_f32 v[60:61], v[64:65], v[126:127], v[60:61] op_sel:[1,0,0]
	v_cvt_f32_ubyte2_e32 v100, v74
	v_cvt_f32_ubyte3_e32 v101, v74
	v_pk_fma_f32 v[90:91], v[54:55], v[96:97], v[90:91] op_sel_hi:[0,1,1]
	v_cvt_f32_ubyte0_e32 v102, v75
	v_cvt_f32_ubyte1_e32 v103, v75
	v_pk_fma_f32 v[88:89], v[54:55], v[100:101], v[88:89] op_sel_hi:[0,1,1]
	v_cvt_f32_ubyte2_e32 v126, v75
	v_cvt_f32_ubyte3_e32 v127, v75
	v_pk_fma_f32 v[84:85], v[66:67], v[102:103], v[84:85] op_sel_hi:[0,1,1]
	v_cvt_f32_ubyte0_e32 v96, v78
	v_cvt_f32_ubyte1_e32 v97, v78
	v_pk_fma_f32 v[80:81], v[66:67], v[126:127], v[80:81] op_sel_hi:[0,1,1]
	v_and_b32_e32 v82, s34, v208
	v_and_b32_e32 v83, s35, v208
	v_and_b32_e32 v86, s34, v209
	v_and_b32_e32 v87, s35, v209
	v_cvt_f32_ubyte2_e32 v100, v78
	v_cvt_f32_ubyte3_e32 v101, v78
	v_pk_fma_f32 v[76:77], v[54:55], v[96:97], v[76:77] op_sel_hi:[0,1,1]
	v_cvt_f32_ubyte0_e32 v102, v79
	v_cvt_f32_ubyte1_e32 v103, v79
	v_pk_fma_f32 v[68:69], v[54:55], v[100:101], v[68:69] op_sel_hi:[0,1,1]
	v_cvt_f32_ubyte2_e32 v126, v79
	v_cvt_f32_ubyte3_e32 v127, v79
	v_pk_fma_f32 v[62:63], v[66:67], v[102:103], v[62:63] op_sel_hi:[0,1,1]
	v_cvt_f32_ubyte0_e32 v96, v82
	v_cvt_f32_ubyte1_e32 v97, v82
	v_pk_fma_f32 v[60:61], v[66:67], v[126:127], v[60:61] op_sel_hi:[0,1,1]
	v_cvt_f32_ubyte2_e32 v100, v82
	v_cvt_f32_ubyte3_e32 v101, v82
	v_pk_fma_f32 v[90:91], v[54:55], v[96:97], v[90:91] op_sel:[1,0,0]
	v_cvt_f32_ubyte0_e32 v102, v83
	v_cvt_f32_ubyte1_e32 v103, v83
	v_pk_fma_f32 v[88:89], v[54:55], v[100:101], v[88:89] op_sel:[1,0,0]
	v_cvt_f32_ubyte2_e32 v126, v83
	v_cvt_f32_ubyte3_e32 v127, v83
	v_pk_fma_f32 v[84:85], v[66:67], v[102:103], v[84:85] op_sel:[1,0,0]
	v_cvt_f32_ubyte0_e32 v96, v86
	v_cvt_f32_ubyte1_e32 v97, v86
	v_pk_fma_f32 v[80:81], v[66:67], v[126:127], v[80:81] op_sel:[1,0,0]
	v_cvt_f32_ubyte2_e32 v100, v86
	v_cvt_f32_ubyte3_e32 v101, v86
	v_pk_fma_f32 v[76:77], v[54:55], v[96:97], v[76:77] op_sel:[1,0,0]
	v_cvt_f32_ubyte0_e32 v102, v87
	v_cvt_f32_ubyte1_e32 v103, v87
	v_pk_fma_f32 v[68:69], v[54:55], v[100:101], v[68:69] op_sel:[1,0,0]
	v_cvt_f32_ubyte2_e32 v126, v87
	v_cvt_f32_ubyte3_e32 v127, v87
	v_pk_fma_f32 v[62:63], v[66:67], v[102:103], v[62:63] op_sel:[1,0,0]
	v_pk_fma_f32 v[60:61], v[66:67], v[126:127], v[60:61] op_sel:[1,0,0]
	s_waitcnt lgkmcnt(0)
	v_lshl_add_u32 v70, v70, 9, v98
	v_lshl_add_u32 v71, v71, 9, v98
	v_lshl_add_u32 v72, v72, 9, v98
	v_lshl_add_u32 v73, v73, 9, v98
	v_lshl_add_u32 v92, v92, 9, v98
	v_lshl_add_u32 v93, v93, 9, v98
	v_lshl_add_u32 v94, v94, 9, v98
	v_lshl_add_u32 v95, v95, 9, v98
	global_load_dwordx2 v[194:195], v70, s[36:37]
	global_load_dwordx2 v[196:197], v71, s[36:37]
	global_load_dwordx2 v[198:199], v72, s[36:37]
	global_load_dwordx2 v[200:201], v73, s[36:37]
	global_load_dwordx2 v[202:203], v92, s[36:37]
	global_load_dwordx2 v[204:205], v93, s[36:37]
	global_load_dwordx2 v[206:207], v94, s[36:37]
	global_load_dwordx2 v[208:209], v95, s[36:37]
	ds_read_b128 v[48:51], v128 offset:864
	ds_read_b128 v[52:55], v128 offset:880
	ds_read_b128 v[56:59], v128 offset:1888
	ds_read_b128 v[64:67], v128 offset:1904
	s_waitcnt vmcnt(40)
	v_and_b32_e32 v74, s34, v0
	v_and_b32_e32 v75, s35, v0
	v_and_b32_e32 v78, s34, v1
	v_and_b32_e32 v79, s35, v1
	v_cvt_f32_ubyte0_e32 v96, v74
	v_cvt_f32_ubyte1_e32 v97, v74
	v_cvt_f32_ubyte2_e32 v100, v74
	v_cvt_f32_ubyte3_e32 v101, v74
	v_pk_fma_f32 v[90:91], v[32:33], v[96:97], v[90:91] op_sel_hi:[0,1,1]
	v_cvt_f32_ubyte0_e32 v102, v75
	v_cvt_f32_ubyte1_e32 v103, v75
	v_pk_fma_f32 v[88:89], v[32:33], v[100:101], v[88:89] op_sel_hi:[0,1,1]
	v_cvt_f32_ubyte2_e32 v126, v75
	v_cvt_f32_ubyte3_e32 v127, v75
	v_pk_fma_f32 v[84:85], v[40:41], v[102:103], v[84:85] op_sel_hi:[0,1,1]
	v_cvt_f32_ubyte0_e32 v96, v78
	v_cvt_f32_ubyte1_e32 v97, v78
	v_pk_fma_f32 v[80:81], v[40:41], v[126:127], v[80:81] op_sel_hi:[0,1,1]
	v_and_b32_e32 v82, s34, v2
	v_and_b32_e32 v83, s35, v2
	v_and_b32_e32 v86, s34, v3
	v_and_b32_e32 v87, s35, v3
	v_cvt_f32_ubyte2_e32 v100, v78
	v_cvt_f32_ubyte3_e32 v101, v78
	v_pk_fma_f32 v[76:77], v[32:33], v[96:97], v[76:77] op_sel_hi:[0,1,1]
	v_cvt_f32_ubyte0_e32 v102, v79
	v_cvt_f32_ubyte1_e32 v103, v79
	v_pk_fma_f32 v[68:69], v[32:33], v[100:101], v[68:69] op_sel_hi:[0,1,1]
	v_cvt_f32_ubyte2_e32 v126, v79
	v_cvt_f32_ubyte3_e32 v127, v79
	v_pk_fma_f32 v[62:63], v[40:41], v[102:103], v[62:63] op_sel_hi:[0,1,1]
	v_cvt_f32_ubyte0_e32 v96, v82
	v_cvt_f32_ubyte1_e32 v97, v82
	v_pk_fma_f32 v[60:61], v[40:41], v[126:127], v[60:61] op_sel_hi:[0,1,1]
	v_cvt_f32_ubyte2_e32 v100, v82
	v_cvt_f32_ubyte3_e32 v101, v82
	v_pk_fma_f32 v[90:91], v[32:33], v[96:97], v[90:91] op_sel:[1,0,0]
	v_cvt_f32_ubyte0_e32 v102, v83
	v_cvt_f32_ubyte1_e32 v103, v83
	v_pk_fma_f32 v[88:89], v[32:33], v[100:101], v[88:89] op_sel:[1,0,0]
	v_cvt_f32_ubyte2_e32 v126, v83
	v_cvt_f32_ubyte3_e32 v127, v83
	v_pk_fma_f32 v[84:85], v[40:41], v[102:103], v[84:85] op_sel:[1,0,0]
	v_cvt_f32_ubyte0_e32 v96, v86
	v_cvt_f32_ubyte1_e32 v97, v86
	v_pk_fma_f32 v[80:81], v[40:41], v[126:127], v[80:81] op_sel:[1,0,0]
	v_and_b32_e32 v74, s34, v4
	v_and_b32_e32 v75, s35, v4
	v_and_b32_e32 v78, s34, v5
	v_and_b32_e32 v79, s35, v5
	v_cvt_f32_ubyte2_e32 v100, v86
	v_cvt_f32_ubyte3_e32 v101, v86
	v_pk_fma_f32 v[76:77], v[32:33], v[96:97], v[76:77] op_sel:[1,0,0]
	v_cvt_f32_ubyte0_e32 v102, v87
	v_cvt_f32_ubyte1_e32 v103, v87
	v_pk_fma_f32 v[68:69], v[32:33], v[100:101], v[68:69] op_sel:[1,0,0]
	v_cvt_f32_ubyte2_e32 v126, v87
	v_cvt_f32_ubyte3_e32 v127, v87
	v_pk_fma_f32 v[62:63], v[40:41], v[102:103], v[62:63] op_sel:[1,0,0]
	v_cvt_f32_ubyte0_e32 v96, v74
	v_cvt_f32_ubyte1_e32 v97, v74
	v_pk_fma_f32 v[60:61], v[40:41], v[126:127], v[60:61] op_sel:[1,0,0]
	v_cvt_f32_ubyte2_e32 v100, v74
	v_cvt_f32_ubyte3_e32 v101, v74
	v_pk_fma_f32 v[90:91], v[34:35], v[96:97], v[90:91] op_sel_hi:[0,1,1]
	v_cvt_f32_ubyte0_e32 v102, v75
	v_cvt_f32_ubyte1_e32 v103, v75
	v_pk_fma_f32 v[88:89], v[34:35], v[100:101], v[88:89] op_sel_hi:[0,1,1]
	v_cvt_f32_ubyte2_e32 v126, v75
	v_cvt_f32_ubyte3_e32 v127, v75
	v_pk_fma_f32 v[84:85], v[42:43], v[102:103], v[84:85] op_sel_hi:[0,1,1]
	v_cvt_f32_ubyte0_e32 v96, v78
	v_cvt_f32_ubyte1_e32 v97, v78
	v_pk_fma_f32 v[80:81], v[42:43], v[126:127], v[80:81] op_sel_hi:[0,1,1]
	v_and_b32_e32 v82, s34, v6
	v_and_b32_e32 v83, s35, v6
	v_and_b32_e32 v86, s34, v7
	v_and_b32_e32 v87, s35, v7
	v_cvt_f32_ubyte2_e32 v100, v78
	v_cvt_f32_ubyte3_e32 v101, v78
	v_pk_fma_f32 v[76:77], v[34:35], v[96:97], v[76:77] op_sel_hi:[0,1,1]
	v_cvt_f32_ubyte0_e32 v102, v79
	v_cvt_f32_ubyte1_e32 v103, v79
	v_pk_fma_f32 v[68:69], v[34:35], v[100:101], v[68:69] op_sel_hi:[0,1,1]
	v_cvt_f32_ubyte2_e32 v126, v79
	v_cvt_f32_ubyte3_e32 v127, v79
	v_pk_fma_f32 v[62:63], v[42:43], v[102:103], v[62:63] op_sel_hi:[0,1,1]
	v_cvt_f32_ubyte0_e32 v96, v82
	v_cvt_f32_ubyte1_e32 v97, v82
	v_pk_fma_f32 v[60:61], v[42:43], v[126:127], v[60:61] op_sel_hi:[0,1,1]
	v_cvt_f32_ubyte2_e32 v100, v82
	v_cvt_f32_ubyte3_e32 v101, v82
	v_pk_fma_f32 v[90:91], v[34:35], v[96:97], v[90:91] op_sel:[1,0,0]
	v_cvt_f32_ubyte0_e32 v102, v83
	v_cvt_f32_ubyte1_e32 v103, v83
	v_pk_fma_f32 v[88:89], v[34:35], v[100:101], v[88:89] op_sel:[1,0,0]
	v_cvt_f32_ubyte2_e32 v126, v83
	v_cvt_f32_ubyte3_e32 v127, v83
	v_pk_fma_f32 v[84:85], v[42:43], v[102:103], v[84:85] op_sel:[1,0,0]
	v_cvt_f32_ubyte0_e32 v96, v86
	v_cvt_f32_ubyte1_e32 v97, v86
	v_pk_fma_f32 v[80:81], v[42:43], v[126:127], v[80:81] op_sel:[1,0,0]
	v_and_b32_e32 v74, s34, v8
	v_and_b32_e32 v75, s35, v8
	v_and_b32_e32 v78, s34, v9
	v_and_b32_e32 v79, s35, v9
	v_cvt_f32_ubyte2_e32 v100, v86
	v_cvt_f32_ubyte3_e32 v101, v86
	v_pk_fma_f32 v[76:77], v[34:35], v[96:97], v[76:77] op_sel:[1,0,0]
	v_cvt_f32_ubyte0_e32 v102, v87
	v_cvt_f32_ubyte1_e32 v103, v87
	v_pk_fma_f32 v[68:69], v[34:35], v[100:101], v[68:69] op_sel:[1,0,0]
	v_cvt_f32_ubyte2_e32 v126, v87
	v_cvt_f32_ubyte3_e32 v127, v87
	v_pk_fma_f32 v[62:63], v[42:43], v[102:103], v[62:63] op_sel:[1,0,0]
	v_cvt_f32_ubyte0_e32 v96, v74
	v_cvt_f32_ubyte1_e32 v97, v74
	v_pk_fma_f32 v[60:61], v[42:43], v[126:127], v[60:61] op_sel:[1,0,0]
	v_cvt_f32_ubyte2_e32 v100, v74
	v_cvt_f32_ubyte3_e32 v101, v74
	v_pk_fma_f32 v[90:91], v[36:37], v[96:97], v[90:91] op_sel_hi:[0,1,1]
	v_cvt_f32_ubyte0_e32 v102, v75
	v_cvt_f32_ubyte1_e32 v103, v75
	v_pk_fma_f32 v[88:89], v[36:37], v[100:101], v[88:89] op_sel_hi:[0,1,1]
	v_cvt_f32_ubyte2_e32 v126, v75
	v_cvt_f32_ubyte3_e32 v127, v75
	v_pk_fma_f32 v[84:85], v[44:45], v[102:103], v[84:85] op_sel_hi:[0,1,1]
	v_cvt_f32_ubyte0_e32 v96, v78
	v_cvt_f32_ubyte1_e32 v97, v78
	v_pk_fma_f32 v[80:81], v[44:45], v[126:127], v[80:81] op_sel_hi:[0,1,1]
	v_and_b32_e32 v82, s34, v10
	v_and_b32_e32 v83, s35, v10
	v_and_b32_e32 v86, s34, v11
	v_and_b32_e32 v87, s35, v11
	v_cvt_f32_ubyte2_e32 v100, v78
	v_cvt_f32_ubyte3_e32 v101, v78
	v_pk_fma_f32 v[76:77], v[36:37], v[96:97], v[76:77] op_sel_hi:[0,1,1]
	v_cvt_f32_ubyte0_e32 v102, v79
	v_cvt_f32_ubyte1_e32 v103, v79
	v_pk_fma_f32 v[68:69], v[36:37], v[100:101], v[68:69] op_sel_hi:[0,1,1]
	v_cvt_f32_ubyte2_e32 v126, v79
	v_cvt_f32_ubyte3_e32 v127, v79
	v_pk_fma_f32 v[62:63], v[44:45], v[102:103], v[62:63] op_sel_hi:[0,1,1]
	v_cvt_f32_ubyte0_e32 v96, v82
	v_cvt_f32_ubyte1_e32 v97, v82
	v_pk_fma_f32 v[60:61], v[44:45], v[126:127], v[60:61] op_sel_hi:[0,1,1]
	v_cvt_f32_ubyte2_e32 v100, v82
	v_cvt_f32_ubyte3_e32 v101, v82
	v_pk_fma_f32 v[90:91], v[36:37], v[96:97], v[90:91] op_sel:[1,0,0]
	v_cvt_f32_ubyte0_e32 v102, v83
	v_cvt_f32_ubyte1_e32 v103, v83
	v_pk_fma_f32 v[88:89], v[36:37], v[100:101], v[88:89] op_sel:[1,0,0]
	v_cvt_f32_ubyte2_e32 v126, v83
	v_cvt_f32_ubyte3_e32 v127, v83
	v_pk_fma_f32 v[84:85], v[44:45], v[102:103], v[84:85] op_sel:[1,0,0]
	v_cvt_f32_ubyte0_e32 v96, v86
	v_cvt_f32_ubyte1_e32 v97, v86
	v_pk_fma_f32 v[80:81], v[44:45], v[126:127], v[80:81] op_sel:[1,0,0]
	v_and_b32_e32 v74, s34, v12
	v_and_b32_e32 v75, s35, v12
	v_and_b32_e32 v78, s34, v13
	v_and_b32_e32 v79, s35, v13
	v_cvt_f32_ubyte2_e32 v100, v86
	v_cvt_f32_ubyte3_e32 v101, v86
	v_pk_fma_f32 v[76:77], v[36:37], v[96:97], v[76:77] op_sel:[1,0,0]
	v_cvt_f32_ubyte0_e32 v102, v87
	v_cvt_f32_ubyte1_e32 v103, v87
	v_pk_fma_f32 v[68:69], v[36:37], v[100:101], v[68:69] op_sel:[1,0,0]
	v_cvt_f32_ubyte2_e32 v126, v87
	v_cvt_f32_ubyte3_e32 v127, v87
	v_pk_fma_f32 v[62:63], v[44:45], v[102:103], v[62:63] op_sel:[1,0,0]
	v_cvt_f32_ubyte0_e32 v96, v74
	v_cvt_f32_ubyte1_e32 v97, v74
	v_pk_fma_f32 v[60:61], v[44:45], v[126:127], v[60:61] op_sel:[1,0,0]
	v_cvt_f32_ubyte2_e32 v100, v74
	v_cvt_f32_ubyte3_e32 v101, v74
	v_pk_fma_f32 v[90:91], v[38:39], v[96:97], v[90:91] op_sel_hi:[0,1,1]
	v_cvt_f32_ubyte0_e32 v102, v75
	v_cvt_f32_ubyte1_e32 v103, v75
	v_pk_fma_f32 v[88:89], v[38:39], v[100:101], v[88:89] op_sel_hi:[0,1,1]
	v_cvt_f32_ubyte2_e32 v126, v75
	v_cvt_f32_ubyte3_e32 v127, v75
	v_pk_fma_f32 v[84:85], v[46:47], v[102:103], v[84:85] op_sel_hi:[0,1,1]
	v_cvt_f32_ubyte0_e32 v96, v78
	v_cvt_f32_ubyte1_e32 v97, v78
	v_pk_fma_f32 v[80:81], v[46:47], v[126:127], v[80:81] op_sel_hi:[0,1,1]
	v_and_b32_e32 v82, s34, v14
	v_and_b32_e32 v83, s35, v14
	v_and_b32_e32 v86, s34, v15
	v_and_b32_e32 v87, s35, v15
	v_cvt_f32_ubyte2_e32 v100, v78
	v_cvt_f32_ubyte3_e32 v101, v78
	v_pk_fma_f32 v[76:77], v[38:39], v[96:97], v[76:77] op_sel_hi:[0,1,1]
	v_cvt_f32_ubyte0_e32 v102, v79
	v_cvt_f32_ubyte1_e32 v103, v79
	v_pk_fma_f32 v[68:69], v[38:39], v[100:101], v[68:69] op_sel_hi:[0,1,1]
	v_cvt_f32_ubyte2_e32 v126, v79
	v_cvt_f32_ubyte3_e32 v127, v79
	v_pk_fma_f32 v[62:63], v[46:47], v[102:103], v[62:63] op_sel_hi:[0,1,1]
	v_cvt_f32_ubyte0_e32 v96, v82
	v_cvt_f32_ubyte1_e32 v97, v82
	v_pk_fma_f32 v[60:61], v[46:47], v[126:127], v[60:61] op_sel_hi:[0,1,1]
	v_cvt_f32_ubyte2_e32 v100, v82
	v_cvt_f32_ubyte3_e32 v101, v82
	v_pk_fma_f32 v[90:91], v[38:39], v[96:97], v[90:91] op_sel:[1,0,0]
	v_cvt_f32_ubyte0_e32 v102, v83
	v_cvt_f32_ubyte1_e32 v103, v83
	v_pk_fma_f32 v[88:89], v[38:39], v[100:101], v[88:89] op_sel:[1,0,0]
	v_cvt_f32_ubyte2_e32 v126, v83
	v_cvt_f32_ubyte3_e32 v127, v83
	v_pk_fma_f32 v[84:85], v[46:47], v[102:103], v[84:85] op_sel:[1,0,0]
	v_cvt_f32_ubyte0_e32 v96, v86
	v_cvt_f32_ubyte1_e32 v97, v86
	v_pk_fma_f32 v[80:81], v[46:47], v[126:127], v[80:81] op_sel:[1,0,0]
	v_cvt_f32_ubyte2_e32 v100, v86
	v_cvt_f32_ubyte3_e32 v101, v86
	v_pk_fma_f32 v[76:77], v[38:39], v[96:97], v[76:77] op_sel:[1,0,0]
	v_cvt_f32_ubyte0_e32 v102, v87
	v_cvt_f32_ubyte1_e32 v103, v87
	v_pk_fma_f32 v[68:69], v[38:39], v[100:101], v[68:69] op_sel:[1,0,0]
	v_cvt_f32_ubyte2_e32 v126, v87
	v_cvt_f32_ubyte3_e32 v127, v87
	v_pk_fma_f32 v[62:63], v[46:47], v[102:103], v[62:63] op_sel:[1,0,0]
	v_pk_fma_f32 v[60:61], v[46:47], v[126:127], v[60:61] op_sel:[1,0,0]
	s_waitcnt lgkmcnt(0)
	ds_read_b128 v[32:35], v128 offset:896
	ds_read_b128 v[36:39], v128 offset:912
	ds_read_b128 v[40:43], v128 offset:1920
	ds_read_b128 v[44:47], v128 offset:1936
	s_waitcnt vmcnt(32)
	v_and_b32_e32 v74, s34, v16
	v_and_b32_e32 v75, s35, v16
	v_and_b32_e32 v78, s34, v17
	v_and_b32_e32 v79, s35, v17
	v_cvt_f32_ubyte0_e32 v96, v74
	v_cvt_f32_ubyte1_e32 v97, v74
	v_cvt_f32_ubyte2_e32 v100, v74
	v_cvt_f32_ubyte3_e32 v101, v74
	v_pk_fma_f32 v[90:91], v[48:49], v[96:97], v[90:91] op_sel_hi:[0,1,1]
	v_cvt_f32_ubyte0_e32 v102, v75
	v_cvt_f32_ubyte1_e32 v103, v75
	v_pk_fma_f32 v[88:89], v[48:49], v[100:101], v[88:89] op_sel_hi:[0,1,1]
	v_cvt_f32_ubyte2_e32 v126, v75
	v_cvt_f32_ubyte3_e32 v127, v75
	v_pk_fma_f32 v[84:85], v[56:57], v[102:103], v[84:85] op_sel_hi:[0,1,1]
	v_cvt_f32_ubyte0_e32 v96, v78
	v_cvt_f32_ubyte1_e32 v97, v78
	v_pk_fma_f32 v[80:81], v[56:57], v[126:127], v[80:81] op_sel_hi:[0,1,1]
	v_and_b32_e32 v82, s34, v18
	v_and_b32_e32 v83, s35, v18
	v_and_b32_e32 v86, s34, v19
	v_and_b32_e32 v87, s35, v19
	v_cvt_f32_ubyte2_e32 v100, v78
	v_cvt_f32_ubyte3_e32 v101, v78
	v_pk_fma_f32 v[76:77], v[48:49], v[96:97], v[76:77] op_sel_hi:[0,1,1]
	v_cvt_f32_ubyte0_e32 v102, v79
	v_cvt_f32_ubyte1_e32 v103, v79
	v_pk_fma_f32 v[68:69], v[48:49], v[100:101], v[68:69] op_sel_hi:[0,1,1]
	v_cvt_f32_ubyte2_e32 v126, v79
	v_cvt_f32_ubyte3_e32 v127, v79
	v_pk_fma_f32 v[62:63], v[56:57], v[102:103], v[62:63] op_sel_hi:[0,1,1]
	v_cvt_f32_ubyte0_e32 v96, v82
	v_cvt_f32_ubyte1_e32 v97, v82
	v_pk_fma_f32 v[60:61], v[56:57], v[126:127], v[60:61] op_sel_hi:[0,1,1]
	v_cvt_f32_ubyte2_e32 v100, v82
	v_cvt_f32_ubyte3_e32 v101, v82
	v_pk_fma_f32 v[90:91], v[48:49], v[96:97], v[90:91] op_sel:[1,0,0]
	v_cvt_f32_ubyte0_e32 v102, v83
	v_cvt_f32_ubyte1_e32 v103, v83
	v_pk_fma_f32 v[88:89], v[48:49], v[100:101], v[88:89] op_sel:[1,0,0]
	v_cvt_f32_ubyte2_e32 v126, v83
	v_cvt_f32_ubyte3_e32 v127, v83
	v_pk_fma_f32 v[84:85], v[56:57], v[102:103], v[84:85] op_sel:[1,0,0]
	v_cvt_f32_ubyte0_e32 v96, v86
	v_cvt_f32_ubyte1_e32 v97, v86
	v_pk_fma_f32 v[80:81], v[56:57], v[126:127], v[80:81] op_sel:[1,0,0]
	v_and_b32_e32 v74, s34, v20
	v_and_b32_e32 v75, s35, v20
	v_and_b32_e32 v78, s34, v21
	v_and_b32_e32 v79, s35, v21
	v_cvt_f32_ubyte2_e32 v100, v86
	v_cvt_f32_ubyte3_e32 v101, v86
	v_pk_fma_f32 v[76:77], v[48:49], v[96:97], v[76:77] op_sel:[1,0,0]
	v_cvt_f32_ubyte0_e32 v102, v87
	v_cvt_f32_ubyte1_e32 v103, v87
	v_pk_fma_f32 v[68:69], v[48:49], v[100:101], v[68:69] op_sel:[1,0,0]
	v_cvt_f32_ubyte2_e32 v126, v87
	v_cvt_f32_ubyte3_e32 v127, v87
	v_pk_fma_f32 v[62:63], v[56:57], v[102:103], v[62:63] op_sel:[1,0,0]
	v_cvt_f32_ubyte0_e32 v96, v74
	v_cvt_f32_ubyte1_e32 v97, v74
	v_pk_fma_f32 v[60:61], v[56:57], v[126:127], v[60:61] op_sel:[1,0,0]
	v_cvt_f32_ubyte2_e32 v100, v74
	v_cvt_f32_ubyte3_e32 v101, v74
	v_pk_fma_f32 v[90:91], v[50:51], v[96:97], v[90:91] op_sel_hi:[0,1,1]
	v_cvt_f32_ubyte0_e32 v102, v75
	v_cvt_f32_ubyte1_e32 v103, v75
	v_pk_fma_f32 v[88:89], v[50:51], v[100:101], v[88:89] op_sel_hi:[0,1,1]
	v_cvt_f32_ubyte2_e32 v126, v75
	v_cvt_f32_ubyte3_e32 v127, v75
	v_pk_fma_f32 v[84:85], v[58:59], v[102:103], v[84:85] op_sel_hi:[0,1,1]
	v_cvt_f32_ubyte0_e32 v96, v78
	v_cvt_f32_ubyte1_e32 v97, v78
	v_pk_fma_f32 v[80:81], v[58:59], v[126:127], v[80:81] op_sel_hi:[0,1,1]
	v_and_b32_e32 v82, s34, v22
	v_and_b32_e32 v83, s35, v22
	v_and_b32_e32 v86, s34, v23
	v_and_b32_e32 v87, s35, v23
	v_cvt_f32_ubyte2_e32 v100, v78
	v_cvt_f32_ubyte3_e32 v101, v78
	v_pk_fma_f32 v[76:77], v[50:51], v[96:97], v[76:77] op_sel_hi:[0,1,1]
	v_cvt_f32_ubyte0_e32 v102, v79
	v_cvt_f32_ubyte1_e32 v103, v79
	v_pk_fma_f32 v[68:69], v[50:51], v[100:101], v[68:69] op_sel_hi:[0,1,1]
	v_cvt_f32_ubyte2_e32 v126, v79
	v_cvt_f32_ubyte3_e32 v127, v79
	v_pk_fma_f32 v[62:63], v[58:59], v[102:103], v[62:63] op_sel_hi:[0,1,1]
	v_cvt_f32_ubyte0_e32 v96, v82
	v_cvt_f32_ubyte1_e32 v97, v82
	v_pk_fma_f32 v[60:61], v[58:59], v[126:127], v[60:61] op_sel_hi:[0,1,1]
	v_cvt_f32_ubyte2_e32 v100, v82
	v_cvt_f32_ubyte3_e32 v101, v82
	v_pk_fma_f32 v[90:91], v[50:51], v[96:97], v[90:91] op_sel:[1,0,0]
	v_cvt_f32_ubyte0_e32 v102, v83
	v_cvt_f32_ubyte1_e32 v103, v83
	v_pk_fma_f32 v[88:89], v[50:51], v[100:101], v[88:89] op_sel:[1,0,0]
	v_cvt_f32_ubyte2_e32 v126, v83
	v_cvt_f32_ubyte3_e32 v127, v83
	v_pk_fma_f32 v[84:85], v[58:59], v[102:103], v[84:85] op_sel:[1,0,0]
	v_cvt_f32_ubyte0_e32 v96, v86
	v_cvt_f32_ubyte1_e32 v97, v86
	v_pk_fma_f32 v[80:81], v[58:59], v[126:127], v[80:81] op_sel:[1,0,0]
	v_and_b32_e32 v74, s34, v24
	v_and_b32_e32 v75, s35, v24
	v_and_b32_e32 v78, s34, v25
	v_and_b32_e32 v79, s35, v25
	v_cvt_f32_ubyte2_e32 v100, v86
	v_cvt_f32_ubyte3_e32 v101, v86
	v_pk_fma_f32 v[76:77], v[50:51], v[96:97], v[76:77] op_sel:[1,0,0]
	v_cvt_f32_ubyte0_e32 v102, v87
	v_cvt_f32_ubyte1_e32 v103, v87
	v_pk_fma_f32 v[68:69], v[50:51], v[100:101], v[68:69] op_sel:[1,0,0]
	v_cvt_f32_ubyte2_e32 v126, v87
	v_cvt_f32_ubyte3_e32 v127, v87
	v_pk_fma_f32 v[62:63], v[58:59], v[102:103], v[62:63] op_sel:[1,0,0]
	v_cvt_f32_ubyte0_e32 v96, v74
	v_cvt_f32_ubyte1_e32 v97, v74
	v_pk_fma_f32 v[60:61], v[58:59], v[126:127], v[60:61] op_sel:[1,0,0]
	v_cvt_f32_ubyte2_e32 v100, v74
	v_cvt_f32_ubyte3_e32 v101, v74
	v_pk_fma_f32 v[90:91], v[52:53], v[96:97], v[90:91] op_sel_hi:[0,1,1]
	v_cvt_f32_ubyte0_e32 v102, v75
	v_cvt_f32_ubyte1_e32 v103, v75
	v_pk_fma_f32 v[88:89], v[52:53], v[100:101], v[88:89] op_sel_hi:[0,1,1]
	v_cvt_f32_ubyte2_e32 v126, v75
	v_cvt_f32_ubyte3_e32 v127, v75
	v_pk_fma_f32 v[84:85], v[64:65], v[102:103], v[84:85] op_sel_hi:[0,1,1]
	v_cvt_f32_ubyte0_e32 v96, v78
	v_cvt_f32_ubyte1_e32 v97, v78
	v_pk_fma_f32 v[80:81], v[64:65], v[126:127], v[80:81] op_sel_hi:[0,1,1]
	v_and_b32_e32 v82, s34, v26
	v_and_b32_e32 v83, s35, v26
	v_and_b32_e32 v86, s34, v27
	v_and_b32_e32 v87, s35, v27
	v_cvt_f32_ubyte2_e32 v100, v78
	v_cvt_f32_ubyte3_e32 v101, v78
	v_pk_fma_f32 v[76:77], v[52:53], v[96:97], v[76:77] op_sel_hi:[0,1,1]
	v_cvt_f32_ubyte0_e32 v102, v79
	v_cvt_f32_ubyte1_e32 v103, v79
	v_pk_fma_f32 v[68:69], v[52:53], v[100:101], v[68:69] op_sel_hi:[0,1,1]
	v_cvt_f32_ubyte2_e32 v126, v79
	v_cvt_f32_ubyte3_e32 v127, v79
	v_pk_fma_f32 v[62:63], v[64:65], v[102:103], v[62:63] op_sel_hi:[0,1,1]
	v_cvt_f32_ubyte0_e32 v96, v82
	v_cvt_f32_ubyte1_e32 v97, v82
	v_pk_fma_f32 v[60:61], v[64:65], v[126:127], v[60:61] op_sel_hi:[0,1,1]
	v_cvt_f32_ubyte2_e32 v100, v82
	v_cvt_f32_ubyte3_e32 v101, v82
	v_pk_fma_f32 v[90:91], v[52:53], v[96:97], v[90:91] op_sel:[1,0,0]
	v_cvt_f32_ubyte0_e32 v102, v83
	v_cvt_f32_ubyte1_e32 v103, v83
	v_pk_fma_f32 v[88:89], v[52:53], v[100:101], v[88:89] op_sel:[1,0,0]
	v_cvt_f32_ubyte2_e32 v126, v83
	v_cvt_f32_ubyte3_e32 v127, v83
	v_pk_fma_f32 v[84:85], v[64:65], v[102:103], v[84:85] op_sel:[1,0,0]
	v_cvt_f32_ubyte0_e32 v96, v86
	v_cvt_f32_ubyte1_e32 v97, v86
	v_pk_fma_f32 v[80:81], v[64:65], v[126:127], v[80:81] op_sel:[1,0,0]
	v_and_b32_e32 v74, s34, v28
	v_and_b32_e32 v75, s35, v28
	v_and_b32_e32 v78, s34, v29
	v_and_b32_e32 v79, s35, v29
	v_cvt_f32_ubyte2_e32 v100, v86
	v_cvt_f32_ubyte3_e32 v101, v86
	v_pk_fma_f32 v[76:77], v[52:53], v[96:97], v[76:77] op_sel:[1,0,0]
	v_cvt_f32_ubyte0_e32 v102, v87
	v_cvt_f32_ubyte1_e32 v103, v87
	v_pk_fma_f32 v[68:69], v[52:53], v[100:101], v[68:69] op_sel:[1,0,0]
	v_cvt_f32_ubyte2_e32 v126, v87
	v_cvt_f32_ubyte3_e32 v127, v87
	v_pk_fma_f32 v[62:63], v[64:65], v[102:103], v[62:63] op_sel:[1,0,0]
	v_cvt_f32_ubyte0_e32 v96, v74
	v_cvt_f32_ubyte1_e32 v97, v74
	v_pk_fma_f32 v[60:61], v[64:65], v[126:127], v[60:61] op_sel:[1,0,0]
	v_cvt_f32_ubyte2_e32 v100, v74
	v_cvt_f32_ubyte3_e32 v101, v74
	v_pk_fma_f32 v[90:91], v[54:55], v[96:97], v[90:91] op_sel_hi:[0,1,1]
	v_cvt_f32_ubyte0_e32 v102, v75
	v_cvt_f32_ubyte1_e32 v103, v75
	v_pk_fma_f32 v[88:89], v[54:55], v[100:101], v[88:89] op_sel_hi:[0,1,1]
	v_cvt_f32_ubyte2_e32 v126, v75
	v_cvt_f32_ubyte3_e32 v127, v75
	v_pk_fma_f32 v[84:85], v[66:67], v[102:103], v[84:85] op_sel_hi:[0,1,1]
	v_cvt_f32_ubyte0_e32 v96, v78
	v_cvt_f32_ubyte1_e32 v97, v78
	v_pk_fma_f32 v[80:81], v[66:67], v[126:127], v[80:81] op_sel_hi:[0,1,1]
	v_and_b32_e32 v82, s34, v30
	v_and_b32_e32 v83, s35, v30
	v_and_b32_e32 v86, s34, v31
	v_and_b32_e32 v87, s35, v31
	v_cvt_f32_ubyte2_e32 v100, v78
	v_cvt_f32_ubyte3_e32 v101, v78
	v_pk_fma_f32 v[76:77], v[54:55], v[96:97], v[76:77] op_sel_hi:[0,1,1]
	v_cvt_f32_ubyte0_e32 v102, v79
	v_cvt_f32_ubyte1_e32 v103, v79
	v_pk_fma_f32 v[68:69], v[54:55], v[100:101], v[68:69] op_sel_hi:[0,1,1]
	v_cvt_f32_ubyte2_e32 v126, v79
	v_cvt_f32_ubyte3_e32 v127, v79
	v_pk_fma_f32 v[62:63], v[66:67], v[102:103], v[62:63] op_sel_hi:[0,1,1]
	v_cvt_f32_ubyte0_e32 v96, v82
	v_cvt_f32_ubyte1_e32 v97, v82
	v_pk_fma_f32 v[60:61], v[66:67], v[126:127], v[60:61] op_sel_hi:[0,1,1]
	v_cvt_f32_ubyte2_e32 v100, v82
	v_cvt_f32_ubyte3_e32 v101, v82
	v_pk_fma_f32 v[90:91], v[54:55], v[96:97], v[90:91] op_sel:[1,0,0]
	v_cvt_f32_ubyte0_e32 v102, v83
	v_cvt_f32_ubyte1_e32 v103, v83
	v_pk_fma_f32 v[88:89], v[54:55], v[100:101], v[88:89] op_sel:[1,0,0]
	v_cvt_f32_ubyte2_e32 v126, v83
	v_cvt_f32_ubyte3_e32 v127, v83
	v_pk_fma_f32 v[84:85], v[66:67], v[102:103], v[84:85] op_sel:[1,0,0]
	v_cvt_f32_ubyte0_e32 v96, v86
	v_cvt_f32_ubyte1_e32 v97, v86
	v_pk_fma_f32 v[80:81], v[66:67], v[126:127], v[80:81] op_sel:[1,0,0]
	v_cvt_f32_ubyte2_e32 v100, v86
	v_cvt_f32_ubyte3_e32 v101, v86
	v_pk_fma_f32 v[76:77], v[54:55], v[96:97], v[76:77] op_sel:[1,0,0]
	v_cvt_f32_ubyte0_e32 v102, v87
	v_cvt_f32_ubyte1_e32 v103, v87
	v_pk_fma_f32 v[68:69], v[54:55], v[100:101], v[68:69] op_sel:[1,0,0]
	v_cvt_f32_ubyte2_e32 v126, v87
	v_cvt_f32_ubyte3_e32 v127, v87
	v_pk_fma_f32 v[62:63], v[66:67], v[102:103], v[62:63] op_sel:[1,0,0]
	v_pk_fma_f32 v[60:61], v[66:67], v[126:127], v[60:61] op_sel:[1,0,0]
	s_waitcnt lgkmcnt(0)
	ds_read_b128 v[48:51], v128 offset:928
	ds_read_b128 v[52:55], v128 offset:944
	ds_read_b128 v[56:59], v128 offset:1952
	ds_read_b128 v[64:67], v128 offset:1968
	s_waitcnt vmcnt(24)
	v_and_b32_e32 v74, s34, v146
	v_and_b32_e32 v75, s35, v146
	v_and_b32_e32 v78, s34, v147
	v_and_b32_e32 v79, s35, v147
	v_cvt_f32_ubyte0_e32 v96, v74
	v_cvt_f32_ubyte1_e32 v97, v74
	v_cvt_f32_ubyte2_e32 v100, v74
	v_cvt_f32_ubyte3_e32 v101, v74
	v_pk_fma_f32 v[90:91], v[32:33], v[96:97], v[90:91] op_sel_hi:[0,1,1]
	v_cvt_f32_ubyte0_e32 v102, v75
	v_cvt_f32_ubyte1_e32 v103, v75
	v_pk_fma_f32 v[88:89], v[32:33], v[100:101], v[88:89] op_sel_hi:[0,1,1]
	v_cvt_f32_ubyte2_e32 v126, v75
	v_cvt_f32_ubyte3_e32 v127, v75
	v_pk_fma_f32 v[84:85], v[40:41], v[102:103], v[84:85] op_sel_hi:[0,1,1]
	v_cvt_f32_ubyte0_e32 v96, v78
	v_cvt_f32_ubyte1_e32 v97, v78
	v_pk_fma_f32 v[80:81], v[40:41], v[126:127], v[80:81] op_sel_hi:[0,1,1]
	v_and_b32_e32 v82, s34, v148
	v_and_b32_e32 v83, s35, v148
	v_and_b32_e32 v86, s34, v149
	v_and_b32_e32 v87, s35, v149
	v_cvt_f32_ubyte2_e32 v100, v78
	v_cvt_f32_ubyte3_e32 v101, v78
	v_pk_fma_f32 v[76:77], v[32:33], v[96:97], v[76:77] op_sel_hi:[0,1,1]
	v_cvt_f32_ubyte0_e32 v102, v79
	v_cvt_f32_ubyte1_e32 v103, v79
	v_pk_fma_f32 v[68:69], v[32:33], v[100:101], v[68:69] op_sel_hi:[0,1,1]
	v_cvt_f32_ubyte2_e32 v126, v79
	v_cvt_f32_ubyte3_e32 v127, v79
	v_pk_fma_f32 v[62:63], v[40:41], v[102:103], v[62:63] op_sel_hi:[0,1,1]
	v_cvt_f32_ubyte0_e32 v96, v82
	v_cvt_f32_ubyte1_e32 v97, v82
	v_pk_fma_f32 v[60:61], v[40:41], v[126:127], v[60:61] op_sel_hi:[0,1,1]
	v_cvt_f32_ubyte2_e32 v100, v82
	v_cvt_f32_ubyte3_e32 v101, v82
	v_pk_fma_f32 v[90:91], v[32:33], v[96:97], v[90:91] op_sel:[1,0,0]
	v_cvt_f32_ubyte0_e32 v102, v83
	v_cvt_f32_ubyte1_e32 v103, v83
	v_pk_fma_f32 v[88:89], v[32:33], v[100:101], v[88:89] op_sel:[1,0,0]
	v_cvt_f32_ubyte2_e32 v126, v83
	v_cvt_f32_ubyte3_e32 v127, v83
	v_pk_fma_f32 v[84:85], v[40:41], v[102:103], v[84:85] op_sel:[1,0,0]
	v_cvt_f32_ubyte0_e32 v96, v86
	v_cvt_f32_ubyte1_e32 v97, v86
	v_pk_fma_f32 v[80:81], v[40:41], v[126:127], v[80:81] op_sel:[1,0,0]
	v_and_b32_e32 v74, s34, v150
	v_and_b32_e32 v75, s35, v150
	v_and_b32_e32 v78, s34, v151
	v_and_b32_e32 v79, s35, v151
	v_cvt_f32_ubyte2_e32 v100, v86
	v_cvt_f32_ubyte3_e32 v101, v86
	v_pk_fma_f32 v[76:77], v[32:33], v[96:97], v[76:77] op_sel:[1,0,0]
	v_cvt_f32_ubyte0_e32 v102, v87
	v_cvt_f32_ubyte1_e32 v103, v87
	v_pk_fma_f32 v[68:69], v[32:33], v[100:101], v[68:69] op_sel:[1,0,0]
	v_cvt_f32_ubyte2_e32 v126, v87
	v_cvt_f32_ubyte3_e32 v127, v87
	v_pk_fma_f32 v[62:63], v[40:41], v[102:103], v[62:63] op_sel:[1,0,0]
	v_cvt_f32_ubyte0_e32 v96, v74
	v_cvt_f32_ubyte1_e32 v97, v74
	v_pk_fma_f32 v[60:61], v[40:41], v[126:127], v[60:61] op_sel:[1,0,0]
	v_cvt_f32_ubyte2_e32 v100, v74
	v_cvt_f32_ubyte3_e32 v101, v74
	v_pk_fma_f32 v[90:91], v[34:35], v[96:97], v[90:91] op_sel_hi:[0,1,1]
	v_cvt_f32_ubyte0_e32 v102, v75
	v_cvt_f32_ubyte1_e32 v103, v75
	v_pk_fma_f32 v[88:89], v[34:35], v[100:101], v[88:89] op_sel_hi:[0,1,1]
	v_cvt_f32_ubyte2_e32 v126, v75
	v_cvt_f32_ubyte3_e32 v127, v75
	v_pk_fma_f32 v[84:85], v[42:43], v[102:103], v[84:85] op_sel_hi:[0,1,1]
	v_cvt_f32_ubyte0_e32 v96, v78
	v_cvt_f32_ubyte1_e32 v97, v78
	v_pk_fma_f32 v[80:81], v[42:43], v[126:127], v[80:81] op_sel_hi:[0,1,1]
	v_and_b32_e32 v82, s34, v152
	v_and_b32_e32 v83, s35, v152
	v_and_b32_e32 v86, s34, v153
	v_and_b32_e32 v87, s35, v153
	v_cvt_f32_ubyte2_e32 v100, v78
	v_cvt_f32_ubyte3_e32 v101, v78
	v_pk_fma_f32 v[76:77], v[34:35], v[96:97], v[76:77] op_sel_hi:[0,1,1]
	v_cvt_f32_ubyte0_e32 v102, v79
	v_cvt_f32_ubyte1_e32 v103, v79
	v_pk_fma_f32 v[68:69], v[34:35], v[100:101], v[68:69] op_sel_hi:[0,1,1]
	v_cvt_f32_ubyte2_e32 v126, v79
	v_cvt_f32_ubyte3_e32 v127, v79
	v_pk_fma_f32 v[62:63], v[42:43], v[102:103], v[62:63] op_sel_hi:[0,1,1]
	v_cvt_f32_ubyte0_e32 v96, v82
	v_cvt_f32_ubyte1_e32 v97, v82
	v_pk_fma_f32 v[60:61], v[42:43], v[126:127], v[60:61] op_sel_hi:[0,1,1]
	v_cvt_f32_ubyte2_e32 v100, v82
	v_cvt_f32_ubyte3_e32 v101, v82
	v_pk_fma_f32 v[90:91], v[34:35], v[96:97], v[90:91] op_sel:[1,0,0]
	v_cvt_f32_ubyte0_e32 v102, v83
	v_cvt_f32_ubyte1_e32 v103, v83
	v_pk_fma_f32 v[88:89], v[34:35], v[100:101], v[88:89] op_sel:[1,0,0]
	v_cvt_f32_ubyte2_e32 v126, v83
	v_cvt_f32_ubyte3_e32 v127, v83
	v_pk_fma_f32 v[84:85], v[42:43], v[102:103], v[84:85] op_sel:[1,0,0]
	v_cvt_f32_ubyte0_e32 v96, v86
	v_cvt_f32_ubyte1_e32 v97, v86
	v_pk_fma_f32 v[80:81], v[42:43], v[126:127], v[80:81] op_sel:[1,0,0]
	v_and_b32_e32 v74, s34, v154
	v_and_b32_e32 v75, s35, v154
	v_and_b32_e32 v78, s34, v155
	v_and_b32_e32 v79, s35, v155
	v_cvt_f32_ubyte2_e32 v100, v86
	v_cvt_f32_ubyte3_e32 v101, v86
	v_pk_fma_f32 v[76:77], v[34:35], v[96:97], v[76:77] op_sel:[1,0,0]
	v_cvt_f32_ubyte0_e32 v102, v87
	v_cvt_f32_ubyte1_e32 v103, v87
	v_pk_fma_f32 v[68:69], v[34:35], v[100:101], v[68:69] op_sel:[1,0,0]
	v_cvt_f32_ubyte2_e32 v126, v87
	v_cvt_f32_ubyte3_e32 v127, v87
	v_pk_fma_f32 v[62:63], v[42:43], v[102:103], v[62:63] op_sel:[1,0,0]
	v_cvt_f32_ubyte0_e32 v96, v74
	v_cvt_f32_ubyte1_e32 v97, v74
	v_pk_fma_f32 v[60:61], v[42:43], v[126:127], v[60:61] op_sel:[1,0,0]
	v_cvt_f32_ubyte2_e32 v100, v74
	v_cvt_f32_ubyte3_e32 v101, v74
	v_pk_fma_f32 v[90:91], v[36:37], v[96:97], v[90:91] op_sel_hi:[0,1,1]
	v_cvt_f32_ubyte0_e32 v102, v75
	v_cvt_f32_ubyte1_e32 v103, v75
	v_pk_fma_f32 v[88:89], v[36:37], v[100:101], v[88:89] op_sel_hi:[0,1,1]
	v_cvt_f32_ubyte2_e32 v126, v75
	v_cvt_f32_ubyte3_e32 v127, v75
	v_pk_fma_f32 v[84:85], v[44:45], v[102:103], v[84:85] op_sel_hi:[0,1,1]
	v_cvt_f32_ubyte0_e32 v96, v78
	v_cvt_f32_ubyte1_e32 v97, v78
	v_pk_fma_f32 v[80:81], v[44:45], v[126:127], v[80:81] op_sel_hi:[0,1,1]
	v_and_b32_e32 v82, s34, v156
	v_and_b32_e32 v83, s35, v156
	v_and_b32_e32 v86, s34, v157
	v_and_b32_e32 v87, s35, v157
	v_cvt_f32_ubyte2_e32 v100, v78
	v_cvt_f32_ubyte3_e32 v101, v78
	v_pk_fma_f32 v[76:77], v[36:37], v[96:97], v[76:77] op_sel_hi:[0,1,1]
	v_cvt_f32_ubyte0_e32 v102, v79
	v_cvt_f32_ubyte1_e32 v103, v79
	v_pk_fma_f32 v[68:69], v[36:37], v[100:101], v[68:69] op_sel_hi:[0,1,1]
	v_cvt_f32_ubyte2_e32 v126, v79
	v_cvt_f32_ubyte3_e32 v127, v79
	v_pk_fma_f32 v[62:63], v[44:45], v[102:103], v[62:63] op_sel_hi:[0,1,1]
	v_cvt_f32_ubyte0_e32 v96, v82
	v_cvt_f32_ubyte1_e32 v97, v82
	v_pk_fma_f32 v[60:61], v[44:45], v[126:127], v[60:61] op_sel_hi:[0,1,1]
	v_cvt_f32_ubyte2_e32 v100, v82
	v_cvt_f32_ubyte3_e32 v101, v82
	v_pk_fma_f32 v[90:91], v[36:37], v[96:97], v[90:91] op_sel:[1,0,0]
	v_cvt_f32_ubyte0_e32 v102, v83
	v_cvt_f32_ubyte1_e32 v103, v83
	v_pk_fma_f32 v[88:89], v[36:37], v[100:101], v[88:89] op_sel:[1,0,0]
	v_cvt_f32_ubyte2_e32 v126, v83
	v_cvt_f32_ubyte3_e32 v127, v83
	v_pk_fma_f32 v[84:85], v[44:45], v[102:103], v[84:85] op_sel:[1,0,0]
	v_cvt_f32_ubyte0_e32 v96, v86
	v_cvt_f32_ubyte1_e32 v97, v86
	v_pk_fma_f32 v[80:81], v[44:45], v[126:127], v[80:81] op_sel:[1,0,0]
	v_and_b32_e32 v74, s34, v158
	v_and_b32_e32 v75, s35, v158
	v_and_b32_e32 v78, s34, v159
	v_and_b32_e32 v79, s35, v159
	v_cvt_f32_ubyte2_e32 v100, v86
	v_cvt_f32_ubyte3_e32 v101, v86
	v_pk_fma_f32 v[76:77], v[36:37], v[96:97], v[76:77] op_sel:[1,0,0]
	v_cvt_f32_ubyte0_e32 v102, v87
	v_cvt_f32_ubyte1_e32 v103, v87
	v_pk_fma_f32 v[68:69], v[36:37], v[100:101], v[68:69] op_sel:[1,0,0]
	v_cvt_f32_ubyte2_e32 v126, v87
	v_cvt_f32_ubyte3_e32 v127, v87
	v_pk_fma_f32 v[62:63], v[44:45], v[102:103], v[62:63] op_sel:[1,0,0]
	v_cvt_f32_ubyte0_e32 v96, v74
	v_cvt_f32_ubyte1_e32 v97, v74
	v_pk_fma_f32 v[60:61], v[44:45], v[126:127], v[60:61] op_sel:[1,0,0]
	v_cvt_f32_ubyte2_e32 v100, v74
	v_cvt_f32_ubyte3_e32 v101, v74
	v_pk_fma_f32 v[90:91], v[38:39], v[96:97], v[90:91] op_sel_hi:[0,1,1]
	v_cvt_f32_ubyte0_e32 v102, v75
	v_cvt_f32_ubyte1_e32 v103, v75
	v_pk_fma_f32 v[88:89], v[38:39], v[100:101], v[88:89] op_sel_hi:[0,1,1]
	v_cvt_f32_ubyte2_e32 v126, v75
	v_cvt_f32_ubyte3_e32 v127, v75
	v_pk_fma_f32 v[84:85], v[46:47], v[102:103], v[84:85] op_sel_hi:[0,1,1]
	v_cvt_f32_ubyte0_e32 v96, v78
	v_cvt_f32_ubyte1_e32 v97, v78
	v_pk_fma_f32 v[80:81], v[46:47], v[126:127], v[80:81] op_sel_hi:[0,1,1]
	v_and_b32_e32 v82, s34, v160
	v_and_b32_e32 v83, s35, v160
	v_and_b32_e32 v86, s34, v161
	v_and_b32_e32 v87, s35, v161
	v_cvt_f32_ubyte2_e32 v100, v78
	v_cvt_f32_ubyte3_e32 v101, v78
	v_pk_fma_f32 v[76:77], v[38:39], v[96:97], v[76:77] op_sel_hi:[0,1,1]
	v_cvt_f32_ubyte0_e32 v102, v79
	v_cvt_f32_ubyte1_e32 v103, v79
	v_pk_fma_f32 v[68:69], v[38:39], v[100:101], v[68:69] op_sel_hi:[0,1,1]
	v_cvt_f32_ubyte2_e32 v126, v79
	v_cvt_f32_ubyte3_e32 v127, v79
	v_pk_fma_f32 v[62:63], v[46:47], v[102:103], v[62:63] op_sel_hi:[0,1,1]
	v_cvt_f32_ubyte0_e32 v96, v82
	v_cvt_f32_ubyte1_e32 v97, v82
	v_pk_fma_f32 v[60:61], v[46:47], v[126:127], v[60:61] op_sel_hi:[0,1,1]
	v_cvt_f32_ubyte2_e32 v100, v82
	v_cvt_f32_ubyte3_e32 v101, v82
	v_pk_fma_f32 v[90:91], v[38:39], v[96:97], v[90:91] op_sel:[1,0,0]
	v_cvt_f32_ubyte0_e32 v102, v83
	v_cvt_f32_ubyte1_e32 v103, v83
	v_pk_fma_f32 v[88:89], v[38:39], v[100:101], v[88:89] op_sel:[1,0,0]
	v_cvt_f32_ubyte2_e32 v126, v83
	v_cvt_f32_ubyte3_e32 v127, v83
	v_pk_fma_f32 v[84:85], v[46:47], v[102:103], v[84:85] op_sel:[1,0,0]
	v_cvt_f32_ubyte0_e32 v96, v86
	v_cvt_f32_ubyte1_e32 v97, v86
	v_pk_fma_f32 v[80:81], v[46:47], v[126:127], v[80:81] op_sel:[1,0,0]
	v_cvt_f32_ubyte2_e32 v100, v86
	v_cvt_f32_ubyte3_e32 v101, v86
	v_pk_fma_f32 v[76:77], v[38:39], v[96:97], v[76:77] op_sel:[1,0,0]
	v_cvt_f32_ubyte0_e32 v102, v87
	v_cvt_f32_ubyte1_e32 v103, v87
	v_pk_fma_f32 v[68:69], v[38:39], v[100:101], v[68:69] op_sel:[1,0,0]
	v_cvt_f32_ubyte2_e32 v126, v87
	v_cvt_f32_ubyte3_e32 v127, v87
	v_pk_fma_f32 v[62:63], v[46:47], v[102:103], v[62:63] op_sel:[1,0,0]
	v_pk_fma_f32 v[60:61], v[46:47], v[126:127], v[60:61] op_sel:[1,0,0]
	s_waitcnt lgkmcnt(0)
	ds_read_b128 v[32:35], v128 offset:960
	ds_read_b128 v[36:39], v128 offset:976
	ds_read_b128 v[40:43], v128 offset:1984
	ds_read_b128 v[44:47], v128 offset:2000
	s_waitcnt vmcnt(16)
	v_and_b32_e32 v74, s34, v162
	v_and_b32_e32 v75, s35, v162
	v_and_b32_e32 v78, s34, v163
	v_and_b32_e32 v79, s35, v163
	v_cvt_f32_ubyte0_e32 v96, v74
	v_cvt_f32_ubyte1_e32 v97, v74
	v_cvt_f32_ubyte2_e32 v100, v74
	v_cvt_f32_ubyte3_e32 v101, v74
	v_pk_fma_f32 v[90:91], v[48:49], v[96:97], v[90:91] op_sel_hi:[0,1,1]
	v_cvt_f32_ubyte0_e32 v102, v75
	v_cvt_f32_ubyte1_e32 v103, v75
	v_pk_fma_f32 v[88:89], v[48:49], v[100:101], v[88:89] op_sel_hi:[0,1,1]
	v_cvt_f32_ubyte2_e32 v126, v75
	v_cvt_f32_ubyte3_e32 v127, v75
	v_pk_fma_f32 v[84:85], v[56:57], v[102:103], v[84:85] op_sel_hi:[0,1,1]
	v_cvt_f32_ubyte0_e32 v96, v78
	v_cvt_f32_ubyte1_e32 v97, v78
	v_pk_fma_f32 v[80:81], v[56:57], v[126:127], v[80:81] op_sel_hi:[0,1,1]
	v_and_b32_e32 v82, s34, v164
	v_and_b32_e32 v83, s35, v164
	v_and_b32_e32 v86, s34, v165
	v_and_b32_e32 v87, s35, v165
	v_cvt_f32_ubyte2_e32 v100, v78
	v_cvt_f32_ubyte3_e32 v101, v78
	v_pk_fma_f32 v[76:77], v[48:49], v[96:97], v[76:77] op_sel_hi:[0,1,1]
	v_cvt_f32_ubyte0_e32 v102, v79
	v_cvt_f32_ubyte1_e32 v103, v79
	v_pk_fma_f32 v[68:69], v[48:49], v[100:101], v[68:69] op_sel_hi:[0,1,1]
	v_cvt_f32_ubyte2_e32 v126, v79
	v_cvt_f32_ubyte3_e32 v127, v79
	v_pk_fma_f32 v[62:63], v[56:57], v[102:103], v[62:63] op_sel_hi:[0,1,1]
	v_cvt_f32_ubyte0_e32 v96, v82
	v_cvt_f32_ubyte1_e32 v97, v82
	v_pk_fma_f32 v[60:61], v[56:57], v[126:127], v[60:61] op_sel_hi:[0,1,1]
	v_cvt_f32_ubyte2_e32 v100, v82
	v_cvt_f32_ubyte3_e32 v101, v82
	v_pk_fma_f32 v[90:91], v[48:49], v[96:97], v[90:91] op_sel:[1,0,0]
	v_cvt_f32_ubyte0_e32 v102, v83
	v_cvt_f32_ubyte1_e32 v103, v83
	v_pk_fma_f32 v[88:89], v[48:49], v[100:101], v[88:89] op_sel:[1,0,0]
	v_cvt_f32_ubyte2_e32 v126, v83
	v_cvt_f32_ubyte3_e32 v127, v83
	v_pk_fma_f32 v[84:85], v[56:57], v[102:103], v[84:85] op_sel:[1,0,0]
	v_cvt_f32_ubyte0_e32 v96, v86
	v_cvt_f32_ubyte1_e32 v97, v86
	v_pk_fma_f32 v[80:81], v[56:57], v[126:127], v[80:81] op_sel:[1,0,0]
	v_and_b32_e32 v74, s34, v166
	v_and_b32_e32 v75, s35, v166
	v_and_b32_e32 v78, s34, v167
	v_and_b32_e32 v79, s35, v167
	v_cvt_f32_ubyte2_e32 v100, v86
	v_cvt_f32_ubyte3_e32 v101, v86
	v_pk_fma_f32 v[76:77], v[48:49], v[96:97], v[76:77] op_sel:[1,0,0]
	v_cvt_f32_ubyte0_e32 v102, v87
	v_cvt_f32_ubyte1_e32 v103, v87
	v_pk_fma_f32 v[68:69], v[48:49], v[100:101], v[68:69] op_sel:[1,0,0]
	v_cvt_f32_ubyte2_e32 v126, v87
	v_cvt_f32_ubyte3_e32 v127, v87
	v_pk_fma_f32 v[62:63], v[56:57], v[102:103], v[62:63] op_sel:[1,0,0]
	v_cvt_f32_ubyte0_e32 v96, v74
	v_cvt_f32_ubyte1_e32 v97, v74
	v_pk_fma_f32 v[60:61], v[56:57], v[126:127], v[60:61] op_sel:[1,0,0]
	v_cvt_f32_ubyte2_e32 v100, v74
	v_cvt_f32_ubyte3_e32 v101, v74
	v_pk_fma_f32 v[90:91], v[50:51], v[96:97], v[90:91] op_sel_hi:[0,1,1]
	v_cvt_f32_ubyte0_e32 v102, v75
	v_cvt_f32_ubyte1_e32 v103, v75
	v_pk_fma_f32 v[88:89], v[50:51], v[100:101], v[88:89] op_sel_hi:[0,1,1]
	v_cvt_f32_ubyte2_e32 v126, v75
	v_cvt_f32_ubyte3_e32 v127, v75
	v_pk_fma_f32 v[84:85], v[58:59], v[102:103], v[84:85] op_sel_hi:[0,1,1]
	v_cvt_f32_ubyte0_e32 v96, v78
	v_cvt_f32_ubyte1_e32 v97, v78
	v_pk_fma_f32 v[80:81], v[58:59], v[126:127], v[80:81] op_sel_hi:[0,1,1]
	v_and_b32_e32 v82, s34, v168
	v_and_b32_e32 v83, s35, v168
	v_and_b32_e32 v86, s34, v169
	v_and_b32_e32 v87, s35, v169
	v_cvt_f32_ubyte2_e32 v100, v78
	v_cvt_f32_ubyte3_e32 v101, v78
	v_pk_fma_f32 v[76:77], v[50:51], v[96:97], v[76:77] op_sel_hi:[0,1,1]
	v_cvt_f32_ubyte0_e32 v102, v79
	v_cvt_f32_ubyte1_e32 v103, v79
	v_pk_fma_f32 v[68:69], v[50:51], v[100:101], v[68:69] op_sel_hi:[0,1,1]
	v_cvt_f32_ubyte2_e32 v126, v79
	v_cvt_f32_ubyte3_e32 v127, v79
	v_pk_fma_f32 v[62:63], v[58:59], v[102:103], v[62:63] op_sel_hi:[0,1,1]
	v_cvt_f32_ubyte0_e32 v96, v82
	v_cvt_f32_ubyte1_e32 v97, v82
	v_pk_fma_f32 v[60:61], v[58:59], v[126:127], v[60:61] op_sel_hi:[0,1,1]
	v_cvt_f32_ubyte2_e32 v100, v82
	v_cvt_f32_ubyte3_e32 v101, v82
	v_pk_fma_f32 v[90:91], v[50:51], v[96:97], v[90:91] op_sel:[1,0,0]
	v_cvt_f32_ubyte0_e32 v102, v83
	v_cvt_f32_ubyte1_e32 v103, v83
	v_pk_fma_f32 v[88:89], v[50:51], v[100:101], v[88:89] op_sel:[1,0,0]
	v_cvt_f32_ubyte2_e32 v126, v83
	v_cvt_f32_ubyte3_e32 v127, v83
	v_pk_fma_f32 v[84:85], v[58:59], v[102:103], v[84:85] op_sel:[1,0,0]
	v_cvt_f32_ubyte0_e32 v96, v86
	v_cvt_f32_ubyte1_e32 v97, v86
	v_pk_fma_f32 v[80:81], v[58:59], v[126:127], v[80:81] op_sel:[1,0,0]
	v_and_b32_e32 v74, s34, v170
	v_and_b32_e32 v75, s35, v170
	v_and_b32_e32 v78, s34, v171
	v_and_b32_e32 v79, s35, v171
	v_cvt_f32_ubyte2_e32 v100, v86
	v_cvt_f32_ubyte3_e32 v101, v86
	v_pk_fma_f32 v[76:77], v[50:51], v[96:97], v[76:77] op_sel:[1,0,0]
	v_cvt_f32_ubyte0_e32 v102, v87
	v_cvt_f32_ubyte1_e32 v103, v87
	v_pk_fma_f32 v[68:69], v[50:51], v[100:101], v[68:69] op_sel:[1,0,0]
	v_cvt_f32_ubyte2_e32 v126, v87
	v_cvt_f32_ubyte3_e32 v127, v87
	v_pk_fma_f32 v[62:63], v[58:59], v[102:103], v[62:63] op_sel:[1,0,0]
	v_cvt_f32_ubyte0_e32 v96, v74
	v_cvt_f32_ubyte1_e32 v97, v74
	v_pk_fma_f32 v[60:61], v[58:59], v[126:127], v[60:61] op_sel:[1,0,0]
	v_cvt_f32_ubyte2_e32 v100, v74
	v_cvt_f32_ubyte3_e32 v101, v74
	v_pk_fma_f32 v[90:91], v[52:53], v[96:97], v[90:91] op_sel_hi:[0,1,1]
	v_cvt_f32_ubyte0_e32 v102, v75
	v_cvt_f32_ubyte1_e32 v103, v75
	v_pk_fma_f32 v[88:89], v[52:53], v[100:101], v[88:89] op_sel_hi:[0,1,1]
	v_cvt_f32_ubyte2_e32 v126, v75
	v_cvt_f32_ubyte3_e32 v127, v75
	v_pk_fma_f32 v[84:85], v[64:65], v[102:103], v[84:85] op_sel_hi:[0,1,1]
	v_cvt_f32_ubyte0_e32 v96, v78
	v_cvt_f32_ubyte1_e32 v97, v78
	v_pk_fma_f32 v[80:81], v[64:65], v[126:127], v[80:81] op_sel_hi:[0,1,1]
	v_and_b32_e32 v82, s34, v172
	v_and_b32_e32 v83, s35, v172
	v_and_b32_e32 v86, s34, v173
	v_and_b32_e32 v87, s35, v173
	v_cvt_f32_ubyte2_e32 v100, v78
	v_cvt_f32_ubyte3_e32 v101, v78
	v_pk_fma_f32 v[76:77], v[52:53], v[96:97], v[76:77] op_sel_hi:[0,1,1]
	v_cvt_f32_ubyte0_e32 v102, v79
	v_cvt_f32_ubyte1_e32 v103, v79
	v_pk_fma_f32 v[68:69], v[52:53], v[100:101], v[68:69] op_sel_hi:[0,1,1]
	v_cvt_f32_ubyte2_e32 v126, v79
	v_cvt_f32_ubyte3_e32 v127, v79
	v_pk_fma_f32 v[62:63], v[64:65], v[102:103], v[62:63] op_sel_hi:[0,1,1]
	v_cvt_f32_ubyte0_e32 v96, v82
	v_cvt_f32_ubyte1_e32 v97, v82
	v_pk_fma_f32 v[60:61], v[64:65], v[126:127], v[60:61] op_sel_hi:[0,1,1]
	v_cvt_f32_ubyte2_e32 v100, v82
	v_cvt_f32_ubyte3_e32 v101, v82
	v_pk_fma_f32 v[90:91], v[52:53], v[96:97], v[90:91] op_sel:[1,0,0]
	v_cvt_f32_ubyte0_e32 v102, v83
	v_cvt_f32_ubyte1_e32 v103, v83
	v_pk_fma_f32 v[88:89], v[52:53], v[100:101], v[88:89] op_sel:[1,0,0]
	v_cvt_f32_ubyte2_e32 v126, v83
	v_cvt_f32_ubyte3_e32 v127, v83
	v_pk_fma_f32 v[84:85], v[64:65], v[102:103], v[84:85] op_sel:[1,0,0]
	v_cvt_f32_ubyte0_e32 v96, v86
	v_cvt_f32_ubyte1_e32 v97, v86
	v_pk_fma_f32 v[80:81], v[64:65], v[126:127], v[80:81] op_sel:[1,0,0]
	v_and_b32_e32 v74, s34, v174
	v_and_b32_e32 v75, s35, v174
	v_and_b32_e32 v78, s34, v175
	v_and_b32_e32 v79, s35, v175
	v_cvt_f32_ubyte2_e32 v100, v86
	v_cvt_f32_ubyte3_e32 v101, v86
	v_pk_fma_f32 v[76:77], v[52:53], v[96:97], v[76:77] op_sel:[1,0,0]
	v_cvt_f32_ubyte0_e32 v102, v87
	v_cvt_f32_ubyte1_e32 v103, v87
	v_pk_fma_f32 v[68:69], v[52:53], v[100:101], v[68:69] op_sel:[1,0,0]
	v_cvt_f32_ubyte2_e32 v126, v87
	v_cvt_f32_ubyte3_e32 v127, v87
	v_pk_fma_f32 v[62:63], v[64:65], v[102:103], v[62:63] op_sel:[1,0,0]
	v_cvt_f32_ubyte0_e32 v96, v74
	v_cvt_f32_ubyte1_e32 v97, v74
	v_pk_fma_f32 v[60:61], v[64:65], v[126:127], v[60:61] op_sel:[1,0,0]
	v_cvt_f32_ubyte2_e32 v100, v74
	v_cvt_f32_ubyte3_e32 v101, v74
	v_pk_fma_f32 v[90:91], v[54:55], v[96:97], v[90:91] op_sel_hi:[0,1,1]
	v_cvt_f32_ubyte0_e32 v102, v75
	v_cvt_f32_ubyte1_e32 v103, v75
	v_pk_fma_f32 v[88:89], v[54:55], v[100:101], v[88:89] op_sel_hi:[0,1,1]
	v_cvt_f32_ubyte2_e32 v126, v75
	v_cvt_f32_ubyte3_e32 v127, v75
	v_pk_fma_f32 v[84:85], v[66:67], v[102:103], v[84:85] op_sel_hi:[0,1,1]
	v_cvt_f32_ubyte0_e32 v96, v78
	v_cvt_f32_ubyte1_e32 v97, v78
	v_pk_fma_f32 v[80:81], v[66:67], v[126:127], v[80:81] op_sel_hi:[0,1,1]
	v_and_b32_e32 v82, s34, v176
	v_and_b32_e32 v83, s35, v176
	v_and_b32_e32 v86, s34, v177
	v_and_b32_e32 v87, s35, v177
	v_cvt_f32_ubyte2_e32 v100, v78
	v_cvt_f32_ubyte3_e32 v101, v78
	v_pk_fma_f32 v[76:77], v[54:55], v[96:97], v[76:77] op_sel_hi:[0,1,1]
	v_cvt_f32_ubyte0_e32 v102, v79
	v_cvt_f32_ubyte1_e32 v103, v79
	v_pk_fma_f32 v[68:69], v[54:55], v[100:101], v[68:69] op_sel_hi:[0,1,1]
	v_cvt_f32_ubyte2_e32 v126, v79
	v_cvt_f32_ubyte3_e32 v127, v79
	v_pk_fma_f32 v[62:63], v[66:67], v[102:103], v[62:63] op_sel_hi:[0,1,1]
	v_cvt_f32_ubyte0_e32 v96, v82
	v_cvt_f32_ubyte1_e32 v97, v82
	v_pk_fma_f32 v[60:61], v[66:67], v[126:127], v[60:61] op_sel_hi:[0,1,1]
	v_cvt_f32_ubyte2_e32 v100, v82
	v_cvt_f32_ubyte3_e32 v101, v82
	v_pk_fma_f32 v[90:91], v[54:55], v[96:97], v[90:91] op_sel:[1,0,0]
	v_cvt_f32_ubyte0_e32 v102, v83
	v_cvt_f32_ubyte1_e32 v103, v83
	v_pk_fma_f32 v[88:89], v[54:55], v[100:101], v[88:89] op_sel:[1,0,0]
	v_cvt_f32_ubyte2_e32 v126, v83
	v_cvt_f32_ubyte3_e32 v127, v83
	v_pk_fma_f32 v[84:85], v[66:67], v[102:103], v[84:85] op_sel:[1,0,0]
	v_cvt_f32_ubyte0_e32 v96, v86
	v_cvt_f32_ubyte1_e32 v97, v86
	v_pk_fma_f32 v[80:81], v[66:67], v[126:127], v[80:81] op_sel:[1,0,0]
	v_cvt_f32_ubyte2_e32 v100, v86
	v_cvt_f32_ubyte3_e32 v101, v86
	v_pk_fma_f32 v[76:77], v[54:55], v[96:97], v[76:77] op_sel:[1,0,0]
	v_cvt_f32_ubyte0_e32 v102, v87
	v_cvt_f32_ubyte1_e32 v103, v87
	v_pk_fma_f32 v[68:69], v[54:55], v[100:101], v[68:69] op_sel:[1,0,0]
	v_cvt_f32_ubyte2_e32 v126, v87
	v_cvt_f32_ubyte3_e32 v127, v87
	v_pk_fma_f32 v[62:63], v[66:67], v[102:103], v[62:63] op_sel:[1,0,0]
	v_pk_fma_f32 v[60:61], v[66:67], v[126:127], v[60:61] op_sel:[1,0,0]
	s_waitcnt lgkmcnt(0)
	ds_read_b128 v[48:51], v128 offset:992
	ds_read_b128 v[52:55], v128 offset:1008
	ds_read_b128 v[56:59], v128 offset:2016
	ds_read_b128 v[64:67], v128 offset:2032
	s_waitcnt vmcnt(8)
	v_and_b32_e32 v74, s34, v178
	v_and_b32_e32 v75, s35, v178
	v_and_b32_e32 v78, s34, v179
	v_and_b32_e32 v79, s35, v179
	v_cvt_f32_ubyte0_e32 v96, v74
	v_cvt_f32_ubyte1_e32 v97, v74
	v_cvt_f32_ubyte2_e32 v100, v74
	v_cvt_f32_ubyte3_e32 v101, v74
	v_pk_fma_f32 v[90:91], v[32:33], v[96:97], v[90:91] op_sel_hi:[0,1,1]
	v_cvt_f32_ubyte0_e32 v102, v75
	v_cvt_f32_ubyte1_e32 v103, v75
	v_pk_fma_f32 v[88:89], v[32:33], v[100:101], v[88:89] op_sel_hi:[0,1,1]
	v_cvt_f32_ubyte2_e32 v126, v75
	v_cvt_f32_ubyte3_e32 v127, v75
	v_pk_fma_f32 v[84:85], v[40:41], v[102:103], v[84:85] op_sel_hi:[0,1,1]
	v_cvt_f32_ubyte0_e32 v96, v78
	v_cvt_f32_ubyte1_e32 v97, v78
	v_pk_fma_f32 v[80:81], v[40:41], v[126:127], v[80:81] op_sel_hi:[0,1,1]
	v_and_b32_e32 v82, s34, v180
	v_and_b32_e32 v83, s35, v180
	v_and_b32_e32 v86, s34, v181
	v_and_b32_e32 v87, s35, v181
	v_cvt_f32_ubyte2_e32 v100, v78
	v_cvt_f32_ubyte3_e32 v101, v78
	v_pk_fma_f32 v[76:77], v[32:33], v[96:97], v[76:77] op_sel_hi:[0,1,1]
	v_cvt_f32_ubyte0_e32 v102, v79
	v_cvt_f32_ubyte1_e32 v103, v79
	v_pk_fma_f32 v[68:69], v[32:33], v[100:101], v[68:69] op_sel_hi:[0,1,1]
	v_cvt_f32_ubyte2_e32 v126, v79
	v_cvt_f32_ubyte3_e32 v127, v79
	v_pk_fma_f32 v[62:63], v[40:41], v[102:103], v[62:63] op_sel_hi:[0,1,1]
	v_cvt_f32_ubyte0_e32 v96, v82
	v_cvt_f32_ubyte1_e32 v97, v82
	v_pk_fma_f32 v[60:61], v[40:41], v[126:127], v[60:61] op_sel_hi:[0,1,1]
	v_cvt_f32_ubyte2_e32 v100, v82
	v_cvt_f32_ubyte3_e32 v101, v82
	v_pk_fma_f32 v[90:91], v[32:33], v[96:97], v[90:91] op_sel:[1,0,0]
	v_cvt_f32_ubyte0_e32 v102, v83
	v_cvt_f32_ubyte1_e32 v103, v83
	v_pk_fma_f32 v[88:89], v[32:33], v[100:101], v[88:89] op_sel:[1,0,0]
	v_cvt_f32_ubyte2_e32 v126, v83
	v_cvt_f32_ubyte3_e32 v127, v83
	v_pk_fma_f32 v[84:85], v[40:41], v[102:103], v[84:85] op_sel:[1,0,0]
	v_cvt_f32_ubyte0_e32 v96, v86
	v_cvt_f32_ubyte1_e32 v97, v86
	v_pk_fma_f32 v[80:81], v[40:41], v[126:127], v[80:81] op_sel:[1,0,0]
	v_and_b32_e32 v74, s34, v182
	v_and_b32_e32 v75, s35, v182
	v_and_b32_e32 v78, s34, v183
	v_and_b32_e32 v79, s35, v183
	v_cvt_f32_ubyte2_e32 v100, v86
	v_cvt_f32_ubyte3_e32 v101, v86
	v_pk_fma_f32 v[76:77], v[32:33], v[96:97], v[76:77] op_sel:[1,0,0]
	v_cvt_f32_ubyte0_e32 v102, v87
	v_cvt_f32_ubyte1_e32 v103, v87
	v_pk_fma_f32 v[68:69], v[32:33], v[100:101], v[68:69] op_sel:[1,0,0]
	v_cvt_f32_ubyte2_e32 v126, v87
	v_cvt_f32_ubyte3_e32 v127, v87
	v_pk_fma_f32 v[62:63], v[40:41], v[102:103], v[62:63] op_sel:[1,0,0]
	v_cvt_f32_ubyte0_e32 v96, v74
	v_cvt_f32_ubyte1_e32 v97, v74
	v_pk_fma_f32 v[60:61], v[40:41], v[126:127], v[60:61] op_sel:[1,0,0]
	v_cvt_f32_ubyte2_e32 v100, v74
	v_cvt_f32_ubyte3_e32 v101, v74
	v_pk_fma_f32 v[90:91], v[34:35], v[96:97], v[90:91] op_sel_hi:[0,1,1]
	v_cvt_f32_ubyte0_e32 v102, v75
	v_cvt_f32_ubyte1_e32 v103, v75
	v_pk_fma_f32 v[88:89], v[34:35], v[100:101], v[88:89] op_sel_hi:[0,1,1]
	v_cvt_f32_ubyte2_e32 v126, v75
	v_cvt_f32_ubyte3_e32 v127, v75
	v_pk_fma_f32 v[84:85], v[42:43], v[102:103], v[84:85] op_sel_hi:[0,1,1]
	v_cvt_f32_ubyte0_e32 v96, v78
	v_cvt_f32_ubyte1_e32 v97, v78
	v_pk_fma_f32 v[80:81], v[42:43], v[126:127], v[80:81] op_sel_hi:[0,1,1]
	v_and_b32_e32 v82, s34, v184
	v_and_b32_e32 v83, s35, v184
	v_and_b32_e32 v86, s34, v185
	v_and_b32_e32 v87, s35, v185
	v_cvt_f32_ubyte2_e32 v100, v78
	v_cvt_f32_ubyte3_e32 v101, v78
	v_pk_fma_f32 v[76:77], v[34:35], v[96:97], v[76:77] op_sel_hi:[0,1,1]
	v_cvt_f32_ubyte0_e32 v102, v79
	v_cvt_f32_ubyte1_e32 v103, v79
	v_pk_fma_f32 v[68:69], v[34:35], v[100:101], v[68:69] op_sel_hi:[0,1,1]
	v_cvt_f32_ubyte2_e32 v126, v79
	v_cvt_f32_ubyte3_e32 v127, v79
	v_pk_fma_f32 v[62:63], v[42:43], v[102:103], v[62:63] op_sel_hi:[0,1,1]
	v_cvt_f32_ubyte0_e32 v96, v82
	v_cvt_f32_ubyte1_e32 v97, v82
	v_pk_fma_f32 v[60:61], v[42:43], v[126:127], v[60:61] op_sel_hi:[0,1,1]
	v_cvt_f32_ubyte2_e32 v100, v82
	v_cvt_f32_ubyte3_e32 v101, v82
	v_pk_fma_f32 v[90:91], v[34:35], v[96:97], v[90:91] op_sel:[1,0,0]
	v_cvt_f32_ubyte0_e32 v102, v83
	v_cvt_f32_ubyte1_e32 v103, v83
	v_pk_fma_f32 v[88:89], v[34:35], v[100:101], v[88:89] op_sel:[1,0,0]
	v_cvt_f32_ubyte2_e32 v126, v83
	v_cvt_f32_ubyte3_e32 v127, v83
	v_pk_fma_f32 v[84:85], v[42:43], v[102:103], v[84:85] op_sel:[1,0,0]
	v_cvt_f32_ubyte0_e32 v96, v86
	v_cvt_f32_ubyte1_e32 v97, v86
	v_pk_fma_f32 v[80:81], v[42:43], v[126:127], v[80:81] op_sel:[1,0,0]
	v_and_b32_e32 v74, s34, v186
	v_and_b32_e32 v75, s35, v186
	v_and_b32_e32 v78, s34, v187
	v_and_b32_e32 v79, s35, v187
	v_cvt_f32_ubyte2_e32 v100, v86
	v_cvt_f32_ubyte3_e32 v101, v86
	v_pk_fma_f32 v[76:77], v[34:35], v[96:97], v[76:77] op_sel:[1,0,0]
	v_cvt_f32_ubyte0_e32 v102, v87
	v_cvt_f32_ubyte1_e32 v103, v87
	v_pk_fma_f32 v[68:69], v[34:35], v[100:101], v[68:69] op_sel:[1,0,0]
	v_cvt_f32_ubyte2_e32 v126, v87
	v_cvt_f32_ubyte3_e32 v127, v87
	v_pk_fma_f32 v[62:63], v[42:43], v[102:103], v[62:63] op_sel:[1,0,0]
	v_cvt_f32_ubyte0_e32 v96, v74
	v_cvt_f32_ubyte1_e32 v97, v74
	v_pk_fma_f32 v[60:61], v[42:43], v[126:127], v[60:61] op_sel:[1,0,0]
	v_cvt_f32_ubyte2_e32 v100, v74
	v_cvt_f32_ubyte3_e32 v101, v74
	v_pk_fma_f32 v[90:91], v[36:37], v[96:97], v[90:91] op_sel_hi:[0,1,1]
	v_cvt_f32_ubyte0_e32 v102, v75
	v_cvt_f32_ubyte1_e32 v103, v75
	v_pk_fma_f32 v[88:89], v[36:37], v[100:101], v[88:89] op_sel_hi:[0,1,1]
	v_cvt_f32_ubyte2_e32 v126, v75
	v_cvt_f32_ubyte3_e32 v127, v75
	v_pk_fma_f32 v[84:85], v[44:45], v[102:103], v[84:85] op_sel_hi:[0,1,1]
	v_cvt_f32_ubyte0_e32 v96, v78
	v_cvt_f32_ubyte1_e32 v97, v78
	v_pk_fma_f32 v[80:81], v[44:45], v[126:127], v[80:81] op_sel_hi:[0,1,1]
	v_and_b32_e32 v82, s34, v188
	v_and_b32_e32 v83, s35, v188
	v_and_b32_e32 v86, s34, v189
	v_and_b32_e32 v87, s35, v189
	v_cvt_f32_ubyte2_e32 v100, v78
	v_cvt_f32_ubyte3_e32 v101, v78
	v_pk_fma_f32 v[76:77], v[36:37], v[96:97], v[76:77] op_sel_hi:[0,1,1]
	v_cvt_f32_ubyte0_e32 v102, v79
	v_cvt_f32_ubyte1_e32 v103, v79
	v_pk_fma_f32 v[68:69], v[36:37], v[100:101], v[68:69] op_sel_hi:[0,1,1]
	v_cvt_f32_ubyte2_e32 v126, v79
	v_cvt_f32_ubyte3_e32 v127, v79
	v_pk_fma_f32 v[62:63], v[44:45], v[102:103], v[62:63] op_sel_hi:[0,1,1]
	v_cvt_f32_ubyte0_e32 v96, v82
	v_cvt_f32_ubyte1_e32 v97, v82
	v_pk_fma_f32 v[60:61], v[44:45], v[126:127], v[60:61] op_sel_hi:[0,1,1]
	v_cvt_f32_ubyte2_e32 v100, v82
	v_cvt_f32_ubyte3_e32 v101, v82
	v_pk_fma_f32 v[90:91], v[36:37], v[96:97], v[90:91] op_sel:[1,0,0]
	v_cvt_f32_ubyte0_e32 v102, v83
	v_cvt_f32_ubyte1_e32 v103, v83
	v_pk_fma_f32 v[88:89], v[36:37], v[100:101], v[88:89] op_sel:[1,0,0]
	v_cvt_f32_ubyte2_e32 v126, v83
	v_cvt_f32_ubyte3_e32 v127, v83
	v_pk_fma_f32 v[84:85], v[44:45], v[102:103], v[84:85] op_sel:[1,0,0]
	v_cvt_f32_ubyte0_e32 v96, v86
	v_cvt_f32_ubyte1_e32 v97, v86
	v_pk_fma_f32 v[80:81], v[44:45], v[126:127], v[80:81] op_sel:[1,0,0]
	v_and_b32_e32 v74, s34, v190
	v_and_b32_e32 v75, s35, v190
	v_and_b32_e32 v78, s34, v191
	v_and_b32_e32 v79, s35, v191
	v_cvt_f32_ubyte2_e32 v100, v86
	v_cvt_f32_ubyte3_e32 v101, v86
	v_pk_fma_f32 v[76:77], v[36:37], v[96:97], v[76:77] op_sel:[1,0,0]
	v_cvt_f32_ubyte0_e32 v102, v87
	v_cvt_f32_ubyte1_e32 v103, v87
	v_pk_fma_f32 v[68:69], v[36:37], v[100:101], v[68:69] op_sel:[1,0,0]
	v_cvt_f32_ubyte2_e32 v126, v87
	v_cvt_f32_ubyte3_e32 v127, v87
	v_pk_fma_f32 v[62:63], v[44:45], v[102:103], v[62:63] op_sel:[1,0,0]
	v_cvt_f32_ubyte0_e32 v96, v74
	v_cvt_f32_ubyte1_e32 v97, v74
	v_pk_fma_f32 v[60:61], v[44:45], v[126:127], v[60:61] op_sel:[1,0,0]
	v_cvt_f32_ubyte2_e32 v100, v74
	v_cvt_f32_ubyte3_e32 v101, v74
	v_pk_fma_f32 v[90:91], v[38:39], v[96:97], v[90:91] op_sel_hi:[0,1,1]
	v_cvt_f32_ubyte0_e32 v102, v75
	v_cvt_f32_ubyte1_e32 v103, v75
	v_pk_fma_f32 v[88:89], v[38:39], v[100:101], v[88:89] op_sel_hi:[0,1,1]
	v_cvt_f32_ubyte2_e32 v126, v75
	v_cvt_f32_ubyte3_e32 v127, v75
	v_pk_fma_f32 v[84:85], v[46:47], v[102:103], v[84:85] op_sel_hi:[0,1,1]
	v_cvt_f32_ubyte0_e32 v96, v78
	v_cvt_f32_ubyte1_e32 v97, v78
	v_pk_fma_f32 v[80:81], v[46:47], v[126:127], v[80:81] op_sel_hi:[0,1,1]
	v_and_b32_e32 v82, s34, v192
	v_and_b32_e32 v83, s35, v192
	v_and_b32_e32 v86, s34, v193
	v_and_b32_e32 v87, s35, v193
	v_cvt_f32_ubyte2_e32 v100, v78
	v_cvt_f32_ubyte3_e32 v101, v78
	v_pk_fma_f32 v[76:77], v[38:39], v[96:97], v[76:77] op_sel_hi:[0,1,1]
	v_cvt_f32_ubyte0_e32 v102, v79
	v_cvt_f32_ubyte1_e32 v103, v79
	v_pk_fma_f32 v[68:69], v[38:39], v[100:101], v[68:69] op_sel_hi:[0,1,1]
	v_cvt_f32_ubyte2_e32 v126, v79
	v_cvt_f32_ubyte3_e32 v127, v79
	v_pk_fma_f32 v[62:63], v[46:47], v[102:103], v[62:63] op_sel_hi:[0,1,1]
	v_cvt_f32_ubyte0_e32 v96, v82
	v_cvt_f32_ubyte1_e32 v97, v82
	v_pk_fma_f32 v[60:61], v[46:47], v[126:127], v[60:61] op_sel_hi:[0,1,1]
	v_cvt_f32_ubyte2_e32 v100, v82
	v_cvt_f32_ubyte3_e32 v101, v82
	v_pk_fma_f32 v[90:91], v[38:39], v[96:97], v[90:91] op_sel:[1,0,0]
	v_cvt_f32_ubyte0_e32 v102, v83
	v_cvt_f32_ubyte1_e32 v103, v83
	v_pk_fma_f32 v[88:89], v[38:39], v[100:101], v[88:89] op_sel:[1,0,0]
	v_cvt_f32_ubyte2_e32 v126, v83
	v_cvt_f32_ubyte3_e32 v127, v83
	v_pk_fma_f32 v[84:85], v[46:47], v[102:103], v[84:85] op_sel:[1,0,0]
	v_cvt_f32_ubyte0_e32 v96, v86
	v_cvt_f32_ubyte1_e32 v97, v86
	v_pk_fma_f32 v[80:81], v[46:47], v[126:127], v[80:81] op_sel:[1,0,0]
	v_cvt_f32_ubyte2_e32 v100, v86
	v_cvt_f32_ubyte3_e32 v101, v86
	v_pk_fma_f32 v[76:77], v[38:39], v[96:97], v[76:77] op_sel:[1,0,0]
	v_cvt_f32_ubyte0_e32 v102, v87
	v_cvt_f32_ubyte1_e32 v103, v87
	v_pk_fma_f32 v[68:69], v[38:39], v[100:101], v[68:69] op_sel:[1,0,0]
	v_cvt_f32_ubyte2_e32 v126, v87
	v_cvt_f32_ubyte3_e32 v127, v87
	v_pk_fma_f32 v[62:63], v[46:47], v[102:103], v[62:63] op_sel:[1,0,0]
	v_pk_fma_f32 v[60:61], v[46:47], v[126:127], v[60:61] op_sel:[1,0,0]
	s_waitcnt lgkmcnt(0)
	s_waitcnt vmcnt(0)
	v_and_b32_e32 v74, s34, v194
	v_and_b32_e32 v75, s35, v194
	v_and_b32_e32 v78, s34, v195
	v_and_b32_e32 v79, s35, v195
	v_cvt_f32_ubyte0_e32 v96, v74
	v_cvt_f32_ubyte1_e32 v97, v74
	v_cvt_f32_ubyte2_e32 v100, v74
	v_cvt_f32_ubyte3_e32 v101, v74
	v_pk_fma_f32 v[90:91], v[48:49], v[96:97], v[90:91] op_sel_hi:[0,1,1]
	v_cvt_f32_ubyte0_e32 v102, v75
	v_cvt_f32_ubyte1_e32 v103, v75
	v_pk_fma_f32 v[88:89], v[48:49], v[100:101], v[88:89] op_sel_hi:[0,1,1]
	v_cvt_f32_ubyte2_e32 v126, v75
	v_cvt_f32_ubyte3_e32 v127, v75
	v_pk_fma_f32 v[84:85], v[56:57], v[102:103], v[84:85] op_sel_hi:[0,1,1]
	v_cvt_f32_ubyte0_e32 v96, v78
	v_cvt_f32_ubyte1_e32 v97, v78
	v_pk_fma_f32 v[80:81], v[56:57], v[126:127], v[80:81] op_sel_hi:[0,1,1]
	v_and_b32_e32 v82, s34, v196
	v_and_b32_e32 v83, s35, v196
	v_and_b32_e32 v86, s34, v197
	v_and_b32_e32 v87, s35, v197
	v_cvt_f32_ubyte2_e32 v100, v78
	v_cvt_f32_ubyte3_e32 v101, v78
	v_pk_fma_f32 v[76:77], v[48:49], v[96:97], v[76:77] op_sel_hi:[0,1,1]
	v_cvt_f32_ubyte0_e32 v102, v79
	v_cvt_f32_ubyte1_e32 v103, v79
	v_pk_fma_f32 v[68:69], v[48:49], v[100:101], v[68:69] op_sel_hi:[0,1,1]
	v_cvt_f32_ubyte2_e32 v126, v79
	v_cvt_f32_ubyte3_e32 v127, v79
	v_pk_fma_f32 v[62:63], v[56:57], v[102:103], v[62:63] op_sel_hi:[0,1,1]
	v_cvt_f32_ubyte0_e32 v96, v82
	v_cvt_f32_ubyte1_e32 v97, v82
	v_pk_fma_f32 v[60:61], v[56:57], v[126:127], v[60:61] op_sel_hi:[0,1,1]
	v_cvt_f32_ubyte2_e32 v100, v82
	v_cvt_f32_ubyte3_e32 v101, v82
	v_pk_fma_f32 v[90:91], v[48:49], v[96:97], v[90:91] op_sel:[1,0,0]
	v_cvt_f32_ubyte0_e32 v102, v83
	v_cvt_f32_ubyte1_e32 v103, v83
	v_pk_fma_f32 v[88:89], v[48:49], v[100:101], v[88:89] op_sel:[1,0,0]
	v_cvt_f32_ubyte2_e32 v126, v83
	v_cvt_f32_ubyte3_e32 v127, v83
	v_pk_fma_f32 v[84:85], v[56:57], v[102:103], v[84:85] op_sel:[1,0,0]
	v_cvt_f32_ubyte0_e32 v96, v86
	v_cvt_f32_ubyte1_e32 v97, v86
	v_pk_fma_f32 v[80:81], v[56:57], v[126:127], v[80:81] op_sel:[1,0,0]
	v_and_b32_e32 v74, s34, v198
	v_and_b32_e32 v75, s35, v198
	v_and_b32_e32 v78, s34, v199
	v_and_b32_e32 v79, s35, v199
	v_cvt_f32_ubyte2_e32 v100, v86
	v_cvt_f32_ubyte3_e32 v101, v86
	v_pk_fma_f32 v[76:77], v[48:49], v[96:97], v[76:77] op_sel:[1,0,0]
	v_cvt_f32_ubyte0_e32 v102, v87
	v_cvt_f32_ubyte1_e32 v103, v87
	v_pk_fma_f32 v[68:69], v[48:49], v[100:101], v[68:69] op_sel:[1,0,0]
	v_cvt_f32_ubyte2_e32 v126, v87
	v_cvt_f32_ubyte3_e32 v127, v87
	v_pk_fma_f32 v[62:63], v[56:57], v[102:103], v[62:63] op_sel:[1,0,0]
	v_cvt_f32_ubyte0_e32 v96, v74
	v_cvt_f32_ubyte1_e32 v97, v74
	v_pk_fma_f32 v[60:61], v[56:57], v[126:127], v[60:61] op_sel:[1,0,0]
	v_cvt_f32_ubyte2_e32 v100, v74
	v_cvt_f32_ubyte3_e32 v101, v74
	v_pk_fma_f32 v[90:91], v[50:51], v[96:97], v[90:91] op_sel_hi:[0,1,1]
	v_cvt_f32_ubyte0_e32 v102, v75
	v_cvt_f32_ubyte1_e32 v103, v75
	v_pk_fma_f32 v[88:89], v[50:51], v[100:101], v[88:89] op_sel_hi:[0,1,1]
	v_cvt_f32_ubyte2_e32 v126, v75
	v_cvt_f32_ubyte3_e32 v127, v75
	v_pk_fma_f32 v[84:85], v[58:59], v[102:103], v[84:85] op_sel_hi:[0,1,1]
	v_cvt_f32_ubyte0_e32 v96, v78
	v_cvt_f32_ubyte1_e32 v97, v78
	v_pk_fma_f32 v[80:81], v[58:59], v[126:127], v[80:81] op_sel_hi:[0,1,1]
	v_and_b32_e32 v82, s34, v200
	v_and_b32_e32 v83, s35, v200
	v_and_b32_e32 v86, s34, v201
	v_and_b32_e32 v87, s35, v201
	v_cvt_f32_ubyte2_e32 v100, v78
	v_cvt_f32_ubyte3_e32 v101, v78
	v_pk_fma_f32 v[76:77], v[50:51], v[96:97], v[76:77] op_sel_hi:[0,1,1]
	v_cvt_f32_ubyte0_e32 v102, v79
	v_cvt_f32_ubyte1_e32 v103, v79
	v_pk_fma_f32 v[68:69], v[50:51], v[100:101], v[68:69] op_sel_hi:[0,1,1]
	v_cvt_f32_ubyte2_e32 v126, v79
	v_cvt_f32_ubyte3_e32 v127, v79
	v_pk_fma_f32 v[62:63], v[58:59], v[102:103], v[62:63] op_sel_hi:[0,1,1]
	v_cvt_f32_ubyte0_e32 v96, v82
	v_cvt_f32_ubyte1_e32 v97, v82
	v_pk_fma_f32 v[60:61], v[58:59], v[126:127], v[60:61] op_sel_hi:[0,1,1]
	v_cvt_f32_ubyte2_e32 v100, v82
	v_cvt_f32_ubyte3_e32 v101, v82
	v_pk_fma_f32 v[90:91], v[50:51], v[96:97], v[90:91] op_sel:[1,0,0]
	v_cvt_f32_ubyte0_e32 v102, v83
	v_cvt_f32_ubyte1_e32 v103, v83
	v_pk_fma_f32 v[88:89], v[50:51], v[100:101], v[88:89] op_sel:[1,0,0]
	v_cvt_f32_ubyte2_e32 v126, v83
	v_cvt_f32_ubyte3_e32 v127, v83
	v_pk_fma_f32 v[84:85], v[58:59], v[102:103], v[84:85] op_sel:[1,0,0]
	v_cvt_f32_ubyte0_e32 v96, v86
	v_cvt_f32_ubyte1_e32 v97, v86
	v_pk_fma_f32 v[80:81], v[58:59], v[126:127], v[80:81] op_sel:[1,0,0]
	v_and_b32_e32 v74, s34, v202
	v_and_b32_e32 v75, s35, v202
	v_and_b32_e32 v78, s34, v203
	v_and_b32_e32 v79, s35, v203
	v_cvt_f32_ubyte2_e32 v100, v86
	v_cvt_f32_ubyte3_e32 v101, v86
	v_pk_fma_f32 v[76:77], v[50:51], v[96:97], v[76:77] op_sel:[1,0,0]
	v_cvt_f32_ubyte0_e32 v102, v87
	v_cvt_f32_ubyte1_e32 v103, v87
	v_pk_fma_f32 v[68:69], v[50:51], v[100:101], v[68:69] op_sel:[1,0,0]
	v_cvt_f32_ubyte2_e32 v126, v87
	v_cvt_f32_ubyte3_e32 v127, v87
	v_pk_fma_f32 v[62:63], v[58:59], v[102:103], v[62:63] op_sel:[1,0,0]
	v_cvt_f32_ubyte0_e32 v96, v74
	v_cvt_f32_ubyte1_e32 v97, v74
	v_pk_fma_f32 v[60:61], v[58:59], v[126:127], v[60:61] op_sel:[1,0,0]
	v_cvt_f32_ubyte2_e32 v100, v74
	v_cvt_f32_ubyte3_e32 v101, v74
	v_pk_fma_f32 v[90:91], v[52:53], v[96:97], v[90:91] op_sel_hi:[0,1,1]
	v_cvt_f32_ubyte0_e32 v102, v75
	v_cvt_f32_ubyte1_e32 v103, v75
	v_pk_fma_f32 v[88:89], v[52:53], v[100:101], v[88:89] op_sel_hi:[0,1,1]
	v_cvt_f32_ubyte2_e32 v126, v75
	v_cvt_f32_ubyte3_e32 v127, v75
	v_pk_fma_f32 v[84:85], v[64:65], v[102:103], v[84:85] op_sel_hi:[0,1,1]
	v_cvt_f32_ubyte0_e32 v96, v78
	v_cvt_f32_ubyte1_e32 v97, v78
	v_pk_fma_f32 v[80:81], v[64:65], v[126:127], v[80:81] op_sel_hi:[0,1,1]
	v_and_b32_e32 v82, s34, v204
	v_and_b32_e32 v83, s35, v204
	v_and_b32_e32 v86, s34, v205
	v_and_b32_e32 v87, s35, v205
	v_cvt_f32_ubyte2_e32 v100, v78
	v_cvt_f32_ubyte3_e32 v101, v78
	v_pk_fma_f32 v[76:77], v[52:53], v[96:97], v[76:77] op_sel_hi:[0,1,1]
	v_cvt_f32_ubyte0_e32 v102, v79
	v_cvt_f32_ubyte1_e32 v103, v79
	v_pk_fma_f32 v[68:69], v[52:53], v[100:101], v[68:69] op_sel_hi:[0,1,1]
	v_cvt_f32_ubyte2_e32 v126, v79
	v_cvt_f32_ubyte3_e32 v127, v79
	v_pk_fma_f32 v[62:63], v[64:65], v[102:103], v[62:63] op_sel_hi:[0,1,1]
	v_cvt_f32_ubyte0_e32 v96, v82
	v_cvt_f32_ubyte1_e32 v97, v82
	v_pk_fma_f32 v[60:61], v[64:65], v[126:127], v[60:61] op_sel_hi:[0,1,1]
	v_cvt_f32_ubyte2_e32 v100, v82
	v_cvt_f32_ubyte3_e32 v101, v82
	v_pk_fma_f32 v[90:91], v[52:53], v[96:97], v[90:91] op_sel:[1,0,0]
	v_cvt_f32_ubyte0_e32 v102, v83
	v_cvt_f32_ubyte1_e32 v103, v83
	v_pk_fma_f32 v[88:89], v[52:53], v[100:101], v[88:89] op_sel:[1,0,0]
	v_cvt_f32_ubyte2_e32 v126, v83
	v_cvt_f32_ubyte3_e32 v127, v83
	v_pk_fma_f32 v[84:85], v[64:65], v[102:103], v[84:85] op_sel:[1,0,0]
	v_cvt_f32_ubyte0_e32 v96, v86
	v_cvt_f32_ubyte1_e32 v97, v86
	v_pk_fma_f32 v[80:81], v[64:65], v[126:127], v[80:81] op_sel:[1,0,0]
	v_and_b32_e32 v74, s34, v206
	v_and_b32_e32 v75, s35, v206
	v_and_b32_e32 v78, s34, v207
	v_and_b32_e32 v79, s35, v207
	v_cvt_f32_ubyte2_e32 v100, v86
	v_cvt_f32_ubyte3_e32 v101, v86
	v_pk_fma_f32 v[76:77], v[52:53], v[96:97], v[76:77] op_sel:[1,0,0]
	v_cvt_f32_ubyte0_e32 v102, v87
	v_cvt_f32_ubyte1_e32 v103, v87
	v_pk_fma_f32 v[68:69], v[52:53], v[100:101], v[68:69] op_sel:[1,0,0]
	v_cvt_f32_ubyte2_e32 v126, v87
	v_cvt_f32_ubyte3_e32 v127, v87
	v_pk_fma_f32 v[62:63], v[64:65], v[102:103], v[62:63] op_sel:[1,0,0]
	v_cvt_f32_ubyte0_e32 v96, v74
	v_cvt_f32_ubyte1_e32 v97, v74
	v_pk_fma_f32 v[60:61], v[64:65], v[126:127], v[60:61] op_sel:[1,0,0]
	v_cvt_f32_ubyte2_e32 v100, v74
	v_cvt_f32_ubyte3_e32 v101, v74
	v_pk_fma_f32 v[90:91], v[54:55], v[96:97], v[90:91] op_sel_hi:[0,1,1]
	v_cvt_f32_ubyte0_e32 v102, v75
	v_cvt_f32_ubyte1_e32 v103, v75
	v_pk_fma_f32 v[88:89], v[54:55], v[100:101], v[88:89] op_sel_hi:[0,1,1]
	v_cvt_f32_ubyte2_e32 v126, v75
	v_cvt_f32_ubyte3_e32 v127, v75
	v_pk_fma_f32 v[84:85], v[66:67], v[102:103], v[84:85] op_sel_hi:[0,1,1]
	v_cvt_f32_ubyte0_e32 v96, v78
	v_cvt_f32_ubyte1_e32 v97, v78
	v_pk_fma_f32 v[80:81], v[66:67], v[126:127], v[80:81] op_sel_hi:[0,1,1]
	v_and_b32_e32 v82, s34, v208
	v_and_b32_e32 v83, s35, v208
	v_and_b32_e32 v86, s34, v209
	v_and_b32_e32 v87, s35, v209
	v_cvt_f32_ubyte2_e32 v100, v78
	v_cvt_f32_ubyte3_e32 v101, v78
	v_pk_fma_f32 v[76:77], v[54:55], v[96:97], v[76:77] op_sel_hi:[0,1,1]
	v_cvt_f32_ubyte0_e32 v102, v79
	v_cvt_f32_ubyte1_e32 v103, v79
	v_pk_fma_f32 v[68:69], v[54:55], v[100:101], v[68:69] op_sel_hi:[0,1,1]
	v_cvt_f32_ubyte2_e32 v126, v79
	v_cvt_f32_ubyte3_e32 v127, v79
	v_pk_fma_f32 v[62:63], v[66:67], v[102:103], v[62:63] op_sel_hi:[0,1,1]
	v_cvt_f32_ubyte0_e32 v96, v82
	v_cvt_f32_ubyte1_e32 v97, v82
	v_pk_fma_f32 v[60:61], v[66:67], v[126:127], v[60:61] op_sel_hi:[0,1,1]
	v_cvt_f32_ubyte2_e32 v100, v82
	v_cvt_f32_ubyte3_e32 v101, v82
	v_pk_fma_f32 v[90:91], v[54:55], v[96:97], v[90:91] op_sel:[1,0,0]
	v_cvt_f32_ubyte0_e32 v102, v83
	v_cvt_f32_ubyte1_e32 v103, v83
	v_pk_fma_f32 v[88:89], v[54:55], v[100:101], v[88:89] op_sel:[1,0,0]
	v_cvt_f32_ubyte2_e32 v126, v83
	v_cvt_f32_ubyte3_e32 v127, v83
	v_pk_fma_f32 v[84:85], v[66:67], v[102:103], v[84:85] op_sel:[1,0,0]
	v_cvt_f32_ubyte0_e32 v96, v86
	v_cvt_f32_ubyte1_e32 v97, v86
	v_pk_fma_f32 v[80:81], v[66:67], v[126:127], v[80:81] op_sel:[1,0,0]
	v_cvt_f32_ubyte2_e32 v100, v86
	v_cvt_f32_ubyte3_e32 v101, v86
	v_pk_fma_f32 v[76:77], v[54:55], v[96:97], v[76:77] op_sel:[1,0,0]
	v_cvt_f32_ubyte0_e32 v102, v87
	v_cvt_f32_ubyte1_e32 v103, v87
	v_pk_fma_f32 v[68:69], v[54:55], v[100:101], v[68:69] op_sel:[1,0,0]
	v_cvt_f32_ubyte2_e32 v126, v87
	v_cvt_f32_ubyte3_e32 v127, v87
	v_pk_fma_f32 v[62:63], v[66:67], v[102:103], v[62:63] op_sel:[1,0,0]
	v_pk_fma_f32 v[60:61], v[66:67], v[126:127], v[60:61] op_sel:[1,0,0]
	s_waitcnt lgkmcnt(0)
	s_branch .LBB0_979
